# GEMM loops: removed the redundant s_waitcnt lgkmcnt(0) between the pre-MFMA barrier and the first MFMA (104 sites), on top of the late stagger barrier
# baseline (speedup 1.0000x reference)
.Llsb_skip_1:
.LBB0_335:
	ds_read_b128 v[128:131], v174
	ds_read_b128 v[132:135], v174 offset:1024
	ds_read_b128 v[158:161], v174 offset:2048
	ds_read_b128 v[178:181], v174 offset:3072
	ds_read_b128 v[182:185], v175
	ds_read_b128 v[186:189], v175 offset:1024
	ds_read_b128 v[190:193], v175 offset:2048
	ds_read_b128 v[194:197], v175 offset:3072
	s_add_u32 s28, s26, 0xfffc0080
	s_addc_u32 s29, s27, -1
	s_cmp_eq_u32 s56, 12
	s_cselect_b32 s31, s5, s29
	s_cselect_b32 s30, s21, s28
	s_cselect_b32 s29, s19, s55
	s_cselect_b32 s28, s53, s54
	v_lshl_add_u64 v[202:203], s[26:27], 0, v[150:151]
	s_add_i32 m0, s7, 0xc000
	ds_read_b128 v[198:201], v176
	ds_read_b128 v[206:209], v176 offset:1024
	ds_read_b128 v[210:213], v176 offset:2048
	ds_read_b128 v[214:217], v176 offset:3072
	ds_read_b128 v[218:221], v176 offset:4096
	ds_read_b128 v[222:225], v176 offset:5120
	ds_read_b128 v[226:229], v176 offset:6144
	ds_read_b128 v[230:233], v176 offset:7168
	global_load_lds_dwordx4 v[202:203], off
	v_lshl_add_u64 v[202:203], s[26:27], 0, v[152:153]
	s_add_i32 m0, s7, 0xe000
	s_nop 0
	global_load_lds_dwordx4 v[202:203], off
	s_waitcnt vmcnt(8)
	s_waitcnt lgkmcnt(0)
	s_barrier
	s_setprio 1
	v_mfma_f32_16x16x32_bf16 v[124:127], v[128:131], v[198:201], v[124:127]
	v_mfma_f32_16x16x32_bf16 v[120:123], v[158:161], v[198:201], v[120:123]
	v_mfma_f32_16x16x32_bf16 v[108:111], v[128:131], v[210:213], v[108:111]
	v_mfma_f32_16x16x32_bf16 v[104:107], v[158:161], v[210:213], v[104:107]
	v_mfma_f32_16x16x32_bf16 v[92:95], v[128:131], v[218:221], v[92:95]
	v_mfma_f32_16x16x32_bf16 v[88:91], v[158:161], v[218:221], v[88:91]
	v_mfma_f32_16x16x32_bf16 v[76:79], v[128:131], v[226:229], v[76:79]
	v_mfma_f32_16x16x32_bf16 v[72:75], v[158:161], v[226:229], v[72:75]
	v_mfma_f32_16x16x32_bf16 v[124:127], v[132:135], v[206:209], v[124:127]
	v_mfma_f32_16x16x32_bf16 v[120:123], v[178:181], v[206:209], v[120:123]
	v_mfma_f32_16x16x32_bf16 v[108:111], v[132:135], v[214:217], v[108:111]
	v_mfma_f32_16x16x32_bf16 v[104:107], v[178:181], v[214:217], v[104:107]
	v_mfma_f32_16x16x32_bf16 v[92:95], v[132:135], v[222:225], v[92:95]
	v_mfma_f32_16x16x32_bf16 v[88:91], v[178:181], v[222:225], v[88:91]
	v_mfma_f32_16x16x32_bf16 v[76:79], v[132:135], v[230:233], v[76:79]
	v_mfma_f32_16x16x32_bf16 v[72:75], v[178:181], v[230:233], v[72:75]
	s_setprio 0
	s_setprio 1
	v_mfma_f32_16x16x32_bf16 v[116:119], v[182:185], v[198:201], v[116:119]
	v_mfma_f32_16x16x32_bf16 v[112:115], v[190:193], v[198:201], v[112:115]
	v_mfma_f32_16x16x32_bf16 v[100:103], v[182:185], v[210:213], v[100:103]
	v_mfma_f32_16x16x32_bf16 v[96:99], v[190:193], v[210:213], v[96:99]
	v_mfma_f32_16x16x32_bf16 v[84:87], v[182:185], v[218:221], v[84:87]
	v_mfma_f32_16x16x32_bf16 v[80:83], v[190:193], v[218:221], v[80:83]
	v_mfma_f32_16x16x32_bf16 v[68:71], v[182:185], v[226:229], v[68:71]
	v_mfma_f32_16x16x32_bf16 v[64:67], v[190:193], v[226:229], v[64:67]
	v_mfma_f32_16x16x32_bf16 v[116:119], v[186:189], v[206:209], v[116:119]
	v_mfma_f32_16x16x32_bf16 v[112:115], v[194:197], v[206:209], v[112:115]
	v_mfma_f32_16x16x32_bf16 v[100:103], v[186:189], v[214:217], v[100:103]
	v_mfma_f32_16x16x32_bf16 v[96:99], v[194:197], v[214:217], v[96:99]
	v_mfma_f32_16x16x32_bf16 v[84:87], v[186:189], v[222:225], v[84:87]
	v_mfma_f32_16x16x32_bf16 v[80:83], v[194:197], v[222:225], v[80:83]
	v_mfma_f32_16x16x32_bf16 v[68:71], v[186:189], v[230:233], v[68:71]
	v_mfma_f32_16x16x32_bf16 v[64:67], v[194:197], v[230:233], v[64:67]
	s_setprio 0
	s_barrier
	s_add_i32 s57, s47, s38
	v_lshl_add_u64 v[202:203], s[28:29], 0, v[140:141]
	s_mov_b32 m0, s57
	ds_read_b128 v[198:201], v176 offset:16384
	ds_read_b128 v[206:209], v176 offset:17408
	ds_read_b128 v[210:213], v176 offset:18432
	ds_read_b128 v[214:217], v176 offset:19456
	ds_read_b128 v[218:221], v176 offset:20480
	ds_read_b128 v[222:225], v176 offset:21504
	ds_read_b128 v[226:229], v176 offset:22528
	ds_read_b128 v[230:233], v176 offset:23552
	global_load_lds_dwordx4 v[202:203], off
	s_add_i32 m0, s57, 0x2000
	s_add_u32 s58, s28, 0x40000
	v_lshl_add_u64 v[234:235], s[28:29], 0, v[142:143]
	s_addc_u32 s59, s29, 0
	s_add_i32 s57, s48, s38
	global_load_lds_dwordx4 v[234:235], off
	v_lshl_add_u64 v[236:237], s[58:59], 0, v[140:141]
	s_mov_b32 m0, s57
	v_lshl_add_u64 v[238:239], s[30:31], 0, v[138:139]
	global_load_lds_dwordx4 v[236:237], off
	v_lshl_add_u64 v[236:237], s[58:59], 0, v[142:143]
	s_add_i32 m0, s57, 0x2000
	s_nop 0
	global_load_lds_dwordx4 v[236:237], off
	v_lshl_add_u64 v[236:237], s[30:31], 0, v[136:137]
	s_mov_b32 m0, s7
	s_nop 0
	global_load_lds_dwordx4 v[236:237], off
	s_mov_b32 m0, s39
	s_nop 0
	global_load_lds_dwordx4 v[238:239], off
	s_waitcnt vmcnt(8)
	s_waitcnt lgkmcnt(0)
	s_barrier
	s_setprio 1
	v_mfma_f32_16x16x32_bf16 v[60:63], v[128:131], v[198:201], v[60:63]
	v_mfma_f32_16x16x32_bf16 v[56:59], v[158:161], v[198:201], v[56:59]
	v_mfma_f32_16x16x32_bf16 v[44:47], v[128:131], v[210:213], v[44:47]
	v_mfma_f32_16x16x32_bf16 v[40:43], v[158:161], v[210:213], v[40:43]
	v_mfma_f32_16x16x32_bf16 v[28:31], v[128:131], v[218:221], v[28:31]
	v_mfma_f32_16x16x32_bf16 v[24:27], v[158:161], v[218:221], v[24:27]
	v_mfma_f32_16x16x32_bf16 v[12:15], v[128:131], v[226:229], v[12:15]
	v_mfma_f32_16x16x32_bf16 v[8:11], v[158:161], v[226:229], v[8:11]
	v_mfma_f32_16x16x32_bf16 v[60:63], v[132:135], v[206:209], v[60:63]
	v_mfma_f32_16x16x32_bf16 v[56:59], v[178:181], v[206:209], v[56:59]
	v_mfma_f32_16x16x32_bf16 v[44:47], v[132:135], v[214:217], v[44:47]
	v_mfma_f32_16x16x32_bf16 v[40:43], v[178:181], v[214:217], v[40:43]
	v_mfma_f32_16x16x32_bf16 v[28:31], v[132:135], v[222:225], v[28:31]
	v_mfma_f32_16x16x32_bf16 v[24:27], v[178:181], v[222:225], v[24:27]
	v_mfma_f32_16x16x32_bf16 v[12:15], v[132:135], v[230:233], v[12:15]
	v_mfma_f32_16x16x32_bf16 v[8:11], v[178:181], v[230:233], v[8:11]
	s_setprio 0
	s_setprio 1
	v_mfma_f32_16x16x32_bf16 v[52:55], v[182:185], v[198:201], v[52:55]
	v_mfma_f32_16x16x32_bf16 v[48:51], v[190:193], v[198:201], v[48:51]
	v_mfma_f32_16x16x32_bf16 v[36:39], v[182:185], v[210:213], v[36:39]
	v_mfma_f32_16x16x32_bf16 v[32:35], v[190:193], v[210:213], v[32:35]
	v_mfma_f32_16x16x32_bf16 v[20:23], v[182:185], v[218:221], v[20:23]
	v_mfma_f32_16x16x32_bf16 v[16:19], v[190:193], v[218:221], v[16:19]
	v_mfma_f32_16x16x32_bf16 v[4:7], v[182:185], v[226:229], v[4:7]
	v_mfma_f32_16x16x32_bf16 v[0:3], v[190:193], v[226:229], v[0:3]
	v_mfma_f32_16x16x32_bf16 v[52:55], v[186:189], v[206:209], v[52:55]
	v_mfma_f32_16x16x32_bf16 v[48:51], v[194:197], v[206:209], v[48:51]
	v_mfma_f32_16x16x32_bf16 v[36:39], v[186:189], v[214:217], v[36:39]
	v_mfma_f32_16x16x32_bf16 v[32:35], v[194:197], v[214:217], v[32:35]
	v_mfma_f32_16x16x32_bf16 v[20:23], v[186:189], v[222:225], v[20:23]
	v_mfma_f32_16x16x32_bf16 v[16:19], v[194:197], v[222:225], v[16:19]
	v_mfma_f32_16x16x32_bf16 v[4:7], v[186:189], v[230:233], v[4:7]
	v_mfma_f32_16x16x32_bf16 v[0:3], v[194:197], v[230:233], v[0:3]
	s_setprio 0
	s_barrier
	s_add_i32 s57, 0, 0x18000
	v_add_u32_e32 v144, s57, v170
	s_add_i32 s58, 0, 0x1c000
	ds_read_b128 v[128:131], v144
	ds_read_b128 v[132:135], v144 offset:1024
	ds_read_b128 v[158:161], v144 offset:2048
	ds_read_b128 v[178:181], v144 offset:3072
	v_add_u32_e32 v144, s58, v170
	ds_read_b128 v[182:185], v144
	ds_read_b128 v[186:189], v144 offset:1024
	ds_read_b128 v[190:193], v144 offset:2048
	ds_read_b128 v[194:197], v144 offset:3072
	s_add_u32 s30, s30, 0x40000
	s_addc_u32 s31, s31, 0
	s_mov_b32 m0, s40
	v_lshl_add_u64 v[240:241], s[30:31], 0, v[136:137]
	ds_read_b128 v[198:201], v176 offset:32768
	ds_read_b128 v[206:209], v176 offset:33792
	ds_read_b128 v[210:213], v176 offset:34816
	ds_read_b128 v[214:217], v176 offset:35840
	ds_read_b128 v[218:221], v176 offset:36864
	ds_read_b128 v[222:225], v176 offset:37888
	ds_read_b128 v[226:229], v176 offset:38912
	ds_read_b128 v[230:233], v176 offset:39936
	global_load_lds_dwordx4 v[240:241], off
	v_lshl_add_u64 v[240:241], s[30:31], 0, v[138:139]
	s_mov_b32 m0, s41
	s_nop 0
	global_load_lds_dwordx4 v[240:241], off
	s_waitcnt vmcnt(8)
	s_waitcnt lgkmcnt(0)
	s_barrier
	s_setprio 1
	v_mfma_f32_16x16x32_bf16 v[124:127], v[128:131], v[198:201], v[124:127]
	v_mfma_f32_16x16x32_bf16 v[120:123], v[158:161], v[198:201], v[120:123]
	v_mfma_f32_16x16x32_bf16 v[108:111], v[128:131], v[210:213], v[108:111]
	v_mfma_f32_16x16x32_bf16 v[104:107], v[158:161], v[210:213], v[104:107]
	v_mfma_f32_16x16x32_bf16 v[92:95], v[128:131], v[218:221], v[92:95]
	v_mfma_f32_16x16x32_bf16 v[88:91], v[158:161], v[218:221], v[88:91]
	v_mfma_f32_16x16x32_bf16 v[76:79], v[128:131], v[226:229], v[76:79]
	v_mfma_f32_16x16x32_bf16 v[72:75], v[158:161], v[226:229], v[72:75]
	v_mfma_f32_16x16x32_bf16 v[124:127], v[132:135], v[206:209], v[124:127]
	v_mfma_f32_16x16x32_bf16 v[120:123], v[178:181], v[206:209], v[120:123]
	v_mfma_f32_16x16x32_bf16 v[108:111], v[132:135], v[214:217], v[108:111]
	v_mfma_f32_16x16x32_bf16 v[104:107], v[178:181], v[214:217], v[104:107]
	v_mfma_f32_16x16x32_bf16 v[92:95], v[132:135], v[222:225], v[92:95]
	v_mfma_f32_16x16x32_bf16 v[88:91], v[178:181], v[222:225], v[88:91]
	v_mfma_f32_16x16x32_bf16 v[76:79], v[132:135], v[230:233], v[76:79]
	v_mfma_f32_16x16x32_bf16 v[72:75], v[178:181], v[230:233], v[72:75]
	s_setprio 0
	s_setprio 1
	v_mfma_f32_16x16x32_bf16 v[116:119], v[182:185], v[198:201], v[116:119]
	v_mfma_f32_16x16x32_bf16 v[112:115], v[190:193], v[198:201], v[112:115]
	v_mfma_f32_16x16x32_bf16 v[100:103], v[182:185], v[210:213], v[100:103]
	v_mfma_f32_16x16x32_bf16 v[96:99], v[190:193], v[210:213], v[96:99]
	v_mfma_f32_16x16x32_bf16 v[84:87], v[182:185], v[218:221], v[84:87]
	v_mfma_f32_16x16x32_bf16 v[80:83], v[190:193], v[218:221], v[80:83]
	v_mfma_f32_16x16x32_bf16 v[68:71], v[182:185], v[226:229], v[68:71]
	v_mfma_f32_16x16x32_bf16 v[64:67], v[190:193], v[226:229], v[64:67]
	v_mfma_f32_16x16x32_bf16 v[116:119], v[186:189], v[206:209], v[116:119]
	v_mfma_f32_16x16x32_bf16 v[112:115], v[194:197], v[206:209], v[112:115]
	v_mfma_f32_16x16x32_bf16 v[100:103], v[186:189], v[214:217], v[100:103]
	v_mfma_f32_16x16x32_bf16 v[96:99], v[194:197], v[214:217], v[96:99]
	v_mfma_f32_16x16x32_bf16 v[84:87], v[186:189], v[222:225], v[84:87]
	v_mfma_f32_16x16x32_bf16 v[80:83], v[194:197], v[222:225], v[80:83]
	v_mfma_f32_16x16x32_bf16 v[68:71], v[186:189], v[230:233], v[68:71]
	v_mfma_f32_16x16x32_bf16 v[64:67], v[194:197], v[230:233], v[64:67]
	s_setprio 0
	s_barrier
	s_add_i32 s30, s57, s38
	v_lshl_add_u64 v[202:203], v[202:203], 0, s[14:15]
	s_mov_b32 m0, s30
	ds_read_b128 v[198:201], v176 offset:49152
	ds_read_b128 v[206:209], v176 offset:50176
	ds_read_b128 v[210:213], v176 offset:51200
	ds_read_b128 v[214:217], v176 offset:52224
	ds_read_b128 v[218:221], v176 offset:53248
	ds_read_b128 v[222:225], v176 offset:54272
	ds_read_b128 v[226:229], v176 offset:55296
	ds_read_b128 v[230:233], v176 offset:56320
	global_load_lds_dwordx4 v[202:203], off
	s_add_i32 m0, s30, 0x2000
	s_add_u32 s28, s28, 0x40080
	v_lshl_add_u64 v[202:203], v[234:235], 0, s[14:15]
	s_addc_u32 s29, s29, 0
	s_add_i32 s30, s58, s38
	global_load_lds_dwordx4 v[202:203], off
	v_lshl_add_u64 v[202:203], s[28:29], 0, v[140:141]
	s_mov_b32 m0, s30
	s_nop 0
	global_load_lds_dwordx4 v[202:203], off
	v_lshl_add_u64 v[202:203], s[28:29], 0, v[142:143]
	s_add_i32 m0, s30, 0x2000
	s_nop 0
	global_load_lds_dwordx4 v[202:203], off
	v_lshl_add_u64 v[202:203], v[236:237], 0, s[14:15]
	s_mov_b32 m0, s43
	s_nop 0
	global_load_lds_dwordx4 v[202:203], off
	v_lshl_add_u64 v[202:203], v[238:239], 0, s[14:15]
	s_mov_b32 m0, s44
	s_nop 0
	global_load_lds_dwordx4 v[202:203], off
	s_waitcnt vmcnt(8)
	s_waitcnt lgkmcnt(0)
	s_barrier
	s_setprio 1
	v_mfma_f32_16x16x32_bf16 v[60:63], v[128:131], v[198:201], v[60:63]
	v_mfma_f32_16x16x32_bf16 v[56:59], v[158:161], v[198:201], v[56:59]
	v_mfma_f32_16x16x32_bf16 v[44:47], v[128:131], v[210:213], v[44:47]
	v_mfma_f32_16x16x32_bf16 v[40:43], v[158:161], v[210:213], v[40:43]
	v_mfma_f32_16x16x32_bf16 v[28:31], v[128:131], v[218:221], v[28:31]
	v_mfma_f32_16x16x32_bf16 v[24:27], v[158:161], v[218:221], v[24:27]
	v_mfma_f32_16x16x32_bf16 v[12:15], v[128:131], v[226:229], v[12:15]
	v_mfma_f32_16x16x32_bf16 v[8:11], v[158:161], v[226:229], v[8:11]
	v_mfma_f32_16x16x32_bf16 v[60:63], v[132:135], v[206:209], v[60:63]
	v_mfma_f32_16x16x32_bf16 v[56:59], v[178:181], v[206:209], v[56:59]
	v_mfma_f32_16x16x32_bf16 v[44:47], v[132:135], v[214:217], v[44:47]
	v_mfma_f32_16x16x32_bf16 v[40:43], v[178:181], v[214:217], v[40:43]
	v_mfma_f32_16x16x32_bf16 v[28:31], v[132:135], v[222:225], v[28:31]
	v_mfma_f32_16x16x32_bf16 v[24:27], v[178:181], v[222:225], v[24:27]
	v_mfma_f32_16x16x32_bf16 v[12:15], v[132:135], v[230:233], v[12:15]
	v_mfma_f32_16x16x32_bf16 v[8:11], v[178:181], v[230:233], v[8:11]
	s_setprio 0
	s_setprio 1
	v_mfma_f32_16x16x32_bf16 v[52:55], v[182:185], v[198:201], v[52:55]
	v_mfma_f32_16x16x32_bf16 v[48:51], v[190:193], v[198:201], v[48:51]
	v_mfma_f32_16x16x32_bf16 v[36:39], v[182:185], v[210:213], v[36:39]
	v_mfma_f32_16x16x32_bf16 v[32:35], v[190:193], v[210:213], v[32:35]
	v_mfma_f32_16x16x32_bf16 v[20:23], v[182:185], v[218:221], v[20:23]
	v_mfma_f32_16x16x32_bf16 v[16:19], v[190:193], v[218:221], v[16:19]
	v_mfma_f32_16x16x32_bf16 v[4:7], v[182:185], v[226:229], v[4:7]
	v_mfma_f32_16x16x32_bf16 v[0:3], v[190:193], v[226:229], v[0:3]
	v_mfma_f32_16x16x32_bf16 v[52:55], v[186:189], v[206:209], v[52:55]
	v_mfma_f32_16x16x32_bf16 v[48:51], v[194:197], v[206:209], v[48:51]
	v_mfma_f32_16x16x32_bf16 v[36:39], v[186:189], v[214:217], v[36:39]
	v_mfma_f32_16x16x32_bf16 v[32:35], v[194:197], v[214:217], v[32:35]
	v_mfma_f32_16x16x32_bf16 v[20:23], v[186:189], v[222:225], v[20:23]
	v_mfma_f32_16x16x32_bf16 v[16:19], v[194:197], v[222:225], v[16:19]
	v_mfma_f32_16x16x32_bf16 v[4:7], v[186:189], v[230:233], v[4:7]
	v_mfma_f32_16x16x32_bf16 v[0:3], v[194:197], v[230:233], v[0:3]
	s_setprio 0
	s_barrier
	s_add_i32 s56, s56, 2
	s_add_u32 s26, s26, 0x100
	s_addc_u32 s27, s27, 0
	s_add_u32 s54, s54, 0x100
	s_addc_u32 s55, s55, 0
	s_cmp_gt_u32 s56, 13
	s_cbranch_scc0 .LBB0_335
	s_and_b64 vcc, exec, s[16:17]
	s_cbranch_vccz .LBB0_338
	s_barrier

.Llsb_skip_2:
.LBB0_487:
	ds_read_b128 v[142:145], v135
	ds_read_b128 v[146:149], v135 offset:1024
	ds_read_b128 v[150:153], v135 offset:2048
	ds_read_b128 v[154:157], v135 offset:3072
	ds_read_b128 v[158:161], v140
	ds_read_b128 v[162:165], v140 offset:1024
	ds_read_b128 v[166:169], v140 offset:2048
	ds_read_b128 v[170:173], v140 offset:3072
	s_add_u32 s28, s26, 0xfffc0080
	s_addc_u32 s29, s27, -1
	s_cmp_eq_u32 s57, 12
	s_cselect_b32 s31, s21, s29
	s_cselect_b32 s30, s53, s28
	s_cselect_b32 s29, s19, s56
	s_cselect_b32 s28, s54, s55
	v_lshl_add_u64 v[202:203], s[26:27], 0, v[128:129]
	s_add_i32 m0, s41, 0xc000
	ds_read_b128 v[174:177], v141
	ds_read_b128 v[178:181], v141 offset:1024
	ds_read_b128 v[182:185], v141 offset:2048
	ds_read_b128 v[186:189], v141 offset:3072
	ds_read_b128 v[190:193], v141 offset:4096
	ds_read_b128 v[194:197], v141 offset:5120
	ds_read_b128 v[198:201], v141 offset:6144
	ds_read_b128 v[206:209], v141 offset:7168
	global_load_lds_dwordx4 v[202:203], off
	v_lshl_add_u64 v[202:203], s[26:27], 0, v[130:131]
	s_add_i32 m0, s41, 0xe000
	s_nop 0
	global_load_lds_dwordx4 v[202:203], off
	s_waitcnt vmcnt(8)
	s_waitcnt lgkmcnt(0)
	s_barrier
	s_setprio 1
	v_mfma_f32_16x16x32_bf16 v[124:127], v[142:145], v[174:177], v[124:127]
	v_mfma_f32_16x16x32_bf16 v[120:123], v[150:153], v[174:177], v[120:123]
	v_mfma_f32_16x16x32_bf16 v[116:119], v[142:145], v[182:185], v[116:119]
	v_mfma_f32_16x16x32_bf16 v[112:115], v[150:153], v[182:185], v[112:115]
	v_mfma_f32_16x16x32_bf16 v[104:107], v[142:145], v[190:193], v[104:107]
	v_mfma_f32_16x16x32_bf16 v[96:99], v[150:153], v[190:193], v[96:99]
	v_mfma_f32_16x16x32_bf16 v[88:91], v[142:145], v[198:201], v[88:91]
	v_mfma_f32_16x16x32_bf16 v[80:83], v[150:153], v[198:201], v[80:83]
	v_mfma_f32_16x16x32_bf16 v[124:127], v[146:149], v[178:181], v[124:127]
	v_mfma_f32_16x16x32_bf16 v[120:123], v[154:157], v[178:181], v[120:123]
	v_mfma_f32_16x16x32_bf16 v[116:119], v[146:149], v[186:189], v[116:119]
	v_mfma_f32_16x16x32_bf16 v[112:115], v[154:157], v[186:189], v[112:115]
	v_mfma_f32_16x16x32_bf16 v[104:107], v[146:149], v[194:197], v[104:107]
	v_mfma_f32_16x16x32_bf16 v[96:99], v[154:157], v[194:197], v[96:99]
	v_mfma_f32_16x16x32_bf16 v[88:91], v[146:149], v[206:209], v[88:91]
	v_mfma_f32_16x16x32_bf16 v[80:83], v[154:157], v[206:209], v[80:83]
	s_setprio 0
	s_setprio 1
	v_mfma_f32_16x16x32_bf16 v[108:111], v[158:161], v[174:177], v[108:111]
	v_mfma_f32_16x16x32_bf16 v[100:103], v[166:169], v[174:177], v[100:103]
	v_mfma_f32_16x16x32_bf16 v[92:95], v[158:161], v[182:185], v[92:95]
	v_mfma_f32_16x16x32_bf16 v[84:87], v[166:169], v[182:185], v[84:87]
	v_mfma_f32_16x16x32_bf16 v[76:79], v[158:161], v[190:193], v[76:79]
	v_mfma_f32_16x16x32_bf16 v[72:75], v[166:169], v[190:193], v[72:75]
	v_mfma_f32_16x16x32_bf16 v[68:71], v[158:161], v[198:201], v[68:71]
	v_mfma_f32_16x16x32_bf16 v[64:67], v[166:169], v[198:201], v[64:67]
	v_mfma_f32_16x16x32_bf16 v[108:111], v[162:165], v[178:181], v[108:111]
	v_mfma_f32_16x16x32_bf16 v[100:103], v[170:173], v[178:181], v[100:103]
	v_mfma_f32_16x16x32_bf16 v[92:95], v[162:165], v[186:189], v[92:95]
	v_mfma_f32_16x16x32_bf16 v[84:87], v[170:173], v[186:189], v[84:87]
	v_mfma_f32_16x16x32_bf16 v[76:79], v[162:165], v[194:197], v[76:79]
	v_mfma_f32_16x16x32_bf16 v[72:75], v[170:173], v[194:197], v[72:75]
	v_mfma_f32_16x16x32_bf16 v[68:71], v[162:165], v[206:209], v[68:71]
	v_mfma_f32_16x16x32_bf16 v[64:67], v[170:173], v[206:209], v[64:67]
	s_setprio 0
	s_barrier
	s_add_i32 s58, s49, s38
	v_lshl_add_u64 v[202:203], s[28:29], 0, v[136:137]
	s_mov_b32 m0, s58
	ds_read_b128 v[174:177], v141 offset:16384
	ds_read_b128 v[178:181], v141 offset:17408
	ds_read_b128 v[182:185], v141 offset:18432
	ds_read_b128 v[186:189], v141 offset:19456
	ds_read_b128 v[190:193], v141 offset:20480
	ds_read_b128 v[194:197], v141 offset:21504
	ds_read_b128 v[198:201], v141 offset:22528
	ds_read_b128 v[206:209], v141 offset:23552
	global_load_lds_dwordx4 v[202:203], off
	s_add_i32 m0, s58, 0x2000
	s_add_u32 s58, s28, 0x40000
	v_lshl_add_u64 v[210:211], s[28:29], 0, v[138:139]
	s_addc_u32 s59, s29, 0
	s_add_i32 s60, s50, s38
	global_load_lds_dwordx4 v[210:211], off
	v_lshl_add_u64 v[212:213], s[58:59], 0, v[136:137]
	s_mov_b32 m0, s60
	v_lshl_add_u64 v[214:215], s[30:31], 0, v[138:139]
	global_load_lds_dwordx4 v[212:213], off
	v_lshl_add_u64 v[212:213], s[58:59], 0, v[138:139]
	s_add_i32 m0, s60, 0x2000
	s_nop 0
	global_load_lds_dwordx4 v[212:213], off
	v_lshl_add_u64 v[212:213], s[30:31], 0, v[136:137]
	s_mov_b32 m0, s41
	s_nop 0
	global_load_lds_dwordx4 v[212:213], off
	s_mov_b32 m0, s42
	s_nop 0
	global_load_lds_dwordx4 v[214:215], off
	s_waitcnt vmcnt(8)
	s_waitcnt lgkmcnt(0)
	s_barrier
	s_setprio 1
	v_mfma_f32_16x16x32_bf16 v[60:63], v[142:145], v[174:177], v[60:63]
	v_mfma_f32_16x16x32_bf16 v[56:59], v[150:153], v[174:177], v[56:59]
	v_mfma_f32_16x16x32_bf16 v[52:55], v[142:145], v[182:185], v[52:55]
	v_mfma_f32_16x16x32_bf16 v[48:51], v[150:153], v[182:185], v[48:51]
	v_mfma_f32_16x16x32_bf16 v[40:43], v[142:145], v[190:193], v[40:43]
	v_mfma_f32_16x16x32_bf16 v[32:35], v[150:153], v[190:193], v[32:35]
	v_mfma_f32_16x16x32_bf16 v[24:27], v[142:145], v[198:201], v[24:27]
	v_mfma_f32_16x16x32_bf16 v[16:19], v[150:153], v[198:201], v[16:19]
	v_mfma_f32_16x16x32_bf16 v[60:63], v[146:149], v[178:181], v[60:63]
	v_mfma_f32_16x16x32_bf16 v[56:59], v[154:157], v[178:181], v[56:59]
	v_mfma_f32_16x16x32_bf16 v[52:55], v[146:149], v[186:189], v[52:55]
	v_mfma_f32_16x16x32_bf16 v[48:51], v[154:157], v[186:189], v[48:51]
	v_mfma_f32_16x16x32_bf16 v[40:43], v[146:149], v[194:197], v[40:43]
	v_mfma_f32_16x16x32_bf16 v[32:35], v[154:157], v[194:197], v[32:35]
	v_mfma_f32_16x16x32_bf16 v[24:27], v[146:149], v[206:209], v[24:27]
	v_mfma_f32_16x16x32_bf16 v[16:19], v[154:157], v[206:209], v[16:19]
	s_setprio 0
	s_setprio 1
	v_mfma_f32_16x16x32_bf16 v[44:47], v[158:161], v[174:177], v[44:47]
	v_mfma_f32_16x16x32_bf16 v[36:39], v[166:169], v[174:177], v[36:39]
	v_mfma_f32_16x16x32_bf16 v[28:31], v[158:161], v[182:185], v[28:31]
	v_mfma_f32_16x16x32_bf16 v[20:23], v[166:169], v[182:185], v[20:23]
	v_mfma_f32_16x16x32_bf16 v[12:15], v[158:161], v[190:193], v[12:15]
	v_mfma_f32_16x16x32_bf16 v[8:11], v[166:169], v[190:193], v[8:11]
	v_mfma_f32_16x16x32_bf16 v[4:7], v[158:161], v[198:201], v[4:7]
	v_mfma_f32_16x16x32_bf16 v[0:3], v[166:169], v[198:201], v[0:3]
	v_mfma_f32_16x16x32_bf16 v[44:47], v[162:165], v[178:181], v[44:47]
	v_mfma_f32_16x16x32_bf16 v[36:39], v[170:173], v[178:181], v[36:39]
	v_mfma_f32_16x16x32_bf16 v[28:31], v[162:165], v[186:189], v[28:31]
	v_mfma_f32_16x16x32_bf16 v[20:23], v[170:173], v[186:189], v[20:23]
	v_mfma_f32_16x16x32_bf16 v[12:15], v[162:165], v[194:197], v[12:15]
	v_mfma_f32_16x16x32_bf16 v[8:11], v[170:173], v[194:197], v[8:11]
	v_mfma_f32_16x16x32_bf16 v[4:7], v[162:165], v[206:209], v[4:7]
	v_mfma_f32_16x16x32_bf16 v[0:3], v[170:173], v[206:209], v[0:3]
	s_setprio 0
	s_barrier
	s_add_i32 s58, 0, 0x18000
	s_add_i32 s59, 0, 0x1c000
	v_add_u32_e32 v154, s58, v133
	v_add_u32_e32 v170, s59, v133
	ds_read_b128 v[142:145], v154
	ds_read_b128 v[146:149], v154 offset:1024
	ds_read_b128 v[150:153], v154 offset:2048
	ds_read_b128 v[154:157], v154 offset:3072
	ds_read_b128 v[158:161], v170
	ds_read_b128 v[162:165], v170 offset:1024
	ds_read_b128 v[166:169], v170 offset:2048
	ds_read_b128 v[170:173], v170 offset:3072
	s_add_u32 s30, s30, 0x40000
	s_addc_u32 s31, s31, 0
	s_mov_b32 m0, s43
	v_lshl_add_u64 v[216:217], s[30:31], 0, v[136:137]
	ds_read_b128 v[174:177], v141 offset:32768
	ds_read_b128 v[178:181], v141 offset:33792
	ds_read_b128 v[182:185], v141 offset:34816
	ds_read_b128 v[186:189], v141 offset:35840
	ds_read_b128 v[190:193], v141 offset:36864
	ds_read_b128 v[194:197], v141 offset:37888
	ds_read_b128 v[198:201], v141 offset:38912
	ds_read_b128 v[206:209], v141 offset:39936
	global_load_lds_dwordx4 v[216:217], off
	v_lshl_add_u64 v[216:217], s[30:31], 0, v[138:139]
	s_mov_b32 m0, s44
	s_nop 0
	global_load_lds_dwordx4 v[216:217], off
	s_waitcnt vmcnt(8)
	s_waitcnt lgkmcnt(0)
	s_barrier
	s_setprio 1
	v_mfma_f32_16x16x32_bf16 v[124:127], v[142:145], v[174:177], v[124:127]
	v_mfma_f32_16x16x32_bf16 v[120:123], v[150:153], v[174:177], v[120:123]
	v_mfma_f32_16x16x32_bf16 v[116:119], v[142:145], v[182:185], v[116:119]
	v_mfma_f32_16x16x32_bf16 v[112:115], v[150:153], v[182:185], v[112:115]
	v_mfma_f32_16x16x32_bf16 v[104:107], v[142:145], v[190:193], v[104:107]
	v_mfma_f32_16x16x32_bf16 v[96:99], v[150:153], v[190:193], v[96:99]
	v_mfma_f32_16x16x32_bf16 v[88:91], v[142:145], v[198:201], v[88:91]
	v_mfma_f32_16x16x32_bf16 v[80:83], v[150:153], v[198:201], v[80:83]
	v_mfma_f32_16x16x32_bf16 v[124:127], v[146:149], v[178:181], v[124:127]
	v_mfma_f32_16x16x32_bf16 v[120:123], v[154:157], v[178:181], v[120:123]
	v_mfma_f32_16x16x32_bf16 v[116:119], v[146:149], v[186:189], v[116:119]
	v_mfma_f32_16x16x32_bf16 v[112:115], v[154:157], v[186:189], v[112:115]
	v_mfma_f32_16x16x32_bf16 v[104:107], v[146:149], v[194:197], v[104:107]
	v_mfma_f32_16x16x32_bf16 v[96:99], v[154:157], v[194:197], v[96:99]
	v_mfma_f32_16x16x32_bf16 v[88:91], v[146:149], v[206:209], v[88:91]
	v_mfma_f32_16x16x32_bf16 v[80:83], v[154:157], v[206:209], v[80:83]
	s_setprio 0
	s_setprio 1
	v_mfma_f32_16x16x32_bf16 v[108:111], v[158:161], v[174:177], v[108:111]
	v_mfma_f32_16x16x32_bf16 v[100:103], v[166:169], v[174:177], v[100:103]
	v_mfma_f32_16x16x32_bf16 v[92:95], v[158:161], v[182:185], v[92:95]
	v_mfma_f32_16x16x32_bf16 v[84:87], v[166:169], v[182:185], v[84:87]
	v_mfma_f32_16x16x32_bf16 v[76:79], v[158:161], v[190:193], v[76:79]
	v_mfma_f32_16x16x32_bf16 v[72:75], v[166:169], v[190:193], v[72:75]
	v_mfma_f32_16x16x32_bf16 v[68:71], v[158:161], v[198:201], v[68:71]
	v_mfma_f32_16x16x32_bf16 v[64:67], v[166:169], v[198:201], v[64:67]
	v_mfma_f32_16x16x32_bf16 v[108:111], v[162:165], v[178:181], v[108:111]
	v_mfma_f32_16x16x32_bf16 v[100:103], v[170:173], v[178:181], v[100:103]
	v_mfma_f32_16x16x32_bf16 v[92:95], v[162:165], v[186:189], v[92:95]
	v_mfma_f32_16x16x32_bf16 v[84:87], v[170:173], v[186:189], v[84:87]
	v_mfma_f32_16x16x32_bf16 v[76:79], v[162:165], v[194:197], v[76:79]
	v_mfma_f32_16x16x32_bf16 v[72:75], v[170:173], v[194:197], v[72:75]
	v_mfma_f32_16x16x32_bf16 v[68:71], v[162:165], v[206:209], v[68:71]
	v_mfma_f32_16x16x32_bf16 v[64:67], v[170:173], v[206:209], v[64:67]
	s_setprio 0
	s_barrier
	s_add_i32 s30, s58, s38
	v_lshl_add_u64 v[202:203], v[202:203], 0, s[6:7]
	s_mov_b32 m0, s30
	ds_read_b128 v[174:177], v141 offset:49152
	ds_read_b128 v[178:181], v141 offset:50176
	ds_read_b128 v[182:185], v141 offset:51200
	ds_read_b128 v[186:189], v141 offset:52224
	ds_read_b128 v[190:193], v141 offset:53248
	ds_read_b128 v[194:197], v141 offset:54272
	ds_read_b128 v[198:201], v141 offset:55296
	ds_read_b128 v[206:209], v141 offset:56320
	global_load_lds_dwordx4 v[202:203], off
	s_add_i32 m0, s30, 0x2000
	s_add_u32 s28, s28, 0x40080
	v_lshl_add_u64 v[202:203], v[210:211], 0, s[6:7]
	s_addc_u32 s29, s29, 0
	s_add_i32 s30, s59, s38
	global_load_lds_dwordx4 v[202:203], off
	v_lshl_add_u64 v[202:203], s[28:29], 0, v[136:137]
	s_mov_b32 m0, s30
	s_nop 0
	global_load_lds_dwordx4 v[202:203], off
	v_lshl_add_u64 v[202:203], s[28:29], 0, v[138:139]
	s_add_i32 m0, s30, 0x2000
	s_nop 0
	global_load_lds_dwordx4 v[202:203], off
	v_lshl_add_u64 v[202:203], v[212:213], 0, s[6:7]
	s_mov_b32 m0, s46
	s_nop 0
	global_load_lds_dwordx4 v[202:203], off
	v_lshl_add_u64 v[202:203], v[214:215], 0, s[6:7]
	s_mov_b32 m0, s47
	s_nop 0
	global_load_lds_dwordx4 v[202:203], off
	s_waitcnt vmcnt(8)
	s_waitcnt lgkmcnt(0)
	s_barrier
	s_setprio 1
	v_mfma_f32_16x16x32_bf16 v[60:63], v[142:145], v[174:177], v[60:63]
	v_mfma_f32_16x16x32_bf16 v[56:59], v[150:153], v[174:177], v[56:59]
	v_mfma_f32_16x16x32_bf16 v[52:55], v[142:145], v[182:185], v[52:55]
	v_mfma_f32_16x16x32_bf16 v[48:51], v[150:153], v[182:185], v[48:51]
	v_mfma_f32_16x16x32_bf16 v[40:43], v[142:145], v[190:193], v[40:43]
	v_mfma_f32_16x16x32_bf16 v[32:35], v[150:153], v[190:193], v[32:35]
	v_mfma_f32_16x16x32_bf16 v[24:27], v[142:145], v[198:201], v[24:27]
	v_mfma_f32_16x16x32_bf16 v[16:19], v[150:153], v[198:201], v[16:19]
	v_mfma_f32_16x16x32_bf16 v[60:63], v[146:149], v[178:181], v[60:63]
	v_mfma_f32_16x16x32_bf16 v[56:59], v[154:157], v[178:181], v[56:59]
	v_mfma_f32_16x16x32_bf16 v[52:55], v[146:149], v[186:189], v[52:55]
	v_mfma_f32_16x16x32_bf16 v[48:51], v[154:157], v[186:189], v[48:51]
	v_mfma_f32_16x16x32_bf16 v[40:43], v[146:149], v[194:197], v[40:43]
	v_mfma_f32_16x16x32_bf16 v[32:35], v[154:157], v[194:197], v[32:35]
	v_mfma_f32_16x16x32_bf16 v[24:27], v[146:149], v[206:209], v[24:27]
	v_mfma_f32_16x16x32_bf16 v[16:19], v[154:157], v[206:209], v[16:19]
	s_setprio 0
	s_setprio 1
	v_mfma_f32_16x16x32_bf16 v[44:47], v[158:161], v[174:177], v[44:47]
	v_mfma_f32_16x16x32_bf16 v[36:39], v[166:169], v[174:177], v[36:39]
	v_mfma_f32_16x16x32_bf16 v[28:31], v[158:161], v[182:185], v[28:31]
	v_mfma_f32_16x16x32_bf16 v[20:23], v[166:169], v[182:185], v[20:23]
	v_mfma_f32_16x16x32_bf16 v[12:15], v[158:161], v[190:193], v[12:15]
	v_mfma_f32_16x16x32_bf16 v[8:11], v[166:169], v[190:193], v[8:11]
	v_mfma_f32_16x16x32_bf16 v[4:7], v[158:161], v[198:201], v[4:7]
	v_mfma_f32_16x16x32_bf16 v[0:3], v[166:169], v[198:201], v[0:3]
	v_mfma_f32_16x16x32_bf16 v[44:47], v[162:165], v[178:181], v[44:47]
	v_mfma_f32_16x16x32_bf16 v[36:39], v[170:173], v[178:181], v[36:39]
	v_mfma_f32_16x16x32_bf16 v[28:31], v[162:165], v[186:189], v[28:31]
	v_mfma_f32_16x16x32_bf16 v[20:23], v[170:173], v[186:189], v[20:23]
	v_mfma_f32_16x16x32_bf16 v[12:15], v[162:165], v[194:197], v[12:15]
	v_mfma_f32_16x16x32_bf16 v[8:11], v[170:173], v[194:197], v[8:11]
	v_mfma_f32_16x16x32_bf16 v[4:7], v[162:165], v[206:209], v[4:7]
	v_mfma_f32_16x16x32_bf16 v[0:3], v[170:173], v[206:209], v[0:3]
	s_setprio 0
	s_barrier
	s_add_i32 s57, s57, 2
	s_add_u32 s26, s26, 0x100
	s_addc_u32 s27, s27, 0
	s_add_u32 s55, s55, 0x100
	s_addc_u32 s56, s56, 0
	s_cmp_gt_u32 s57, 13
	s_cbranch_scc0 .LBB0_487
	s_and_b64 vcc, exec, s[10:11]
	s_cbranch_vccz .LBB0_490
	s_barrier

.LBB0_554:
	ds_read_b128 v[84:87], v80
	ds_read_b128 v[88:91], v80 offset:1024
	ds_read_b128 v[92:95], v80 offset:2048
	ds_read_b128 v[96:99], v80 offset:3072
	s_add_u32 s22, s20, 0xfffd8080
	s_addc_u32 s23, s21, -1
	s_cmp_eq_u32 s57, 4
	s_cselect_b32 s25, s15, s23
	s_cselect_b32 s24, s14, s22
	s_cselect_b32 s23, s53, s56
	s_cselect_b32 s22, s54, s55
	s_mov_b32 m0, s45
	v_lshl_add_u64 v[132:133], s[20:21], 0, v[74:75]
	ds_read_b128 v[100:103], v81
	ds_read_b128 v[104:107], v81 offset:1024
	ds_read_b128 v[108:111], v81 offset:2048
	ds_read_b128 v[112:115], v81 offset:3072
	ds_read_b128 v[116:119], v81 offset:4096
	ds_read_b128 v[120:123], v81 offset:5120
	ds_read_b128 v[124:127], v81 offset:6144
	ds_read_b128 v[128:131], v81 offset:7168
	global_load_lds_dwordx4 v[132:133], off
	v_lshl_add_u64 v[132:133], s[20:21], 0, v[76:77]
	s_mov_b32 m0, s46
	s_nop 0
	global_load_lds_dwordx4 v[132:133], off
	s_waitcnt vmcnt(8)
	s_waitcnt lgkmcnt(0)
	s_barrier
	s_setprio 1
	v_mfma_f32_16x16x32_bf16 v[60:63], v[84:87], v[100:103], v[60:63]
	v_mfma_f32_16x16x32_bf16 v[56:59], v[92:95], v[100:103], v[56:59]
	v_mfma_f32_16x16x32_bf16 v[52:55], v[84:87], v[108:111], v[52:55]
	v_mfma_f32_16x16x32_bf16 v[48:51], v[92:95], v[108:111], v[48:51]
	v_mfma_f32_16x16x32_bf16 v[44:47], v[84:87], v[116:119], v[44:47]
	v_mfma_f32_16x16x32_bf16 v[40:43], v[92:95], v[116:119], v[40:43]
	v_mfma_f32_16x16x32_bf16 v[36:39], v[84:87], v[124:127], v[36:39]
	v_mfma_f32_16x16x32_bf16 v[32:35], v[92:95], v[124:127], v[32:35]
	v_mfma_f32_16x16x32_bf16 v[60:63], v[88:91], v[104:107], v[60:63]
	v_mfma_f32_16x16x32_bf16 v[56:59], v[96:99], v[104:107], v[56:59]
	v_mfma_f32_16x16x32_bf16 v[52:55], v[88:91], v[112:115], v[52:55]
	v_mfma_f32_16x16x32_bf16 v[48:51], v[96:99], v[112:115], v[48:51]
	v_mfma_f32_16x16x32_bf16 v[44:47], v[88:91], v[120:123], v[44:47]
	v_mfma_f32_16x16x32_bf16 v[40:43], v[96:99], v[120:123], v[40:43]
	v_mfma_f32_16x16x32_bf16 v[36:39], v[88:91], v[128:131], v[36:39]
	v_mfma_f32_16x16x32_bf16 v[32:35], v[96:99], v[128:131], v[32:35]
	s_setprio 0
	s_setprio 1
	s_setprio 0
	s_barrier
	s_mov_b32 m0, s47
	v_lshl_add_u64 v[132:133], s[22:23], 0, v[68:69]
	s_add_u32 s58, s22, 0x20000
	ds_read_b128 v[100:103], v81 offset:16384
	ds_read_b128 v[104:107], v81 offset:17408
	ds_read_b128 v[108:111], v81 offset:18432
	ds_read_b128 v[112:115], v81 offset:19456
	ds_read_b128 v[116:119], v81 offset:20480
	ds_read_b128 v[120:123], v81 offset:21504
	ds_read_b128 v[124:127], v81 offset:22528
	ds_read_b128 v[128:131], v81 offset:23552
	global_load_lds_dwordx4 v[132:133], off
	v_lshl_add_u64 v[134:135], s[22:23], 0, v[64:65]
	s_mov_b32 m0, s48
	s_addc_u32 s59, s23, 0
	global_load_lds_dwordx4 v[134:135], off
	v_lshl_add_u64 v[136:137], s[58:59], 0, v[68:69]
	s_mov_b32 m0, s31
	v_lshl_add_u64 v[138:139], s[24:25], 0, v[66:67]
	global_load_lds_dwordx4 v[136:137], off
	v_lshl_add_u64 v[136:137], s[58:59], 0, v[64:65]
	s_mov_b32 m0, s34
	s_nop 0
	global_load_lds_dwordx4 v[136:137], off
	v_lshl_add_u64 v[136:137], s[24:25], 0, v[70:71]
	s_mov_b32 m0, s30
	s_nop 0
	global_load_lds_dwordx4 v[136:137], off
	s_mov_b32 m0, s35
	s_nop 0
	global_load_lds_dwordx4 v[138:139], off
	s_waitcnt vmcnt(8)
	s_waitcnt lgkmcnt(0)
	s_barrier
	s_setprio 1
	v_mfma_f32_16x16x32_bf16 v[28:31], v[84:87], v[100:103], v[28:31]
	v_mfma_f32_16x16x32_bf16 v[24:27], v[92:95], v[100:103], v[24:27]
	v_mfma_f32_16x16x32_bf16 v[20:23], v[84:87], v[108:111], v[20:23]
	v_mfma_f32_16x16x32_bf16 v[16:19], v[92:95], v[108:111], v[16:19]
	v_mfma_f32_16x16x32_bf16 v[12:15], v[84:87], v[116:119], v[12:15]
	v_mfma_f32_16x16x32_bf16 v[8:11], v[92:95], v[116:119], v[8:11]
	v_mfma_f32_16x16x32_bf16 v[4:7], v[84:87], v[124:127], v[4:7]
	v_mfma_f32_16x16x32_bf16 v[0:3], v[92:95], v[124:127], v[0:3]
	v_mfma_f32_16x16x32_bf16 v[28:31], v[88:91], v[104:107], v[28:31]
	v_mfma_f32_16x16x32_bf16 v[24:27], v[96:99], v[104:107], v[24:27]
	v_mfma_f32_16x16x32_bf16 v[20:23], v[88:91], v[112:115], v[20:23]
	v_mfma_f32_16x16x32_bf16 v[16:19], v[96:99], v[112:115], v[16:19]
	v_mfma_f32_16x16x32_bf16 v[12:15], v[88:91], v[120:123], v[12:15]
	v_mfma_f32_16x16x32_bf16 v[8:11], v[96:99], v[120:123], v[8:11]
	v_mfma_f32_16x16x32_bf16 v[4:7], v[88:91], v[128:131], v[4:7]
	v_mfma_f32_16x16x32_bf16 v[0:3], v[96:99], v[128:131], v[0:3]
	s_setprio 0
	s_setprio 1
	s_setprio 0
	s_barrier
	ds_read_b128 v[84:87], v82
	ds_read_b128 v[88:91], v82 offset:1024
	ds_read_b128 v[92:95], v82 offset:2048
	ds_read_b128 v[96:99], v82 offset:3072
	s_add_u32 s24, s24, 0x28000
	s_addc_u32 s25, s25, 0
	s_mov_b32 m0, s36
	v_lshl_add_u64 v[140:141], s[24:25], 0, v[70:71]
	ds_read_b128 v[100:103], v81 offset:32768
	ds_read_b128 v[104:107], v81 offset:33792
	ds_read_b128 v[108:111], v81 offset:34816
	ds_read_b128 v[112:115], v81 offset:35840
	ds_read_b128 v[116:119], v81 offset:36864
	ds_read_b128 v[120:123], v81 offset:37888
	ds_read_b128 v[124:127], v81 offset:38912
	ds_read_b128 v[128:131], v81 offset:39936
	global_load_lds_dwordx4 v[140:141], off
	v_lshl_add_u64 v[140:141], s[24:25], 0, v[66:67]
	s_mov_b32 m0, s38
	s_nop 0
	global_load_lds_dwordx4 v[140:141], off
	s_waitcnt vmcnt(8)
	s_waitcnt lgkmcnt(0)
	s_barrier
	s_setprio 1
	v_mfma_f32_16x16x32_bf16 v[60:63], v[84:87], v[100:103], v[60:63]
	v_mfma_f32_16x16x32_bf16 v[56:59], v[92:95], v[100:103], v[56:59]
	v_mfma_f32_16x16x32_bf16 v[52:55], v[84:87], v[108:111], v[52:55]
	v_mfma_f32_16x16x32_bf16 v[48:51], v[92:95], v[108:111], v[48:51]
	v_mfma_f32_16x16x32_bf16 v[44:47], v[84:87], v[116:119], v[44:47]
	v_mfma_f32_16x16x32_bf16 v[40:43], v[92:95], v[116:119], v[40:43]
	v_mfma_f32_16x16x32_bf16 v[36:39], v[84:87], v[124:127], v[36:39]
	v_mfma_f32_16x16x32_bf16 v[32:35], v[92:95], v[124:127], v[32:35]
	v_mfma_f32_16x16x32_bf16 v[60:63], v[88:91], v[104:107], v[60:63]
	v_mfma_f32_16x16x32_bf16 v[56:59], v[96:99], v[104:107], v[56:59]
	v_mfma_f32_16x16x32_bf16 v[52:55], v[88:91], v[112:115], v[52:55]
	v_mfma_f32_16x16x32_bf16 v[48:51], v[96:99], v[112:115], v[48:51]
	v_mfma_f32_16x16x32_bf16 v[44:47], v[88:91], v[120:123], v[44:47]
	v_mfma_f32_16x16x32_bf16 v[40:43], v[96:99], v[120:123], v[40:43]
	v_mfma_f32_16x16x32_bf16 v[36:39], v[88:91], v[128:131], v[36:39]
	v_mfma_f32_16x16x32_bf16 v[32:35], v[96:99], v[128:131], v[32:35]
	s_setprio 0
	s_setprio 1
	s_setprio 0
	s_barrier
	s_mov_b32 m0, s49
	v_lshl_add_u64 v[132:133], v[132:133], 0, s[4:5]
	s_add_u32 s22, s22, 0x20080
	ds_read_b128 v[100:103], v81 offset:49152
	ds_read_b128 v[104:107], v81 offset:50176
	ds_read_b128 v[108:111], v81 offset:51200
	ds_read_b128 v[112:115], v81 offset:52224
	ds_read_b128 v[116:119], v81 offset:53248
	ds_read_b128 v[120:123], v81 offset:54272
	ds_read_b128 v[124:127], v81 offset:55296
	ds_read_b128 v[128:131], v81 offset:56320
	global_load_lds_dwordx4 v[132:133], off
	v_lshl_add_u64 v[132:133], v[134:135], 0, s[4:5]
	s_mov_b32 m0, s50
	s_addc_u32 s23, s23, 0
	global_load_lds_dwordx4 v[132:133], off
	v_lshl_add_u64 v[132:133], s[22:23], 0, v[68:69]
	s_mov_b32 m0, s43
	s_nop 0
	global_load_lds_dwordx4 v[132:133], off
	v_lshl_add_u64 v[132:133], s[22:23], 0, v[64:65]
	s_mov_b32 m0, s44
	s_nop 0
	global_load_lds_dwordx4 v[132:133], off
	v_lshl_add_u64 v[132:133], v[136:137], 0, s[4:5]
	s_mov_b32 m0, s41
	s_nop 0
	global_load_lds_dwordx4 v[132:133], off
	v_lshl_add_u64 v[132:133], v[138:139], 0, s[4:5]
	s_mov_b32 m0, s42
	s_nop 0
	global_load_lds_dwordx4 v[132:133], off
	s_waitcnt vmcnt(8)
	s_waitcnt lgkmcnt(0)
	s_barrier
	s_setprio 1
	v_mfma_f32_16x16x32_bf16 v[28:31], v[84:87], v[100:103], v[28:31]
	v_mfma_f32_16x16x32_bf16 v[24:27], v[92:95], v[100:103], v[24:27]
	v_mfma_f32_16x16x32_bf16 v[20:23], v[84:87], v[108:111], v[20:23]
	v_mfma_f32_16x16x32_bf16 v[16:19], v[92:95], v[108:111], v[16:19]
	v_mfma_f32_16x16x32_bf16 v[12:15], v[84:87], v[116:119], v[12:15]
	v_mfma_f32_16x16x32_bf16 v[8:11], v[92:95], v[116:119], v[8:11]
	v_mfma_f32_16x16x32_bf16 v[4:7], v[84:87], v[124:127], v[4:7]
	v_mfma_f32_16x16x32_bf16 v[0:3], v[92:95], v[124:127], v[0:3]
	v_mfma_f32_16x16x32_bf16 v[28:31], v[88:91], v[104:107], v[28:31]
	v_mfma_f32_16x16x32_bf16 v[24:27], v[96:99], v[104:107], v[24:27]
	v_mfma_f32_16x16x32_bf16 v[20:23], v[88:91], v[112:115], v[20:23]
	v_mfma_f32_16x16x32_bf16 v[16:19], v[96:99], v[112:115], v[16:19]
	v_mfma_f32_16x16x32_bf16 v[12:15], v[88:91], v[120:123], v[12:15]
	v_mfma_f32_16x16x32_bf16 v[8:11], v[96:99], v[120:123], v[8:11]
	v_mfma_f32_16x16x32_bf16 v[4:7], v[88:91], v[128:131], v[4:7]
	v_mfma_f32_16x16x32_bf16 v[0:3], v[96:99], v[128:131], v[0:3]
	s_setprio 0
	s_setprio 1
	s_setprio 0
	s_barrier
	s_add_i32 s57, s57, 2
	s_add_u32 s20, s20, 0x100
	s_addc_u32 s21, s21, 0
	s_add_u32 s55, s55, 0x100
	s_addc_u32 s56, s56, 0
	s_cmp_gt_u32 s57, 5
	s_cbranch_scc0 .LBB0_554
	s_and_b64 vcc, exec, s[6:7]
	s_cbranch_vccz .LBB0_557
	s_barrier

.Llsb_skip_3:
.LBB0_791:
	ds_read_b128 v[44:47], v200
	ds_read_b128 v[52:55], v200 offset:1024
	ds_read_b128 v[112:115], v200 offset:2048
	ds_read_b128 v[124:127], v200 offset:3072
	ds_read_b128 v[136:139], v201
	ds_read_b128 v[148:151], v201 offset:1024
	ds_read_b128 v[152:155], v201 offset:2048
	ds_read_b128 v[156:159], v201 offset:3072
	s_add_u32 s24, s22, 0xfffd8080
	s_addc_u32 s25, s23, -1
	s_cmp_eq_u32 s56, 6
	s_cselect_b32 s27, s19, s25
	s_cselect_b32 s26, s18, s24
	s_cselect_b32 s25, s21, s55
	s_cselect_b32 s24, s20, s54
	s_mov_b32 m0, s39
	v_lshl_add_u64 v[236:237], s[22:23], 0, v[178:179]
	ds_read_b128 v[160:163], v202
	ds_read_b128 v[208:211], v202 offset:1024
	ds_read_b128 v[212:215], v202 offset:2048
	ds_read_b128 v[216:219], v202 offset:3072
	ds_read_b128 v[220:223], v202 offset:4096
	ds_read_b128 v[224:227], v202 offset:5120
	ds_read_b128 v[228:231], v202 offset:6144
	ds_read_b128 v[232:235], v202 offset:7168
	global_load_lds_dwordx4 v[236:237], off
	v_lshl_add_u64 v[236:237], s[22:23], 0, v[180:181]
	s_mov_b32 m0, s40
	s_nop 0
	global_load_lds_dwordx4 v[236:237], off
	s_waitcnt vmcnt(8)
	s_waitcnt lgkmcnt(0)
	s_barrier
	s_setprio 1
	v_mfma_f32_16x16x32_bf16 v[144:147], v[44:47], v[160:163], v[144:147]
	v_mfma_f32_16x16x32_bf16 v[140:143], v[112:115], v[160:163], v[140:143]
	v_mfma_f32_16x16x32_bf16 v[120:123], v[44:47], v[212:215], v[120:123]
	v_mfma_f32_16x16x32_bf16 v[116:119], v[112:115], v[212:215], v[116:119]
	v_mfma_f32_16x16x32_bf16 v[100:103], v[44:47], v[220:223], v[100:103]
	v_mfma_f32_16x16x32_bf16 v[96:99], v[112:115], v[220:223], v[96:99]
	v_mfma_f32_16x16x32_bf16 v[84:87], v[44:47], v[228:231], v[84:87]
	v_mfma_f32_16x16x32_bf16 v[80:83], v[112:115], v[228:231], v[80:83]
	v_mfma_f32_16x16x32_bf16 v[144:147], v[52:55], v[208:211], v[144:147]
	v_mfma_f32_16x16x32_bf16 v[140:143], v[124:127], v[208:211], v[140:143]
	v_mfma_f32_16x16x32_bf16 v[120:123], v[52:55], v[216:219], v[120:123]
	v_mfma_f32_16x16x32_bf16 v[116:119], v[124:127], v[216:219], v[116:119]
	v_mfma_f32_16x16x32_bf16 v[100:103], v[52:55], v[224:227], v[100:103]
	v_mfma_f32_16x16x32_bf16 v[96:99], v[124:127], v[224:227], v[96:99]
	v_mfma_f32_16x16x32_bf16 v[84:87], v[52:55], v[232:235], v[84:87]
	v_mfma_f32_16x16x32_bf16 v[80:83], v[124:127], v[232:235], v[80:83]
	s_setprio 0
	s_setprio 1
	v_mfma_f32_16x16x32_bf16 v[132:135], v[136:139], v[160:163], v[132:135]
	v_mfma_f32_16x16x32_bf16 v[128:131], v[152:155], v[160:163], v[128:131]
	v_mfma_f32_16x16x32_bf16 v[108:111], v[136:139], v[212:215], v[108:111]
	v_mfma_f32_16x16x32_bf16 v[104:107], v[152:155], v[212:215], v[104:107]
	v_mfma_f32_16x16x32_bf16 v[92:95], v[136:139], v[220:223], v[92:95]
	v_mfma_f32_16x16x32_bf16 v[88:91], v[152:155], v[220:223], v[88:91]
	v_mfma_f32_16x16x32_bf16 v[76:79], v[136:139], v[228:231], v[76:79]
	v_mfma_f32_16x16x32_bf16 v[72:75], v[152:155], v[228:231], v[72:75]
	v_mfma_f32_16x16x32_bf16 v[132:135], v[148:151], v[208:211], v[132:135]
	v_mfma_f32_16x16x32_bf16 v[128:131], v[156:159], v[208:211], v[128:131]
	v_mfma_f32_16x16x32_bf16 v[108:111], v[148:151], v[216:219], v[108:111]
	v_mfma_f32_16x16x32_bf16 v[104:107], v[156:159], v[216:219], v[104:107]
	v_mfma_f32_16x16x32_bf16 v[92:95], v[148:151], v[224:227], v[92:95]
	v_mfma_f32_16x16x32_bf16 v[88:91], v[156:159], v[224:227], v[88:91]
	v_mfma_f32_16x16x32_bf16 v[76:79], v[148:151], v[232:235], v[76:79]
	v_mfma_f32_16x16x32_bf16 v[72:75], v[156:159], v[232:235], v[72:75]
	s_setprio 0
	s_barrier
	s_mov_b32 m0, s41
	v_lshl_add_u64 v[236:237], s[24:25], 0, v[168:169]
	s_add_u32 s58, s24, 0x28000
	ds_read_b128 v[160:163], v202 offset:16384
	ds_read_b128 v[208:211], v202 offset:17408
	ds_read_b128 v[212:215], v202 offset:18432
	ds_read_b128 v[216:219], v202 offset:19456
	ds_read_b128 v[220:223], v202 offset:20480
	ds_read_b128 v[224:227], v202 offset:21504
	ds_read_b128 v[228:231], v202 offset:22528
	ds_read_b128 v[232:235], v202 offset:23552
	global_load_lds_dwordx4 v[236:237], off
	v_lshl_add_u64 v[238:239], s[24:25], 0, v[164:165]
	s_mov_b32 m0, s43
	s_addc_u32 s59, s25, 0
	global_load_lds_dwordx4 v[238:239], off
	v_lshl_add_u64 v[240:241], s[58:59], 0, v[168:169]
	s_mov_b32 m0, s44
	v_lshl_add_u64 v[242:243], s[26:27], 0, v[166:167]
	global_load_lds_dwordx4 v[240:241], off
	v_lshl_add_u64 v[240:241], s[58:59], 0, v[164:165]
	s_mov_b32 m0, s45
	s_nop 0
	global_load_lds_dwordx4 v[240:241], off
	v_lshl_add_u64 v[240:241], s[26:27], 0, v[170:171]
	s_mov_b32 m0, s30
	s_nop 0
	global_load_lds_dwordx4 v[240:241], off
	s_mov_b32 m0, s31
	s_nop 0
	global_load_lds_dwordx4 v[242:243], off
	s_waitcnt vmcnt(8)
	s_waitcnt lgkmcnt(0)
	s_barrier
	s_setprio 1
	v_mfma_f32_16x16x32_bf16 v[68:71], v[44:47], v[160:163], v[68:71]
	v_mfma_f32_16x16x32_bf16 v[64:67], v[112:115], v[160:163], v[64:67]
	v_mfma_f32_16x16x32_bf16 v[48:51], v[44:47], v[212:215], v[48:51]
	v_mfma_f32_16x16x32_bf16 v[40:43], v[112:115], v[212:215], v[40:43]
	v_mfma_f32_16x16x32_bf16 v[28:31], v[44:47], v[220:223], v[28:31]
	v_mfma_f32_16x16x32_bf16 v[24:27], v[112:115], v[220:223], v[24:27]
	v_mfma_f32_16x16x32_bf16 v[12:15], v[44:47], v[228:231], v[12:15]
	v_mfma_f32_16x16x32_bf16 v[8:11], v[112:115], v[228:231], v[8:11]
	v_mfma_f32_16x16x32_bf16 v[68:71], v[52:55], v[208:211], v[68:71]
	v_mfma_f32_16x16x32_bf16 v[64:67], v[124:127], v[208:211], v[64:67]
	v_mfma_f32_16x16x32_bf16 v[48:51], v[52:55], v[216:219], v[48:51]
	v_mfma_f32_16x16x32_bf16 v[40:43], v[124:127], v[216:219], v[40:43]
	v_mfma_f32_16x16x32_bf16 v[28:31], v[52:55], v[224:227], v[28:31]
	v_mfma_f32_16x16x32_bf16 v[24:27], v[124:127], v[224:227], v[24:27]
	v_mfma_f32_16x16x32_bf16 v[12:15], v[52:55], v[232:235], v[12:15]
	v_mfma_f32_16x16x32_bf16 v[8:11], v[124:127], v[232:235], v[8:11]
	s_setprio 0
	s_setprio 1
	v_mfma_f32_16x16x32_bf16 v[36:39], v[136:139], v[212:215], v[36:39]
	v_mfma_f32_16x16x32_bf16 v[32:35], v[152:155], v[212:215], v[32:35]
	v_mfma_f32_16x16x32_bf16 v[20:23], v[136:139], v[220:223], v[20:23]
	v_mfma_f32_16x16x32_bf16 v[16:19], v[152:155], v[220:223], v[16:19]
	v_mfma_f32_16x16x32_bf16 v[4:7], v[136:139], v[228:231], v[4:7]
	v_mfma_f32_16x16x32_bf16 v[0:3], v[152:155], v[228:231], v[0:3]
	v_mfma_f32_16x16x32_bf16 v[44:47], v[136:139], v[160:163], v[60:63]
	v_mfma_f32_16x16x32_bf16 v[52:55], v[152:155], v[160:163], v[56:59]
	v_mfma_f32_16x16x32_bf16 v[36:39], v[148:151], v[216:219], v[36:39]
	v_mfma_f32_16x16x32_bf16 v[32:35], v[156:159], v[216:219], v[32:35]
	v_mfma_f32_16x16x32_bf16 v[20:23], v[148:151], v[224:227], v[20:23]
	v_mfma_f32_16x16x32_bf16 v[16:19], v[156:159], v[224:227], v[16:19]
	v_mfma_f32_16x16x32_bf16 v[4:7], v[148:151], v[232:235], v[4:7]
	v_mfma_f32_16x16x32_bf16 v[0:3], v[156:159], v[232:235], v[0:3]
	v_mfma_f32_16x16x32_bf16 v[44:47], v[148:151], v[208:211], v[44:47]
	v_mfma_f32_16x16x32_bf16 v[52:55], v[156:159], v[208:211], v[52:55]
	s_setprio 0
	s_barrier
	ds_read_b128 v[56:59], v203
	ds_read_b128 v[60:63], v203 offset:1024
	ds_read_b128 v[112:115], v203 offset:2048
	ds_read_b128 v[124:127], v203 offset:3072
	ds_read_b128 v[136:139], v205
	ds_read_b128 v[148:151], v205 offset:1024
	ds_read_b128 v[152:155], v205 offset:2048
	ds_read_b128 v[156:159], v205 offset:3072
	s_add_u32 s26, s26, 0x28000
	s_addc_u32 s27, s27, 0
	s_mov_b32 m0, s33
	v_lshl_add_u64 v[244:245], s[26:27], 0, v[170:171]
	ds_read_b128 v[160:163], v202 offset:32768
	ds_read_b128 v[208:211], v202 offset:33792
	ds_read_b128 v[212:215], v202 offset:34816
	ds_read_b128 v[216:219], v202 offset:35840
	ds_read_b128 v[220:223], v202 offset:36864
	ds_read_b128 v[224:227], v202 offset:37888
	ds_read_b128 v[228:231], v202 offset:38912
	ds_read_b128 v[232:235], v202 offset:39936
	global_load_lds_dwordx4 v[244:245], off
	v_lshl_add_u64 v[244:245], s[26:27], 0, v[166:167]
	s_mov_b32 m0, s34
	s_nop 0
	global_load_lds_dwordx4 v[244:245], off
	s_waitcnt vmcnt(8)
	s_waitcnt lgkmcnt(0)
	s_barrier
	s_setprio 1
	v_mfma_f32_16x16x32_bf16 v[144:147], v[56:59], v[160:163], v[144:147]
	v_mfma_f32_16x16x32_bf16 v[140:143], v[112:115], v[160:163], v[140:143]
	v_mfma_f32_16x16x32_bf16 v[120:123], v[56:59], v[212:215], v[120:123]
	v_mfma_f32_16x16x32_bf16 v[116:119], v[112:115], v[212:215], v[116:119]
	v_mfma_f32_16x16x32_bf16 v[100:103], v[56:59], v[220:223], v[100:103]
	v_mfma_f32_16x16x32_bf16 v[96:99], v[112:115], v[220:223], v[96:99]
	v_mfma_f32_16x16x32_bf16 v[84:87], v[56:59], v[228:231], v[84:87]
	v_mfma_f32_16x16x32_bf16 v[80:83], v[112:115], v[228:231], v[80:83]
	v_mfma_f32_16x16x32_bf16 v[144:147], v[60:63], v[208:211], v[144:147]
	v_mfma_f32_16x16x32_bf16 v[140:143], v[124:127], v[208:211], v[140:143]
	v_mfma_f32_16x16x32_bf16 v[120:123], v[60:63], v[216:219], v[120:123]
	v_mfma_f32_16x16x32_bf16 v[116:119], v[124:127], v[216:219], v[116:119]
	v_mfma_f32_16x16x32_bf16 v[100:103], v[60:63], v[224:227], v[100:103]
	v_mfma_f32_16x16x32_bf16 v[96:99], v[124:127], v[224:227], v[96:99]
	v_mfma_f32_16x16x32_bf16 v[84:87], v[60:63], v[232:235], v[84:87]
	v_mfma_f32_16x16x32_bf16 v[80:83], v[124:127], v[232:235], v[80:83]
	s_setprio 0
	s_setprio 1
	v_mfma_f32_16x16x32_bf16 v[132:135], v[136:139], v[160:163], v[132:135]
	v_mfma_f32_16x16x32_bf16 v[128:131], v[152:155], v[160:163], v[128:131]
	v_mfma_f32_16x16x32_bf16 v[108:111], v[136:139], v[212:215], v[108:111]
	v_mfma_f32_16x16x32_bf16 v[104:107], v[152:155], v[212:215], v[104:107]
	v_mfma_f32_16x16x32_bf16 v[92:95], v[136:139], v[220:223], v[92:95]
	v_mfma_f32_16x16x32_bf16 v[88:91], v[152:155], v[220:223], v[88:91]
	v_mfma_f32_16x16x32_bf16 v[76:79], v[136:139], v[228:231], v[76:79]
	v_mfma_f32_16x16x32_bf16 v[72:75], v[152:155], v[228:231], v[72:75]
	v_mfma_f32_16x16x32_bf16 v[132:135], v[148:151], v[208:211], v[132:135]
	v_mfma_f32_16x16x32_bf16 v[128:131], v[156:159], v[208:211], v[128:131]
	v_mfma_f32_16x16x32_bf16 v[108:111], v[148:151], v[216:219], v[108:111]
	v_mfma_f32_16x16x32_bf16 v[104:107], v[156:159], v[216:219], v[104:107]
	v_mfma_f32_16x16x32_bf16 v[92:95], v[148:151], v[224:227], v[92:95]
	v_mfma_f32_16x16x32_bf16 v[88:91], v[156:159], v[224:227], v[88:91]
	v_mfma_f32_16x16x32_bf16 v[76:79], v[148:151], v[232:235], v[76:79]
	v_mfma_f32_16x16x32_bf16 v[72:75], v[156:159], v[232:235], v[72:75]
	s_setprio 0
	s_barrier
	s_mov_b32 m0, s46
	v_lshl_add_u64 v[236:237], v[236:237], 0, s[14:15]
	s_add_u32 s24, s24, 0x28080
	ds_read_b128 v[160:163], v202 offset:49152
	ds_read_b128 v[208:211], v202 offset:50176
	ds_read_b128 v[212:215], v202 offset:51200
	ds_read_b128 v[216:219], v202 offset:52224
	ds_read_b128 v[220:223], v202 offset:53248
	ds_read_b128 v[224:227], v202 offset:54272
	ds_read_b128 v[228:231], v202 offset:55296
	ds_read_b128 v[232:235], v202 offset:56320
	global_load_lds_dwordx4 v[236:237], off
	v_lshl_add_u64 v[236:237], v[238:239], 0, s[14:15]
	s_mov_b32 m0, s47
	s_addc_u32 s25, s25, 0
	global_load_lds_dwordx4 v[236:237], off
	v_lshl_add_u64 v[236:237], s[24:25], 0, v[168:169]
	s_mov_b32 m0, s48
	s_nop 0
	global_load_lds_dwordx4 v[236:237], off
	v_lshl_add_u64 v[236:237], s[24:25], 0, v[164:165]
	s_mov_b32 m0, s49
	s_nop 0
	global_load_lds_dwordx4 v[236:237], off
	v_lshl_add_u64 v[236:237], v[240:241], 0, s[14:15]
	s_mov_b32 m0, s37
	s_nop 0
	global_load_lds_dwordx4 v[236:237], off
	v_lshl_add_u64 v[236:237], v[242:243], 0, s[14:15]
	s_mov_b32 m0, s38
	s_nop 0
	global_load_lds_dwordx4 v[236:237], off
	s_waitcnt vmcnt(8)
	s_waitcnt lgkmcnt(0)
	s_barrier
	s_setprio 1
	v_mfma_f32_16x16x32_bf16 v[68:71], v[56:59], v[160:163], v[68:71]
	v_mfma_f32_16x16x32_bf16 v[64:67], v[112:115], v[160:163], v[64:67]
	v_mfma_f32_16x16x32_bf16 v[48:51], v[56:59], v[212:215], v[48:51]
	v_mfma_f32_16x16x32_bf16 v[40:43], v[112:115], v[212:215], v[40:43]
	v_mfma_f32_16x16x32_bf16 v[28:31], v[56:59], v[220:223], v[28:31]
	v_mfma_f32_16x16x32_bf16 v[24:27], v[112:115], v[220:223], v[24:27]
	v_mfma_f32_16x16x32_bf16 v[12:15], v[56:59], v[228:231], v[12:15]
	v_mfma_f32_16x16x32_bf16 v[8:11], v[112:115], v[228:231], v[8:11]
	v_mfma_f32_16x16x32_bf16 v[68:71], v[60:63], v[208:211], v[68:71]
	v_mfma_f32_16x16x32_bf16 v[64:67], v[124:127], v[208:211], v[64:67]
	v_mfma_f32_16x16x32_bf16 v[48:51], v[60:63], v[216:219], v[48:51]
	v_mfma_f32_16x16x32_bf16 v[40:43], v[124:127], v[216:219], v[40:43]
	v_mfma_f32_16x16x32_bf16 v[28:31], v[60:63], v[224:227], v[28:31]
	v_mfma_f32_16x16x32_bf16 v[24:27], v[124:127], v[224:227], v[24:27]
	v_mfma_f32_16x16x32_bf16 v[12:15], v[60:63], v[232:235], v[12:15]
	v_mfma_f32_16x16x32_bf16 v[8:11], v[124:127], v[232:235], v[8:11]
	s_setprio 0
	s_setprio 1
	v_mfma_f32_16x16x32_bf16 v[44:47], v[136:139], v[160:163], v[44:47]
	v_mfma_f32_16x16x32_bf16 v[60:63], v[148:151], v[208:211], v[44:47]
	v_mfma_f32_16x16x32_bf16 v[44:47], v[152:155], v[160:163], v[52:55]
	v_mfma_f32_16x16x32_bf16 v[36:39], v[136:139], v[212:215], v[36:39]
	v_mfma_f32_16x16x32_bf16 v[32:35], v[152:155], v[212:215], v[32:35]
	v_mfma_f32_16x16x32_bf16 v[20:23], v[136:139], v[220:223], v[20:23]
	v_mfma_f32_16x16x32_bf16 v[16:19], v[152:155], v[220:223], v[16:19]
	v_mfma_f32_16x16x32_bf16 v[4:7], v[136:139], v[228:231], v[4:7]
	v_mfma_f32_16x16x32_bf16 v[0:3], v[152:155], v[228:231], v[0:3]
	v_mfma_f32_16x16x32_bf16 v[56:59], v[156:159], v[208:211], v[44:47]
	v_mfma_f32_16x16x32_bf16 v[36:39], v[148:151], v[216:219], v[36:39]
	v_mfma_f32_16x16x32_bf16 v[32:35], v[156:159], v[216:219], v[32:35]
	v_mfma_f32_16x16x32_bf16 v[20:23], v[148:151], v[224:227], v[20:23]
	v_mfma_f32_16x16x32_bf16 v[16:19], v[156:159], v[224:227], v[16:19]
	v_mfma_f32_16x16x32_bf16 v[4:7], v[148:151], v[232:235], v[4:7]
	v_mfma_f32_16x16x32_bf16 v[0:3], v[156:159], v[232:235], v[0:3]
	s_setprio 0
	s_barrier
	s_add_i32 s56, s56, 2
	s_add_u32 s22, s22, 0x100
	s_addc_u32 s23, s23, 0
	s_add_u32 s54, s54, 0x100
	s_addc_u32 s55, s55, 0
	s_cmp_gt_u32 s56, 7
	s_cbranch_scc0 .LBB0_791
	s_and_b64 vcc, exec, s[16:17]
	s_cbranch_vccz .LBB0_794
	s_barrier

.Llsb_skip_4:
.LBB0_807:
	ds_read_b128 v[128:131], v175
	ds_read_b128 v[132:135], v175 offset:1024
	ds_read_b128 v[136:139], v175 offset:2048
	ds_read_b128 v[140:143], v175 offset:3072
	ds_read_b128 v[144:147], v176
	ds_read_b128 v[160:163], v176 offset:1024
	ds_read_b128 v[164:167], v176 offset:2048
	ds_read_b128 v[168:171], v176 offset:3072
	s_add_u32 s30, s28, 0xfffe0080
	s_addc_u32 s31, s29, -1
	s_cmp_eq_u32 s56, 4
	s_cselect_b32 s35, s17, s31
	s_cselect_b32 s34, s52, s30
	s_cselect_b32 s31, s19, s55
	s_cselect_b32 s30, s53, s54
	s_mov_b32 m0, s46
	v_lshl_add_u64 v[182:183], s[28:29], 0, v[156:157]
	ds_read_b128 v[178:181], v177
	ds_read_b128 v[188:191], v177 offset:1024
	ds_read_b128 v[192:195], v177 offset:2048
	ds_read_b128 v[196:199], v177 offset:3072
	ds_read_b128 v[200:203], v177 offset:4096
	ds_read_b128 v[206:209], v177 offset:5120
	ds_read_b128 v[210:213], v177 offset:6144
	ds_read_b128 v[214:217], v177 offset:7168
	global_load_lds_dwordx4 v[182:183], off
	v_lshl_add_u64 v[182:183], s[28:29], 0, v[158:159]
	s_mov_b32 m0, s47
	s_nop 0
	global_load_lds_dwordx4 v[182:183], off
	s_waitcnt vmcnt(8)
	s_waitcnt lgkmcnt(0)
	s_barrier
	s_setprio 1
	v_mfma_f32_16x16x32_bf16 v[124:127], v[128:131], v[178:181], v[124:127]
	v_mfma_f32_16x16x32_bf16 v[120:123], v[136:139], v[178:181], v[120:123]
	v_mfma_f32_16x16x32_bf16 v[108:111], v[128:131], v[192:195], v[108:111]
	v_mfma_f32_16x16x32_bf16 v[104:107], v[136:139], v[192:195], v[104:107]
	v_mfma_f32_16x16x32_bf16 v[92:95], v[128:131], v[200:203], v[92:95]
	v_mfma_f32_16x16x32_bf16 v[88:91], v[136:139], v[200:203], v[88:91]
	v_mfma_f32_16x16x32_bf16 v[76:79], v[128:131], v[210:213], v[76:79]
	v_mfma_f32_16x16x32_bf16 v[72:75], v[136:139], v[210:213], v[72:75]
	v_mfma_f32_16x16x32_bf16 v[124:127], v[132:135], v[188:191], v[124:127]
	v_mfma_f32_16x16x32_bf16 v[120:123], v[140:143], v[188:191], v[120:123]
	v_mfma_f32_16x16x32_bf16 v[108:111], v[132:135], v[196:199], v[108:111]
	v_mfma_f32_16x16x32_bf16 v[104:107], v[140:143], v[196:199], v[104:107]
	v_mfma_f32_16x16x32_bf16 v[92:95], v[132:135], v[206:209], v[92:95]
	v_mfma_f32_16x16x32_bf16 v[88:91], v[140:143], v[206:209], v[88:91]
	v_mfma_f32_16x16x32_bf16 v[76:79], v[132:135], v[214:217], v[76:79]
	v_mfma_f32_16x16x32_bf16 v[72:75], v[140:143], v[214:217], v[72:75]
	s_setprio 0
	s_setprio 1
	v_mfma_f32_16x16x32_bf16 v[116:119], v[144:147], v[178:181], v[116:119]
	v_mfma_f32_16x16x32_bf16 v[112:115], v[164:167], v[178:181], v[112:115]
	v_mfma_f32_16x16x32_bf16 v[100:103], v[144:147], v[192:195], v[100:103]
	v_mfma_f32_16x16x32_bf16 v[96:99], v[164:167], v[192:195], v[96:99]
	v_mfma_f32_16x16x32_bf16 v[84:87], v[144:147], v[200:203], v[84:87]
	v_mfma_f32_16x16x32_bf16 v[80:83], v[164:167], v[200:203], v[80:83]
	v_mfma_f32_16x16x32_bf16 v[68:71], v[144:147], v[210:213], v[68:71]
	v_mfma_f32_16x16x32_bf16 v[64:67], v[164:167], v[210:213], v[64:67]
	v_mfma_f32_16x16x32_bf16 v[116:119], v[160:163], v[188:191], v[116:119]
	v_mfma_f32_16x16x32_bf16 v[112:115], v[168:171], v[188:191], v[112:115]
	v_mfma_f32_16x16x32_bf16 v[100:103], v[160:163], v[196:199], v[100:103]
	v_mfma_f32_16x16x32_bf16 v[96:99], v[168:171], v[196:199], v[96:99]
	v_mfma_f32_16x16x32_bf16 v[84:87], v[160:163], v[206:209], v[84:87]
	v_mfma_f32_16x16x32_bf16 v[80:83], v[168:171], v[206:209], v[80:83]
	v_mfma_f32_16x16x32_bf16 v[68:71], v[160:163], v[214:217], v[68:71]
	v_mfma_f32_16x16x32_bf16 v[64:67], v[168:171], v[214:217], v[64:67]
	s_setprio 0
	s_barrier
	s_mov_b32 m0, s48
	v_lshl_add_u64 v[182:183], s[30:31], 0, v[152:153]
	s_add_u32 s58, s30, 0x20000
	ds_read_b128 v[178:181], v177 offset:16384
	ds_read_b128 v[188:191], v177 offset:17408
	ds_read_b128 v[192:195], v177 offset:18432
	ds_read_b128 v[196:199], v177 offset:19456
	ds_read_b128 v[200:203], v177 offset:20480
	ds_read_b128 v[206:209], v177 offset:21504
	ds_read_b128 v[210:213], v177 offset:22528
	ds_read_b128 v[214:217], v177 offset:23552
	global_load_lds_dwordx4 v[182:183], off
	v_lshl_add_u64 v[218:219], s[30:31], 0, v[148:149]
	s_mov_b32 m0, s49
	s_addc_u32 s59, s31, 0
	global_load_lds_dwordx4 v[218:219], off
	v_lshl_add_u64 v[220:221], s[58:59], 0, v[152:153]
	s_mov_b32 m0, s50
	v_lshl_add_u64 v[222:223], s[34:35], 0, v[150:151]
	global_load_lds_dwordx4 v[220:221], off
	v_lshl_add_u64 v[220:221], s[58:59], 0, v[148:149]
	s_add_i32 m0, s50, 0x2000
	s_nop 0
	global_load_lds_dwordx4 v[220:221], off
	v_lshl_add_u64 v[220:221], s[34:35], 0, v[154:155]
	s_mov_b32 m0, s27
	s_nop 0
	global_load_lds_dwordx4 v[220:221], off
	s_mov_b32 m0, s39
	s_nop 0
	global_load_lds_dwordx4 v[222:223], off
	s_waitcnt vmcnt(8)
	s_waitcnt lgkmcnt(0)
	s_barrier
	s_setprio 1
	v_mfma_f32_16x16x32_bf16 v[60:63], v[128:131], v[178:181], v[60:63]
	v_mfma_f32_16x16x32_bf16 v[56:59], v[136:139], v[178:181], v[56:59]
	v_mfma_f32_16x16x32_bf16 v[44:47], v[128:131], v[192:195], v[44:47]
	v_mfma_f32_16x16x32_bf16 v[40:43], v[136:139], v[192:195], v[40:43]
	v_mfma_f32_16x16x32_bf16 v[28:31], v[128:131], v[200:203], v[28:31]
	v_mfma_f32_16x16x32_bf16 v[24:27], v[136:139], v[200:203], v[24:27]
	v_mfma_f32_16x16x32_bf16 v[12:15], v[128:131], v[210:213], v[12:15]
	v_mfma_f32_16x16x32_bf16 v[8:11], v[136:139], v[210:213], v[8:11]
	v_mfma_f32_16x16x32_bf16 v[60:63], v[132:135], v[188:191], v[60:63]
	v_mfma_f32_16x16x32_bf16 v[56:59], v[140:143], v[188:191], v[56:59]
	v_mfma_f32_16x16x32_bf16 v[44:47], v[132:135], v[196:199], v[44:47]
	v_mfma_f32_16x16x32_bf16 v[40:43], v[140:143], v[196:199], v[40:43]
	v_mfma_f32_16x16x32_bf16 v[28:31], v[132:135], v[206:209], v[28:31]
	v_mfma_f32_16x16x32_bf16 v[24:27], v[140:143], v[206:209], v[24:27]
	v_mfma_f32_16x16x32_bf16 v[12:15], v[132:135], v[214:217], v[12:15]
	v_mfma_f32_16x16x32_bf16 v[8:11], v[140:143], v[214:217], v[8:11]
	s_setprio 0
	s_setprio 1
	v_mfma_f32_16x16x32_bf16 v[52:55], v[144:147], v[178:181], v[52:55]
	v_mfma_f32_16x16x32_bf16 v[48:51], v[164:167], v[178:181], v[48:51]
	v_mfma_f32_16x16x32_bf16 v[36:39], v[144:147], v[192:195], v[36:39]
	v_mfma_f32_16x16x32_bf16 v[32:35], v[164:167], v[192:195], v[32:35]
	v_mfma_f32_16x16x32_bf16 v[20:23], v[144:147], v[200:203], v[20:23]
	v_mfma_f32_16x16x32_bf16 v[16:19], v[164:167], v[200:203], v[16:19]
	v_mfma_f32_16x16x32_bf16 v[4:7], v[144:147], v[210:213], v[4:7]
	v_mfma_f32_16x16x32_bf16 v[0:3], v[164:167], v[210:213], v[0:3]
	v_mfma_f32_16x16x32_bf16 v[52:55], v[160:163], v[188:191], v[52:55]
	v_mfma_f32_16x16x32_bf16 v[48:51], v[168:171], v[188:191], v[48:51]
	v_mfma_f32_16x16x32_bf16 v[36:39], v[160:163], v[196:199], v[36:39]
	v_mfma_f32_16x16x32_bf16 v[32:35], v[168:171], v[196:199], v[32:35]
	v_mfma_f32_16x16x32_bf16 v[20:23], v[160:163], v[206:209], v[20:23]
	v_mfma_f32_16x16x32_bf16 v[16:19], v[168:171], v[206:209], v[16:19]
	v_mfma_f32_16x16x32_bf16 v[4:7], v[160:163], v[214:217], v[4:7]
	v_mfma_f32_16x16x32_bf16 v[0:3], v[168:171], v[214:217], v[0:3]
	s_setprio 0
	s_barrier
	s_add_i32 s57, 0, 0x18000
	s_add_i32 s58, 0, 0x1c000
	v_add_u32_e32 v140, s57, v173
	v_add_u32_e32 v168, s58, v173
	ds_read_b128 v[128:131], v140
	ds_read_b128 v[132:135], v140 offset:1024
	ds_read_b128 v[136:139], v140 offset:2048
	ds_read_b128 v[140:143], v140 offset:3072
	ds_read_b128 v[144:147], v168
	ds_read_b128 v[160:163], v168 offset:1024
	ds_read_b128 v[164:167], v168 offset:2048
	ds_read_b128 v[168:171], v168 offset:3072
	s_add_u32 s34, s34, 0x20000
	s_addc_u32 s35, s35, 0
	s_mov_b32 m0, s40
	v_lshl_add_u64 v[224:225], s[34:35], 0, v[154:155]
	ds_read_b128 v[178:181], v177 offset:32768
	ds_read_b128 v[188:191], v177 offset:33792
	ds_read_b128 v[192:195], v177 offset:34816
	ds_read_b128 v[196:199], v177 offset:35840
	ds_read_b128 v[200:203], v177 offset:36864
	ds_read_b128 v[206:209], v177 offset:37888
	ds_read_b128 v[210:213], v177 offset:38912
	ds_read_b128 v[214:217], v177 offset:39936
	global_load_lds_dwordx4 v[224:225], off
	v_lshl_add_u64 v[224:225], s[34:35], 0, v[150:151]
	s_mov_b32 m0, s41
	s_nop 0
	global_load_lds_dwordx4 v[224:225], off
	s_waitcnt vmcnt(8)
	s_waitcnt lgkmcnt(0)
	s_barrier
	s_setprio 1
	v_mfma_f32_16x16x32_bf16 v[124:127], v[128:131], v[178:181], v[124:127]
	v_mfma_f32_16x16x32_bf16 v[120:123], v[136:139], v[178:181], v[120:123]
	v_mfma_f32_16x16x32_bf16 v[108:111], v[128:131], v[192:195], v[108:111]
	v_mfma_f32_16x16x32_bf16 v[104:107], v[136:139], v[192:195], v[104:107]
	v_mfma_f32_16x16x32_bf16 v[92:95], v[128:131], v[200:203], v[92:95]
	v_mfma_f32_16x16x32_bf16 v[88:91], v[136:139], v[200:203], v[88:91]
	v_mfma_f32_16x16x32_bf16 v[76:79], v[128:131], v[210:213], v[76:79]
	v_mfma_f32_16x16x32_bf16 v[72:75], v[136:139], v[210:213], v[72:75]
	v_mfma_f32_16x16x32_bf16 v[124:127], v[132:135], v[188:191], v[124:127]
	v_mfma_f32_16x16x32_bf16 v[120:123], v[140:143], v[188:191], v[120:123]
	v_mfma_f32_16x16x32_bf16 v[108:111], v[132:135], v[196:199], v[108:111]
	v_mfma_f32_16x16x32_bf16 v[104:107], v[140:143], v[196:199], v[104:107]
	v_mfma_f32_16x16x32_bf16 v[92:95], v[132:135], v[206:209], v[92:95]
	v_mfma_f32_16x16x32_bf16 v[88:91], v[140:143], v[206:209], v[88:91]
	v_mfma_f32_16x16x32_bf16 v[76:79], v[132:135], v[214:217], v[76:79]
	v_mfma_f32_16x16x32_bf16 v[72:75], v[140:143], v[214:217], v[72:75]
	s_setprio 0
	s_setprio 1
	v_mfma_f32_16x16x32_bf16 v[116:119], v[144:147], v[178:181], v[116:119]
	v_mfma_f32_16x16x32_bf16 v[112:115], v[164:167], v[178:181], v[112:115]
	v_mfma_f32_16x16x32_bf16 v[100:103], v[144:147], v[192:195], v[100:103]
	v_mfma_f32_16x16x32_bf16 v[96:99], v[164:167], v[192:195], v[96:99]
	v_mfma_f32_16x16x32_bf16 v[84:87], v[144:147], v[200:203], v[84:87]
	v_mfma_f32_16x16x32_bf16 v[80:83], v[164:167], v[200:203], v[80:83]
	v_mfma_f32_16x16x32_bf16 v[68:71], v[144:147], v[210:213], v[68:71]
	v_mfma_f32_16x16x32_bf16 v[64:67], v[164:167], v[210:213], v[64:67]
	v_mfma_f32_16x16x32_bf16 v[116:119], v[160:163], v[188:191], v[116:119]
	v_mfma_f32_16x16x32_bf16 v[112:115], v[168:171], v[188:191], v[112:115]
	v_mfma_f32_16x16x32_bf16 v[100:103], v[160:163], v[196:199], v[100:103]
	v_mfma_f32_16x16x32_bf16 v[96:99], v[168:171], v[196:199], v[96:99]
	v_mfma_f32_16x16x32_bf16 v[84:87], v[160:163], v[206:209], v[84:87]
	v_mfma_f32_16x16x32_bf16 v[80:83], v[168:171], v[206:209], v[80:83]
	v_mfma_f32_16x16x32_bf16 v[68:71], v[160:163], v[214:217], v[68:71]
	v_mfma_f32_16x16x32_bf16 v[64:67], v[168:171], v[214:217], v[64:67]
	s_setprio 0
	s_barrier
	s_add_i32 s34, s57, s38
	v_lshl_add_u64 v[182:183], v[182:183], 0, s[10:11]
	s_mov_b32 m0, s34
	ds_read_b128 v[178:181], v177 offset:49152
	ds_read_b128 v[188:191], v177 offset:50176
	ds_read_b128 v[192:195], v177 offset:51200
	ds_read_b128 v[196:199], v177 offset:52224
	ds_read_b128 v[200:203], v177 offset:53248
	ds_read_b128 v[206:209], v177 offset:54272
	ds_read_b128 v[210:213], v177 offset:55296
	ds_read_b128 v[214:217], v177 offset:56320
	global_load_lds_dwordx4 v[182:183], off
	s_add_i32 m0, s34, 0x2000
	s_add_u32 s30, s30, 0x20080
	v_lshl_add_u64 v[182:183], v[218:219], 0, s[10:11]
	s_addc_u32 s31, s31, 0
	s_add_i32 s34, s58, s38
	global_load_lds_dwordx4 v[182:183], off
	v_lshl_add_u64 v[182:183], s[30:31], 0, v[152:153]
	s_mov_b32 m0, s34
	s_nop 0
	global_load_lds_dwordx4 v[182:183], off
	v_lshl_add_u64 v[182:183], s[30:31], 0, v[148:149]
	s_add_i32 m0, s34, 0x2000
	s_nop 0
	global_load_lds_dwordx4 v[182:183], off
	v_lshl_add_u64 v[182:183], v[220:221], 0, s[10:11]
	s_mov_b32 m0, s42
	s_nop 0
	global_load_lds_dwordx4 v[182:183], off
	v_lshl_add_u64 v[182:183], v[222:223], 0, s[10:11]
	s_mov_b32 m0, s43
	s_nop 0
	global_load_lds_dwordx4 v[182:183], off
	s_waitcnt vmcnt(8)
	s_waitcnt lgkmcnt(0)
	s_barrier
	s_setprio 1
	v_mfma_f32_16x16x32_bf16 v[60:63], v[128:131], v[178:181], v[60:63]
	v_mfma_f32_16x16x32_bf16 v[56:59], v[136:139], v[178:181], v[56:59]
	v_mfma_f32_16x16x32_bf16 v[44:47], v[128:131], v[192:195], v[44:47]
	v_mfma_f32_16x16x32_bf16 v[40:43], v[136:139], v[192:195], v[40:43]
	v_mfma_f32_16x16x32_bf16 v[28:31], v[128:131], v[200:203], v[28:31]
	v_mfma_f32_16x16x32_bf16 v[24:27], v[136:139], v[200:203], v[24:27]
	v_mfma_f32_16x16x32_bf16 v[12:15], v[128:131], v[210:213], v[12:15]
	v_mfma_f32_16x16x32_bf16 v[8:11], v[136:139], v[210:213], v[8:11]
	v_mfma_f32_16x16x32_bf16 v[60:63], v[132:135], v[188:191], v[60:63]
	v_mfma_f32_16x16x32_bf16 v[56:59], v[140:143], v[188:191], v[56:59]
	v_mfma_f32_16x16x32_bf16 v[44:47], v[132:135], v[196:199], v[44:47]
	v_mfma_f32_16x16x32_bf16 v[40:43], v[140:143], v[196:199], v[40:43]
	v_mfma_f32_16x16x32_bf16 v[28:31], v[132:135], v[206:209], v[28:31]
	v_mfma_f32_16x16x32_bf16 v[24:27], v[140:143], v[206:209], v[24:27]
	v_mfma_f32_16x16x32_bf16 v[12:15], v[132:135], v[214:217], v[12:15]
	v_mfma_f32_16x16x32_bf16 v[8:11], v[140:143], v[214:217], v[8:11]
	s_setprio 0
	s_setprio 1
	v_mfma_f32_16x16x32_bf16 v[52:55], v[144:147], v[178:181], v[52:55]
	v_mfma_f32_16x16x32_bf16 v[48:51], v[164:167], v[178:181], v[48:51]
	v_mfma_f32_16x16x32_bf16 v[36:39], v[144:147], v[192:195], v[36:39]
	v_mfma_f32_16x16x32_bf16 v[32:35], v[164:167], v[192:195], v[32:35]
	v_mfma_f32_16x16x32_bf16 v[20:23], v[144:147], v[200:203], v[20:23]
	v_mfma_f32_16x16x32_bf16 v[16:19], v[164:167], v[200:203], v[16:19]
	v_mfma_f32_16x16x32_bf16 v[4:7], v[144:147], v[210:213], v[4:7]
	v_mfma_f32_16x16x32_bf16 v[0:3], v[164:167], v[210:213], v[0:3]
	v_mfma_f32_16x16x32_bf16 v[52:55], v[160:163], v[188:191], v[52:55]
	v_mfma_f32_16x16x32_bf16 v[48:51], v[168:171], v[188:191], v[48:51]
	v_mfma_f32_16x16x32_bf16 v[36:39], v[160:163], v[196:199], v[36:39]
	v_mfma_f32_16x16x32_bf16 v[32:35], v[168:171], v[196:199], v[32:35]
	v_mfma_f32_16x16x32_bf16 v[20:23], v[160:163], v[206:209], v[20:23]
	v_mfma_f32_16x16x32_bf16 v[16:19], v[168:171], v[206:209], v[16:19]
	v_mfma_f32_16x16x32_bf16 v[4:7], v[160:163], v[214:217], v[4:7]
	v_mfma_f32_16x16x32_bf16 v[0:3], v[168:171], v[214:217], v[0:3]
	s_setprio 0
	s_barrier
	s_add_i32 s56, s56, 2
	s_add_u32 s28, s28, 0x100
	s_addc_u32 s29, s29, 0
	s_add_u32 s54, s54, 0x100
	s_addc_u32 s55, s55, 0
	s_cmp_gt_u32 s56, 5
	s_cbranch_scc0 .LBB0_807
	s_and_b64 vcc, exec, s[14:15]
	s_cbranch_vccz .LBB0_810
	s_barrier

.Llsb_skip_5:
.LBB0_893:
	ds_read_b128 v[128:131], v189
	ds_read_b128 v[132:135], v189 offset:1024
	ds_read_b128 v[136:139], v189 offset:2048
	ds_read_b128 v[140:143], v189 offset:3072
	ds_read_b128 v[144:147], v190
	ds_read_b128 v[164:167], v190 offset:1024
	ds_read_b128 v[168:171], v190 offset:2048
	ds_read_b128 v[172:175], v190 offset:3072
	s_add_u32 s28, s26, 0xfffe0080
	s_addc_u32 s29, s27, -1
	s_cmp_eq_u32 s52, 4
	s_cselect_b32 s31, s19, s29
	s_cselect_b32 s30, s48, s28
	s_cselect_b32 s29, s17, s51
	s_cselect_b32 s28, s49, s50
	v_lshl_add_u64 v[226:227], s[26:27], 0, v[156:157]
	s_add_i32 m0, s25, 0xc000
	ds_read_b128 v[192:195], v191
	ds_read_b128 v[196:199], v191 offset:1024
	ds_read_b128 v[200:203], v191 offset:2048
	ds_read_b128 v[206:209], v191 offset:3072
	ds_read_b128 v[210:213], v191 offset:4096
	ds_read_b128 v[214:217], v191 offset:5120
	ds_read_b128 v[218:221], v191 offset:6144
	ds_read_b128 v[222:225], v191 offset:7168
	global_load_lds_dwordx4 v[226:227], off
	v_lshl_add_u64 v[226:227], s[26:27], 0, v[158:159]
	s_add_i32 m0, s25, 0xe000
	s_nop 0
	global_load_lds_dwordx4 v[226:227], off
	s_waitcnt vmcnt(8)
	s_waitcnt lgkmcnt(0)
	s_barrier
	s_setprio 1
	v_mfma_f32_16x16x32_bf16 v[124:127], v[128:131], v[192:195], v[124:127]
	v_mfma_f32_16x16x32_bf16 v[120:123], v[136:139], v[192:195], v[120:123]
	v_mfma_f32_16x16x32_bf16 v[108:111], v[128:131], v[200:203], v[108:111]
	v_mfma_f32_16x16x32_bf16 v[104:107], v[136:139], v[200:203], v[104:107]
	v_mfma_f32_16x16x32_bf16 v[92:95], v[128:131], v[210:213], v[92:95]
	v_mfma_f32_16x16x32_bf16 v[88:91], v[136:139], v[210:213], v[88:91]
	v_mfma_f32_16x16x32_bf16 v[76:79], v[128:131], v[218:221], v[76:79]
	v_mfma_f32_16x16x32_bf16 v[72:75], v[136:139], v[218:221], v[72:75]
	v_mfma_f32_16x16x32_bf16 v[124:127], v[132:135], v[196:199], v[124:127]
	v_mfma_f32_16x16x32_bf16 v[120:123], v[140:143], v[196:199], v[120:123]
	v_mfma_f32_16x16x32_bf16 v[108:111], v[132:135], v[206:209], v[108:111]
	v_mfma_f32_16x16x32_bf16 v[104:107], v[140:143], v[206:209], v[104:107]
	v_mfma_f32_16x16x32_bf16 v[92:95], v[132:135], v[214:217], v[92:95]
	v_mfma_f32_16x16x32_bf16 v[88:91], v[140:143], v[214:217], v[88:91]
	v_mfma_f32_16x16x32_bf16 v[76:79], v[132:135], v[222:225], v[76:79]
	v_mfma_f32_16x16x32_bf16 v[72:75], v[140:143], v[222:225], v[72:75]
	s_setprio 0
	s_setprio 1
	v_mfma_f32_16x16x32_bf16 v[116:119], v[144:147], v[192:195], v[116:119]
	v_mfma_f32_16x16x32_bf16 v[112:115], v[168:171], v[192:195], v[112:115]
	v_mfma_f32_16x16x32_bf16 v[100:103], v[144:147], v[200:203], v[100:103]
	v_mfma_f32_16x16x32_bf16 v[96:99], v[168:171], v[200:203], v[96:99]
	v_mfma_f32_16x16x32_bf16 v[84:87], v[144:147], v[210:213], v[84:87]
	v_mfma_f32_16x16x32_bf16 v[80:83], v[168:171], v[210:213], v[80:83]
	v_mfma_f32_16x16x32_bf16 v[68:71], v[144:147], v[218:221], v[68:71]
	v_mfma_f32_16x16x32_bf16 v[64:67], v[168:171], v[218:221], v[64:67]
	v_mfma_f32_16x16x32_bf16 v[116:119], v[164:167], v[196:199], v[116:119]
	v_mfma_f32_16x16x32_bf16 v[112:115], v[172:175], v[196:199], v[112:115]
	v_mfma_f32_16x16x32_bf16 v[100:103], v[164:167], v[206:209], v[100:103]
	v_mfma_f32_16x16x32_bf16 v[96:99], v[172:175], v[206:209], v[96:99]
	v_mfma_f32_16x16x32_bf16 v[84:87], v[164:167], v[214:217], v[84:87]
	v_mfma_f32_16x16x32_bf16 v[80:83], v[172:175], v[214:217], v[80:83]
	v_mfma_f32_16x16x32_bf16 v[68:71], v[164:167], v[222:225], v[68:71]
	v_mfma_f32_16x16x32_bf16 v[64:67], v[172:175], v[222:225], v[64:67]
	s_setprio 0
	s_barrier
	s_add_i32 s53, s44, s36
	v_lshl_add_u64 v[226:227], s[28:29], 0, v[150:151]
	s_mov_b32 m0, s53
	ds_read_b128 v[192:195], v191 offset:16384
	ds_read_b128 v[196:199], v191 offset:17408
	ds_read_b128 v[200:203], v191 offset:18432
	ds_read_b128 v[206:209], v191 offset:19456
	ds_read_b128 v[210:213], v191 offset:20480
	ds_read_b128 v[214:217], v191 offset:21504
	ds_read_b128 v[218:221], v191 offset:22528
	ds_read_b128 v[222:225], v191 offset:23552
	global_load_lds_dwordx4 v[226:227], off
	s_add_i32 m0, s53, 0x2000
	s_add_u32 s54, s28, 0x20000
	v_lshl_add_u64 v[228:229], s[28:29], 0, v[154:155]
	s_addc_u32 s55, s29, 0
	s_add_i32 s53, s45, s36
	global_load_lds_dwordx4 v[228:229], off
	v_lshl_add_u64 v[230:231], s[54:55], 0, v[150:151]
	s_mov_b32 m0, s53
	v_lshl_add_u64 v[232:233], s[30:31], 0, v[152:153]
	global_load_lds_dwordx4 v[230:231], off
	v_lshl_add_u64 v[230:231], s[54:55], 0, v[154:155]
	s_add_i32 m0, s53, 0x2000
	s_nop 0
	global_load_lds_dwordx4 v[230:231], off
	v_lshl_add_u64 v[230:231], s[30:31], 0, v[148:149]
	s_mov_b32 m0, s25
	s_nop 0
	global_load_lds_dwordx4 v[230:231], off
	s_mov_b32 m0, s37
	s_nop 0
	global_load_lds_dwordx4 v[232:233], off
	s_waitcnt vmcnt(8)
	s_waitcnt lgkmcnt(0)
	s_barrier
	s_setprio 1
	v_mfma_f32_16x16x32_bf16 v[60:63], v[128:131], v[192:195], v[60:63]
	v_mfma_f32_16x16x32_bf16 v[56:59], v[136:139], v[192:195], v[56:59]
	v_mfma_f32_16x16x32_bf16 v[44:47], v[128:131], v[200:203], v[44:47]
	v_mfma_f32_16x16x32_bf16 v[40:43], v[136:139], v[200:203], v[40:43]
	v_mfma_f32_16x16x32_bf16 v[28:31], v[128:131], v[210:213], v[28:31]
	v_mfma_f32_16x16x32_bf16 v[24:27], v[136:139], v[210:213], v[24:27]
	v_mfma_f32_16x16x32_bf16 v[12:15], v[128:131], v[218:221], v[12:15]
	v_mfma_f32_16x16x32_bf16 v[8:11], v[136:139], v[218:221], v[8:11]
	v_mfma_f32_16x16x32_bf16 v[60:63], v[132:135], v[196:199], v[60:63]
	v_mfma_f32_16x16x32_bf16 v[56:59], v[140:143], v[196:199], v[56:59]
	v_mfma_f32_16x16x32_bf16 v[44:47], v[132:135], v[206:209], v[44:47]
	v_mfma_f32_16x16x32_bf16 v[40:43], v[140:143], v[206:209], v[40:43]
	v_mfma_f32_16x16x32_bf16 v[28:31], v[132:135], v[214:217], v[28:31]
	v_mfma_f32_16x16x32_bf16 v[24:27], v[140:143], v[214:217], v[24:27]
	v_mfma_f32_16x16x32_bf16 v[12:15], v[132:135], v[222:225], v[12:15]
	v_mfma_f32_16x16x32_bf16 v[8:11], v[140:143], v[222:225], v[8:11]
	s_setprio 0
	s_setprio 1
	v_mfma_f32_16x16x32_bf16 v[52:55], v[144:147], v[192:195], v[52:55]
	v_mfma_f32_16x16x32_bf16 v[48:51], v[168:171], v[192:195], v[48:51]
	v_mfma_f32_16x16x32_bf16 v[36:39], v[144:147], v[200:203], v[36:39]
	v_mfma_f32_16x16x32_bf16 v[32:35], v[168:171], v[200:203], v[32:35]
	v_mfma_f32_16x16x32_bf16 v[20:23], v[144:147], v[210:213], v[20:23]
	v_mfma_f32_16x16x32_bf16 v[16:19], v[168:171], v[210:213], v[16:19]
	v_mfma_f32_16x16x32_bf16 v[4:7], v[144:147], v[218:221], v[4:7]
	v_mfma_f32_16x16x32_bf16 v[0:3], v[168:171], v[218:221], v[0:3]
	v_mfma_f32_16x16x32_bf16 v[52:55], v[164:167], v[196:199], v[52:55]
	v_mfma_f32_16x16x32_bf16 v[48:51], v[172:175], v[196:199], v[48:51]
	v_mfma_f32_16x16x32_bf16 v[36:39], v[164:167], v[206:209], v[36:39]
	v_mfma_f32_16x16x32_bf16 v[32:35], v[172:175], v[206:209], v[32:35]
	v_mfma_f32_16x16x32_bf16 v[20:23], v[164:167], v[214:217], v[20:23]
	v_mfma_f32_16x16x32_bf16 v[16:19], v[172:175], v[214:217], v[16:19]
	v_mfma_f32_16x16x32_bf16 v[4:7], v[164:167], v[222:225], v[4:7]
	v_mfma_f32_16x16x32_bf16 v[0:3], v[172:175], v[222:225], v[0:3]
	s_setprio 0
	s_barrier
	s_add_i32 s53, 0, 0x18000
	s_add_i32 s54, 0, 0x1c000
	v_add_u32_e32 v140, s53, v187
	v_add_u32_e32 v172, s54, v187
	ds_read_b128 v[128:131], v140
	ds_read_b128 v[132:135], v140 offset:1024
	ds_read_b128 v[136:139], v140 offset:2048
	ds_read_b128 v[140:143], v140 offset:3072
	ds_read_b128 v[144:147], v172
	ds_read_b128 v[164:167], v172 offset:1024
	ds_read_b128 v[168:171], v172 offset:2048
	ds_read_b128 v[172:175], v172 offset:3072
	s_add_u32 s30, s30, 0x20000
	s_addc_u32 s31, s31, 0
	s_mov_b32 m0, s38
	v_lshl_add_u64 v[234:235], s[30:31], 0, v[148:149]
	ds_read_b128 v[192:195], v191 offset:32768
	ds_read_b128 v[196:199], v191 offset:33792
	ds_read_b128 v[200:203], v191 offset:34816
	ds_read_b128 v[206:209], v191 offset:35840
	ds_read_b128 v[210:213], v191 offset:36864
	ds_read_b128 v[214:217], v191 offset:37888
	ds_read_b128 v[218:221], v191 offset:38912
	ds_read_b128 v[222:225], v191 offset:39936
	global_load_lds_dwordx4 v[234:235], off
	v_lshl_add_u64 v[234:235], s[30:31], 0, v[152:153]
	s_mov_b32 m0, s39
	s_nop 0
	global_load_lds_dwordx4 v[234:235], off
	s_waitcnt vmcnt(8)
	s_waitcnt lgkmcnt(0)
	s_barrier
	s_setprio 1
	v_mfma_f32_16x16x32_bf16 v[124:127], v[128:131], v[192:195], v[124:127]
	v_mfma_f32_16x16x32_bf16 v[120:123], v[136:139], v[192:195], v[120:123]
	v_mfma_f32_16x16x32_bf16 v[108:111], v[128:131], v[200:203], v[108:111]
	v_mfma_f32_16x16x32_bf16 v[104:107], v[136:139], v[200:203], v[104:107]
	v_mfma_f32_16x16x32_bf16 v[92:95], v[128:131], v[210:213], v[92:95]
	v_mfma_f32_16x16x32_bf16 v[88:91], v[136:139], v[210:213], v[88:91]
	v_mfma_f32_16x16x32_bf16 v[76:79], v[128:131], v[218:221], v[76:79]
	v_mfma_f32_16x16x32_bf16 v[72:75], v[136:139], v[218:221], v[72:75]
	v_mfma_f32_16x16x32_bf16 v[124:127], v[132:135], v[196:199], v[124:127]
	v_mfma_f32_16x16x32_bf16 v[120:123], v[140:143], v[196:199], v[120:123]
	v_mfma_f32_16x16x32_bf16 v[108:111], v[132:135], v[206:209], v[108:111]
	v_mfma_f32_16x16x32_bf16 v[104:107], v[140:143], v[206:209], v[104:107]
	v_mfma_f32_16x16x32_bf16 v[92:95], v[132:135], v[214:217], v[92:95]
	v_mfma_f32_16x16x32_bf16 v[88:91], v[140:143], v[214:217], v[88:91]
	v_mfma_f32_16x16x32_bf16 v[76:79], v[132:135], v[222:225], v[76:79]
	v_mfma_f32_16x16x32_bf16 v[72:75], v[140:143], v[222:225], v[72:75]
	s_setprio 0
	s_setprio 1
	v_mfma_f32_16x16x32_bf16 v[116:119], v[144:147], v[192:195], v[116:119]
	v_mfma_f32_16x16x32_bf16 v[112:115], v[168:171], v[192:195], v[112:115]
	v_mfma_f32_16x16x32_bf16 v[100:103], v[144:147], v[200:203], v[100:103]
	v_mfma_f32_16x16x32_bf16 v[96:99], v[168:171], v[200:203], v[96:99]
	v_mfma_f32_16x16x32_bf16 v[84:87], v[144:147], v[210:213], v[84:87]
	v_mfma_f32_16x16x32_bf16 v[80:83], v[168:171], v[210:213], v[80:83]
	v_mfma_f32_16x16x32_bf16 v[68:71], v[144:147], v[218:221], v[68:71]
	v_mfma_f32_16x16x32_bf16 v[64:67], v[168:171], v[218:221], v[64:67]
	v_mfma_f32_16x16x32_bf16 v[116:119], v[164:167], v[196:199], v[116:119]
	v_mfma_f32_16x16x32_bf16 v[112:115], v[172:175], v[196:199], v[112:115]
	v_mfma_f32_16x16x32_bf16 v[100:103], v[164:167], v[206:209], v[100:103]
	v_mfma_f32_16x16x32_bf16 v[96:99], v[172:175], v[206:209], v[96:99]
	v_mfma_f32_16x16x32_bf16 v[84:87], v[164:167], v[214:217], v[84:87]
	v_mfma_f32_16x16x32_bf16 v[80:83], v[172:175], v[214:217], v[80:83]
	v_mfma_f32_16x16x32_bf16 v[68:71], v[164:167], v[222:225], v[68:71]
	v_mfma_f32_16x16x32_bf16 v[64:67], v[172:175], v[222:225], v[64:67]
	s_setprio 0
	s_barrier
	s_add_i32 s30, s53, s36
	v_lshl_add_u64 v[226:227], v[226:227], 0, s[12:13]
	s_mov_b32 m0, s30
	ds_read_b128 v[192:195], v191 offset:49152
	ds_read_b128 v[196:199], v191 offset:50176
	ds_read_b128 v[200:203], v191 offset:51200
	ds_read_b128 v[206:209], v191 offset:52224
	ds_read_b128 v[210:213], v191 offset:53248
	ds_read_b128 v[214:217], v191 offset:54272
	ds_read_b128 v[218:221], v191 offset:55296
	ds_read_b128 v[222:225], v191 offset:56320
	global_load_lds_dwordx4 v[226:227], off
	s_add_i32 m0, s30, 0x2000
	s_add_u32 s28, s28, 0x20080
	v_lshl_add_u64 v[226:227], v[228:229], 0, s[12:13]
	s_addc_u32 s29, s29, 0
	s_add_i32 s30, s54, s36
	global_load_lds_dwordx4 v[226:227], off
	v_lshl_add_u64 v[226:227], s[28:29], 0, v[150:151]
	s_mov_b32 m0, s30
	s_nop 0
	global_load_lds_dwordx4 v[226:227], off
	v_lshl_add_u64 v[226:227], s[28:29], 0, v[154:155]
	s_add_i32 m0, s30, 0x2000
	s_nop 0
	global_load_lds_dwordx4 v[226:227], off
	v_lshl_add_u64 v[226:227], v[230:231], 0, s[12:13]
	s_mov_b32 m0, s41
	s_nop 0
	global_load_lds_dwordx4 v[226:227], off
	v_lshl_add_u64 v[226:227], v[232:233], 0, s[12:13]
	s_mov_b32 m0, s42
	s_nop 0
	global_load_lds_dwordx4 v[226:227], off
	s_waitcnt vmcnt(8)
	s_waitcnt lgkmcnt(0)
	s_barrier
	s_setprio 1
	v_mfma_f32_16x16x32_bf16 v[60:63], v[128:131], v[192:195], v[60:63]
	v_mfma_f32_16x16x32_bf16 v[56:59], v[136:139], v[192:195], v[56:59]
	v_mfma_f32_16x16x32_bf16 v[44:47], v[128:131], v[200:203], v[44:47]
	v_mfma_f32_16x16x32_bf16 v[40:43], v[136:139], v[200:203], v[40:43]
	v_mfma_f32_16x16x32_bf16 v[28:31], v[128:131], v[210:213], v[28:31]
	v_mfma_f32_16x16x32_bf16 v[24:27], v[136:139], v[210:213], v[24:27]
	v_mfma_f32_16x16x32_bf16 v[12:15], v[128:131], v[218:221], v[12:15]
	v_mfma_f32_16x16x32_bf16 v[8:11], v[136:139], v[218:221], v[8:11]
	v_mfma_f32_16x16x32_bf16 v[60:63], v[132:135], v[196:199], v[60:63]
	v_mfma_f32_16x16x32_bf16 v[56:59], v[140:143], v[196:199], v[56:59]
	v_mfma_f32_16x16x32_bf16 v[44:47], v[132:135], v[206:209], v[44:47]
	v_mfma_f32_16x16x32_bf16 v[40:43], v[140:143], v[206:209], v[40:43]
	v_mfma_f32_16x16x32_bf16 v[28:31], v[132:135], v[214:217], v[28:31]
	v_mfma_f32_16x16x32_bf16 v[24:27], v[140:143], v[214:217], v[24:27]
	v_mfma_f32_16x16x32_bf16 v[12:15], v[132:135], v[222:225], v[12:15]
	v_mfma_f32_16x16x32_bf16 v[8:11], v[140:143], v[222:225], v[8:11]
	s_setprio 0
	s_setprio 1
	v_mfma_f32_16x16x32_bf16 v[52:55], v[144:147], v[192:195], v[52:55]
	v_mfma_f32_16x16x32_bf16 v[48:51], v[168:171], v[192:195], v[48:51]
	v_mfma_f32_16x16x32_bf16 v[36:39], v[144:147], v[200:203], v[36:39]
	v_mfma_f32_16x16x32_bf16 v[32:35], v[168:171], v[200:203], v[32:35]
	v_mfma_f32_16x16x32_bf16 v[20:23], v[144:147], v[210:213], v[20:23]
	v_mfma_f32_16x16x32_bf16 v[16:19], v[168:171], v[210:213], v[16:19]
	v_mfma_f32_16x16x32_bf16 v[4:7], v[144:147], v[218:221], v[4:7]
	v_mfma_f32_16x16x32_bf16 v[0:3], v[168:171], v[218:221], v[0:3]
	v_mfma_f32_16x16x32_bf16 v[52:55], v[164:167], v[196:199], v[52:55]
	v_mfma_f32_16x16x32_bf16 v[48:51], v[172:175], v[196:199], v[48:51]
	v_mfma_f32_16x16x32_bf16 v[36:39], v[164:167], v[206:209], v[36:39]
	v_mfma_f32_16x16x32_bf16 v[32:35], v[172:175], v[206:209], v[32:35]
	v_mfma_f32_16x16x32_bf16 v[20:23], v[164:167], v[214:217], v[20:23]
	v_mfma_f32_16x16x32_bf16 v[16:19], v[172:175], v[214:217], v[16:19]
	v_mfma_f32_16x16x32_bf16 v[4:7], v[164:167], v[222:225], v[4:7]
	v_mfma_f32_16x16x32_bf16 v[0:3], v[172:175], v[222:225], v[0:3]
	s_setprio 0
	s_barrier
	s_add_i32 s52, s52, 2
	s_add_u32 s26, s26, 0x100
	s_addc_u32 s27, s27, 0
	s_add_u32 s50, s50, 0x100
	s_addc_u32 s51, s51, 0
	s_cmp_gt_u32 s52, 5
	s_cbranch_scc0 .LBB0_893
	s_and_b64 vcc, exec, s[14:15]
	s_cbranch_vccz .LBB0_896
	s_barrier

.Llsb_skip_6:
.LBB0_913:
	ds_read_b128 v[136:139], v154
	ds_read_b128 v[140:143], v154 offset:1024
	ds_read_b128 v[144:147], v154 offset:2048
	ds_read_b128 v[158:161], v154 offset:3072
	ds_read_b128 v[162:165], v155
	ds_read_b128 v[166:169], v155 offset:1024
	ds_read_b128 v[170:173], v155 offset:2048
	ds_read_b128 v[180:183], v155 offset:3072
	s_add_u32 s28, s26, 0xfffa0080
	s_addc_u32 s29, s27, -1
	s_cmp_eq_u32 s57, 4
	s_cselect_b32 s31, s23, s29
	s_cselect_b32 s30, s22, s28
	s_cselect_b32 s29, s25, s56
	s_cselect_b32 s28, s24, s55
	v_lshl_add_u64 v[148:149], s[26:27], 0, v[132:133]
	s_add_i32 m0, s37, 0xc000
	ds_read_b128 v[184:187], v156
	ds_read_b128 v[188:191], v156 offset:1024
	ds_read_b128 v[192:195], v156 offset:2048
	ds_read_b128 v[196:199], v156 offset:3072
	ds_read_b128 v[200:203], v156 offset:4096
	ds_read_b128 v[206:209], v156 offset:5120
	ds_read_b128 v[210:213], v156 offset:6144
	ds_read_b128 v[214:217], v156 offset:7168
	global_load_lds_dwordx4 v[148:149], off
	v_lshl_add_u64 v[148:149], s[26:27], 0, v[134:135]
	s_add_i32 m0, s37, 0xe000
	s_nop 0
	global_load_lds_dwordx4 v[148:149], off
	s_waitcnt vmcnt(8)
	s_waitcnt lgkmcnt(0)
	s_barrier
	s_setprio 1
	v_mfma_f32_16x16x32_bf16 v[124:127], v[136:139], v[184:187], v[124:127]
	v_mfma_f32_16x16x32_bf16 v[120:123], v[144:147], v[184:187], v[120:123]
	v_mfma_f32_16x16x32_bf16 v[112:115], v[136:139], v[192:195], v[112:115]
	v_mfma_f32_16x16x32_bf16 v[104:107], v[144:147], v[192:195], v[104:107]
	v_mfma_f32_16x16x32_bf16 v[96:99], v[136:139], v[200:203], v[96:99]
	v_mfma_f32_16x16x32_bf16 v[88:91], v[144:147], v[200:203], v[88:91]
	v_mfma_f32_16x16x32_bf16 v[80:83], v[136:139], v[210:213], v[80:83]
	v_mfma_f32_16x16x32_bf16 v[72:75], v[144:147], v[210:213], v[72:75]
	v_mfma_f32_16x16x32_bf16 v[124:127], v[140:143], v[188:191], v[124:127]
	v_mfma_f32_16x16x32_bf16 v[120:123], v[158:161], v[188:191], v[120:123]
	v_mfma_f32_16x16x32_bf16 v[112:115], v[140:143], v[196:199], v[112:115]
	v_mfma_f32_16x16x32_bf16 v[104:107], v[158:161], v[196:199], v[104:107]
	v_mfma_f32_16x16x32_bf16 v[96:99], v[140:143], v[206:209], v[96:99]
	v_mfma_f32_16x16x32_bf16 v[88:91], v[158:161], v[206:209], v[88:91]
	v_mfma_f32_16x16x32_bf16 v[80:83], v[140:143], v[214:217], v[80:83]
	v_mfma_f32_16x16x32_bf16 v[72:75], v[158:161], v[214:217], v[72:75]
	s_setprio 0
	s_setprio 1
	v_mfma_f32_16x16x32_bf16 v[116:119], v[162:165], v[184:187], v[116:119]
	v_mfma_f32_16x16x32_bf16 v[108:111], v[170:173], v[184:187], v[108:111]
	v_mfma_f32_16x16x32_bf16 v[100:103], v[162:165], v[192:195], v[100:103]
	v_mfma_f32_16x16x32_bf16 v[92:95], v[170:173], v[192:195], v[92:95]
	v_mfma_f32_16x16x32_bf16 v[84:87], v[162:165], v[200:203], v[84:87]
	v_mfma_f32_16x16x32_bf16 v[76:79], v[170:173], v[200:203], v[76:79]
	v_mfma_f32_16x16x32_bf16 v[68:71], v[162:165], v[210:213], v[68:71]
	v_mfma_f32_16x16x32_bf16 v[64:67], v[170:173], v[210:213], v[64:67]
	v_mfma_f32_16x16x32_bf16 v[116:119], v[166:169], v[188:191], v[116:119]
	v_mfma_f32_16x16x32_bf16 v[108:111], v[180:183], v[188:191], v[108:111]
	v_mfma_f32_16x16x32_bf16 v[100:103], v[166:169], v[196:199], v[100:103]
	v_mfma_f32_16x16x32_bf16 v[92:95], v[180:183], v[196:199], v[92:95]
	v_mfma_f32_16x16x32_bf16 v[84:87], v[166:169], v[206:209], v[84:87]
	v_mfma_f32_16x16x32_bf16 v[76:79], v[180:183], v[206:209], v[76:79]
	v_mfma_f32_16x16x32_bf16 v[68:71], v[166:169], v[214:217], v[68:71]
	v_mfma_f32_16x16x32_bf16 v[64:67], v[180:183], v[214:217], v[64:67]
	s_setprio 0
	s_barrier
	s_add_i32 s58, s44, s36
	v_lshl_add_u64 v[148:149], s[28:29], 0, v[130:131]
	s_mov_b32 m0, s58
	ds_read_b128 v[184:187], v156 offset:16384
	ds_read_b128 v[188:191], v156 offset:17408
	ds_read_b128 v[192:195], v156 offset:18432
	ds_read_b128 v[196:199], v156 offset:19456
	ds_read_b128 v[200:203], v156 offset:20480
	ds_read_b128 v[206:209], v156 offset:21504
	ds_read_b128 v[210:213], v156 offset:22528
	ds_read_b128 v[214:217], v156 offset:23552
	global_load_lds_dwordx4 v[148:149], off
	s_add_i32 m0, s58, 0x2000
	s_add_u32 s58, s28, 0x60000
	v_lshl_add_u64 v[174:175], s[28:29], 0, v[128:129]
	s_addc_u32 s59, s29, 0
	s_add_i32 s60, s45, s36
	global_load_lds_dwordx4 v[174:175], off
	v_lshl_add_u64 v[218:219], s[58:59], 0, v[130:131]
	s_mov_b32 m0, s60
	v_lshl_add_u64 v[220:221], s[30:31], 0, v[128:129]
	global_load_lds_dwordx4 v[218:219], off
	v_lshl_add_u64 v[218:219], s[58:59], 0, v[128:129]
	s_add_i32 m0, s60, 0x2000
	s_nop 0
	global_load_lds_dwordx4 v[218:219], off
	v_lshl_add_u64 v[218:219], s[30:31], 0, v[130:131]
	s_mov_b32 m0, s37
	s_nop 0
	global_load_lds_dwordx4 v[218:219], off
	s_mov_b32 m0, s38
	s_nop 0
	global_load_lds_dwordx4 v[220:221], off
	s_waitcnt vmcnt(8)
	s_waitcnt lgkmcnt(0)
	s_barrier
	s_setprio 1
	v_mfma_f32_16x16x32_bf16 v[60:63], v[136:139], v[184:187], v[60:63]
	v_mfma_f32_16x16x32_bf16 v[56:59], v[144:147], v[184:187], v[56:59]
	v_mfma_f32_16x16x32_bf16 v[48:51], v[136:139], v[192:195], v[48:51]
	v_mfma_f32_16x16x32_bf16 v[40:43], v[144:147], v[192:195], v[40:43]
	v_mfma_f32_16x16x32_bf16 v[32:35], v[136:139], v[200:203], v[32:35]
	v_mfma_f32_16x16x32_bf16 v[24:27], v[144:147], v[200:203], v[24:27]
	v_mfma_f32_16x16x32_bf16 v[16:19], v[136:139], v[210:213], v[16:19]
	v_mfma_f32_16x16x32_bf16 v[8:11], v[144:147], v[210:213], v[8:11]
	v_mfma_f32_16x16x32_bf16 v[60:63], v[140:143], v[188:191], v[60:63]
	v_mfma_f32_16x16x32_bf16 v[56:59], v[158:161], v[188:191], v[56:59]
	v_mfma_f32_16x16x32_bf16 v[48:51], v[140:143], v[196:199], v[48:51]
	v_mfma_f32_16x16x32_bf16 v[40:43], v[158:161], v[196:199], v[40:43]
	v_mfma_f32_16x16x32_bf16 v[32:35], v[140:143], v[206:209], v[32:35]
	v_mfma_f32_16x16x32_bf16 v[24:27], v[158:161], v[206:209], v[24:27]
	v_mfma_f32_16x16x32_bf16 v[16:19], v[140:143], v[214:217], v[16:19]
	v_mfma_f32_16x16x32_bf16 v[8:11], v[158:161], v[214:217], v[8:11]
	s_setprio 0
	s_setprio 1
	v_mfma_f32_16x16x32_bf16 v[52:55], v[162:165], v[184:187], v[52:55]
	v_mfma_f32_16x16x32_bf16 v[44:47], v[170:173], v[184:187], v[44:47]
	v_mfma_f32_16x16x32_bf16 v[36:39], v[162:165], v[192:195], v[36:39]
	v_mfma_f32_16x16x32_bf16 v[28:31], v[170:173], v[192:195], v[28:31]
	v_mfma_f32_16x16x32_bf16 v[20:23], v[162:165], v[200:203], v[20:23]
	v_mfma_f32_16x16x32_bf16 v[12:15], v[170:173], v[200:203], v[12:15]
	v_mfma_f32_16x16x32_bf16 v[4:7], v[162:165], v[210:213], v[4:7]
	v_mfma_f32_16x16x32_bf16 v[0:3], v[170:173], v[210:213], v[0:3]
	v_mfma_f32_16x16x32_bf16 v[52:55], v[166:169], v[188:191], v[52:55]
	v_mfma_f32_16x16x32_bf16 v[44:47], v[180:183], v[188:191], v[44:47]
	v_mfma_f32_16x16x32_bf16 v[36:39], v[166:169], v[196:199], v[36:39]
	v_mfma_f32_16x16x32_bf16 v[28:31], v[180:183], v[196:199], v[28:31]
	v_mfma_f32_16x16x32_bf16 v[20:23], v[166:169], v[206:209], v[20:23]
	v_mfma_f32_16x16x32_bf16 v[12:15], v[180:183], v[206:209], v[12:15]
	v_mfma_f32_16x16x32_bf16 v[4:7], v[166:169], v[214:217], v[4:7]
	v_mfma_f32_16x16x32_bf16 v[0:3], v[180:183], v[214:217], v[0:3]
	s_setprio 0
	s_barrier
	s_add_i32 s58, 0, 0x18000
	v_add_u32_e32 v157, s58, v152
	s_add_i32 s59, 0, 0x1c000
	ds_read_b128 v[136:139], v157
	ds_read_b128 v[140:143], v157 offset:1024
	ds_read_b128 v[144:147], v157 offset:2048
	ds_read_b128 v[158:161], v157 offset:3072
	v_add_u32_e32 v157, s59, v152
	ds_read_b128 v[162:165], v157
	ds_read_b128 v[166:169], v157 offset:1024
	ds_read_b128 v[170:173], v157 offset:2048
	ds_read_b128 v[180:183], v157 offset:3072
	s_add_u32 s30, s30, 0x60000
	s_addc_u32 s31, s31, 0
	s_mov_b32 m0, s39
	v_lshl_add_u64 v[222:223], s[30:31], 0, v[130:131]
	ds_read_b128 v[184:187], v156 offset:32768
	ds_read_b128 v[188:191], v156 offset:33792
	ds_read_b128 v[192:195], v156 offset:34816
	ds_read_b128 v[196:199], v156 offset:35840
	ds_read_b128 v[200:203], v156 offset:36864
	ds_read_b128 v[206:209], v156 offset:37888
	ds_read_b128 v[210:213], v156 offset:38912
	ds_read_b128 v[214:217], v156 offset:39936
	global_load_lds_dwordx4 v[222:223], off
	v_lshl_add_u64 v[222:223], s[30:31], 0, v[128:129]
	s_mov_b32 m0, s40
	s_nop 0
	global_load_lds_dwordx4 v[222:223], off
	s_waitcnt vmcnt(8)
	s_waitcnt lgkmcnt(0)
	s_barrier
	s_setprio 1
	v_mfma_f32_16x16x32_bf16 v[124:127], v[136:139], v[184:187], v[124:127]
	v_mfma_f32_16x16x32_bf16 v[120:123], v[144:147], v[184:187], v[120:123]
	v_mfma_f32_16x16x32_bf16 v[112:115], v[136:139], v[192:195], v[112:115]
	v_mfma_f32_16x16x32_bf16 v[104:107], v[144:147], v[192:195], v[104:107]
	v_mfma_f32_16x16x32_bf16 v[96:99], v[136:139], v[200:203], v[96:99]
	v_mfma_f32_16x16x32_bf16 v[88:91], v[144:147], v[200:203], v[88:91]
	v_mfma_f32_16x16x32_bf16 v[80:83], v[136:139], v[210:213], v[80:83]
	v_mfma_f32_16x16x32_bf16 v[72:75], v[144:147], v[210:213], v[72:75]
	v_mfma_f32_16x16x32_bf16 v[124:127], v[140:143], v[188:191], v[124:127]
	v_mfma_f32_16x16x32_bf16 v[120:123], v[158:161], v[188:191], v[120:123]
	v_mfma_f32_16x16x32_bf16 v[112:115], v[140:143], v[196:199], v[112:115]
	v_mfma_f32_16x16x32_bf16 v[104:107], v[158:161], v[196:199], v[104:107]
	v_mfma_f32_16x16x32_bf16 v[96:99], v[140:143], v[206:209], v[96:99]
	v_mfma_f32_16x16x32_bf16 v[88:91], v[158:161], v[206:209], v[88:91]
	v_mfma_f32_16x16x32_bf16 v[80:83], v[140:143], v[214:217], v[80:83]
	v_mfma_f32_16x16x32_bf16 v[72:75], v[158:161], v[214:217], v[72:75]
	s_setprio 0
	s_setprio 1
	v_mfma_f32_16x16x32_bf16 v[116:119], v[162:165], v[184:187], v[116:119]
	v_mfma_f32_16x16x32_bf16 v[108:111], v[170:173], v[184:187], v[108:111]
	v_mfma_f32_16x16x32_bf16 v[100:103], v[162:165], v[192:195], v[100:103]
	v_mfma_f32_16x16x32_bf16 v[92:95], v[170:173], v[192:195], v[92:95]
	v_mfma_f32_16x16x32_bf16 v[84:87], v[162:165], v[200:203], v[84:87]
	v_mfma_f32_16x16x32_bf16 v[76:79], v[170:173], v[200:203], v[76:79]
	v_mfma_f32_16x16x32_bf16 v[68:71], v[162:165], v[210:213], v[68:71]
	v_mfma_f32_16x16x32_bf16 v[64:67], v[170:173], v[210:213], v[64:67]
	v_mfma_f32_16x16x32_bf16 v[116:119], v[166:169], v[188:191], v[116:119]
	v_mfma_f32_16x16x32_bf16 v[108:111], v[180:183], v[188:191], v[108:111]
	v_mfma_f32_16x16x32_bf16 v[100:103], v[166:169], v[196:199], v[100:103]
	v_mfma_f32_16x16x32_bf16 v[92:95], v[180:183], v[196:199], v[92:95]
	v_mfma_f32_16x16x32_bf16 v[84:87], v[166:169], v[206:209], v[84:87]
	v_mfma_f32_16x16x32_bf16 v[76:79], v[180:183], v[206:209], v[76:79]
	v_mfma_f32_16x16x32_bf16 v[68:71], v[166:169], v[214:217], v[68:71]
	v_mfma_f32_16x16x32_bf16 v[64:67], v[180:183], v[214:217], v[64:67]
	s_setprio 0
	s_barrier
	s_add_i32 s30, s58, s36
	v_lshl_add_u64 v[148:149], v[148:149], 0, s[16:17]
	s_mov_b32 m0, s30
	ds_read_b128 v[184:187], v156 offset:49152
	ds_read_b128 v[188:191], v156 offset:50176
	ds_read_b128 v[192:195], v156 offset:51200
	ds_read_b128 v[196:199], v156 offset:52224
	ds_read_b128 v[200:203], v156 offset:53248
	ds_read_b128 v[206:209], v156 offset:54272
	ds_read_b128 v[210:213], v156 offset:55296
	ds_read_b128 v[214:217], v156 offset:56320
	global_load_lds_dwordx4 v[148:149], off
	s_add_i32 m0, s30, 0x2000
	s_add_u32 s28, s28, 0x60080
	v_lshl_add_u64 v[148:149], v[174:175], 0, s[16:17]
	s_addc_u32 s29, s29, 0
	s_add_i32 s30, s59, s36
	global_load_lds_dwordx4 v[148:149], off
	v_lshl_add_u64 v[148:149], s[28:29], 0, v[130:131]
	s_mov_b32 m0, s30
	s_nop 0
	global_load_lds_dwordx4 v[148:149], off
	v_lshl_add_u64 v[148:149], s[28:29], 0, v[128:129]
	s_add_i32 m0, s30, 0x2000
	s_nop 0
	global_load_lds_dwordx4 v[148:149], off
	v_lshl_add_u64 v[148:149], v[218:219], 0, s[16:17]
	s_mov_b32 m0, s41
	s_nop 0
	global_load_lds_dwordx4 v[148:149], off
	v_lshl_add_u64 v[148:149], v[220:221], 0, s[16:17]
	s_mov_b32 m0, s42
	s_nop 0
	global_load_lds_dwordx4 v[148:149], off
	s_waitcnt vmcnt(8)
	s_waitcnt lgkmcnt(0)
	s_barrier
	s_setprio 1
	v_mfma_f32_16x16x32_bf16 v[60:63], v[136:139], v[184:187], v[60:63]
	v_mfma_f32_16x16x32_bf16 v[56:59], v[144:147], v[184:187], v[56:59]
	v_mfma_f32_16x16x32_bf16 v[48:51], v[136:139], v[192:195], v[48:51]
	v_mfma_f32_16x16x32_bf16 v[40:43], v[144:147], v[192:195], v[40:43]
	v_mfma_f32_16x16x32_bf16 v[32:35], v[136:139], v[200:203], v[32:35]
	v_mfma_f32_16x16x32_bf16 v[24:27], v[144:147], v[200:203], v[24:27]
	v_mfma_f32_16x16x32_bf16 v[16:19], v[136:139], v[210:213], v[16:19]
	v_mfma_f32_16x16x32_bf16 v[8:11], v[144:147], v[210:213], v[8:11]
	v_mfma_f32_16x16x32_bf16 v[60:63], v[140:143], v[188:191], v[60:63]
	v_mfma_f32_16x16x32_bf16 v[56:59], v[158:161], v[188:191], v[56:59]
	v_mfma_f32_16x16x32_bf16 v[48:51], v[140:143], v[196:199], v[48:51]
	v_mfma_f32_16x16x32_bf16 v[40:43], v[158:161], v[196:199], v[40:43]
	v_mfma_f32_16x16x32_bf16 v[32:35], v[140:143], v[206:209], v[32:35]
	v_mfma_f32_16x16x32_bf16 v[24:27], v[158:161], v[206:209], v[24:27]
	v_mfma_f32_16x16x32_bf16 v[16:19], v[140:143], v[214:217], v[16:19]
	v_mfma_f32_16x16x32_bf16 v[8:11], v[158:161], v[214:217], v[8:11]
	s_setprio 0
	s_setprio 1
	v_mfma_f32_16x16x32_bf16 v[52:55], v[162:165], v[184:187], v[52:55]
	v_mfma_f32_16x16x32_bf16 v[44:47], v[170:173], v[184:187], v[44:47]
	v_mfma_f32_16x16x32_bf16 v[36:39], v[162:165], v[192:195], v[36:39]
	v_mfma_f32_16x16x32_bf16 v[28:31], v[170:173], v[192:195], v[28:31]
	v_mfma_f32_16x16x32_bf16 v[20:23], v[162:165], v[200:203], v[20:23]
	v_mfma_f32_16x16x32_bf16 v[12:15], v[170:173], v[200:203], v[12:15]
	v_mfma_f32_16x16x32_bf16 v[4:7], v[162:165], v[210:213], v[4:7]
	v_mfma_f32_16x16x32_bf16 v[0:3], v[170:173], v[210:213], v[0:3]
	v_mfma_f32_16x16x32_bf16 v[52:55], v[166:169], v[188:191], v[52:55]
	v_mfma_f32_16x16x32_bf16 v[44:47], v[180:183], v[188:191], v[44:47]
	v_mfma_f32_16x16x32_bf16 v[36:39], v[166:169], v[196:199], v[36:39]
	v_mfma_f32_16x16x32_bf16 v[28:31], v[180:183], v[196:199], v[28:31]
	v_mfma_f32_16x16x32_bf16 v[20:23], v[166:169], v[206:209], v[20:23]
	v_mfma_f32_16x16x32_bf16 v[12:15], v[180:183], v[206:209], v[12:15]
	v_mfma_f32_16x16x32_bf16 v[4:7], v[166:169], v[214:217], v[4:7]
	v_mfma_f32_16x16x32_bf16 v[0:3], v[180:183], v[214:217], v[0:3]
	s_setprio 0
	s_barrier
	s_add_i32 s57, s57, 2
	s_add_u32 s26, s26, 0x100
	s_addc_u32 s27, s27, 0
	s_add_u32 s55, s55, 0x100
	s_addc_u32 s56, s56, 0
	s_cmp_gt_u32 s57, 5
	s_cbranch_scc0 .LBB0_913
	s_and_b64 vcc, exec, s[18:19]
	s_cbranch_vccz .LBB0_916
	s_barrier

.LBB0_1003:
	v_add_u32_e32 v140, s50, v195
	v_add_u32_e32 v156, s51, v195
	s_add_u32 s6, s24, s26
	ds_read_b128 v[128:131], v140
	ds_read_b128 v[132:135], v140 offset:1024
	ds_read_b128 v[136:139], v140 offset:2048
	ds_read_b128 v[140:143], v140 offset:3072
	ds_read_b128 v[144:147], v156
	ds_read_b128 v[148:151], v156 offset:1024
	ds_read_b128 v[152:155], v156 offset:2048
	ds_read_b128 v[156:159], v156 offset:3072
	s_addc_u32 s28, s25, s27
	s_add_u32 s6, s6, 0x100
	s_addc_u32 s28, s28, 0
	s_add_u32 s63, s60, s26
	s_addc_u32 s29, s61, s27
	s_cmpk_eq_i32 s26, 0xb00
	s_cselect_b32 s31, s5, s28
	s_cselect_b32 s30, s4, s6
	s_cselect_b32 s29, s23, s29
	s_cselect_b32 s28, s22, s63
	v_lshl_add_u64 v[202:203], v[184:185], 0, s[26:27]
	s_add_i32 m0, s40, 0xc000
	ds_read_b128 v[160:163], v197
	ds_read_b128 v[164:167], v197 offset:1024
	ds_read_b128 v[188:191], v197 offset:2048
	ds_read_b128 v[198:201], v197 offset:3072
	ds_read_b128 v[206:209], v197 offset:4096
	ds_read_b128 v[210:213], v197 offset:5120
	ds_read_b128 v[214:217], v197 offset:6144
	ds_read_b128 v[218:221], v197 offset:7168
	global_load_lds_dwordx4 v[202:203], off
	v_lshl_add_u64 v[202:203], v[186:187], 0, s[26:27]
	s_add_i32 m0, s40, 0xe000
	s_nop 0
	global_load_lds_dwordx4 v[202:203], off
	s_waitcnt vmcnt(8)
	s_waitcnt lgkmcnt(0)
	s_barrier
	s_setprio 1
	v_mfma_f32_16x16x32_bf16 v[124:127], v[128:131], v[160:163], v[124:127]
	v_mfma_f32_16x16x32_bf16 v[120:123], v[136:139], v[160:163], v[120:123]
	v_mfma_f32_16x16x32_bf16 v[108:111], v[128:131], v[188:191], v[108:111]
	v_mfma_f32_16x16x32_bf16 v[104:107], v[136:139], v[188:191], v[104:107]
	v_mfma_f32_16x16x32_bf16 v[92:95], v[128:131], v[206:209], v[92:95]
	v_mfma_f32_16x16x32_bf16 v[88:91], v[136:139], v[206:209], v[88:91]
	v_mfma_f32_16x16x32_bf16 v[76:79], v[128:131], v[214:217], v[76:79]
	v_mfma_f32_16x16x32_bf16 v[72:75], v[136:139], v[214:217], v[72:75]
	v_mfma_f32_16x16x32_bf16 v[124:127], v[132:135], v[164:167], v[124:127]
	v_mfma_f32_16x16x32_bf16 v[120:123], v[140:143], v[164:167], v[120:123]
	v_mfma_f32_16x16x32_bf16 v[108:111], v[132:135], v[198:201], v[108:111]
	v_mfma_f32_16x16x32_bf16 v[104:107], v[140:143], v[198:201], v[104:107]
	v_mfma_f32_16x16x32_bf16 v[92:95], v[132:135], v[210:213], v[92:95]
	v_mfma_f32_16x16x32_bf16 v[88:91], v[140:143], v[210:213], v[88:91]
	v_mfma_f32_16x16x32_bf16 v[76:79], v[132:135], v[218:221], v[76:79]
	v_mfma_f32_16x16x32_bf16 v[72:75], v[140:143], v[218:221], v[72:75]
	s_setprio 0
	s_setprio 1
	v_mfma_f32_16x16x32_bf16 v[116:119], v[144:147], v[160:163], v[116:119]
	v_mfma_f32_16x16x32_bf16 v[112:115], v[152:155], v[160:163], v[112:115]
	v_mfma_f32_16x16x32_bf16 v[100:103], v[144:147], v[188:191], v[100:103]
	v_mfma_f32_16x16x32_bf16 v[96:99], v[152:155], v[188:191], v[96:99]
	v_mfma_f32_16x16x32_bf16 v[84:87], v[144:147], v[206:209], v[84:87]
	v_mfma_f32_16x16x32_bf16 v[80:83], v[152:155], v[206:209], v[80:83]
	v_mfma_f32_16x16x32_bf16 v[68:71], v[144:147], v[214:217], v[68:71]
	v_mfma_f32_16x16x32_bf16 v[64:67], v[152:155], v[214:217], v[64:67]
	v_mfma_f32_16x16x32_bf16 v[116:119], v[148:151], v[164:167], v[116:119]
	v_mfma_f32_16x16x32_bf16 v[112:115], v[156:159], v[164:167], v[112:115]
	v_mfma_f32_16x16x32_bf16 v[100:103], v[148:151], v[198:201], v[100:103]
	v_mfma_f32_16x16x32_bf16 v[96:99], v[156:159], v[198:201], v[96:99]
	v_mfma_f32_16x16x32_bf16 v[84:87], v[148:151], v[210:213], v[84:87]
	v_mfma_f32_16x16x32_bf16 v[80:83], v[156:159], v[210:213], v[80:83]
	v_mfma_f32_16x16x32_bf16 v[68:71], v[148:151], v[218:221], v[68:71]
	v_mfma_f32_16x16x32_bf16 v[64:67], v[156:159], v[218:221], v[64:67]
	s_setprio 0
	s_barrier
	s_add_i32 s6, s50, s39
	v_lshl_add_u64 v[202:203], s[28:29], 0, v[170:171]
	s_mov_b32 m0, s6
	ds_read_b128 v[160:163], v197 offset:16384
	ds_read_b128 v[164:167], v197 offset:17408
	ds_read_b128 v[188:191], v197 offset:18432
	ds_read_b128 v[198:201], v197 offset:19456
	ds_read_b128 v[206:209], v197 offset:20480
	ds_read_b128 v[210:213], v197 offset:21504
	ds_read_b128 v[214:217], v197 offset:22528
	ds_read_b128 v[218:221], v197 offset:23552
	global_load_lds_dwordx4 v[202:203], off
	s_add_i32 m0, s6, 0x2000
	s_add_u32 s64, s28, 0x60000
	v_lshl_add_u64 v[222:223], s[28:29], 0, v[174:175]
	s_addc_u32 s65, s29, 0
	s_add_i32 s6, s51, s39
	global_load_lds_dwordx4 v[222:223], off
	v_lshl_add_u64 v[224:225], s[64:65], 0, v[170:171]
	s_mov_b32 m0, s6
	v_lshl_add_u64 v[226:227], s[30:31], 0, v[172:173]
	global_load_lds_dwordx4 v[224:225], off
	v_lshl_add_u64 v[224:225], s[64:65], 0, v[174:175]
	s_add_i32 m0, s6, 0x2000
	s_nop 0
	global_load_lds_dwordx4 v[224:225], off
	v_lshl_add_u64 v[224:225], s[30:31], 0, v[168:169]
	s_mov_b32 m0, s40
	s_nop 0
	global_load_lds_dwordx4 v[224:225], off
	s_mov_b32 m0, s41
	s_nop 0
	global_load_lds_dwordx4 v[226:227], off
	s_waitcnt vmcnt(8)
	s_waitcnt lgkmcnt(0)
	s_barrier
	s_setprio 1
	v_mfma_f32_16x16x32_bf16 v[60:63], v[128:131], v[160:163], v[60:63]
	v_mfma_f32_16x16x32_bf16 v[56:59], v[136:139], v[160:163], v[56:59]
	v_mfma_f32_16x16x32_bf16 v[44:47], v[128:131], v[188:191], v[44:47]
	v_mfma_f32_16x16x32_bf16 v[40:43], v[136:139], v[188:191], v[40:43]
	v_mfma_f32_16x16x32_bf16 v[28:31], v[128:131], v[206:209], v[28:31]
	v_mfma_f32_16x16x32_bf16 v[24:27], v[136:139], v[206:209], v[24:27]
	v_mfma_f32_16x16x32_bf16 v[12:15], v[128:131], v[214:217], v[12:15]
	v_mfma_f32_16x16x32_bf16 v[8:11], v[136:139], v[214:217], v[8:11]
	v_mfma_f32_16x16x32_bf16 v[60:63], v[132:135], v[164:167], v[60:63]
	v_mfma_f32_16x16x32_bf16 v[56:59], v[140:143], v[164:167], v[56:59]
	v_mfma_f32_16x16x32_bf16 v[44:47], v[132:135], v[198:201], v[44:47]
	v_mfma_f32_16x16x32_bf16 v[40:43], v[140:143], v[198:201], v[40:43]
	v_mfma_f32_16x16x32_bf16 v[28:31], v[132:135], v[210:213], v[28:31]
	v_mfma_f32_16x16x32_bf16 v[24:27], v[140:143], v[210:213], v[24:27]
	v_mfma_f32_16x16x32_bf16 v[12:15], v[132:135], v[218:221], v[12:15]
	v_mfma_f32_16x16x32_bf16 v[8:11], v[140:143], v[218:221], v[8:11]
	s_setprio 0
	s_setprio 1
	v_mfma_f32_16x16x32_bf16 v[52:55], v[144:147], v[160:163], v[52:55]
	v_mfma_f32_16x16x32_bf16 v[48:51], v[152:155], v[160:163], v[48:51]
	v_mfma_f32_16x16x32_bf16 v[36:39], v[144:147], v[188:191], v[36:39]
	v_mfma_f32_16x16x32_bf16 v[32:35], v[152:155], v[188:191], v[32:35]
	v_mfma_f32_16x16x32_bf16 v[20:23], v[144:147], v[206:209], v[20:23]
	v_mfma_f32_16x16x32_bf16 v[16:19], v[152:155], v[206:209], v[16:19]
	v_mfma_f32_16x16x32_bf16 v[4:7], v[144:147], v[214:217], v[4:7]
	v_mfma_f32_16x16x32_bf16 v[0:3], v[152:155], v[214:217], v[0:3]
	v_mfma_f32_16x16x32_bf16 v[52:55], v[148:151], v[164:167], v[52:55]
	v_mfma_f32_16x16x32_bf16 v[48:51], v[156:159], v[164:167], v[48:51]
	v_mfma_f32_16x16x32_bf16 v[36:39], v[148:151], v[198:201], v[36:39]
	v_mfma_f32_16x16x32_bf16 v[32:35], v[156:159], v[198:201], v[32:35]
	v_mfma_f32_16x16x32_bf16 v[20:23], v[148:151], v[210:213], v[20:23]
	v_mfma_f32_16x16x32_bf16 v[16:19], v[156:159], v[210:213], v[16:19]
	v_mfma_f32_16x16x32_bf16 v[4:7], v[148:151], v[218:221], v[4:7]
	v_mfma_f32_16x16x32_bf16 v[0:3], v[156:159], v[218:221], v[0:3]
	s_setprio 0
	s_barrier
	s_add_i32 s6, 0, 0x18000
	s_add_i32 s63, 0, 0x1c000
	v_add_u32_e32 v140, s6, v195
	v_add_u32_e32 v156, s63, v195
	ds_read_b128 v[128:131], v140
	ds_read_b128 v[132:135], v140 offset:1024
	ds_read_b128 v[136:139], v140 offset:2048
	ds_read_b128 v[140:143], v140 offset:3072
	ds_read_b128 v[144:147], v156
	ds_read_b128 v[148:151], v156 offset:1024
	ds_read_b128 v[152:155], v156 offset:2048
	ds_read_b128 v[156:159], v156 offset:3072
	s_add_u32 s30, s30, 0x60000
	s_addc_u32 s31, s31, 0
	s_mov_b32 m0, s42
	v_lshl_add_u64 v[228:229], s[30:31], 0, v[168:169]
	ds_read_b128 v[160:163], v197 offset:32768
	ds_read_b128 v[164:167], v197 offset:33792
	ds_read_b128 v[188:191], v197 offset:34816
	ds_read_b128 v[198:201], v197 offset:35840
	ds_read_b128 v[206:209], v197 offset:36864
	ds_read_b128 v[210:213], v197 offset:37888
	ds_read_b128 v[214:217], v197 offset:38912
	ds_read_b128 v[218:221], v197 offset:39936
	global_load_lds_dwordx4 v[228:229], off
	v_lshl_add_u64 v[228:229], s[30:31], 0, v[172:173]
	s_mov_b32 m0, s43
	s_nop 0
	global_load_lds_dwordx4 v[228:229], off
	s_waitcnt vmcnt(8)
	s_waitcnt lgkmcnt(0)
	s_barrier
	s_setprio 1
	v_mfma_f32_16x16x32_bf16 v[124:127], v[128:131], v[160:163], v[124:127]
	v_mfma_f32_16x16x32_bf16 v[120:123], v[136:139], v[160:163], v[120:123]
	v_mfma_f32_16x16x32_bf16 v[108:111], v[128:131], v[188:191], v[108:111]
	v_mfma_f32_16x16x32_bf16 v[104:107], v[136:139], v[188:191], v[104:107]
	v_mfma_f32_16x16x32_bf16 v[92:95], v[128:131], v[206:209], v[92:95]
	v_mfma_f32_16x16x32_bf16 v[88:91], v[136:139], v[206:209], v[88:91]
	v_mfma_f32_16x16x32_bf16 v[76:79], v[128:131], v[214:217], v[76:79]
	v_mfma_f32_16x16x32_bf16 v[72:75], v[136:139], v[214:217], v[72:75]
	v_mfma_f32_16x16x32_bf16 v[124:127], v[132:135], v[164:167], v[124:127]
	v_mfma_f32_16x16x32_bf16 v[120:123], v[140:143], v[164:167], v[120:123]
	v_mfma_f32_16x16x32_bf16 v[108:111], v[132:135], v[198:201], v[108:111]
	v_mfma_f32_16x16x32_bf16 v[104:107], v[140:143], v[198:201], v[104:107]
	v_mfma_f32_16x16x32_bf16 v[92:95], v[132:135], v[210:213], v[92:95]
	v_mfma_f32_16x16x32_bf16 v[88:91], v[140:143], v[210:213], v[88:91]
	v_mfma_f32_16x16x32_bf16 v[76:79], v[132:135], v[218:221], v[76:79]
	v_mfma_f32_16x16x32_bf16 v[72:75], v[140:143], v[218:221], v[72:75]
	s_setprio 0
	s_setprio 1
	v_mfma_f32_16x16x32_bf16 v[116:119], v[144:147], v[160:163], v[116:119]
	v_mfma_f32_16x16x32_bf16 v[112:115], v[152:155], v[160:163], v[112:115]
	v_mfma_f32_16x16x32_bf16 v[100:103], v[144:147], v[188:191], v[100:103]
	v_mfma_f32_16x16x32_bf16 v[96:99], v[152:155], v[188:191], v[96:99]
	v_mfma_f32_16x16x32_bf16 v[84:87], v[144:147], v[206:209], v[84:87]
	v_mfma_f32_16x16x32_bf16 v[80:83], v[152:155], v[206:209], v[80:83]
	v_mfma_f32_16x16x32_bf16 v[68:71], v[144:147], v[214:217], v[68:71]
	v_mfma_f32_16x16x32_bf16 v[64:67], v[152:155], v[214:217], v[64:67]
	v_mfma_f32_16x16x32_bf16 v[116:119], v[148:151], v[164:167], v[116:119]
	v_mfma_f32_16x16x32_bf16 v[112:115], v[156:159], v[164:167], v[112:115]
	v_mfma_f32_16x16x32_bf16 v[100:103], v[148:151], v[198:201], v[100:103]
	v_mfma_f32_16x16x32_bf16 v[96:99], v[156:159], v[198:201], v[96:99]
	v_mfma_f32_16x16x32_bf16 v[84:87], v[148:151], v[210:213], v[84:87]
	v_mfma_f32_16x16x32_bf16 v[80:83], v[156:159], v[210:213], v[80:83]
	v_mfma_f32_16x16x32_bf16 v[68:71], v[148:151], v[218:221], v[68:71]
	v_mfma_f32_16x16x32_bf16 v[64:67], v[156:159], v[218:221], v[64:67]
	s_setprio 0
	s_barrier
	s_add_i32 s6, s6, s39
	v_lshl_add_u64 v[202:203], v[202:203], 0, s[14:15]
	s_mov_b32 m0, s6
	ds_read_b128 v[160:163], v197 offset:49152
	ds_read_b128 v[164:167], v197 offset:50176
	ds_read_b128 v[188:191], v197 offset:51200
	ds_read_b128 v[198:201], v197 offset:52224
	ds_read_b128 v[206:209], v197 offset:53248
	ds_read_b128 v[210:213], v197 offset:54272
	ds_read_b128 v[214:217], v197 offset:55296
	ds_read_b128 v[218:221], v197 offset:56320
	global_load_lds_dwordx4 v[202:203], off
	s_add_i32 m0, s6, 0x2000
	s_add_u32 s28, s28, 0x60080
	v_lshl_add_u64 v[202:203], v[222:223], 0, s[14:15]
	s_addc_u32 s29, s29, 0
	s_add_i32 s6, s63, s39
	global_load_lds_dwordx4 v[202:203], off
	v_lshl_add_u64 v[202:203], s[28:29], 0, v[170:171]
	s_mov_b32 m0, s6
	s_nop 0
	global_load_lds_dwordx4 v[202:203], off
	v_lshl_add_u64 v[202:203], s[28:29], 0, v[174:175]
	s_add_i32 m0, s6, 0x2000
	s_nop 0
	global_load_lds_dwordx4 v[202:203], off
	v_lshl_add_u64 v[202:203], v[224:225], 0, s[14:15]
	s_mov_b32 m0, s46
	s_nop 0
	global_load_lds_dwordx4 v[202:203], off
	v_lshl_add_u64 v[202:203], v[226:227], 0, s[14:15]
	s_mov_b32 m0, s47
	s_nop 0
	global_load_lds_dwordx4 v[202:203], off
	s_waitcnt vmcnt(8)
	s_waitcnt lgkmcnt(0)
	s_barrier
	s_setprio 1
	v_mfma_f32_16x16x32_bf16 v[60:63], v[128:131], v[160:163], v[60:63]
	v_mfma_f32_16x16x32_bf16 v[56:59], v[136:139], v[160:163], v[56:59]
	v_mfma_f32_16x16x32_bf16 v[44:47], v[128:131], v[188:191], v[44:47]
	v_mfma_f32_16x16x32_bf16 v[40:43], v[136:139], v[188:191], v[40:43]
	v_mfma_f32_16x16x32_bf16 v[28:31], v[128:131], v[206:209], v[28:31]
	v_mfma_f32_16x16x32_bf16 v[24:27], v[136:139], v[206:209], v[24:27]
	v_mfma_f32_16x16x32_bf16 v[12:15], v[128:131], v[214:217], v[12:15]
	v_mfma_f32_16x16x32_bf16 v[8:11], v[136:139], v[214:217], v[8:11]
	v_mfma_f32_16x16x32_bf16 v[60:63], v[132:135], v[164:167], v[60:63]
	v_mfma_f32_16x16x32_bf16 v[56:59], v[140:143], v[164:167], v[56:59]
	v_mfma_f32_16x16x32_bf16 v[44:47], v[132:135], v[198:201], v[44:47]
	v_mfma_f32_16x16x32_bf16 v[40:43], v[140:143], v[198:201], v[40:43]
	v_mfma_f32_16x16x32_bf16 v[28:31], v[132:135], v[210:213], v[28:31]
	v_mfma_f32_16x16x32_bf16 v[24:27], v[140:143], v[210:213], v[24:27]
	v_mfma_f32_16x16x32_bf16 v[12:15], v[132:135], v[218:221], v[12:15]
	v_mfma_f32_16x16x32_bf16 v[8:11], v[140:143], v[218:221], v[8:11]
	s_setprio 0
	s_setprio 1
	v_mfma_f32_16x16x32_bf16 v[52:55], v[144:147], v[160:163], v[52:55]
	v_mfma_f32_16x16x32_bf16 v[48:51], v[152:155], v[160:163], v[48:51]
	v_mfma_f32_16x16x32_bf16 v[36:39], v[144:147], v[188:191], v[36:39]
	v_mfma_f32_16x16x32_bf16 v[32:35], v[152:155], v[188:191], v[32:35]
	v_mfma_f32_16x16x32_bf16 v[20:23], v[144:147], v[206:209], v[20:23]
	v_mfma_f32_16x16x32_bf16 v[16:19], v[152:155], v[206:209], v[16:19]
	v_mfma_f32_16x16x32_bf16 v[4:7], v[144:147], v[214:217], v[4:7]
	v_mfma_f32_16x16x32_bf16 v[0:3], v[152:155], v[214:217], v[0:3]
	v_mfma_f32_16x16x32_bf16 v[52:55], v[148:151], v[164:167], v[52:55]
	v_mfma_f32_16x16x32_bf16 v[48:51], v[156:159], v[164:167], v[48:51]
	v_mfma_f32_16x16x32_bf16 v[36:39], v[148:151], v[198:201], v[36:39]
	v_mfma_f32_16x16x32_bf16 v[32:35], v[156:159], v[198:201], v[32:35]
	v_mfma_f32_16x16x32_bf16 v[20:23], v[148:151], v[210:213], v[20:23]
	v_mfma_f32_16x16x32_bf16 v[16:19], v[156:159], v[210:213], v[16:19]
	v_mfma_f32_16x16x32_bf16 v[4:7], v[148:151], v[218:221], v[4:7]
	v_mfma_f32_16x16x32_bf16 v[0:3], v[156:159], v[218:221], v[0:3]
	s_setprio 0
	s_barrier
	s_add_i32 s6, s62, 2
	s_add_u32 s26, s26, 0x100
	s_addc_u32 s27, s27, 0
	s_cmp_gt_u32 s62, 21
	s_mov_b32 s62, s6
	s_cbranch_scc1 .LBB0_1010

.Llsb_skip_8:
.LBB0_1088:
	ds_read_b128 v[128:131], v212
	ds_read_b128 v[132:135], v212 offset:1024
	ds_read_b128 v[136:139], v212 offset:2048
	ds_read_b128 v[140:143], v212 offset:3072
	ds_read_b128 v[144:147], v213
	ds_read_b128 v[148:151], v213 offset:1024
	ds_read_b128 v[152:155], v213 offset:2048
	ds_read_b128 v[156:159], v213 offset:3072
	s_add_u32 s22, s20, 0xfffc0080
	s_addc_u32 s23, s21, -1
	s_cmp_eq_u32 s54, 12
	s_cselect_b32 s25, s13, s23
	s_cselect_b32 s24, s50, s22
	s_cselect_b32 s23, s11, s53
	s_cselect_b32 s22, s51, s52
	v_lshl_add_u64 v[202:203], s[20:21], 0, v[182:183]
	s_add_i32 m0, s28, 0xc000
	ds_read_b128 v[160:163], v214
	ds_read_b128 v[164:167], v214 offset:1024
	ds_read_b128 v[168:171], v214 offset:2048
	ds_read_b128 v[172:175], v214 offset:3072
	ds_read_b128 v[190:193], v214 offset:4096
	ds_read_b128 v[194:197], v214 offset:5120
	ds_read_b128 v[198:201], v214 offset:6144
	ds_read_b128 v[216:219], v214 offset:7168
	global_load_lds_dwordx4 v[202:203], off
	v_lshl_add_u64 v[202:203], s[20:21], 0, v[184:185]
	s_add_i32 m0, s28, 0xe000
	s_nop 0
	global_load_lds_dwordx4 v[202:203], off
	s_waitcnt vmcnt(8)
	s_waitcnt lgkmcnt(0)
	s_barrier
	s_setprio 1
	v_mfma_f32_16x16x32_bf16 v[124:127], v[128:131], v[160:163], v[124:127]
	v_mfma_f32_16x16x32_bf16 v[120:123], v[136:139], v[160:163], v[120:123]
	v_mfma_f32_16x16x32_bf16 v[112:115], v[128:131], v[168:171], v[112:115]
	v_mfma_f32_16x16x32_bf16 v[104:107], v[136:139], v[168:171], v[104:107]
	v_mfma_f32_16x16x32_bf16 v[96:99], v[128:131], v[190:193], v[96:99]
	v_mfma_f32_16x16x32_bf16 v[88:91], v[136:139], v[190:193], v[88:91]
	v_mfma_f32_16x16x32_bf16 v[84:87], v[128:131], v[198:201], v[84:87]
	v_mfma_f32_16x16x32_bf16 v[76:79], v[136:139], v[198:201], v[76:79]
	v_mfma_f32_16x16x32_bf16 v[124:127], v[132:135], v[164:167], v[124:127]
	v_mfma_f32_16x16x32_bf16 v[120:123], v[140:143], v[164:167], v[120:123]
	v_mfma_f32_16x16x32_bf16 v[112:115], v[132:135], v[172:175], v[112:115]
	v_mfma_f32_16x16x32_bf16 v[104:107], v[140:143], v[172:175], v[104:107]
	v_mfma_f32_16x16x32_bf16 v[96:99], v[132:135], v[194:197], v[96:99]
	v_mfma_f32_16x16x32_bf16 v[88:91], v[140:143], v[194:197], v[88:91]
	v_mfma_f32_16x16x32_bf16 v[84:87], v[132:135], v[216:219], v[84:87]
	v_mfma_f32_16x16x32_bf16 v[76:79], v[140:143], v[216:219], v[76:79]
	s_setprio 0
	s_setprio 1
	v_mfma_f32_16x16x32_bf16 v[116:119], v[144:147], v[160:163], v[116:119]
	v_mfma_f32_16x16x32_bf16 v[108:111], v[152:155], v[160:163], v[108:111]
	v_mfma_f32_16x16x32_bf16 v[100:103], v[144:147], v[168:171], v[100:103]
	v_mfma_f32_16x16x32_bf16 v[92:95], v[152:155], v[168:171], v[92:95]
	v_mfma_f32_16x16x32_bf16 v[80:83], v[144:147], v[190:193], v[80:83]
	v_mfma_f32_16x16x32_bf16 v[72:75], v[152:155], v[190:193], v[72:75]
	v_mfma_f32_16x16x32_bf16 v[68:71], v[144:147], v[198:201], v[68:71]
	v_mfma_f32_16x16x32_bf16 v[64:67], v[152:155], v[198:201], v[64:67]
	v_mfma_f32_16x16x32_bf16 v[116:119], v[148:151], v[164:167], v[116:119]
	v_mfma_f32_16x16x32_bf16 v[108:111], v[156:159], v[164:167], v[108:111]
	v_mfma_f32_16x16x32_bf16 v[100:103], v[148:151], v[172:175], v[100:103]
	v_mfma_f32_16x16x32_bf16 v[92:95], v[156:159], v[172:175], v[92:95]
	v_mfma_f32_16x16x32_bf16 v[80:83], v[148:151], v[194:197], v[80:83]
	v_mfma_f32_16x16x32_bf16 v[72:75], v[156:159], v[194:197], v[72:75]
	v_mfma_f32_16x16x32_bf16 v[68:71], v[148:151], v[216:219], v[68:71]
	v_mfma_f32_16x16x32_bf16 v[64:67], v[156:159], v[216:219], v[64:67]
	s_setprio 0
	s_barrier
	s_add_i32 s55, s43, s27
	v_lshl_add_u64 v[202:203], s[22:23], 0, v[176:177]
	s_mov_b32 m0, s55
	ds_read_b128 v[160:163], v214 offset:16384
	ds_read_b128 v[164:167], v214 offset:17408
	ds_read_b128 v[168:171], v214 offset:18432
	ds_read_b128 v[172:175], v214 offset:19456
	ds_read_b128 v[190:193], v214 offset:20480
	ds_read_b128 v[194:197], v214 offset:21504
	ds_read_b128 v[198:201], v214 offset:22528
	ds_read_b128 v[216:219], v214 offset:23552
	global_load_lds_dwordx4 v[202:203], off
	s_add_i32 m0, s55, 0x2000
	s_add_u32 s56, s22, 0x40000
	v_lshl_add_u64 v[220:221], s[22:23], 0, v[178:179]
	s_addc_u32 s57, s23, 0
	s_add_i32 s55, s44, s27
	global_load_lds_dwordx4 v[220:221], off
	v_lshl_add_u64 v[222:223], s[56:57], 0, v[176:177]
	s_mov_b32 m0, s55
	v_lshl_add_u64 v[224:225], s[24:25], 0, v[178:179]
	global_load_lds_dwordx4 v[222:223], off
	v_lshl_add_u64 v[222:223], s[56:57], 0, v[178:179]
	s_add_i32 m0, s55, 0x2000
	s_nop 0
	global_load_lds_dwordx4 v[222:223], off
	v_lshl_add_u64 v[222:223], s[24:25], 0, v[176:177]
	s_mov_b32 m0, s28
	s_nop 0
	global_load_lds_dwordx4 v[222:223], off
	s_mov_b32 m0, s29
	s_nop 0
	global_load_lds_dwordx4 v[224:225], off
	s_waitcnt vmcnt(8)
	s_waitcnt lgkmcnt(0)
	s_barrier
	s_setprio 1
	v_mfma_f32_16x16x32_bf16 v[60:63], v[128:131], v[160:163], v[60:63]
	v_mfma_f32_16x16x32_bf16 v[56:59], v[136:139], v[160:163], v[56:59]
	v_mfma_f32_16x16x32_bf16 v[48:51], v[128:131], v[168:171], v[48:51]
	v_mfma_f32_16x16x32_bf16 v[40:43], v[136:139], v[168:171], v[40:43]
	v_mfma_f32_16x16x32_bf16 v[32:35], v[128:131], v[190:193], v[32:35]
	v_mfma_f32_16x16x32_bf16 v[24:27], v[136:139], v[190:193], v[24:27]
	v_mfma_f32_16x16x32_bf16 v[20:23], v[128:131], v[198:201], v[20:23]
	v_mfma_f32_16x16x32_bf16 v[12:15], v[136:139], v[198:201], v[12:15]
	v_mfma_f32_16x16x32_bf16 v[60:63], v[132:135], v[164:167], v[60:63]
	v_mfma_f32_16x16x32_bf16 v[56:59], v[140:143], v[164:167], v[56:59]
	v_mfma_f32_16x16x32_bf16 v[48:51], v[132:135], v[172:175], v[48:51]
	v_mfma_f32_16x16x32_bf16 v[40:43], v[140:143], v[172:175], v[40:43]
	v_mfma_f32_16x16x32_bf16 v[32:35], v[132:135], v[194:197], v[32:35]
	v_mfma_f32_16x16x32_bf16 v[24:27], v[140:143], v[194:197], v[24:27]
	v_mfma_f32_16x16x32_bf16 v[20:23], v[132:135], v[216:219], v[20:23]
	v_mfma_f32_16x16x32_bf16 v[12:15], v[140:143], v[216:219], v[12:15]
	s_setprio 0
	s_setprio 1
	v_mfma_f32_16x16x32_bf16 v[52:55], v[144:147], v[160:163], v[52:55]
	v_mfma_f32_16x16x32_bf16 v[44:47], v[152:155], v[160:163], v[44:47]
	v_mfma_f32_16x16x32_bf16 v[36:39], v[144:147], v[168:171], v[36:39]
	v_mfma_f32_16x16x32_bf16 v[28:31], v[152:155], v[168:171], v[28:31]
	v_mfma_f32_16x16x32_bf16 v[16:19], v[144:147], v[190:193], v[16:19]
	v_mfma_f32_16x16x32_bf16 v[8:11], v[152:155], v[190:193], v[8:11]
	v_mfma_f32_16x16x32_bf16 v[4:7], v[144:147], v[198:201], v[4:7]
	v_mfma_f32_16x16x32_bf16 v[0:3], v[152:155], v[198:201], v[0:3]
	v_mfma_f32_16x16x32_bf16 v[52:55], v[148:151], v[164:167], v[52:55]
	v_mfma_f32_16x16x32_bf16 v[44:47], v[156:159], v[164:167], v[44:47]
	v_mfma_f32_16x16x32_bf16 v[36:39], v[148:151], v[172:175], v[36:39]
	v_mfma_f32_16x16x32_bf16 v[28:31], v[156:159], v[172:175], v[28:31]
	v_mfma_f32_16x16x32_bf16 v[16:19], v[148:151], v[194:197], v[16:19]
	v_mfma_f32_16x16x32_bf16 v[8:11], v[156:159], v[194:197], v[8:11]
	v_mfma_f32_16x16x32_bf16 v[4:7], v[148:151], v[216:219], v[4:7]
	v_mfma_f32_16x16x32_bf16 v[0:3], v[156:159], v[216:219], v[0:3]
	s_setprio 0
	s_barrier
	s_add_i32 s55, 0, 0x18000
	s_add_i32 s56, 0, 0x1c000
	v_add_u32_e32 v140, s55, v210
	v_add_u32_e32 v156, s56, v210
	ds_read_b128 v[128:131], v140
	ds_read_b128 v[132:135], v140 offset:1024
	ds_read_b128 v[136:139], v140 offset:2048
	ds_read_b128 v[140:143], v140 offset:3072
	ds_read_b128 v[144:147], v156
	ds_read_b128 v[148:151], v156 offset:1024
	ds_read_b128 v[152:155], v156 offset:2048
	ds_read_b128 v[156:159], v156 offset:3072
	s_add_u32 s24, s24, 0x40000
	s_addc_u32 s25, s25, 0
	s_mov_b32 m0, s30
	v_lshl_add_u64 v[226:227], s[24:25], 0, v[176:177]
	ds_read_b128 v[160:163], v214 offset:32768
	ds_read_b128 v[164:167], v214 offset:33792
	ds_read_b128 v[168:171], v214 offset:34816
	ds_read_b128 v[172:175], v214 offset:35840
	ds_read_b128 v[190:193], v214 offset:36864
	ds_read_b128 v[194:197], v214 offset:37888
	ds_read_b128 v[198:201], v214 offset:38912
	ds_read_b128 v[216:219], v214 offset:39936
	global_load_lds_dwordx4 v[226:227], off
	v_lshl_add_u64 v[226:227], s[24:25], 0, v[178:179]
	s_mov_b32 m0, s31
	s_nop 0
	global_load_lds_dwordx4 v[226:227], off
	s_waitcnt vmcnt(8)
	s_waitcnt lgkmcnt(0)
	s_barrier
	s_setprio 1
	v_mfma_f32_16x16x32_bf16 v[124:127], v[128:131], v[160:163], v[124:127]
	v_mfma_f32_16x16x32_bf16 v[120:123], v[136:139], v[160:163], v[120:123]
	v_mfma_f32_16x16x32_bf16 v[112:115], v[128:131], v[168:171], v[112:115]
	v_mfma_f32_16x16x32_bf16 v[104:107], v[136:139], v[168:171], v[104:107]
	v_mfma_f32_16x16x32_bf16 v[96:99], v[128:131], v[190:193], v[96:99]
	v_mfma_f32_16x16x32_bf16 v[88:91], v[136:139], v[190:193], v[88:91]
	v_mfma_f32_16x16x32_bf16 v[84:87], v[128:131], v[198:201], v[84:87]
	v_mfma_f32_16x16x32_bf16 v[76:79], v[136:139], v[198:201], v[76:79]
	v_mfma_f32_16x16x32_bf16 v[124:127], v[132:135], v[164:167], v[124:127]
	v_mfma_f32_16x16x32_bf16 v[120:123], v[140:143], v[164:167], v[120:123]
	v_mfma_f32_16x16x32_bf16 v[112:115], v[132:135], v[172:175], v[112:115]
	v_mfma_f32_16x16x32_bf16 v[104:107], v[140:143], v[172:175], v[104:107]
	v_mfma_f32_16x16x32_bf16 v[96:99], v[132:135], v[194:197], v[96:99]
	v_mfma_f32_16x16x32_bf16 v[88:91], v[140:143], v[194:197], v[88:91]
	v_mfma_f32_16x16x32_bf16 v[84:87], v[132:135], v[216:219], v[84:87]
	v_mfma_f32_16x16x32_bf16 v[76:79], v[140:143], v[216:219], v[76:79]
	s_setprio 0
	s_setprio 1
	v_mfma_f32_16x16x32_bf16 v[116:119], v[144:147], v[160:163], v[116:119]
	v_mfma_f32_16x16x32_bf16 v[108:111], v[152:155], v[160:163], v[108:111]
	v_mfma_f32_16x16x32_bf16 v[100:103], v[144:147], v[168:171], v[100:103]
	v_mfma_f32_16x16x32_bf16 v[92:95], v[152:155], v[168:171], v[92:95]
	v_mfma_f32_16x16x32_bf16 v[80:83], v[144:147], v[190:193], v[80:83]
	v_mfma_f32_16x16x32_bf16 v[72:75], v[152:155], v[190:193], v[72:75]
	v_mfma_f32_16x16x32_bf16 v[68:71], v[144:147], v[198:201], v[68:71]
	v_mfma_f32_16x16x32_bf16 v[64:67], v[152:155], v[198:201], v[64:67]
	v_mfma_f32_16x16x32_bf16 v[116:119], v[148:151], v[164:167], v[116:119]
	v_mfma_f32_16x16x32_bf16 v[108:111], v[156:159], v[164:167], v[108:111]
	v_mfma_f32_16x16x32_bf16 v[100:103], v[148:151], v[172:175], v[100:103]
	v_mfma_f32_16x16x32_bf16 v[92:95], v[156:159], v[172:175], v[92:95]
	v_mfma_f32_16x16x32_bf16 v[80:83], v[148:151], v[194:197], v[80:83]
	v_mfma_f32_16x16x32_bf16 v[72:75], v[156:159], v[194:197], v[72:75]
	v_mfma_f32_16x16x32_bf16 v[68:71], v[148:151], v[216:219], v[68:71]
	v_mfma_f32_16x16x32_bf16 v[64:67], v[156:159], v[216:219], v[64:67]
	s_setprio 0
	s_barrier
	s_add_i32 s24, s55, s27
	v_lshl_add_u64 v[202:203], v[202:203], 0, s[6:7]
	s_mov_b32 m0, s24
	ds_read_b128 v[160:163], v214 offset:49152
	ds_read_b128 v[164:167], v214 offset:50176
	ds_read_b128 v[168:171], v214 offset:51200
	ds_read_b128 v[172:175], v214 offset:52224
	ds_read_b128 v[190:193], v214 offset:53248
	ds_read_b128 v[194:197], v214 offset:54272
	ds_read_b128 v[198:201], v214 offset:55296
	ds_read_b128 v[216:219], v214 offset:56320
	global_load_lds_dwordx4 v[202:203], off
	s_add_i32 m0, s24, 0x2000
	s_add_u32 s22, s22, 0x40080
	v_lshl_add_u64 v[202:203], v[220:221], 0, s[6:7]
	s_addc_u32 s23, s23, 0
	s_add_i32 s24, s56, s27
	global_load_lds_dwordx4 v[202:203], off
	v_lshl_add_u64 v[202:203], s[22:23], 0, v[176:177]
	s_mov_b32 m0, s24
	s_nop 0
	global_load_lds_dwordx4 v[202:203], off
	v_lshl_add_u64 v[202:203], s[22:23], 0, v[178:179]
	s_add_i32 m0, s24, 0x2000
	s_nop 0
	global_load_lds_dwordx4 v[202:203], off
	v_lshl_add_u64 v[202:203], v[222:223], 0, s[6:7]
	s_mov_b32 m0, s40
	s_nop 0
	global_load_lds_dwordx4 v[202:203], off
	v_lshl_add_u64 v[202:203], v[224:225], 0, s[6:7]
	s_mov_b32 m0, s41
	s_nop 0
	global_load_lds_dwordx4 v[202:203], off
	s_waitcnt vmcnt(8)
	s_waitcnt lgkmcnt(0)
	s_barrier
	s_setprio 1
	v_mfma_f32_16x16x32_bf16 v[60:63], v[128:131], v[160:163], v[60:63]
	v_mfma_f32_16x16x32_bf16 v[56:59], v[136:139], v[160:163], v[56:59]
	v_mfma_f32_16x16x32_bf16 v[48:51], v[128:131], v[168:171], v[48:51]
	v_mfma_f32_16x16x32_bf16 v[40:43], v[136:139], v[168:171], v[40:43]
	v_mfma_f32_16x16x32_bf16 v[32:35], v[128:131], v[190:193], v[32:35]
	v_mfma_f32_16x16x32_bf16 v[24:27], v[136:139], v[190:193], v[24:27]
	v_mfma_f32_16x16x32_bf16 v[20:23], v[128:131], v[198:201], v[20:23]
	v_mfma_f32_16x16x32_bf16 v[12:15], v[136:139], v[198:201], v[12:15]
	v_mfma_f32_16x16x32_bf16 v[60:63], v[132:135], v[164:167], v[60:63]
	v_mfma_f32_16x16x32_bf16 v[56:59], v[140:143], v[164:167], v[56:59]
	v_mfma_f32_16x16x32_bf16 v[48:51], v[132:135], v[172:175], v[48:51]
	v_mfma_f32_16x16x32_bf16 v[40:43], v[140:143], v[172:175], v[40:43]
	v_mfma_f32_16x16x32_bf16 v[32:35], v[132:135], v[194:197], v[32:35]
	v_mfma_f32_16x16x32_bf16 v[24:27], v[140:143], v[194:197], v[24:27]
	v_mfma_f32_16x16x32_bf16 v[20:23], v[132:135], v[216:219], v[20:23]
	v_mfma_f32_16x16x32_bf16 v[12:15], v[140:143], v[216:219], v[12:15]
	s_setprio 0
	s_setprio 1
	v_mfma_f32_16x16x32_bf16 v[52:55], v[144:147], v[160:163], v[52:55]
	v_mfma_f32_16x16x32_bf16 v[44:47], v[152:155], v[160:163], v[44:47]
	v_mfma_f32_16x16x32_bf16 v[36:39], v[144:147], v[168:171], v[36:39]
	v_mfma_f32_16x16x32_bf16 v[28:31], v[152:155], v[168:171], v[28:31]
	v_mfma_f32_16x16x32_bf16 v[16:19], v[144:147], v[190:193], v[16:19]
	v_mfma_f32_16x16x32_bf16 v[8:11], v[152:155], v[190:193], v[8:11]
	v_mfma_f32_16x16x32_bf16 v[4:7], v[144:147], v[198:201], v[4:7]
	v_mfma_f32_16x16x32_bf16 v[0:3], v[152:155], v[198:201], v[0:3]
	v_mfma_f32_16x16x32_bf16 v[52:55], v[148:151], v[164:167], v[52:55]
	v_mfma_f32_16x16x32_bf16 v[44:47], v[156:159], v[164:167], v[44:47]
	v_mfma_f32_16x16x32_bf16 v[36:39], v[148:151], v[172:175], v[36:39]
	v_mfma_f32_16x16x32_bf16 v[28:31], v[156:159], v[172:175], v[28:31]
	v_mfma_f32_16x16x32_bf16 v[16:19], v[148:151], v[194:197], v[16:19]
	v_mfma_f32_16x16x32_bf16 v[8:11], v[156:159], v[194:197], v[8:11]
	v_mfma_f32_16x16x32_bf16 v[4:7], v[148:151], v[216:219], v[4:7]
	v_mfma_f32_16x16x32_bf16 v[0:3], v[156:159], v[216:219], v[0:3]
	s_setprio 0
	s_barrier
	s_add_i32 s54, s54, 2
	s_add_u32 s20, s20, 0x100
	s_addc_u32 s21, s21, 0
	s_add_u32 s52, s52, 0x100
	s_addc_u32 s53, s53, 0
	s_cmp_gt_u32 s54, 13
	s_cbranch_scc0 .LBB0_1088
	s_and_b64 vcc, exec, s[8:9]
	s_cbranch_vccz .LBB0_1091
	s_barrier

.LBB0_1111:
	s_ashr_i32 s17, s16, 31
	s_lshl_b64 s[20:21], s[16:17], 19
	s_add_u32 s17, s34, s20
	s_addc_u32 s19, s35, s21
	s_ashr_i32 s64, s63, 31
	ds_read_b128 v[0:3], v130
	ds_read_b128 v[4:7], v130 offset:1024
	ds_read_b128 v[8:11], v130 offset:2048
	ds_read_b128 v[12:15], v130 offset:3072
	ds_read_b128 v[16:19], v131
	ds_read_b128 v[20:23], v131 offset:1024
	ds_read_b128 v[24:27], v131 offset:2048
	ds_read_b128 v[28:31], v131 offset:3072
	s_add_u32 s20, s17, s63
	s_addc_u32 s21, s19, s64
	s_and_b64 s[24:25], s[22:23], exec
	s_cselect_b32 s31, s21, s29
	s_cselect_b32 s30, s20, s28
	s_ashr_i32 s19, s18, 31
	s_lshl_b64 s[24:25], s[18:19], 19
	s_add_u32 s17, s36, s24
	s_addc_u32 s19, s37, s25
	s_add_u32 s24, s17, s63
	s_addc_u32 s25, s19, s64
	s_and_b64 s[64:65], s[22:23], exec
	s_cselect_b32 s27, s25, s27
	s_cselect_b32 s26, s24, s26
	s_add_u32 s28, s28, 0x40080
	s_addc_u32 s29, s29, 0
	s_mov_b32 m0, s50
	v_lshl_add_u64 v[64:65], s[28:29], 0, v[176:177]
	ds_read_b128 v[32:35], v132
	ds_read_b128 v[36:39], v132 offset:1024
	ds_read_b128 v[40:43], v132 offset:2048
	ds_read_b128 v[44:47], v132 offset:3072
	ds_read_b128 v[48:51], v132 offset:4096
	ds_read_b128 v[52:55], v132 offset:5120
	ds_read_b128 v[56:59], v132 offset:6144
	ds_read_b128 v[60:63], v132 offset:7168
	global_load_lds_dwordx4 v[64:65], off
	v_lshl_add_u64 v[64:65], s[28:29], 0, v[178:179]
	s_mov_b32 m0, s51
	s_nop 0
	global_load_lds_dwordx4 v[64:65], off
	s_waitcnt vmcnt(8)
	s_waitcnt lgkmcnt(0)
	s_barrier
	s_setprio 1
	v_mfma_f32_16x16x32_bf16 v[64:67], v[0:3], v[32:35], 0
	v_mfma_f32_16x16x32_bf16 v[68:71], v[8:11], v[32:35], 0
	v_mfma_f32_16x16x32_bf16 v[72:75], v[0:3], v[40:43], 0
	v_mfma_f32_16x16x32_bf16 v[76:79], v[8:11], v[40:43], 0
	v_mfma_f32_16x16x32_bf16 v[80:83], v[0:3], v[48:51], 0
	v_mfma_f32_16x16x32_bf16 v[84:87], v[8:11], v[48:51], 0
	v_mfma_f32_16x16x32_bf16 v[88:91], v[0:3], v[56:59], 0
	v_mfma_f32_16x16x32_bf16 v[92:95], v[8:11], v[56:59], 0
	v_mfma_f32_16x16x32_bf16 v[64:67], v[4:7], v[36:39], v[64:67]
	v_mfma_f32_16x16x32_bf16 v[68:71], v[12:15], v[36:39], v[68:71]
	v_mfma_f32_16x16x32_bf16 v[72:75], v[4:7], v[44:47], v[72:75]
	v_mfma_f32_16x16x32_bf16 v[76:79], v[12:15], v[44:47], v[76:79]
	v_mfma_f32_16x16x32_bf16 v[80:83], v[4:7], v[52:55], v[80:83]
	v_mfma_f32_16x16x32_bf16 v[84:87], v[12:15], v[52:55], v[84:87]
	v_mfma_f32_16x16x32_bf16 v[88:91], v[4:7], v[60:63], v[88:91]
	v_mfma_f32_16x16x32_bf16 v[92:95], v[12:15], v[60:63], v[92:95]
	s_setprio 0
	s_setprio 1
	v_mfma_f32_16x16x32_bf16 v[96:99], v[16:19], v[32:35], 0
	v_mfma_f32_16x16x32_bf16 v[32:35], v[24:27], v[32:35], 0
	v_mfma_f32_16x16x32_bf16 v[96:99], v[20:23], v[36:39], v[96:99]
	v_mfma_f32_16x16x32_bf16 v[32:35], v[28:31], v[36:39], v[32:35]
	v_mfma_f32_16x16x32_bf16 v[36:39], v[16:19], v[40:43], 0
	v_mfma_f32_16x16x32_bf16 v[40:43], v[24:27], v[40:43], 0
	v_mfma_f32_16x16x32_bf16 v[36:39], v[20:23], v[44:47], v[36:39]
	v_mfma_f32_16x16x32_bf16 v[40:43], v[28:31], v[44:47], v[40:43]
	v_mfma_f32_16x16x32_bf16 v[44:47], v[16:19], v[48:51], 0
	v_mfma_f32_16x16x32_bf16 v[48:51], v[24:27], v[48:51], 0
	v_mfma_f32_16x16x32_bf16 v[100:103], v[28:31], v[52:55], v[48:51]
	v_mfma_f32_16x16x32_bf16 v[48:51], v[16:19], v[56:59], 0
	v_mfma_f32_16x16x32_bf16 v[104:107], v[20:23], v[60:63], v[48:51]
	v_mfma_f32_16x16x32_bf16 v[48:51], v[24:27], v[56:59], 0
	v_mfma_f32_16x16x32_bf16 v[44:47], v[20:23], v[52:55], v[44:47]
	v_mfma_f32_16x16x32_bf16 v[108:111], v[28:31], v[60:63], v[48:51]
	s_setprio 0
	s_barrier
	s_mov_b32 m0, s52
	v_lshl_add_u64 v[246:247], s[26:27], 0, v[176:177]
	s_add_u32 s28, s26, 0x40000
	s_nop 0
	ds_read_b128 v[48:51], v132 offset:16384
	ds_read_b128 v[52:55], v132 offset:17408
	ds_read_b128 v[56:59], v132 offset:18432
	ds_read_b128 v[60:63], v132 offset:19456
	ds_read_b128 v[112:115], v132 offset:20480
	ds_read_b128 v[116:119], v132 offset:21504
	ds_read_b128 v[120:123], v132 offset:22528
	ds_read_b128 v[124:127], v132 offset:23552
	global_load_lds_dwordx4 v[246:247], off
	v_lshl_add_u64 v[248:249], s[26:27], 0, v[178:179]
	s_mov_b32 m0, s53
	s_addc_u32 s29, s27, 0
	global_load_lds_dwordx4 v[248:249], off
	v_lshl_add_u64 v[136:137], s[28:29], 0, v[176:177]
	s_mov_b32 m0, s54
	v_lshl_add_u64 v[250:251], s[30:31], 0, v[176:177]
	global_load_lds_dwordx4 v[136:137], off
	v_lshl_add_u64 v[136:137], s[28:29], 0, v[178:179]
	s_mov_b32 m0, s55
	v_lshl_add_u64 v[252:253], s[30:31], 0, v[178:179]
	global_load_lds_dwordx4 v[136:137], off
	s_mov_b32 m0, s38
	s_nop 0
	global_load_lds_dwordx4 v[250:251], off
	s_mov_b32 m0, s39
	s_nop 0
	global_load_lds_dwordx4 v[252:253], off
	s_waitcnt vmcnt(8)
	s_waitcnt lgkmcnt(0)
	s_barrier
	s_setprio 1
	v_mfma_f32_16x16x32_bf16 v[136:139], v[0:3], v[48:51], 0
	v_mfma_f32_16x16x32_bf16 v[144:147], v[0:3], v[56:59], 0
	v_mfma_f32_16x16x32_bf16 v[152:155], v[0:3], v[112:115], 0
	v_mfma_f32_16x16x32_bf16 v[0:3], v[0:3], v[120:123], 0
	v_mfma_f32_16x16x32_bf16 v[140:143], v[8:11], v[48:51], 0
	v_mfma_f32_16x16x32_bf16 v[148:151], v[8:11], v[56:59], 0
	v_mfma_f32_16x16x32_bf16 v[156:159], v[8:11], v[112:115], 0
	v_mfma_f32_16x16x32_bf16 v[160:163], v[4:7], v[124:127], v[0:3]
	v_mfma_f32_16x16x32_bf16 v[0:3], v[8:11], v[120:123], 0
	v_mfma_f32_16x16x32_bf16 v[136:139], v[4:7], v[52:55], v[136:139]
	v_mfma_f32_16x16x32_bf16 v[140:143], v[12:15], v[52:55], v[140:143]
	v_mfma_f32_16x16x32_bf16 v[144:147], v[4:7], v[60:63], v[144:147]
	v_mfma_f32_16x16x32_bf16 v[148:151], v[12:15], v[60:63], v[148:151]
	v_mfma_f32_16x16x32_bf16 v[152:155], v[4:7], v[116:119], v[152:155]
	v_mfma_f32_16x16x32_bf16 v[156:159], v[12:15], v[116:119], v[156:159]
	v_mfma_f32_16x16x32_bf16 v[164:167], v[12:15], v[124:127], v[0:3]
	s_setprio 0
	s_setprio 1
	v_mfma_f32_16x16x32_bf16 v[0:3], v[16:19], v[48:51], 0
	v_mfma_f32_16x16x32_bf16 v[168:171], v[20:23], v[52:55], v[0:3]
	v_mfma_f32_16x16x32_bf16 v[0:3], v[24:27], v[48:51], 0
	v_mfma_f32_16x16x32_bf16 v[172:175], v[28:31], v[52:55], v[0:3]
	v_mfma_f32_16x16x32_bf16 v[0:3], v[16:19], v[56:59], 0
	v_mfma_f32_16x16x32_bf16 v[180:183], v[20:23], v[60:63], v[0:3]
	v_mfma_f32_16x16x32_bf16 v[0:3], v[24:27], v[56:59], 0
	v_mfma_f32_16x16x32_bf16 v[184:187], v[28:31], v[60:63], v[0:3]
	v_mfma_f32_16x16x32_bf16 v[0:3], v[16:19], v[112:115], 0
	v_mfma_f32_16x16x32_bf16 v[188:191], v[20:23], v[116:119], v[0:3]
	v_mfma_f32_16x16x32_bf16 v[0:3], v[24:27], v[112:115], 0
	v_mfma_f32_16x16x32_bf16 v[192:195], v[28:31], v[116:119], v[0:3]
	v_mfma_f32_16x16x32_bf16 v[0:3], v[16:19], v[120:123], 0
	v_mfma_f32_16x16x32_bf16 v[196:199], v[20:23], v[124:127], v[0:3]
	v_mfma_f32_16x16x32_bf16 v[0:3], v[24:27], v[120:123], 0
	v_mfma_f32_16x16x32_bf16 v[200:203], v[28:31], v[124:127], v[0:3]
	s_setprio 0
	s_barrier
	ds_read_b128 v[112:115], v133
	ds_read_b128 v[116:119], v133 offset:1024
	ds_read_b128 v[120:123], v133 offset:2048
	ds_read_b128 v[124:127], v133 offset:3072
	ds_read_b128 v[206:209], v134
	ds_read_b128 v[210:213], v134 offset:1024
	ds_read_b128 v[214:217], v134 offset:2048
	ds_read_b128 v[218:221], v134 offset:3072
	s_add_u32 s28, s30, 0x40000
	s_addc_u32 s29, s31, 0
	s_mov_b32 m0, s40
	v_lshl_add_u64 v[0:1], s[28:29], 0, v[176:177]
	ds_read_b128 v[48:51], v132 offset:32768
	ds_read_b128 v[52:55], v132 offset:33792
	ds_read_b128 v[222:225], v132 offset:34816
	ds_read_b128 v[226:229], v132 offset:35840
	ds_read_b128 v[230:233], v132 offset:36864
	ds_read_b128 v[234:237], v132 offset:37888
	ds_read_b128 v[238:241], v132 offset:38912
	ds_read_b128 v[242:245], v132 offset:39936
	global_load_lds_dwordx4 v[0:1], off
	v_lshl_add_u64 v[0:1], s[28:29], 0, v[178:179]
	s_mov_b32 m0, s41
	s_nop 0
	global_load_lds_dwordx4 v[0:1], off
	s_waitcnt vmcnt(8)
	s_waitcnt lgkmcnt(0)
	s_barrier
	s_setprio 1
	v_mfma_f32_16x16x32_bf16 v[0:3], v[112:115], v[48:51], v[64:67]
	v_mfma_f32_16x16x32_bf16 v[24:27], v[116:119], v[52:55], v[0:3]
	v_mfma_f32_16x16x32_bf16 v[0:3], v[120:123], v[48:51], v[68:71]
	v_mfma_f32_16x16x32_bf16 v[28:31], v[124:127], v[52:55], v[0:3]
	v_mfma_f32_16x16x32_bf16 v[0:3], v[112:115], v[222:225], v[72:75]
	v_mfma_f32_16x16x32_bf16 v[16:19], v[116:119], v[226:229], v[0:3]
	v_mfma_f32_16x16x32_bf16 v[0:3], v[120:123], v[222:225], v[76:79]
	v_mfma_f32_16x16x32_bf16 v[20:23], v[124:127], v[226:229], v[0:3]
	v_mfma_f32_16x16x32_bf16 v[0:3], v[112:115], v[230:233], v[80:83]
	v_mfma_f32_16x16x32_bf16 v[8:11], v[116:119], v[234:237], v[0:3]
	v_mfma_f32_16x16x32_bf16 v[0:3], v[120:123], v[230:233], v[84:87]
	v_mfma_f32_16x16x32_bf16 v[12:15], v[124:127], v[234:237], v[0:3]
	v_mfma_f32_16x16x32_bf16 v[0:3], v[112:115], v[238:241], v[88:91]
	v_mfma_f32_16x16x32_bf16 v[4:7], v[120:123], v[238:241], v[92:95]
	v_mfma_f32_16x16x32_bf16 v[0:3], v[116:119], v[242:245], v[0:3]
	v_mfma_f32_16x16x32_bf16 v[4:7], v[124:127], v[242:245], v[4:7]
	s_setprio 0
	s_setprio 1
	v_mfma_f32_16x16x32_bf16 v[32:35], v[214:217], v[48:51], v[32:35]
	v_mfma_f32_16x16x32_bf16 v[60:63], v[218:221], v[52:55], v[32:35]
	v_mfma_f32_16x16x32_bf16 v[32:35], v[206:209], v[222:225], v[36:39]
	v_mfma_f32_16x16x32_bf16 v[56:59], v[206:209], v[48:51], v[96:99]
	v_mfma_f32_16x16x32_bf16 v[48:51], v[210:213], v[226:229], v[32:35]
	v_mfma_f32_16x16x32_bf16 v[32:35], v[214:217], v[222:225], v[40:43]
	v_mfma_f32_16x16x32_bf16 v[56:59], v[210:213], v[52:55], v[56:59]
	v_mfma_f32_16x16x32_bf16 v[52:55], v[218:221], v[226:229], v[32:35]
	v_mfma_f32_16x16x32_bf16 v[32:35], v[206:209], v[230:233], v[44:47]
	v_mfma_f32_16x16x32_bf16 v[40:43], v[210:213], v[234:237], v[32:35]
	v_mfma_f32_16x16x32_bf16 v[32:35], v[214:217], v[230:233], v[100:103]
	v_mfma_f32_16x16x32_bf16 v[44:47], v[218:221], v[234:237], v[32:35]
	v_mfma_f32_16x16x32_bf16 v[32:35], v[206:209], v[238:241], v[104:107]
	v_mfma_f32_16x16x32_bf16 v[36:39], v[214:217], v[238:241], v[108:111]
	v_mfma_f32_16x16x32_bf16 v[32:35], v[210:213], v[242:245], v[32:35]
	v_mfma_f32_16x16x32_bf16 v[36:39], v[218:221], v[242:245], v[36:39]
	s_setprio 0
	s_barrier
	s_mov_b32 m0, s59
	v_lshl_add_u64 v[64:65], v[246:247], 0, s[8:9]
	s_add_u32 s26, s26, 0x40080
	ds_read_b128 v[88:91], v132 offset:49152
	ds_read_b128 v[96:99], v132 offset:50176
	ds_read_b128 v[104:107], v132 offset:51200
	ds_read_b128 v[108:111], v132 offset:52224
	ds_read_b128 v[222:225], v132 offset:53248
	ds_read_b128 v[226:229], v132 offset:54272
	ds_read_b128 v[230:233], v132 offset:55296
	ds_read_b128 v[234:237], v132 offset:56320
	global_load_lds_dwordx4 v[64:65], off
	v_lshl_add_u64 v[64:65], v[248:249], 0, s[8:9]
	s_mov_b32 m0, s60
	s_addc_u32 s27, s27, 0
	global_load_lds_dwordx4 v[64:65], off
	v_lshl_add_u64 v[64:65], s[26:27], 0, v[176:177]
	s_mov_b32 m0, s61
	s_nop 0
	global_load_lds_dwordx4 v[64:65], off
	v_lshl_add_u64 v[64:65], s[26:27], 0, v[178:179]
	s_mov_b32 m0, s62
	s_nop 0
	global_load_lds_dwordx4 v[64:65], off
	v_lshl_add_u64 v[64:65], v[250:251], 0, s[8:9]
	s_mov_b32 m0, s42
	s_nop 0
	global_load_lds_dwordx4 v[64:65], off
	v_lshl_add_u64 v[64:65], v[252:253], 0, s[8:9]
	s_mov_b32 m0, s43
	s_nop 0
	global_load_lds_dwordx4 v[64:65], off
	s_waitcnt vmcnt(8)
	s_waitcnt lgkmcnt(0)
	s_barrier
	s_setprio 1
	v_mfma_f32_16x16x32_bf16 v[64:67], v[112:115], v[88:91], v[136:139]
	v_mfma_f32_16x16x32_bf16 v[92:95], v[116:119], v[96:99], v[64:67]
	v_mfma_f32_16x16x32_bf16 v[64:67], v[120:123], v[88:91], v[140:143]
	v_mfma_f32_16x16x32_bf16 v[100:103], v[124:127], v[96:99], v[64:67]
	v_mfma_f32_16x16x32_bf16 v[64:67], v[112:115], v[104:107], v[144:147]
	v_mfma_f32_16x16x32_bf16 v[80:83], v[116:119], v[108:111], v[64:67]
	v_mfma_f32_16x16x32_bf16 v[64:67], v[120:123], v[104:107], v[148:151]
	v_mfma_f32_16x16x32_bf16 v[84:87], v[124:127], v[108:111], v[64:67]
	v_mfma_f32_16x16x32_bf16 v[64:67], v[112:115], v[222:225], v[152:155]
	v_mfma_f32_16x16x32_bf16 v[72:75], v[116:119], v[226:229], v[64:67]
	v_mfma_f32_16x16x32_bf16 v[64:67], v[120:123], v[222:225], v[156:159]
	v_mfma_f32_16x16x32_bf16 v[76:79], v[124:127], v[226:229], v[64:67]
	v_mfma_f32_16x16x32_bf16 v[64:67], v[112:115], v[230:233], v[160:163]
	v_mfma_f32_16x16x32_bf16 v[68:71], v[120:123], v[230:233], v[164:167]
	v_mfma_f32_16x16x32_bf16 v[64:67], v[116:119], v[234:237], v[64:67]
	v_mfma_f32_16x16x32_bf16 v[68:71], v[124:127], v[234:237], v[68:71]
	s_setprio 0
	s_setprio 1
	v_mfma_f32_16x16x32_bf16 v[112:115], v[206:209], v[88:91], v[168:171]
	v_mfma_f32_16x16x32_bf16 v[88:91], v[214:217], v[88:91], v[172:175]
	v_mfma_f32_16x16x32_bf16 v[124:127], v[218:221], v[96:99], v[88:91]
	v_mfma_f32_16x16x32_bf16 v[88:91], v[206:209], v[104:107], v[180:183]
	v_mfma_f32_16x16x32_bf16 v[120:123], v[210:213], v[96:99], v[112:115]
	v_mfma_f32_16x16x32_bf16 v[112:115], v[210:213], v[108:111], v[88:91]
	v_mfma_f32_16x16x32_bf16 v[88:91], v[214:217], v[104:107], v[184:187]
	v_mfma_f32_16x16x32_bf16 v[116:119], v[218:221], v[108:111], v[88:91]
	v_mfma_f32_16x16x32_bf16 v[88:91], v[206:209], v[222:225], v[188:191]
	v_mfma_f32_16x16x32_bf16 v[104:107], v[210:213], v[226:229], v[88:91]
	v_mfma_f32_16x16x32_bf16 v[88:91], v[214:217], v[222:225], v[192:195]
	v_mfma_f32_16x16x32_bf16 v[108:111], v[218:221], v[226:229], v[88:91]
	v_mfma_f32_16x16x32_bf16 v[88:91], v[206:209], v[230:233], v[196:199]
	v_mfma_f32_16x16x32_bf16 v[96:99], v[214:217], v[230:233], v[200:203]
	v_mfma_f32_16x16x32_bf16 v[88:91], v[210:213], v[234:237], v[88:91]
	v_mfma_f32_16x16x32_bf16 v[96:99], v[218:221], v[234:237], v[96:99]
	s_setprio 0
	s_barrier
	s_and_b64 vcc, exec, s[2:3]
	s_cbranch_vccnz .LBB0_1113
	s_barrier

.Llsb_skip_9:
.LBB0_1243:
	ds_read_b128 v[150:153], v147
	ds_read_b128 v[154:157], v147 offset:1024
	ds_read_b128 v[158:161], v147 offset:2048
	ds_read_b128 v[162:165], v147 offset:3072
	ds_read_b128 v[166:169], v148
	ds_read_b128 v[170:173], v148 offset:1024
	ds_read_b128 v[174:177], v148 offset:2048
	ds_read_b128 v[178:181], v148 offset:3072
	s_add_u32 s24, s22, 0xfffc0080
	s_addc_u32 s25, s23, -1
	s_cmp_eq_u32 s51, 12
	s_cselect_b32 s27, s15, s25
	s_cselect_b32 s26, s47, s24
	s_cselect_b32 s25, s13, s50
	s_cselect_b32 s24, s48, s49
	v_lshl_add_u64 v[202:203], s[22:23], 0, v[136:137]
	s_add_i32 m0, s21, 0xc000
	ds_read_b128 v[182:185], v149
	ds_read_b128 v[186:189], v149 offset:1024
	ds_read_b128 v[190:193], v149 offset:2048
	ds_read_b128 v[194:197], v149 offset:3072
	ds_read_b128 v[198:201], v149 offset:4096
	ds_read_b128 v[206:209], v149 offset:5120
	ds_read_b128 v[210:213], v149 offset:6144
	ds_read_b128 v[214:217], v149 offset:7168
	global_load_lds_dwordx4 v[202:203], off
	v_lshl_add_u64 v[202:203], s[22:23], 0, v[138:139]
	s_add_i32 m0, s21, 0xe000
	s_nop 0
	global_load_lds_dwordx4 v[202:203], off
	s_waitcnt vmcnt(8)
	s_waitcnt lgkmcnt(0)
	s_barrier
	s_setprio 1
	v_mfma_f32_16x16x32_bf16 v[124:127], v[150:153], v[182:185], v[124:127]
	v_mfma_f32_16x16x32_bf16 v[120:123], v[158:161], v[182:185], v[120:123]
	v_mfma_f32_16x16x32_bf16 v[108:111], v[150:153], v[190:193], v[108:111]
	v_mfma_f32_16x16x32_bf16 v[104:107], v[158:161], v[190:193], v[104:107]
	v_mfma_f32_16x16x32_bf16 v[92:95], v[150:153], v[198:201], v[92:95]
	v_mfma_f32_16x16x32_bf16 v[88:91], v[158:161], v[198:201], v[88:91]
	v_mfma_f32_16x16x32_bf16 v[76:79], v[150:153], v[210:213], v[76:79]
	v_mfma_f32_16x16x32_bf16 v[72:75], v[158:161], v[210:213], v[72:75]
	v_mfma_f32_16x16x32_bf16 v[124:127], v[154:157], v[186:189], v[124:127]
	v_mfma_f32_16x16x32_bf16 v[120:123], v[162:165], v[186:189], v[120:123]
	v_mfma_f32_16x16x32_bf16 v[108:111], v[154:157], v[194:197], v[108:111]
	v_mfma_f32_16x16x32_bf16 v[104:107], v[162:165], v[194:197], v[104:107]
	v_mfma_f32_16x16x32_bf16 v[92:95], v[154:157], v[206:209], v[92:95]
	v_mfma_f32_16x16x32_bf16 v[88:91], v[162:165], v[206:209], v[88:91]
	v_mfma_f32_16x16x32_bf16 v[76:79], v[154:157], v[214:217], v[76:79]
	v_mfma_f32_16x16x32_bf16 v[72:75], v[162:165], v[214:217], v[72:75]
	s_setprio 0
	s_setprio 1
	v_mfma_f32_16x16x32_bf16 v[116:119], v[166:169], v[182:185], v[116:119]
	v_mfma_f32_16x16x32_bf16 v[112:115], v[174:177], v[182:185], v[112:115]
	v_mfma_f32_16x16x32_bf16 v[100:103], v[166:169], v[190:193], v[100:103]
	v_mfma_f32_16x16x32_bf16 v[96:99], v[174:177], v[190:193], v[96:99]
	v_mfma_f32_16x16x32_bf16 v[84:87], v[166:169], v[198:201], v[84:87]
	v_mfma_f32_16x16x32_bf16 v[80:83], v[174:177], v[198:201], v[80:83]
	v_mfma_f32_16x16x32_bf16 v[68:71], v[166:169], v[210:213], v[68:71]
	v_mfma_f32_16x16x32_bf16 v[64:67], v[174:177], v[210:213], v[64:67]
	v_mfma_f32_16x16x32_bf16 v[116:119], v[170:173], v[186:189], v[116:119]
	v_mfma_f32_16x16x32_bf16 v[112:115], v[178:181], v[186:189], v[112:115]
	v_mfma_f32_16x16x32_bf16 v[100:103], v[170:173], v[194:197], v[100:103]
	v_mfma_f32_16x16x32_bf16 v[96:99], v[178:181], v[194:197], v[96:99]
	v_mfma_f32_16x16x32_bf16 v[84:87], v[170:173], v[206:209], v[84:87]
	v_mfma_f32_16x16x32_bf16 v[80:83], v[178:181], v[206:209], v[80:83]
	v_mfma_f32_16x16x32_bf16 v[68:71], v[170:173], v[214:217], v[68:71]
	v_mfma_f32_16x16x32_bf16 v[64:67], v[178:181], v[214:217], v[64:67]
	s_setprio 0
	s_barrier
	s_add_i32 s52, s43, s34
	v_lshl_add_u64 v[202:203], s[24:25], 0, v[130:131]
	s_mov_b32 m0, s52
	ds_read_b128 v[182:185], v149 offset:16384
	ds_read_b128 v[186:189], v149 offset:17408
	ds_read_b128 v[190:193], v149 offset:18432
	ds_read_b128 v[194:197], v149 offset:19456
	ds_read_b128 v[198:201], v149 offset:20480
	ds_read_b128 v[206:209], v149 offset:21504
	ds_read_b128 v[210:213], v149 offset:22528
	ds_read_b128 v[214:217], v149 offset:23552
	global_load_lds_dwordx4 v[202:203], off
	s_add_i32 m0, s52, 0x2000
	s_add_u32 s52, s24, 0x40000
	v_lshl_add_u64 v[218:219], s[24:25], 0, v[134:135]
	s_addc_u32 s53, s25, 0
	s_add_i32 s54, s44, s34
	global_load_lds_dwordx4 v[218:219], off
	v_lshl_add_u64 v[220:221], s[52:53], 0, v[130:131]
	s_mov_b32 m0, s54
	v_lshl_add_u64 v[222:223], s[26:27], 0, v[132:133]
	global_load_lds_dwordx4 v[220:221], off
	v_lshl_add_u64 v[220:221], s[52:53], 0, v[134:135]
	s_add_i32 m0, s54, 0x2000
	s_nop 0
	global_load_lds_dwordx4 v[220:221], off
	v_lshl_add_u64 v[220:221], s[26:27], 0, v[128:129]
	s_mov_b32 m0, s21
	s_nop 0
	global_load_lds_dwordx4 v[220:221], off
	s_mov_b32 m0, s35
	s_nop 0
	global_load_lds_dwordx4 v[222:223], off
	s_waitcnt vmcnt(8)
	s_waitcnt lgkmcnt(0)
	s_barrier
	s_setprio 1
	v_mfma_f32_16x16x32_bf16 v[60:63], v[150:153], v[182:185], v[60:63]
	v_mfma_f32_16x16x32_bf16 v[56:59], v[158:161], v[182:185], v[56:59]
	v_mfma_f32_16x16x32_bf16 v[44:47], v[150:153], v[190:193], v[44:47]
	v_mfma_f32_16x16x32_bf16 v[40:43], v[158:161], v[190:193], v[40:43]
	v_mfma_f32_16x16x32_bf16 v[28:31], v[150:153], v[198:201], v[28:31]
	v_mfma_f32_16x16x32_bf16 v[24:27], v[158:161], v[198:201], v[24:27]
	v_mfma_f32_16x16x32_bf16 v[12:15], v[150:153], v[210:213], v[12:15]
	v_mfma_f32_16x16x32_bf16 v[8:11], v[158:161], v[210:213], v[8:11]
	v_mfma_f32_16x16x32_bf16 v[60:63], v[154:157], v[186:189], v[60:63]
	v_mfma_f32_16x16x32_bf16 v[56:59], v[162:165], v[186:189], v[56:59]
	v_mfma_f32_16x16x32_bf16 v[44:47], v[154:157], v[194:197], v[44:47]
	v_mfma_f32_16x16x32_bf16 v[40:43], v[162:165], v[194:197], v[40:43]
	v_mfma_f32_16x16x32_bf16 v[28:31], v[154:157], v[206:209], v[28:31]
	v_mfma_f32_16x16x32_bf16 v[24:27], v[162:165], v[206:209], v[24:27]
	v_mfma_f32_16x16x32_bf16 v[12:15], v[154:157], v[214:217], v[12:15]
	v_mfma_f32_16x16x32_bf16 v[8:11], v[162:165], v[214:217], v[8:11]
	s_setprio 0
	s_setprio 1
	v_mfma_f32_16x16x32_bf16 v[52:55], v[166:169], v[182:185], v[52:55]
	v_mfma_f32_16x16x32_bf16 v[48:51], v[174:177], v[182:185], v[48:51]
	v_mfma_f32_16x16x32_bf16 v[36:39], v[166:169], v[190:193], v[36:39]
	v_mfma_f32_16x16x32_bf16 v[32:35], v[174:177], v[190:193], v[32:35]
	v_mfma_f32_16x16x32_bf16 v[20:23], v[166:169], v[198:201], v[20:23]
	v_mfma_f32_16x16x32_bf16 v[16:19], v[174:177], v[198:201], v[16:19]
	v_mfma_f32_16x16x32_bf16 v[4:7], v[166:169], v[210:213], v[4:7]
	v_mfma_f32_16x16x32_bf16 v[0:3], v[174:177], v[210:213], v[0:3]
	v_mfma_f32_16x16x32_bf16 v[52:55], v[170:173], v[186:189], v[52:55]
	v_mfma_f32_16x16x32_bf16 v[48:51], v[178:181], v[186:189], v[48:51]
	v_mfma_f32_16x16x32_bf16 v[36:39], v[170:173], v[194:197], v[36:39]
	v_mfma_f32_16x16x32_bf16 v[32:35], v[178:181], v[194:197], v[32:35]
	v_mfma_f32_16x16x32_bf16 v[20:23], v[170:173], v[206:209], v[20:23]
	v_mfma_f32_16x16x32_bf16 v[16:19], v[178:181], v[206:209], v[16:19]
	v_mfma_f32_16x16x32_bf16 v[4:7], v[170:173], v[214:217], v[4:7]
	v_mfma_f32_16x16x32_bf16 v[0:3], v[178:181], v[214:217], v[0:3]
	s_setprio 0
	s_barrier
	s_add_i32 s52, 0, 0x18000
	s_add_i32 s53, 0, 0x1c000
	v_add_u32_e32 v162, s52, v145
	v_add_u32_e32 v178, s53, v145
	ds_read_b128 v[150:153], v162
	ds_read_b128 v[154:157], v162 offset:1024
	ds_read_b128 v[158:161], v162 offset:2048
	ds_read_b128 v[162:165], v162 offset:3072
	ds_read_b128 v[166:169], v178
	ds_read_b128 v[170:173], v178 offset:1024
	ds_read_b128 v[174:177], v178 offset:2048
	ds_read_b128 v[178:181], v178 offset:3072
	s_add_u32 s26, s26, 0x40000
	s_addc_u32 s27, s27, 0
	s_mov_b32 m0, s36
	v_lshl_add_u64 v[224:225], s[26:27], 0, v[128:129]
	ds_read_b128 v[182:185], v149 offset:32768
	ds_read_b128 v[186:189], v149 offset:33792
	ds_read_b128 v[190:193], v149 offset:34816
	ds_read_b128 v[194:197], v149 offset:35840
	ds_read_b128 v[198:201], v149 offset:36864
	ds_read_b128 v[206:209], v149 offset:37888
	ds_read_b128 v[210:213], v149 offset:38912
	ds_read_b128 v[214:217], v149 offset:39936
	global_load_lds_dwordx4 v[224:225], off
	v_lshl_add_u64 v[224:225], s[26:27], 0, v[132:133]
	s_mov_b32 m0, s37
	s_nop 0
	global_load_lds_dwordx4 v[224:225], off
	s_waitcnt vmcnt(8)
	s_waitcnt lgkmcnt(0)
	s_barrier
	s_setprio 1
	v_mfma_f32_16x16x32_bf16 v[124:127], v[150:153], v[182:185], v[124:127]
	v_mfma_f32_16x16x32_bf16 v[120:123], v[158:161], v[182:185], v[120:123]
	v_mfma_f32_16x16x32_bf16 v[108:111], v[150:153], v[190:193], v[108:111]
	v_mfma_f32_16x16x32_bf16 v[104:107], v[158:161], v[190:193], v[104:107]
	v_mfma_f32_16x16x32_bf16 v[92:95], v[150:153], v[198:201], v[92:95]
	v_mfma_f32_16x16x32_bf16 v[88:91], v[158:161], v[198:201], v[88:91]
	v_mfma_f32_16x16x32_bf16 v[76:79], v[150:153], v[210:213], v[76:79]
	v_mfma_f32_16x16x32_bf16 v[72:75], v[158:161], v[210:213], v[72:75]
	v_mfma_f32_16x16x32_bf16 v[124:127], v[154:157], v[186:189], v[124:127]
	v_mfma_f32_16x16x32_bf16 v[120:123], v[162:165], v[186:189], v[120:123]
	v_mfma_f32_16x16x32_bf16 v[108:111], v[154:157], v[194:197], v[108:111]
	v_mfma_f32_16x16x32_bf16 v[104:107], v[162:165], v[194:197], v[104:107]
	v_mfma_f32_16x16x32_bf16 v[92:95], v[154:157], v[206:209], v[92:95]
	v_mfma_f32_16x16x32_bf16 v[88:91], v[162:165], v[206:209], v[88:91]
	v_mfma_f32_16x16x32_bf16 v[76:79], v[154:157], v[214:217], v[76:79]
	v_mfma_f32_16x16x32_bf16 v[72:75], v[162:165], v[214:217], v[72:75]
	s_setprio 0
	s_setprio 1
	v_mfma_f32_16x16x32_bf16 v[116:119], v[166:169], v[182:185], v[116:119]
	v_mfma_f32_16x16x32_bf16 v[112:115], v[174:177], v[182:185], v[112:115]
	v_mfma_f32_16x16x32_bf16 v[100:103], v[166:169], v[190:193], v[100:103]
	v_mfma_f32_16x16x32_bf16 v[96:99], v[174:177], v[190:193], v[96:99]
	v_mfma_f32_16x16x32_bf16 v[84:87], v[166:169], v[198:201], v[84:87]
	v_mfma_f32_16x16x32_bf16 v[80:83], v[174:177], v[198:201], v[80:83]
	v_mfma_f32_16x16x32_bf16 v[68:71], v[166:169], v[210:213], v[68:71]
	v_mfma_f32_16x16x32_bf16 v[64:67], v[174:177], v[210:213], v[64:67]
	v_mfma_f32_16x16x32_bf16 v[116:119], v[170:173], v[186:189], v[116:119]
	v_mfma_f32_16x16x32_bf16 v[112:115], v[178:181], v[186:189], v[112:115]
	v_mfma_f32_16x16x32_bf16 v[100:103], v[170:173], v[194:197], v[100:103]
	v_mfma_f32_16x16x32_bf16 v[96:99], v[178:181], v[194:197], v[96:99]
	v_mfma_f32_16x16x32_bf16 v[84:87], v[170:173], v[206:209], v[84:87]
	v_mfma_f32_16x16x32_bf16 v[80:83], v[178:181], v[206:209], v[80:83]
	v_mfma_f32_16x16x32_bf16 v[68:71], v[170:173], v[214:217], v[68:71]
	v_mfma_f32_16x16x32_bf16 v[64:67], v[178:181], v[214:217], v[64:67]
	s_setprio 0
	s_barrier
	s_add_i32 s26, s52, s34
	v_lshl_add_u64 v[202:203], v[202:203], 0, s[8:9]
	s_mov_b32 m0, s26
	ds_read_b128 v[182:185], v149 offset:49152
	ds_read_b128 v[186:189], v149 offset:50176
	ds_read_b128 v[190:193], v149 offset:51200
	ds_read_b128 v[194:197], v149 offset:52224
	ds_read_b128 v[198:201], v149 offset:53248
	ds_read_b128 v[206:209], v149 offset:54272
	ds_read_b128 v[210:213], v149 offset:55296
	ds_read_b128 v[214:217], v149 offset:56320
	global_load_lds_dwordx4 v[202:203], off
	s_add_i32 m0, s26, 0x2000
	s_add_u32 s24, s24, 0x40080
	v_lshl_add_u64 v[202:203], v[218:219], 0, s[8:9]
	s_addc_u32 s25, s25, 0
	s_add_i32 s26, s53, s34
	global_load_lds_dwordx4 v[202:203], off
	v_lshl_add_u64 v[202:203], s[24:25], 0, v[130:131]
	s_mov_b32 m0, s26
	s_nop 0
	global_load_lds_dwordx4 v[202:203], off
	v_lshl_add_u64 v[202:203], s[24:25], 0, v[134:135]
	s_add_i32 m0, s26, 0x2000
	s_nop 0
	global_load_lds_dwordx4 v[202:203], off
	v_lshl_add_u64 v[202:203], v[220:221], 0, s[8:9]
	s_mov_b32 m0, s40
	s_nop 0
	global_load_lds_dwordx4 v[202:203], off
	v_lshl_add_u64 v[202:203], v[222:223], 0, s[8:9]
	s_mov_b32 m0, s41
	s_nop 0
	global_load_lds_dwordx4 v[202:203], off
	s_waitcnt vmcnt(8)
	s_waitcnt lgkmcnt(0)
	s_barrier
	s_setprio 1
	v_mfma_f32_16x16x32_bf16 v[60:63], v[150:153], v[182:185], v[60:63]
	v_mfma_f32_16x16x32_bf16 v[56:59], v[158:161], v[182:185], v[56:59]
	v_mfma_f32_16x16x32_bf16 v[44:47], v[150:153], v[190:193], v[44:47]
	v_mfma_f32_16x16x32_bf16 v[40:43], v[158:161], v[190:193], v[40:43]
	v_mfma_f32_16x16x32_bf16 v[28:31], v[150:153], v[198:201], v[28:31]
	v_mfma_f32_16x16x32_bf16 v[24:27], v[158:161], v[198:201], v[24:27]
	v_mfma_f32_16x16x32_bf16 v[12:15], v[150:153], v[210:213], v[12:15]
	v_mfma_f32_16x16x32_bf16 v[8:11], v[158:161], v[210:213], v[8:11]
	v_mfma_f32_16x16x32_bf16 v[60:63], v[154:157], v[186:189], v[60:63]
	v_mfma_f32_16x16x32_bf16 v[56:59], v[162:165], v[186:189], v[56:59]
	v_mfma_f32_16x16x32_bf16 v[44:47], v[154:157], v[194:197], v[44:47]
	v_mfma_f32_16x16x32_bf16 v[40:43], v[162:165], v[194:197], v[40:43]
	v_mfma_f32_16x16x32_bf16 v[28:31], v[154:157], v[206:209], v[28:31]
	v_mfma_f32_16x16x32_bf16 v[24:27], v[162:165], v[206:209], v[24:27]
	v_mfma_f32_16x16x32_bf16 v[12:15], v[154:157], v[214:217], v[12:15]
	v_mfma_f32_16x16x32_bf16 v[8:11], v[162:165], v[214:217], v[8:11]
	s_setprio 0
	s_setprio 1
	v_mfma_f32_16x16x32_bf16 v[52:55], v[166:169], v[182:185], v[52:55]
	v_mfma_f32_16x16x32_bf16 v[48:51], v[174:177], v[182:185], v[48:51]
	v_mfma_f32_16x16x32_bf16 v[36:39], v[166:169], v[190:193], v[36:39]
	v_mfma_f32_16x16x32_bf16 v[32:35], v[174:177], v[190:193], v[32:35]
	v_mfma_f32_16x16x32_bf16 v[20:23], v[166:169], v[198:201], v[20:23]
	v_mfma_f32_16x16x32_bf16 v[16:19], v[174:177], v[198:201], v[16:19]
	v_mfma_f32_16x16x32_bf16 v[4:7], v[166:169], v[210:213], v[4:7]
	v_mfma_f32_16x16x32_bf16 v[0:3], v[174:177], v[210:213], v[0:3]
	v_mfma_f32_16x16x32_bf16 v[52:55], v[170:173], v[186:189], v[52:55]
	v_mfma_f32_16x16x32_bf16 v[48:51], v[178:181], v[186:189], v[48:51]
	v_mfma_f32_16x16x32_bf16 v[36:39], v[170:173], v[194:197], v[36:39]
	v_mfma_f32_16x16x32_bf16 v[32:35], v[178:181], v[194:197], v[32:35]
	v_mfma_f32_16x16x32_bf16 v[20:23], v[170:173], v[206:209], v[20:23]
	v_mfma_f32_16x16x32_bf16 v[16:19], v[178:181], v[206:209], v[16:19]
	v_mfma_f32_16x16x32_bf16 v[4:7], v[170:173], v[214:217], v[4:7]
	v_mfma_f32_16x16x32_bf16 v[0:3], v[178:181], v[214:217], v[0:3]
	s_setprio 0
	s_barrier
	s_add_i32 s51, s51, 2
	s_add_u32 s22, s22, 0x100
	s_addc_u32 s23, s23, 0
	s_add_u32 s49, s49, 0x100
	s_addc_u32 s50, s50, 0
	s_cmp_gt_u32 s51, 13
	s_cbranch_scc0 .LBB0_1243
	s_and_b64 vcc, exec, s[10:11]
	s_cbranch_vccz .LBB0_1246
	s_barrier

.Llsb_skip_10:
.LBB0_1324:
	ds_read_b128 v[128:131], v212
	ds_read_b128 v[132:135], v212 offset:1024
	ds_read_b128 v[136:139], v212 offset:2048
	ds_read_b128 v[140:143], v212 offset:3072
	ds_read_b128 v[144:147], v213
	ds_read_b128 v[148:151], v213 offset:1024
	ds_read_b128 v[152:155], v213 offset:2048
	ds_read_b128 v[156:159], v213 offset:3072
	s_add_u32 s18, s16, 0xfff50080
	s_addc_u32 s19, s17, -1
	s_cmp_eq_u32 s52, 40
	s_cselect_b32 s21, s5, s19
	s_cselect_b32 s20, s4, s18
	s_cselect_b32 s19, s15, s51
	s_cselect_b32 s18, s14, s50
	v_lshl_add_u64 v[202:203], s[16:17], 0, v[182:183]
	s_add_i32 m0, s23, 0xc000
	ds_read_b128 v[160:163], v214
	ds_read_b128 v[164:167], v214 offset:1024
	ds_read_b128 v[168:171], v214 offset:2048
	ds_read_b128 v[172:175], v214 offset:3072
	ds_read_b128 v[190:193], v214 offset:4096
	ds_read_b128 v[194:197], v214 offset:5120
	ds_read_b128 v[198:201], v214 offset:6144
	ds_read_b128 v[216:219], v214 offset:7168
	global_load_lds_dwordx4 v[202:203], off
	v_lshl_add_u64 v[202:203], s[16:17], 0, v[184:185]
	s_add_i32 m0, s23, 0xe000
	s_nop 0
	global_load_lds_dwordx4 v[202:203], off
	s_waitcnt vmcnt(8)
	s_waitcnt lgkmcnt(0)
	s_barrier
	s_setprio 1
	v_mfma_f32_16x16x32_bf16 v[124:127], v[128:131], v[160:163], v[124:127]
	v_mfma_f32_16x16x32_bf16 v[120:123], v[136:139], v[160:163], v[120:123]
	v_mfma_f32_16x16x32_bf16 v[112:115], v[128:131], v[168:171], v[112:115]
	v_mfma_f32_16x16x32_bf16 v[104:107], v[136:139], v[168:171], v[104:107]
	v_mfma_f32_16x16x32_bf16 v[96:99], v[128:131], v[190:193], v[96:99]
	v_mfma_f32_16x16x32_bf16 v[88:91], v[136:139], v[190:193], v[88:91]
	v_mfma_f32_16x16x32_bf16 v[84:87], v[128:131], v[198:201], v[84:87]
	v_mfma_f32_16x16x32_bf16 v[76:79], v[136:139], v[198:201], v[76:79]
	v_mfma_f32_16x16x32_bf16 v[124:127], v[132:135], v[164:167], v[124:127]
	v_mfma_f32_16x16x32_bf16 v[120:123], v[140:143], v[164:167], v[120:123]
	v_mfma_f32_16x16x32_bf16 v[112:115], v[132:135], v[172:175], v[112:115]
	v_mfma_f32_16x16x32_bf16 v[104:107], v[140:143], v[172:175], v[104:107]
	v_mfma_f32_16x16x32_bf16 v[96:99], v[132:135], v[194:197], v[96:99]
	v_mfma_f32_16x16x32_bf16 v[88:91], v[140:143], v[194:197], v[88:91]
	v_mfma_f32_16x16x32_bf16 v[84:87], v[132:135], v[216:219], v[84:87]
	v_mfma_f32_16x16x32_bf16 v[76:79], v[140:143], v[216:219], v[76:79]
	s_setprio 0
	s_setprio 1
	v_mfma_f32_16x16x32_bf16 v[116:119], v[144:147], v[160:163], v[116:119]
	v_mfma_f32_16x16x32_bf16 v[108:111], v[152:155], v[160:163], v[108:111]
	v_mfma_f32_16x16x32_bf16 v[100:103], v[144:147], v[168:171], v[100:103]
	v_mfma_f32_16x16x32_bf16 v[92:95], v[152:155], v[168:171], v[92:95]
	v_mfma_f32_16x16x32_bf16 v[80:83], v[144:147], v[190:193], v[80:83]
	v_mfma_f32_16x16x32_bf16 v[72:75], v[152:155], v[190:193], v[72:75]
	v_mfma_f32_16x16x32_bf16 v[68:71], v[144:147], v[198:201], v[68:71]
	v_mfma_f32_16x16x32_bf16 v[64:67], v[152:155], v[198:201], v[64:67]
	v_mfma_f32_16x16x32_bf16 v[116:119], v[148:151], v[164:167], v[116:119]
	v_mfma_f32_16x16x32_bf16 v[108:111], v[156:159], v[164:167], v[108:111]
	v_mfma_f32_16x16x32_bf16 v[100:103], v[148:151], v[172:175], v[100:103]
	v_mfma_f32_16x16x32_bf16 v[92:95], v[156:159], v[172:175], v[92:95]
	v_mfma_f32_16x16x32_bf16 v[80:83], v[148:151], v[194:197], v[80:83]
	v_mfma_f32_16x16x32_bf16 v[72:75], v[156:159], v[194:197], v[72:75]
	v_mfma_f32_16x16x32_bf16 v[68:71], v[148:151], v[216:219], v[68:71]
	v_mfma_f32_16x16x32_bf16 v[64:67], v[156:159], v[216:219], v[64:67]
	s_setprio 0
	s_barrier
	s_add_i32 s53, s35, s22
	v_lshl_add_u64 v[202:203], s[18:19], 0, v[176:177]
	s_mov_b32 m0, s53
	ds_read_b128 v[160:163], v214 offset:16384
	ds_read_b128 v[164:167], v214 offset:17408
	ds_read_b128 v[168:171], v214 offset:18432
	ds_read_b128 v[172:175], v214 offset:19456
	ds_read_b128 v[190:193], v214 offset:20480
	ds_read_b128 v[194:197], v214 offset:21504
	ds_read_b128 v[198:201], v214 offset:22528
	ds_read_b128 v[216:219], v214 offset:23552
	global_load_lds_dwordx4 v[202:203], off
	s_add_i32 m0, s53, 0x2000
	s_add_u32 s54, s18, 0xb0000
	v_lshl_add_u64 v[220:221], s[18:19], 0, v[178:179]
	s_addc_u32 s55, s19, 0
	s_add_i32 s53, s40, s22
	global_load_lds_dwordx4 v[220:221], off
	v_lshl_add_u64 v[222:223], s[54:55], 0, v[176:177]
	s_mov_b32 m0, s53
	v_lshl_add_u64 v[224:225], s[20:21], 0, v[178:179]
	global_load_lds_dwordx4 v[222:223], off
	v_lshl_add_u64 v[222:223], s[54:55], 0, v[178:179]
	s_add_i32 m0, s53, 0x2000
	s_nop 0
	global_load_lds_dwordx4 v[222:223], off
	v_lshl_add_u64 v[222:223], s[20:21], 0, v[176:177]
	s_mov_b32 m0, s23
	s_nop 0
	global_load_lds_dwordx4 v[222:223], off
	s_mov_b32 m0, s24
	s_nop 0
	global_load_lds_dwordx4 v[224:225], off
	s_waitcnt vmcnt(8)
	s_waitcnt lgkmcnt(0)
	s_barrier
	s_setprio 1
	v_mfma_f32_16x16x32_bf16 v[60:63], v[128:131], v[160:163], v[60:63]
	v_mfma_f32_16x16x32_bf16 v[56:59], v[136:139], v[160:163], v[56:59]
	v_mfma_f32_16x16x32_bf16 v[48:51], v[128:131], v[168:171], v[48:51]
	v_mfma_f32_16x16x32_bf16 v[40:43], v[136:139], v[168:171], v[40:43]
	v_mfma_f32_16x16x32_bf16 v[32:35], v[128:131], v[190:193], v[32:35]
	v_mfma_f32_16x16x32_bf16 v[24:27], v[136:139], v[190:193], v[24:27]
	v_mfma_f32_16x16x32_bf16 v[20:23], v[128:131], v[198:201], v[20:23]
	v_mfma_f32_16x16x32_bf16 v[12:15], v[136:139], v[198:201], v[12:15]
	v_mfma_f32_16x16x32_bf16 v[60:63], v[132:135], v[164:167], v[60:63]
	v_mfma_f32_16x16x32_bf16 v[56:59], v[140:143], v[164:167], v[56:59]
	v_mfma_f32_16x16x32_bf16 v[48:51], v[132:135], v[172:175], v[48:51]
	v_mfma_f32_16x16x32_bf16 v[40:43], v[140:143], v[172:175], v[40:43]
	v_mfma_f32_16x16x32_bf16 v[32:35], v[132:135], v[194:197], v[32:35]
	v_mfma_f32_16x16x32_bf16 v[24:27], v[140:143], v[194:197], v[24:27]
	v_mfma_f32_16x16x32_bf16 v[20:23], v[132:135], v[216:219], v[20:23]
	v_mfma_f32_16x16x32_bf16 v[12:15], v[140:143], v[216:219], v[12:15]
	s_setprio 0
	s_setprio 1
	v_mfma_f32_16x16x32_bf16 v[52:55], v[144:147], v[160:163], v[52:55]
	v_mfma_f32_16x16x32_bf16 v[44:47], v[152:155], v[160:163], v[44:47]
	v_mfma_f32_16x16x32_bf16 v[36:39], v[144:147], v[168:171], v[36:39]
	v_mfma_f32_16x16x32_bf16 v[28:31], v[152:155], v[168:171], v[28:31]
	v_mfma_f32_16x16x32_bf16 v[16:19], v[144:147], v[190:193], v[16:19]
	v_mfma_f32_16x16x32_bf16 v[8:11], v[152:155], v[190:193], v[8:11]
	v_mfma_f32_16x16x32_bf16 v[4:7], v[144:147], v[198:201], v[4:7]
	v_mfma_f32_16x16x32_bf16 v[0:3], v[152:155], v[198:201], v[0:3]
	v_mfma_f32_16x16x32_bf16 v[52:55], v[148:151], v[164:167], v[52:55]
	v_mfma_f32_16x16x32_bf16 v[44:47], v[156:159], v[164:167], v[44:47]
	v_mfma_f32_16x16x32_bf16 v[36:39], v[148:151], v[172:175], v[36:39]
	v_mfma_f32_16x16x32_bf16 v[28:31], v[156:159], v[172:175], v[28:31]
	v_mfma_f32_16x16x32_bf16 v[16:19], v[148:151], v[194:197], v[16:19]
	v_mfma_f32_16x16x32_bf16 v[8:11], v[156:159], v[194:197], v[8:11]
	v_mfma_f32_16x16x32_bf16 v[4:7], v[148:151], v[216:219], v[4:7]
	v_mfma_f32_16x16x32_bf16 v[0:3], v[156:159], v[216:219], v[0:3]
	s_setprio 0
	s_barrier
	s_add_i32 s53, 0, 0x18000
	s_add_i32 s54, 0, 0x1c000
	v_add_u32_e32 v140, s53, v210
	v_add_u32_e32 v156, s54, v210
	ds_read_b128 v[128:131], v140
	ds_read_b128 v[132:135], v140 offset:1024
	ds_read_b128 v[136:139], v140 offset:2048
	ds_read_b128 v[140:143], v140 offset:3072
	ds_read_b128 v[144:147], v156
	ds_read_b128 v[148:151], v156 offset:1024
	ds_read_b128 v[152:155], v156 offset:2048
	ds_read_b128 v[156:159], v156 offset:3072
	s_add_u32 s20, s20, 0xb0000
	s_addc_u32 s21, s21, 0
	s_mov_b32 m0, s25
	v_lshl_add_u64 v[226:227], s[20:21], 0, v[176:177]
	ds_read_b128 v[160:163], v214 offset:32768
	ds_read_b128 v[164:167], v214 offset:33792
	ds_read_b128 v[168:171], v214 offset:34816
	ds_read_b128 v[172:175], v214 offset:35840
	ds_read_b128 v[190:193], v214 offset:36864
	ds_read_b128 v[194:197], v214 offset:37888
	ds_read_b128 v[198:201], v214 offset:38912
	ds_read_b128 v[216:219], v214 offset:39936
	global_load_lds_dwordx4 v[226:227], off
	v_lshl_add_u64 v[226:227], s[20:21], 0, v[178:179]
	s_mov_b32 m0, s26
	s_nop 0
	global_load_lds_dwordx4 v[226:227], off
	s_waitcnt vmcnt(8)
	s_waitcnt lgkmcnt(0)
	s_barrier
	s_setprio 1
	v_mfma_f32_16x16x32_bf16 v[124:127], v[128:131], v[160:163], v[124:127]
	v_mfma_f32_16x16x32_bf16 v[120:123], v[136:139], v[160:163], v[120:123]
	v_mfma_f32_16x16x32_bf16 v[112:115], v[128:131], v[168:171], v[112:115]
	v_mfma_f32_16x16x32_bf16 v[104:107], v[136:139], v[168:171], v[104:107]
	v_mfma_f32_16x16x32_bf16 v[96:99], v[128:131], v[190:193], v[96:99]
	v_mfma_f32_16x16x32_bf16 v[88:91], v[136:139], v[190:193], v[88:91]
	v_mfma_f32_16x16x32_bf16 v[84:87], v[128:131], v[198:201], v[84:87]
	v_mfma_f32_16x16x32_bf16 v[76:79], v[136:139], v[198:201], v[76:79]
	v_mfma_f32_16x16x32_bf16 v[124:127], v[132:135], v[164:167], v[124:127]
	v_mfma_f32_16x16x32_bf16 v[120:123], v[140:143], v[164:167], v[120:123]
	v_mfma_f32_16x16x32_bf16 v[112:115], v[132:135], v[172:175], v[112:115]
	v_mfma_f32_16x16x32_bf16 v[104:107], v[140:143], v[172:175], v[104:107]
	v_mfma_f32_16x16x32_bf16 v[96:99], v[132:135], v[194:197], v[96:99]
	v_mfma_f32_16x16x32_bf16 v[88:91], v[140:143], v[194:197], v[88:91]
	v_mfma_f32_16x16x32_bf16 v[84:87], v[132:135], v[216:219], v[84:87]
	v_mfma_f32_16x16x32_bf16 v[76:79], v[140:143], v[216:219], v[76:79]
	s_setprio 0
	s_setprio 1
	v_mfma_f32_16x16x32_bf16 v[116:119], v[144:147], v[160:163], v[116:119]
	v_mfma_f32_16x16x32_bf16 v[108:111], v[152:155], v[160:163], v[108:111]
	v_mfma_f32_16x16x32_bf16 v[100:103], v[144:147], v[168:171], v[100:103]
	v_mfma_f32_16x16x32_bf16 v[92:95], v[152:155], v[168:171], v[92:95]
	v_mfma_f32_16x16x32_bf16 v[80:83], v[144:147], v[190:193], v[80:83]
	v_mfma_f32_16x16x32_bf16 v[72:75], v[152:155], v[190:193], v[72:75]
	v_mfma_f32_16x16x32_bf16 v[68:71], v[144:147], v[198:201], v[68:71]
	v_mfma_f32_16x16x32_bf16 v[64:67], v[152:155], v[198:201], v[64:67]
	v_mfma_f32_16x16x32_bf16 v[116:119], v[148:151], v[164:167], v[116:119]
	v_mfma_f32_16x16x32_bf16 v[108:111], v[156:159], v[164:167], v[108:111]
	v_mfma_f32_16x16x32_bf16 v[100:103], v[148:151], v[172:175], v[100:103]
	v_mfma_f32_16x16x32_bf16 v[92:95], v[156:159], v[172:175], v[92:95]
	v_mfma_f32_16x16x32_bf16 v[80:83], v[148:151], v[194:197], v[80:83]
	v_mfma_f32_16x16x32_bf16 v[72:75], v[156:159], v[194:197], v[72:75]
	v_mfma_f32_16x16x32_bf16 v[68:71], v[148:151], v[216:219], v[68:71]
	v_mfma_f32_16x16x32_bf16 v[64:67], v[156:159], v[216:219], v[64:67]
	s_setprio 0
	s_barrier
	s_add_i32 s20, s53, s22
	v_lshl_add_u64 v[202:203], v[202:203], 0, s[10:11]
	s_mov_b32 m0, s20
	ds_read_b128 v[160:163], v214 offset:49152
	ds_read_b128 v[164:167], v214 offset:50176
	ds_read_b128 v[168:171], v214 offset:51200
	ds_read_b128 v[172:175], v214 offset:52224
	ds_read_b128 v[190:193], v214 offset:53248
	ds_read_b128 v[194:197], v214 offset:54272
	ds_read_b128 v[198:201], v214 offset:55296
	ds_read_b128 v[216:219], v214 offset:56320
	global_load_lds_dwordx4 v[202:203], off
	s_add_i32 m0, s20, 0x2000
	s_add_u32 s18, s18, 0xb0080
	v_lshl_add_u64 v[202:203], v[220:221], 0, s[10:11]
	s_addc_u32 s19, s19, 0
	s_add_i32 s20, s54, s22
	global_load_lds_dwordx4 v[202:203], off
	v_lshl_add_u64 v[202:203], s[18:19], 0, v[176:177]
	s_mov_b32 m0, s20
	s_nop 0
	global_load_lds_dwordx4 v[202:203], off
	v_lshl_add_u64 v[202:203], s[18:19], 0, v[178:179]
	s_add_i32 m0, s20, 0x2000
	s_nop 0
	global_load_lds_dwordx4 v[202:203], off
	v_lshl_add_u64 v[202:203], v[222:223], 0, s[10:11]
	s_mov_b32 m0, s29
	s_nop 0
	global_load_lds_dwordx4 v[202:203], off
	v_lshl_add_u64 v[202:203], v[224:225], 0, s[10:11]
	s_mov_b32 m0, s30
	s_nop 0
	global_load_lds_dwordx4 v[202:203], off
	s_waitcnt vmcnt(8)
	s_waitcnt lgkmcnt(0)
	s_barrier
	s_setprio 1
	v_mfma_f32_16x16x32_bf16 v[60:63], v[128:131], v[160:163], v[60:63]
	v_mfma_f32_16x16x32_bf16 v[56:59], v[136:139], v[160:163], v[56:59]
	v_mfma_f32_16x16x32_bf16 v[48:51], v[128:131], v[168:171], v[48:51]
	v_mfma_f32_16x16x32_bf16 v[40:43], v[136:139], v[168:171], v[40:43]
	v_mfma_f32_16x16x32_bf16 v[32:35], v[128:131], v[190:193], v[32:35]
	v_mfma_f32_16x16x32_bf16 v[24:27], v[136:139], v[190:193], v[24:27]
	v_mfma_f32_16x16x32_bf16 v[20:23], v[128:131], v[198:201], v[20:23]
	v_mfma_f32_16x16x32_bf16 v[12:15], v[136:139], v[198:201], v[12:15]
	v_mfma_f32_16x16x32_bf16 v[60:63], v[132:135], v[164:167], v[60:63]
	v_mfma_f32_16x16x32_bf16 v[56:59], v[140:143], v[164:167], v[56:59]
	v_mfma_f32_16x16x32_bf16 v[48:51], v[132:135], v[172:175], v[48:51]
	v_mfma_f32_16x16x32_bf16 v[40:43], v[140:143], v[172:175], v[40:43]
	v_mfma_f32_16x16x32_bf16 v[32:35], v[132:135], v[194:197], v[32:35]
	v_mfma_f32_16x16x32_bf16 v[24:27], v[140:143], v[194:197], v[24:27]
	v_mfma_f32_16x16x32_bf16 v[20:23], v[132:135], v[216:219], v[20:23]
	v_mfma_f32_16x16x32_bf16 v[12:15], v[140:143], v[216:219], v[12:15]
	s_setprio 0
	s_setprio 1
	v_mfma_f32_16x16x32_bf16 v[52:55], v[144:147], v[160:163], v[52:55]
	v_mfma_f32_16x16x32_bf16 v[44:47], v[152:155], v[160:163], v[44:47]
	v_mfma_f32_16x16x32_bf16 v[36:39], v[144:147], v[168:171], v[36:39]
	v_mfma_f32_16x16x32_bf16 v[28:31], v[152:155], v[168:171], v[28:31]
	v_mfma_f32_16x16x32_bf16 v[16:19], v[144:147], v[190:193], v[16:19]
	v_mfma_f32_16x16x32_bf16 v[8:11], v[152:155], v[190:193], v[8:11]
	v_mfma_f32_16x16x32_bf16 v[4:7], v[144:147], v[198:201], v[4:7]
	v_mfma_f32_16x16x32_bf16 v[0:3], v[152:155], v[198:201], v[0:3]
	v_mfma_f32_16x16x32_bf16 v[52:55], v[148:151], v[164:167], v[52:55]
	v_mfma_f32_16x16x32_bf16 v[44:47], v[156:159], v[164:167], v[44:47]
	v_mfma_f32_16x16x32_bf16 v[36:39], v[148:151], v[172:175], v[36:39]
	v_mfma_f32_16x16x32_bf16 v[28:31], v[156:159], v[172:175], v[28:31]
	v_mfma_f32_16x16x32_bf16 v[16:19], v[148:151], v[194:197], v[16:19]
	v_mfma_f32_16x16x32_bf16 v[8:11], v[156:159], v[194:197], v[8:11]
	v_mfma_f32_16x16x32_bf16 v[4:7], v[148:151], v[216:219], v[4:7]
	v_mfma_f32_16x16x32_bf16 v[0:3], v[156:159], v[216:219], v[0:3]
	s_setprio 0
	s_barrier
	s_add_i32 s52, s52, 2
	s_add_u32 s16, s16, 0x100
	s_addc_u32 s17, s17, 0
	s_add_u32 s50, s50, 0x100
	s_addc_u32 s51, s51, 0
	s_cmp_gt_u32 s52, 41
	s_cbranch_scc0 .LBB0_1324
	s_and_b64 vcc, exec, s[12:13]
	s_cbranch_vccz .LBB0_1327
	s_barrier

.Llsb_skip_11:
.LBB0_1352:
	s_add_u32 s25, s14, s24
	s_addc_u32 s30, s15, 0
	s_add_u32 s28, s25, 0x100
	s_addc_u32 s29, s30, 0
	s_and_b64 s[26:27], s[22:23], exec
	s_cselect_b32 s27, s17, s29
	s_cselect_b32 s26, s16, s28
	s_add_u32 s24, s12, s24
	s_addc_u32 s28, s13, 0
	s_add_u32 s24, s24, 0x100
	s_addc_u32 s28, s28, 0
	ds_read_b128 v[136:139], v131
	ds_read_b128 v[140:143], v131 offset:1024
	ds_read_b128 v[144:147], v131 offset:2048
	ds_read_b128 v[148:151], v131 offset:3072
	ds_read_b128 v[152:155], v132
	ds_read_b128 v[156:159], v132 offset:1024
	ds_read_b128 v[160:163], v132 offset:2048
	ds_read_b128 v[164:167], v132 offset:3072
	s_and_b64 s[22:23], s[22:23], exec
	s_cselect_b32 s29, s19, s28
	s_cselect_b32 s28, s18, s24
	s_add_u32 s34, s25, 0xb0080
	s_addc_u32 s35, s30, 0
	s_add_u32 s30, s28, 0xb0000
	s_addc_u32 s31, s29, 0
	s_add_i32 s66, 0, 0x1c000
	s_add_u32 s24, s26, 0xb0000
	s_addc_u32 s25, s27, 0
	s_add_i32 s65, s58, s41
	s_add_i32 s63, s65, 0x2000
	s_add_u32 s22, s28, 0xb0080
	s_addc_u32 s23, s29, 0
	s_add_i32 s64, s66, s41
	s_add_i32 s62, s64, 0x2000
	s_mov_b32 m0, s52
	v_lshl_add_u64 v[206:207], s[34:35], 0, v[176:177]
	ds_read_b128 v[168:171], v133
	ds_read_b128 v[172:175], v133 offset:1024
	ds_read_b128 v[180:183], v133 offset:2048
	ds_read_b128 v[184:187], v133 offset:3072
	ds_read_b128 v[188:191], v133 offset:4096
	ds_read_b128 v[192:195], v133 offset:5120
	ds_read_b128 v[196:199], v133 offset:6144
	ds_read_b128 v[200:203], v133 offset:7168
	global_load_lds_dwordx4 v[206:207], off
	v_lshl_add_u64 v[206:207], s[34:35], 0, v[178:179]
	s_mov_b32 m0, s53
	s_nop 0
	global_load_lds_dwordx4 v[206:207], off
	s_waitcnt vmcnt(8)
	s_waitcnt lgkmcnt(0)
	s_barrier
	s_setprio 1
	v_mfma_f32_16x16x32_bf16 v[124:127], v[136:139], v[168:171], v[124:127]
	v_mfma_f32_16x16x32_bf16 v[120:123], v[144:147], v[168:171], v[120:123]
	v_mfma_f32_16x16x32_bf16 v[116:119], v[136:139], v[180:183], v[116:119]
	v_mfma_f32_16x16x32_bf16 v[112:115], v[144:147], v[180:183], v[112:115]
	v_mfma_f32_16x16x32_bf16 v[108:111], v[136:139], v[188:191], v[108:111]
	v_mfma_f32_16x16x32_bf16 v[100:103], v[144:147], v[188:191], v[100:103]
	v_mfma_f32_16x16x32_bf16 v[92:95], v[136:139], v[196:199], v[92:95]
	v_mfma_f32_16x16x32_bf16 v[84:87], v[144:147], v[196:199], v[84:87]
	v_mfma_f32_16x16x32_bf16 v[124:127], v[140:143], v[172:175], v[124:127]
	v_mfma_f32_16x16x32_bf16 v[120:123], v[148:151], v[172:175], v[120:123]
	v_mfma_f32_16x16x32_bf16 v[116:119], v[140:143], v[184:187], v[116:119]
	v_mfma_f32_16x16x32_bf16 v[112:115], v[148:151], v[184:187], v[112:115]
	v_mfma_f32_16x16x32_bf16 v[108:111], v[140:143], v[192:195], v[108:111]
	v_mfma_f32_16x16x32_bf16 v[100:103], v[148:151], v[192:195], v[100:103]
	v_mfma_f32_16x16x32_bf16 v[92:95], v[140:143], v[200:203], v[92:95]
	v_mfma_f32_16x16x32_bf16 v[84:87], v[148:151], v[200:203], v[84:87]
	s_setprio 0
	s_setprio 1
	v_mfma_f32_16x16x32_bf16 v[104:107], v[152:155], v[168:171], v[104:107]
	v_mfma_f32_16x16x32_bf16 v[96:99], v[160:163], v[168:171], v[96:99]
	v_mfma_f32_16x16x32_bf16 v[88:91], v[152:155], v[180:183], v[88:91]
	v_mfma_f32_16x16x32_bf16 v[80:83], v[160:163], v[180:183], v[80:83]
	v_mfma_f32_16x16x32_bf16 v[76:79], v[152:155], v[188:191], v[76:79]
	v_mfma_f32_16x16x32_bf16 v[72:75], v[160:163], v[188:191], v[72:75]
	v_mfma_f32_16x16x32_bf16 v[68:71], v[152:155], v[196:199], v[68:71]
	v_mfma_f32_16x16x32_bf16 v[64:67], v[160:163], v[196:199], v[64:67]
	v_mfma_f32_16x16x32_bf16 v[104:107], v[156:159], v[172:175], v[104:107]
	v_mfma_f32_16x16x32_bf16 v[96:99], v[164:167], v[172:175], v[96:99]
	v_mfma_f32_16x16x32_bf16 v[88:91], v[156:159], v[184:187], v[88:91]
	v_mfma_f32_16x16x32_bf16 v[80:83], v[164:167], v[184:187], v[80:83]
	v_mfma_f32_16x16x32_bf16 v[76:79], v[156:159], v[192:195], v[76:79]
	v_mfma_f32_16x16x32_bf16 v[72:75], v[164:167], v[192:195], v[72:75]
	v_mfma_f32_16x16x32_bf16 v[68:71], v[156:159], v[200:203], v[68:71]
	v_mfma_f32_16x16x32_bf16 v[64:67], v[164:167], v[200:203], v[64:67]
	s_setprio 0
	s_barrier
	s_mov_b32 m0, s54
	v_lshl_add_u64 v[206:207], s[28:29], 0, v[176:177]
	ds_read_b128 v[168:171], v133 offset:16384
	ds_read_b128 v[172:175], v133 offset:17408
	ds_read_b128 v[180:183], v133 offset:18432
	ds_read_b128 v[184:187], v133 offset:19456
	ds_read_b128 v[188:191], v133 offset:20480
	ds_read_b128 v[192:195], v133 offset:21504
	ds_read_b128 v[196:199], v133 offset:22528
	ds_read_b128 v[200:203], v133 offset:23552
	global_load_lds_dwordx4 v[206:207], off
	v_lshl_add_u64 v[208:209], s[28:29], 0, v[178:179]
	s_mov_b32 m0, s55
	v_lshl_add_u64 v[210:211], s[30:31], 0, v[176:177]
	global_load_lds_dwordx4 v[208:209], off
	s_mov_b32 m0, s56
	v_lshl_add_u64 v[212:213], s[26:27], 0, v[178:179]
	global_load_lds_dwordx4 v[210:211], off
	v_lshl_add_u64 v[210:211], s[30:31], 0, v[178:179]
	s_mov_b32 m0, s57
	s_nop 0
	global_load_lds_dwordx4 v[210:211], off
	v_lshl_add_u64 v[210:211], s[26:27], 0, v[176:177]
	s_mov_b32 m0, s42
	s_nop 0
	global_load_lds_dwordx4 v[210:211], off
	s_mov_b32 m0, s43
	s_nop 0
	global_load_lds_dwordx4 v[212:213], off
	s_waitcnt vmcnt(8)
	s_waitcnt lgkmcnt(0)
	s_barrier
	s_setprio 1
	v_mfma_f32_16x16x32_bf16 v[60:63], v[136:139], v[168:171], v[60:63]
	v_mfma_f32_16x16x32_bf16 v[56:59], v[144:147], v[168:171], v[56:59]
	v_mfma_f32_16x16x32_bf16 v[52:55], v[136:139], v[180:183], v[52:55]
	v_mfma_f32_16x16x32_bf16 v[48:51], v[144:147], v[180:183], v[48:51]
	v_mfma_f32_16x16x32_bf16 v[40:43], v[136:139], v[188:191], v[40:43]
	v_mfma_f32_16x16x32_bf16 v[32:35], v[144:147], v[188:191], v[32:35]
	v_mfma_f32_16x16x32_bf16 v[24:27], v[136:139], v[196:199], v[24:27]
	v_mfma_f32_16x16x32_bf16 v[16:19], v[144:147], v[196:199], v[16:19]
	v_mfma_f32_16x16x32_bf16 v[60:63], v[140:143], v[172:175], v[60:63]
	v_mfma_f32_16x16x32_bf16 v[56:59], v[148:151], v[172:175], v[56:59]
	v_mfma_f32_16x16x32_bf16 v[52:55], v[140:143], v[184:187], v[52:55]
	v_mfma_f32_16x16x32_bf16 v[48:51], v[148:151], v[184:187], v[48:51]
	v_mfma_f32_16x16x32_bf16 v[40:43], v[140:143], v[192:195], v[40:43]
	v_mfma_f32_16x16x32_bf16 v[32:35], v[148:151], v[192:195], v[32:35]
	v_mfma_f32_16x16x32_bf16 v[24:27], v[140:143], v[200:203], v[24:27]
	v_mfma_f32_16x16x32_bf16 v[16:19], v[148:151], v[200:203], v[16:19]
	s_setprio 0
	s_setprio 1
	v_mfma_f32_16x16x32_bf16 v[44:47], v[152:155], v[168:171], v[44:47]
	v_mfma_f32_16x16x32_bf16 v[36:39], v[160:163], v[168:171], v[36:39]
	v_mfma_f32_16x16x32_bf16 v[28:31], v[152:155], v[180:183], v[28:31]
	v_mfma_f32_16x16x32_bf16 v[20:23], v[160:163], v[180:183], v[20:23]
	v_mfma_f32_16x16x32_bf16 v[12:15], v[152:155], v[188:191], v[12:15]
	v_mfma_f32_16x16x32_bf16 v[8:11], v[160:163], v[188:191], v[8:11]
	v_mfma_f32_16x16x32_bf16 v[4:7], v[152:155], v[196:199], v[4:7]
	v_mfma_f32_16x16x32_bf16 v[0:3], v[160:163], v[196:199], v[0:3]
	v_mfma_f32_16x16x32_bf16 v[44:47], v[156:159], v[172:175], v[44:47]
	v_mfma_f32_16x16x32_bf16 v[36:39], v[164:167], v[172:175], v[36:39]
	v_mfma_f32_16x16x32_bf16 v[28:31], v[156:159], v[184:187], v[28:31]
	v_mfma_f32_16x16x32_bf16 v[20:23], v[164:167], v[184:187], v[20:23]
	v_mfma_f32_16x16x32_bf16 v[12:15], v[156:159], v[192:195], v[12:15]
	v_mfma_f32_16x16x32_bf16 v[8:11], v[164:167], v[192:195], v[8:11]
	v_mfma_f32_16x16x32_bf16 v[4:7], v[156:159], v[200:203], v[4:7]
	v_mfma_f32_16x16x32_bf16 v[0:3], v[164:167], v[200:203], v[0:3]
	s_setprio 0
	s_barrier
	v_add_u32_e32 v135, s66, v128
	ds_read_b128 v[136:139], v134
	ds_read_b128 v[140:143], v134 offset:1024
	ds_read_b128 v[144:147], v134 offset:2048
	ds_read_b128 v[148:151], v134 offset:3072
	ds_read_b128 v[152:155], v135
	ds_read_b128 v[156:159], v135 offset:1024
	ds_read_b128 v[160:163], v135 offset:2048
	ds_read_b128 v[164:167], v135 offset:3072
	s_mov_b32 m0, s44
	v_lshl_add_u64 v[214:215], s[24:25], 0, v[176:177]
	ds_read_b128 v[168:171], v133 offset:32768
	ds_read_b128 v[172:175], v133 offset:33792
	ds_read_b128 v[180:183], v133 offset:34816
	ds_read_b128 v[184:187], v133 offset:35840
	ds_read_b128 v[188:191], v133 offset:36864
	ds_read_b128 v[192:195], v133 offset:37888
	ds_read_b128 v[196:199], v133 offset:38912
	ds_read_b128 v[200:203], v133 offset:39936
	global_load_lds_dwordx4 v[214:215], off
	v_lshl_add_u64 v[214:215], s[24:25], 0, v[178:179]
	s_mov_b32 m0, s45
	s_nop 0
	global_load_lds_dwordx4 v[214:215], off
	s_waitcnt vmcnt(8)
	s_waitcnt lgkmcnt(0)
	s_barrier
	s_setprio 1
	v_mfma_f32_16x16x32_bf16 v[124:127], v[136:139], v[168:171], v[124:127]
	v_mfma_f32_16x16x32_bf16 v[120:123], v[144:147], v[168:171], v[120:123]
	v_mfma_f32_16x16x32_bf16 v[116:119], v[136:139], v[180:183], v[116:119]
	v_mfma_f32_16x16x32_bf16 v[112:115], v[144:147], v[180:183], v[112:115]
	v_mfma_f32_16x16x32_bf16 v[108:111], v[136:139], v[188:191], v[108:111]
	v_mfma_f32_16x16x32_bf16 v[100:103], v[144:147], v[188:191], v[100:103]
	v_mfma_f32_16x16x32_bf16 v[92:95], v[136:139], v[196:199], v[92:95]
	v_mfma_f32_16x16x32_bf16 v[84:87], v[144:147], v[196:199], v[84:87]
	v_mfma_f32_16x16x32_bf16 v[124:127], v[140:143], v[172:175], v[124:127]
	v_mfma_f32_16x16x32_bf16 v[120:123], v[148:151], v[172:175], v[120:123]
	v_mfma_f32_16x16x32_bf16 v[116:119], v[140:143], v[184:187], v[116:119]
	v_mfma_f32_16x16x32_bf16 v[112:115], v[148:151], v[184:187], v[112:115]
	v_mfma_f32_16x16x32_bf16 v[108:111], v[140:143], v[192:195], v[108:111]
	v_mfma_f32_16x16x32_bf16 v[100:103], v[148:151], v[192:195], v[100:103]
	v_mfma_f32_16x16x32_bf16 v[92:95], v[140:143], v[200:203], v[92:95]
	v_mfma_f32_16x16x32_bf16 v[84:87], v[148:151], v[200:203], v[84:87]
	s_setprio 0
	s_setprio 1
	v_mfma_f32_16x16x32_bf16 v[104:107], v[152:155], v[168:171], v[104:107]
	v_mfma_f32_16x16x32_bf16 v[96:99], v[160:163], v[168:171], v[96:99]
	v_mfma_f32_16x16x32_bf16 v[88:91], v[152:155], v[180:183], v[88:91]
	v_mfma_f32_16x16x32_bf16 v[80:83], v[160:163], v[180:183], v[80:83]
	v_mfma_f32_16x16x32_bf16 v[76:79], v[152:155], v[188:191], v[76:79]
	v_mfma_f32_16x16x32_bf16 v[72:75], v[160:163], v[188:191], v[72:75]
	v_mfma_f32_16x16x32_bf16 v[68:71], v[152:155], v[196:199], v[68:71]
	v_mfma_f32_16x16x32_bf16 v[64:67], v[160:163], v[196:199], v[64:67]
	v_mfma_f32_16x16x32_bf16 v[104:107], v[156:159], v[172:175], v[104:107]
	v_mfma_f32_16x16x32_bf16 v[96:99], v[164:167], v[172:175], v[96:99]
	v_mfma_f32_16x16x32_bf16 v[88:91], v[156:159], v[184:187], v[88:91]
	v_mfma_f32_16x16x32_bf16 v[80:83], v[164:167], v[184:187], v[80:83]
	v_mfma_f32_16x16x32_bf16 v[76:79], v[156:159], v[192:195], v[76:79]
	v_mfma_f32_16x16x32_bf16 v[72:75], v[164:167], v[192:195], v[72:75]
	v_mfma_f32_16x16x32_bf16 v[68:71], v[156:159], v[200:203], v[68:71]
	v_mfma_f32_16x16x32_bf16 v[64:67], v[164:167], v[200:203], v[64:67]
	s_setprio 0
	s_barrier
	s_mov_b32 m0, s65
	v_lshl_add_u64 v[206:207], v[206:207], 0, s[8:9]
	ds_read_b128 v[168:171], v133 offset:49152
	ds_read_b128 v[172:175], v133 offset:50176
	ds_read_b128 v[180:183], v133 offset:51200
	ds_read_b128 v[184:187], v133 offset:52224
	ds_read_b128 v[188:191], v133 offset:53248
	ds_read_b128 v[192:195], v133 offset:54272
	ds_read_b128 v[196:199], v133 offset:55296
	ds_read_b128 v[200:203], v133 offset:56320
	global_load_lds_dwordx4 v[206:207], off
	v_lshl_add_u64 v[206:207], v[208:209], 0, s[8:9]
	s_mov_b32 m0, s63
	s_nop 0
	global_load_lds_dwordx4 v[206:207], off
	v_lshl_add_u64 v[206:207], s[22:23], 0, v[176:177]
	s_mov_b32 m0, s64
	s_nop 0
	global_load_lds_dwordx4 v[206:207], off
	v_lshl_add_u64 v[206:207], s[22:23], 0, v[178:179]
	s_mov_b32 m0, s62
	s_nop 0
	global_load_lds_dwordx4 v[206:207], off
	v_lshl_add_u64 v[206:207], v[210:211], 0, s[8:9]
	s_mov_b32 m0, s47
	s_nop 0
	global_load_lds_dwordx4 v[206:207], off
	v_lshl_add_u64 v[206:207], v[212:213], 0, s[8:9]
	s_mov_b32 m0, s48
	s_nop 0
	global_load_lds_dwordx4 v[206:207], off
	s_waitcnt vmcnt(8)
	s_waitcnt lgkmcnt(0)
	s_barrier
	s_setprio 1
	v_mfma_f32_16x16x32_bf16 v[60:63], v[136:139], v[168:171], v[60:63]
	v_mfma_f32_16x16x32_bf16 v[56:59], v[144:147], v[168:171], v[56:59]
	v_mfma_f32_16x16x32_bf16 v[52:55], v[136:139], v[180:183], v[52:55]
	v_mfma_f32_16x16x32_bf16 v[48:51], v[144:147], v[180:183], v[48:51]
	v_mfma_f32_16x16x32_bf16 v[40:43], v[136:139], v[188:191], v[40:43]
	v_mfma_f32_16x16x32_bf16 v[32:35], v[144:147], v[188:191], v[32:35]
	v_mfma_f32_16x16x32_bf16 v[24:27], v[136:139], v[196:199], v[24:27]
	v_mfma_f32_16x16x32_bf16 v[16:19], v[144:147], v[196:199], v[16:19]
	v_mfma_f32_16x16x32_bf16 v[60:63], v[140:143], v[172:175], v[60:63]
	v_mfma_f32_16x16x32_bf16 v[56:59], v[148:151], v[172:175], v[56:59]
	v_mfma_f32_16x16x32_bf16 v[52:55], v[140:143], v[184:187], v[52:55]
	v_mfma_f32_16x16x32_bf16 v[48:51], v[148:151], v[184:187], v[48:51]
	v_mfma_f32_16x16x32_bf16 v[40:43], v[140:143], v[192:195], v[40:43]
	v_mfma_f32_16x16x32_bf16 v[32:35], v[148:151], v[192:195], v[32:35]
	v_mfma_f32_16x16x32_bf16 v[24:27], v[140:143], v[200:203], v[24:27]
	v_mfma_f32_16x16x32_bf16 v[16:19], v[148:151], v[200:203], v[16:19]
	s_setprio 0
	s_setprio 1
	v_mfma_f32_16x16x32_bf16 v[44:47], v[152:155], v[168:171], v[44:47]
	v_mfma_f32_16x16x32_bf16 v[36:39], v[160:163], v[168:171], v[36:39]
	v_mfma_f32_16x16x32_bf16 v[28:31], v[152:155], v[180:183], v[28:31]
	v_mfma_f32_16x16x32_bf16 v[20:23], v[160:163], v[180:183], v[20:23]
	v_mfma_f32_16x16x32_bf16 v[12:15], v[152:155], v[188:191], v[12:15]
	v_mfma_f32_16x16x32_bf16 v[8:11], v[160:163], v[188:191], v[8:11]
	v_mfma_f32_16x16x32_bf16 v[4:7], v[152:155], v[196:199], v[4:7]
	v_mfma_f32_16x16x32_bf16 v[0:3], v[160:163], v[196:199], v[0:3]
	v_mfma_f32_16x16x32_bf16 v[44:47], v[156:159], v[172:175], v[44:47]
	v_mfma_f32_16x16x32_bf16 v[36:39], v[164:167], v[172:175], v[36:39]
	v_mfma_f32_16x16x32_bf16 v[28:31], v[156:159], v[184:187], v[28:31]
	v_mfma_f32_16x16x32_bf16 v[20:23], v[164:167], v[184:187], v[20:23]
	v_mfma_f32_16x16x32_bf16 v[12:15], v[156:159], v[192:195], v[12:15]
	v_mfma_f32_16x16x32_bf16 v[8:11], v[164:167], v[192:195], v[8:11]
	v_mfma_f32_16x16x32_bf16 v[4:7], v[156:159], v[200:203], v[4:7]
	v_mfma_f32_16x16x32_bf16 v[0:3], v[164:167], v[200:203], v[0:3]
	s_setprio 0
	s_barrier
	s_movk_i32 s24, 0x100
	s_andn2_b64 vcc, exec, s[20:21]
	s_mov_b64 s[22:23], -1
	s_mov_b64 s[20:21], 0
	s_cbranch_vccz .LBB0_1352
	s_and_b64 vcc, exec, s[10:11]
	s_cbranch_vccz .LBB0_1355
	s_barrier

.Llsb_skip_13:
.LBB0_1639:
	ds_read_b128 v[142:145], v135
	ds_read_b128 v[146:149], v135 offset:1024
	ds_read_b128 v[150:153], v135 offset:2048
	ds_read_b128 v[154:157], v135 offset:3072
	ds_read_b128 v[158:161], v140
	ds_read_b128 v[162:165], v140 offset:1024
	ds_read_b128 v[166:169], v140 offset:2048
	ds_read_b128 v[170:173], v140 offset:3072
	s_add_u32 s30, s28, 0xfffc0080
	s_addc_u32 s31, s29, -1
	s_cmp_eq_u32 s60, 12
	s_cselect_b32 s35, s23, s31
	s_cselect_b32 s34, s56, s30
	s_cselect_b32 s31, s21, s59
	s_cselect_b32 s30, s57, s58
	v_lshl_add_u64 v[202:203], s[28:29], 0, v[128:129]
	s_add_i32 m0, s43, 0xc000
	ds_read_b128 v[174:177], v141
	ds_read_b128 v[178:181], v141 offset:1024
	ds_read_b128 v[182:185], v141 offset:2048
	ds_read_b128 v[186:189], v141 offset:3072
	ds_read_b128 v[190:193], v141 offset:4096
	ds_read_b128 v[194:197], v141 offset:5120
	ds_read_b128 v[198:201], v141 offset:6144
	ds_read_b128 v[206:209], v141 offset:7168
	global_load_lds_dwordx4 v[202:203], off
	v_lshl_add_u64 v[202:203], s[28:29], 0, v[130:131]
	s_add_i32 m0, s43, 0xe000
	s_nop 0
	global_load_lds_dwordx4 v[202:203], off
	s_waitcnt vmcnt(8)
	s_waitcnt lgkmcnt(0)
	s_barrier
	s_setprio 1
	v_mfma_f32_16x16x32_bf16 v[124:127], v[142:145], v[174:177], v[124:127]
	v_mfma_f32_16x16x32_bf16 v[120:123], v[150:153], v[174:177], v[120:123]
	v_mfma_f32_16x16x32_bf16 v[116:119], v[142:145], v[182:185], v[116:119]
	v_mfma_f32_16x16x32_bf16 v[112:115], v[150:153], v[182:185], v[112:115]
	v_mfma_f32_16x16x32_bf16 v[104:107], v[142:145], v[190:193], v[104:107]
	v_mfma_f32_16x16x32_bf16 v[96:99], v[150:153], v[190:193], v[96:99]
	v_mfma_f32_16x16x32_bf16 v[88:91], v[142:145], v[198:201], v[88:91]
	v_mfma_f32_16x16x32_bf16 v[80:83], v[150:153], v[198:201], v[80:83]
	v_mfma_f32_16x16x32_bf16 v[124:127], v[146:149], v[178:181], v[124:127]
	v_mfma_f32_16x16x32_bf16 v[120:123], v[154:157], v[178:181], v[120:123]
	v_mfma_f32_16x16x32_bf16 v[116:119], v[146:149], v[186:189], v[116:119]
	v_mfma_f32_16x16x32_bf16 v[112:115], v[154:157], v[186:189], v[112:115]
	v_mfma_f32_16x16x32_bf16 v[104:107], v[146:149], v[194:197], v[104:107]
	v_mfma_f32_16x16x32_bf16 v[96:99], v[154:157], v[194:197], v[96:99]
	v_mfma_f32_16x16x32_bf16 v[88:91], v[146:149], v[206:209], v[88:91]
	v_mfma_f32_16x16x32_bf16 v[80:83], v[154:157], v[206:209], v[80:83]
	s_setprio 0
	s_setprio 1
	v_mfma_f32_16x16x32_bf16 v[108:111], v[158:161], v[174:177], v[108:111]
	v_mfma_f32_16x16x32_bf16 v[100:103], v[166:169], v[174:177], v[100:103]
	v_mfma_f32_16x16x32_bf16 v[92:95], v[158:161], v[182:185], v[92:95]
	v_mfma_f32_16x16x32_bf16 v[84:87], v[166:169], v[182:185], v[84:87]
	v_mfma_f32_16x16x32_bf16 v[76:79], v[158:161], v[190:193], v[76:79]
	v_mfma_f32_16x16x32_bf16 v[72:75], v[166:169], v[190:193], v[72:75]
	v_mfma_f32_16x16x32_bf16 v[68:71], v[158:161], v[198:201], v[68:71]
	v_mfma_f32_16x16x32_bf16 v[64:67], v[166:169], v[198:201], v[64:67]
	v_mfma_f32_16x16x32_bf16 v[108:111], v[162:165], v[178:181], v[108:111]
	v_mfma_f32_16x16x32_bf16 v[100:103], v[170:173], v[178:181], v[100:103]
	v_mfma_f32_16x16x32_bf16 v[92:95], v[162:165], v[186:189], v[92:95]
	v_mfma_f32_16x16x32_bf16 v[84:87], v[170:173], v[186:189], v[84:87]
	v_mfma_f32_16x16x32_bf16 v[76:79], v[162:165], v[194:197], v[76:79]
	v_mfma_f32_16x16x32_bf16 v[72:75], v[170:173], v[194:197], v[72:75]
	v_mfma_f32_16x16x32_bf16 v[68:71], v[162:165], v[206:209], v[68:71]
	v_mfma_f32_16x16x32_bf16 v[64:67], v[170:173], v[206:209], v[64:67]
	s_setprio 0
	s_barrier
	s_add_i32 s61, s51, s40
	v_lshl_add_u64 v[202:203], s[30:31], 0, v[136:137]
	s_mov_b32 m0, s61
	ds_read_b128 v[174:177], v141 offset:16384
	ds_read_b128 v[178:181], v141 offset:17408
	ds_read_b128 v[182:185], v141 offset:18432
	ds_read_b128 v[186:189], v141 offset:19456
	ds_read_b128 v[190:193], v141 offset:20480
	ds_read_b128 v[194:197], v141 offset:21504
	ds_read_b128 v[198:201], v141 offset:22528
	ds_read_b128 v[206:209], v141 offset:23552
	global_load_lds_dwordx4 v[202:203], off
	s_add_i32 m0, s61, 0x2000
	s_add_u32 s62, s30, 0x40000
	v_lshl_add_u64 v[210:211], s[30:31], 0, v[138:139]
	s_addc_u32 s63, s31, 0
	s_add_i32 s61, s52, s40
	global_load_lds_dwordx4 v[210:211], off
	v_lshl_add_u64 v[212:213], s[62:63], 0, v[136:137]
	s_mov_b32 m0, s61
	v_lshl_add_u64 v[214:215], s[34:35], 0, v[138:139]
	global_load_lds_dwordx4 v[212:213], off
	v_lshl_add_u64 v[212:213], s[62:63], 0, v[138:139]
	s_add_i32 m0, s61, 0x2000
	s_nop 0
	global_load_lds_dwordx4 v[212:213], off
	v_lshl_add_u64 v[212:213], s[34:35], 0, v[136:137]
	s_mov_b32 m0, s43
	s_nop 0
	global_load_lds_dwordx4 v[212:213], off
	s_mov_b32 m0, s44
	s_nop 0
	global_load_lds_dwordx4 v[214:215], off
	s_waitcnt vmcnt(8)
	s_waitcnt lgkmcnt(0)
	s_barrier
	s_setprio 1
	v_mfma_f32_16x16x32_bf16 v[60:63], v[142:145], v[174:177], v[60:63]
	v_mfma_f32_16x16x32_bf16 v[56:59], v[150:153], v[174:177], v[56:59]
	v_mfma_f32_16x16x32_bf16 v[52:55], v[142:145], v[182:185], v[52:55]
	v_mfma_f32_16x16x32_bf16 v[48:51], v[150:153], v[182:185], v[48:51]
	v_mfma_f32_16x16x32_bf16 v[40:43], v[142:145], v[190:193], v[40:43]
	v_mfma_f32_16x16x32_bf16 v[32:35], v[150:153], v[190:193], v[32:35]
	v_mfma_f32_16x16x32_bf16 v[24:27], v[142:145], v[198:201], v[24:27]
	v_mfma_f32_16x16x32_bf16 v[16:19], v[150:153], v[198:201], v[16:19]
	v_mfma_f32_16x16x32_bf16 v[60:63], v[146:149], v[178:181], v[60:63]
	v_mfma_f32_16x16x32_bf16 v[56:59], v[154:157], v[178:181], v[56:59]
	v_mfma_f32_16x16x32_bf16 v[52:55], v[146:149], v[186:189], v[52:55]
	v_mfma_f32_16x16x32_bf16 v[48:51], v[154:157], v[186:189], v[48:51]
	v_mfma_f32_16x16x32_bf16 v[40:43], v[146:149], v[194:197], v[40:43]
	v_mfma_f32_16x16x32_bf16 v[32:35], v[154:157], v[194:197], v[32:35]
	v_mfma_f32_16x16x32_bf16 v[24:27], v[146:149], v[206:209], v[24:27]
	v_mfma_f32_16x16x32_bf16 v[16:19], v[154:157], v[206:209], v[16:19]
	s_setprio 0
	s_setprio 1
	v_mfma_f32_16x16x32_bf16 v[44:47], v[158:161], v[174:177], v[44:47]
	v_mfma_f32_16x16x32_bf16 v[36:39], v[166:169], v[174:177], v[36:39]
	v_mfma_f32_16x16x32_bf16 v[28:31], v[158:161], v[182:185], v[28:31]
	v_mfma_f32_16x16x32_bf16 v[20:23], v[166:169], v[182:185], v[20:23]
	v_mfma_f32_16x16x32_bf16 v[12:15], v[158:161], v[190:193], v[12:15]
	v_mfma_f32_16x16x32_bf16 v[8:11], v[166:169], v[190:193], v[8:11]
	v_mfma_f32_16x16x32_bf16 v[4:7], v[158:161], v[198:201], v[4:7]
	v_mfma_f32_16x16x32_bf16 v[0:3], v[166:169], v[198:201], v[0:3]
	v_mfma_f32_16x16x32_bf16 v[44:47], v[162:165], v[178:181], v[44:47]
	v_mfma_f32_16x16x32_bf16 v[36:39], v[170:173], v[178:181], v[36:39]
	v_mfma_f32_16x16x32_bf16 v[28:31], v[162:165], v[186:189], v[28:31]
	v_mfma_f32_16x16x32_bf16 v[20:23], v[170:173], v[186:189], v[20:23]
	v_mfma_f32_16x16x32_bf16 v[12:15], v[162:165], v[194:197], v[12:15]
	v_mfma_f32_16x16x32_bf16 v[8:11], v[170:173], v[194:197], v[8:11]
	v_mfma_f32_16x16x32_bf16 v[4:7], v[162:165], v[206:209], v[4:7]
	v_mfma_f32_16x16x32_bf16 v[0:3], v[170:173], v[206:209], v[0:3]
	s_setprio 0
	s_barrier
	s_add_i32 s61, 0, 0x18000
	s_add_i32 s62, 0, 0x1c000
	v_add_u32_e32 v154, s61, v133
	v_add_u32_e32 v170, s62, v133
	ds_read_b128 v[142:145], v154
	ds_read_b128 v[146:149], v154 offset:1024
	ds_read_b128 v[150:153], v154 offset:2048
	ds_read_b128 v[154:157], v154 offset:3072
	ds_read_b128 v[158:161], v170
	ds_read_b128 v[162:165], v170 offset:1024
	ds_read_b128 v[166:169], v170 offset:2048
	ds_read_b128 v[170:173], v170 offset:3072
	s_add_u32 s34, s34, 0x40000
	s_addc_u32 s35, s35, 0
	s_mov_b32 m0, s45
	v_lshl_add_u64 v[216:217], s[34:35], 0, v[136:137]
	ds_read_b128 v[174:177], v141 offset:32768
	ds_read_b128 v[178:181], v141 offset:33792
	ds_read_b128 v[182:185], v141 offset:34816
	ds_read_b128 v[186:189], v141 offset:35840
	ds_read_b128 v[190:193], v141 offset:36864
	ds_read_b128 v[194:197], v141 offset:37888
	ds_read_b128 v[198:201], v141 offset:38912
	ds_read_b128 v[206:209], v141 offset:39936
	global_load_lds_dwordx4 v[216:217], off
	v_lshl_add_u64 v[216:217], s[34:35], 0, v[138:139]
	s_mov_b32 m0, s46
	s_nop 0
	global_load_lds_dwordx4 v[216:217], off
	s_waitcnt vmcnt(8)
	s_waitcnt lgkmcnt(0)
	s_barrier
	s_setprio 1
	v_mfma_f32_16x16x32_bf16 v[124:127], v[142:145], v[174:177], v[124:127]
	v_mfma_f32_16x16x32_bf16 v[120:123], v[150:153], v[174:177], v[120:123]
	v_mfma_f32_16x16x32_bf16 v[116:119], v[142:145], v[182:185], v[116:119]
	v_mfma_f32_16x16x32_bf16 v[112:115], v[150:153], v[182:185], v[112:115]
	v_mfma_f32_16x16x32_bf16 v[104:107], v[142:145], v[190:193], v[104:107]
	v_mfma_f32_16x16x32_bf16 v[96:99], v[150:153], v[190:193], v[96:99]
	v_mfma_f32_16x16x32_bf16 v[88:91], v[142:145], v[198:201], v[88:91]
	v_mfma_f32_16x16x32_bf16 v[80:83], v[150:153], v[198:201], v[80:83]
	v_mfma_f32_16x16x32_bf16 v[124:127], v[146:149], v[178:181], v[124:127]
	v_mfma_f32_16x16x32_bf16 v[120:123], v[154:157], v[178:181], v[120:123]
	v_mfma_f32_16x16x32_bf16 v[116:119], v[146:149], v[186:189], v[116:119]
	v_mfma_f32_16x16x32_bf16 v[112:115], v[154:157], v[186:189], v[112:115]
	v_mfma_f32_16x16x32_bf16 v[104:107], v[146:149], v[194:197], v[104:107]
	v_mfma_f32_16x16x32_bf16 v[96:99], v[154:157], v[194:197], v[96:99]
	v_mfma_f32_16x16x32_bf16 v[88:91], v[146:149], v[206:209], v[88:91]
	v_mfma_f32_16x16x32_bf16 v[80:83], v[154:157], v[206:209], v[80:83]
	s_setprio 0
	s_setprio 1
	v_mfma_f32_16x16x32_bf16 v[108:111], v[158:161], v[174:177], v[108:111]
	v_mfma_f32_16x16x32_bf16 v[100:103], v[166:169], v[174:177], v[100:103]
	v_mfma_f32_16x16x32_bf16 v[92:95], v[158:161], v[182:185], v[92:95]
	v_mfma_f32_16x16x32_bf16 v[84:87], v[166:169], v[182:185], v[84:87]
	v_mfma_f32_16x16x32_bf16 v[76:79], v[158:161], v[190:193], v[76:79]
	v_mfma_f32_16x16x32_bf16 v[72:75], v[166:169], v[190:193], v[72:75]
	v_mfma_f32_16x16x32_bf16 v[68:71], v[158:161], v[198:201], v[68:71]
	v_mfma_f32_16x16x32_bf16 v[64:67], v[166:169], v[198:201], v[64:67]
	v_mfma_f32_16x16x32_bf16 v[108:111], v[162:165], v[178:181], v[108:111]
	v_mfma_f32_16x16x32_bf16 v[100:103], v[170:173], v[178:181], v[100:103]
	v_mfma_f32_16x16x32_bf16 v[92:95], v[162:165], v[186:189], v[92:95]
	v_mfma_f32_16x16x32_bf16 v[84:87], v[170:173], v[186:189], v[84:87]
	v_mfma_f32_16x16x32_bf16 v[76:79], v[162:165], v[194:197], v[76:79]
	v_mfma_f32_16x16x32_bf16 v[72:75], v[170:173], v[194:197], v[72:75]
	v_mfma_f32_16x16x32_bf16 v[68:71], v[162:165], v[206:209], v[68:71]
	v_mfma_f32_16x16x32_bf16 v[64:67], v[170:173], v[206:209], v[64:67]
	s_setprio 0
	s_barrier
	s_add_i32 s34, s61, s40
	v_lshl_add_u64 v[202:203], v[202:203], 0, s[6:7]
	s_mov_b32 m0, s34
	ds_read_b128 v[174:177], v141 offset:49152
	ds_read_b128 v[178:181], v141 offset:50176
	ds_read_b128 v[182:185], v141 offset:51200
	ds_read_b128 v[186:189], v141 offset:52224
	ds_read_b128 v[190:193], v141 offset:53248
	ds_read_b128 v[194:197], v141 offset:54272
	ds_read_b128 v[198:201], v141 offset:55296
	ds_read_b128 v[206:209], v141 offset:56320
	global_load_lds_dwordx4 v[202:203], off
	s_add_i32 m0, s34, 0x2000
	s_add_u32 s30, s30, 0x40080
	v_lshl_add_u64 v[202:203], v[210:211], 0, s[6:7]
	s_addc_u32 s31, s31, 0
	s_add_i32 s34, s62, s40
	global_load_lds_dwordx4 v[202:203], off
	v_lshl_add_u64 v[202:203], s[30:31], 0, v[136:137]
	s_mov_b32 m0, s34
	s_nop 0
	global_load_lds_dwordx4 v[202:203], off
	v_lshl_add_u64 v[202:203], s[30:31], 0, v[138:139]
	s_add_i32 m0, s34, 0x2000
	s_nop 0
	global_load_lds_dwordx4 v[202:203], off
	v_lshl_add_u64 v[202:203], v[212:213], 0, s[6:7]
	s_mov_b32 m0, s48
	s_nop 0
	global_load_lds_dwordx4 v[202:203], off
	v_lshl_add_u64 v[202:203], v[214:215], 0, s[6:7]
	s_mov_b32 m0, s49
	s_nop 0
	global_load_lds_dwordx4 v[202:203], off
	s_waitcnt vmcnt(8)
	s_waitcnt lgkmcnt(0)
	s_barrier
	s_setprio 1
	v_mfma_f32_16x16x32_bf16 v[60:63], v[142:145], v[174:177], v[60:63]
	v_mfma_f32_16x16x32_bf16 v[56:59], v[150:153], v[174:177], v[56:59]
	v_mfma_f32_16x16x32_bf16 v[52:55], v[142:145], v[182:185], v[52:55]
	v_mfma_f32_16x16x32_bf16 v[48:51], v[150:153], v[182:185], v[48:51]
	v_mfma_f32_16x16x32_bf16 v[40:43], v[142:145], v[190:193], v[40:43]
	v_mfma_f32_16x16x32_bf16 v[32:35], v[150:153], v[190:193], v[32:35]
	v_mfma_f32_16x16x32_bf16 v[24:27], v[142:145], v[198:201], v[24:27]
	v_mfma_f32_16x16x32_bf16 v[16:19], v[150:153], v[198:201], v[16:19]
	v_mfma_f32_16x16x32_bf16 v[60:63], v[146:149], v[178:181], v[60:63]
	v_mfma_f32_16x16x32_bf16 v[56:59], v[154:157], v[178:181], v[56:59]
	v_mfma_f32_16x16x32_bf16 v[52:55], v[146:149], v[186:189], v[52:55]
	v_mfma_f32_16x16x32_bf16 v[48:51], v[154:157], v[186:189], v[48:51]
	v_mfma_f32_16x16x32_bf16 v[40:43], v[146:149], v[194:197], v[40:43]
	v_mfma_f32_16x16x32_bf16 v[32:35], v[154:157], v[194:197], v[32:35]
	v_mfma_f32_16x16x32_bf16 v[24:27], v[146:149], v[206:209], v[24:27]
	v_mfma_f32_16x16x32_bf16 v[16:19], v[154:157], v[206:209], v[16:19]
	s_setprio 0
	s_setprio 1
	v_mfma_f32_16x16x32_bf16 v[44:47], v[158:161], v[174:177], v[44:47]
	v_mfma_f32_16x16x32_bf16 v[36:39], v[166:169], v[174:177], v[36:39]
	v_mfma_f32_16x16x32_bf16 v[28:31], v[158:161], v[182:185], v[28:31]
	v_mfma_f32_16x16x32_bf16 v[20:23], v[166:169], v[182:185], v[20:23]
	v_mfma_f32_16x16x32_bf16 v[12:15], v[158:161], v[190:193], v[12:15]
	v_mfma_f32_16x16x32_bf16 v[8:11], v[166:169], v[190:193], v[8:11]
	v_mfma_f32_16x16x32_bf16 v[4:7], v[158:161], v[198:201], v[4:7]
	v_mfma_f32_16x16x32_bf16 v[0:3], v[166:169], v[198:201], v[0:3]
	v_mfma_f32_16x16x32_bf16 v[44:47], v[162:165], v[178:181], v[44:47]
	v_mfma_f32_16x16x32_bf16 v[36:39], v[170:173], v[178:181], v[36:39]
	v_mfma_f32_16x16x32_bf16 v[28:31], v[162:165], v[186:189], v[28:31]
	v_mfma_f32_16x16x32_bf16 v[20:23], v[170:173], v[186:189], v[20:23]
	v_mfma_f32_16x16x32_bf16 v[12:15], v[162:165], v[194:197], v[12:15]
	v_mfma_f32_16x16x32_bf16 v[8:11], v[170:173], v[194:197], v[8:11]
	v_mfma_f32_16x16x32_bf16 v[4:7], v[162:165], v[206:209], v[4:7]
	v_mfma_f32_16x16x32_bf16 v[0:3], v[170:173], v[206:209], v[0:3]
	s_setprio 0
	s_barrier
	s_add_i32 s60, s60, 2
	s_add_u32 s28, s28, 0x100
	s_addc_u32 s29, s29, 0
	s_add_u32 s58, s58, 0x100
	s_addc_u32 s59, s59, 0
	s_cmp_gt_u32 s60, 13
	s_cbranch_scc0 .LBB0_1639
	s_and_b64 vcc, exec, s[10:11]
	s_cbranch_vccz .LBB0_1642
	s_barrier

.LBB0_1706:
	ds_read_b128 v[84:87], v80
	ds_read_b128 v[88:91], v80 offset:1024
	ds_read_b128 v[92:95], v80 offset:2048
	ds_read_b128 v[96:99], v80 offset:3072
	s_add_u32 s26, s24, 0xfffd8080
	s_addc_u32 s27, s25, -1
	s_cmp_eq_u32 s62, 4
	s_cselect_b32 s29, s19, s27
	s_cselect_b32 s28, s18, s26
	s_cselect_b32 s27, s58, s61
	s_cselect_b32 s26, s59, s60
	s_mov_b32 m0, s50
	v_lshl_add_u64 v[132:133], s[24:25], 0, v[74:75]
	ds_read_b128 v[100:103], v81
	ds_read_b128 v[104:107], v81 offset:1024
	ds_read_b128 v[108:111], v81 offset:2048
	ds_read_b128 v[112:115], v81 offset:3072
	ds_read_b128 v[116:119], v81 offset:4096
	ds_read_b128 v[120:123], v81 offset:5120
	ds_read_b128 v[124:127], v81 offset:6144
	ds_read_b128 v[128:131], v81 offset:7168
	global_load_lds_dwordx4 v[132:133], off
	v_lshl_add_u64 v[132:133], s[24:25], 0, v[76:77]
	s_mov_b32 m0, s51
	s_nop 0
	global_load_lds_dwordx4 v[132:133], off
	s_waitcnt vmcnt(8)
	s_waitcnt lgkmcnt(0)
	s_barrier
	s_setprio 1
	v_mfma_f32_16x16x32_bf16 v[60:63], v[84:87], v[100:103], v[60:63]
	v_mfma_f32_16x16x32_bf16 v[56:59], v[92:95], v[100:103], v[56:59]
	v_mfma_f32_16x16x32_bf16 v[52:55], v[84:87], v[108:111], v[52:55]
	v_mfma_f32_16x16x32_bf16 v[48:51], v[92:95], v[108:111], v[48:51]
	v_mfma_f32_16x16x32_bf16 v[44:47], v[84:87], v[116:119], v[44:47]
	v_mfma_f32_16x16x32_bf16 v[40:43], v[92:95], v[116:119], v[40:43]
	v_mfma_f32_16x16x32_bf16 v[36:39], v[84:87], v[124:127], v[36:39]
	v_mfma_f32_16x16x32_bf16 v[32:35], v[92:95], v[124:127], v[32:35]
	v_mfma_f32_16x16x32_bf16 v[60:63], v[88:91], v[104:107], v[60:63]
	v_mfma_f32_16x16x32_bf16 v[56:59], v[96:99], v[104:107], v[56:59]
	v_mfma_f32_16x16x32_bf16 v[52:55], v[88:91], v[112:115], v[52:55]
	v_mfma_f32_16x16x32_bf16 v[48:51], v[96:99], v[112:115], v[48:51]
	v_mfma_f32_16x16x32_bf16 v[44:47], v[88:91], v[120:123], v[44:47]
	v_mfma_f32_16x16x32_bf16 v[40:43], v[96:99], v[120:123], v[40:43]
	v_mfma_f32_16x16x32_bf16 v[36:39], v[88:91], v[128:131], v[36:39]
	v_mfma_f32_16x16x32_bf16 v[32:35], v[96:99], v[128:131], v[32:35]
	s_setprio 0
	s_setprio 1
	s_setprio 0
	s_barrier
	s_mov_b32 m0, s52
	v_lshl_add_u64 v[132:133], s[26:27], 0, v[68:69]
	s_add_u32 s64, s26, 0x20000
	ds_read_b128 v[100:103], v81 offset:16384
	ds_read_b128 v[104:107], v81 offset:17408
	ds_read_b128 v[108:111], v81 offset:18432
	ds_read_b128 v[112:115], v81 offset:19456
	ds_read_b128 v[116:119], v81 offset:20480
	ds_read_b128 v[120:123], v81 offset:21504
	ds_read_b128 v[124:127], v81 offset:22528
	ds_read_b128 v[128:131], v81 offset:23552
	global_load_lds_dwordx4 v[132:133], off
	v_lshl_add_u64 v[134:135], s[26:27], 0, v[64:65]
	s_mov_b32 m0, s53
	s_addc_u32 s65, s27, 0
	global_load_lds_dwordx4 v[134:135], off
	v_lshl_add_u64 v[136:137], s[64:65], 0, v[68:69]
	s_mov_b32 m0, s38
	v_lshl_add_u64 v[138:139], s[28:29], 0, v[66:67]
	global_load_lds_dwordx4 v[136:137], off
	v_lshl_add_u64 v[136:137], s[64:65], 0, v[64:65]
	s_mov_b32 m0, s39
	s_nop 0
	global_load_lds_dwordx4 v[136:137], off
	v_lshl_add_u64 v[136:137], s[28:29], 0, v[70:71]
	s_mov_b32 m0, s36
	s_nop 0
	global_load_lds_dwordx4 v[136:137], off
	s_mov_b32 m0, s40
	s_nop 0
	global_load_lds_dwordx4 v[138:139], off
	s_waitcnt vmcnt(8)
	s_waitcnt lgkmcnt(0)
	s_barrier
	s_setprio 1
	v_mfma_f32_16x16x32_bf16 v[28:31], v[84:87], v[100:103], v[28:31]
	v_mfma_f32_16x16x32_bf16 v[24:27], v[92:95], v[100:103], v[24:27]
	v_mfma_f32_16x16x32_bf16 v[20:23], v[84:87], v[108:111], v[20:23]
	v_mfma_f32_16x16x32_bf16 v[16:19], v[92:95], v[108:111], v[16:19]
	v_mfma_f32_16x16x32_bf16 v[12:15], v[84:87], v[116:119], v[12:15]
	v_mfma_f32_16x16x32_bf16 v[8:11], v[92:95], v[116:119], v[8:11]
	v_mfma_f32_16x16x32_bf16 v[4:7], v[84:87], v[124:127], v[4:7]
	v_mfma_f32_16x16x32_bf16 v[0:3], v[92:95], v[124:127], v[0:3]
	v_mfma_f32_16x16x32_bf16 v[28:31], v[88:91], v[104:107], v[28:31]
	v_mfma_f32_16x16x32_bf16 v[24:27], v[96:99], v[104:107], v[24:27]
	v_mfma_f32_16x16x32_bf16 v[20:23], v[88:91], v[112:115], v[20:23]
	v_mfma_f32_16x16x32_bf16 v[16:19], v[96:99], v[112:115], v[16:19]
	v_mfma_f32_16x16x32_bf16 v[12:15], v[88:91], v[120:123], v[12:15]
	v_mfma_f32_16x16x32_bf16 v[8:11], v[96:99], v[120:123], v[8:11]
	v_mfma_f32_16x16x32_bf16 v[4:7], v[88:91], v[128:131], v[4:7]
	v_mfma_f32_16x16x32_bf16 v[0:3], v[96:99], v[128:131], v[0:3]
	s_setprio 0
	s_setprio 1
	s_setprio 0
	s_barrier
	ds_read_b128 v[84:87], v82
	ds_read_b128 v[88:91], v82 offset:1024
	ds_read_b128 v[92:95], v82 offset:2048
	ds_read_b128 v[96:99], v82 offset:3072
	s_add_u32 s28, s28, 0x28000
	s_addc_u32 s29, s29, 0
	s_mov_b32 m0, s41
	v_lshl_add_u64 v[140:141], s[28:29], 0, v[70:71]
	ds_read_b128 v[100:103], v81 offset:32768
	ds_read_b128 v[104:107], v81 offset:33792
	ds_read_b128 v[108:111], v81 offset:34816
	ds_read_b128 v[112:115], v81 offset:35840
	ds_read_b128 v[116:119], v81 offset:36864
	ds_read_b128 v[120:123], v81 offset:37888
	ds_read_b128 v[124:127], v81 offset:38912
	ds_read_b128 v[128:131], v81 offset:39936
	global_load_lds_dwordx4 v[140:141], off
	v_lshl_add_u64 v[140:141], s[28:29], 0, v[66:67]
	s_mov_b32 m0, s42
	s_nop 0
	global_load_lds_dwordx4 v[140:141], off
	s_waitcnt vmcnt(8)
	s_waitcnt lgkmcnt(0)
	s_barrier
	s_setprio 1
	v_mfma_f32_16x16x32_bf16 v[60:63], v[84:87], v[100:103], v[60:63]
	v_mfma_f32_16x16x32_bf16 v[56:59], v[92:95], v[100:103], v[56:59]
	v_mfma_f32_16x16x32_bf16 v[52:55], v[84:87], v[108:111], v[52:55]
	v_mfma_f32_16x16x32_bf16 v[48:51], v[92:95], v[108:111], v[48:51]
	v_mfma_f32_16x16x32_bf16 v[44:47], v[84:87], v[116:119], v[44:47]
	v_mfma_f32_16x16x32_bf16 v[40:43], v[92:95], v[116:119], v[40:43]
	v_mfma_f32_16x16x32_bf16 v[36:39], v[84:87], v[124:127], v[36:39]
	v_mfma_f32_16x16x32_bf16 v[32:35], v[92:95], v[124:127], v[32:35]
	v_mfma_f32_16x16x32_bf16 v[60:63], v[88:91], v[104:107], v[60:63]
	v_mfma_f32_16x16x32_bf16 v[56:59], v[96:99], v[104:107], v[56:59]
	v_mfma_f32_16x16x32_bf16 v[52:55], v[88:91], v[112:115], v[52:55]
	v_mfma_f32_16x16x32_bf16 v[48:51], v[96:99], v[112:115], v[48:51]
	v_mfma_f32_16x16x32_bf16 v[44:47], v[88:91], v[120:123], v[44:47]
	v_mfma_f32_16x16x32_bf16 v[40:43], v[96:99], v[120:123], v[40:43]
	v_mfma_f32_16x16x32_bf16 v[36:39], v[88:91], v[128:131], v[36:39]
	v_mfma_f32_16x16x32_bf16 v[32:35], v[96:99], v[128:131], v[32:35]
	s_setprio 0
	s_setprio 1
	s_setprio 0
	s_barrier
	s_mov_b32 m0, s54
	v_lshl_add_u64 v[132:133], v[132:133], 0, s[4:5]
	s_add_u32 s26, s26, 0x20080
	ds_read_b128 v[100:103], v81 offset:49152
	ds_read_b128 v[104:107], v81 offset:50176
	ds_read_b128 v[108:111], v81 offset:51200
	ds_read_b128 v[112:115], v81 offset:52224
	ds_read_b128 v[116:119], v81 offset:53248
	ds_read_b128 v[120:123], v81 offset:54272
	ds_read_b128 v[124:127], v81 offset:55296
	ds_read_b128 v[128:131], v81 offset:56320
	global_load_lds_dwordx4 v[132:133], off
	v_lshl_add_u64 v[132:133], v[134:135], 0, s[4:5]
	s_mov_b32 m0, s55
	s_addc_u32 s27, s27, 0
	global_load_lds_dwordx4 v[132:133], off
	v_lshl_add_u64 v[132:133], s[26:27], 0, v[68:69]
	s_mov_b32 m0, s48
	s_nop 0
	global_load_lds_dwordx4 v[132:133], off
	v_lshl_add_u64 v[132:133], s[26:27], 0, v[64:65]
	s_mov_b32 m0, s49
	s_nop 0
	global_load_lds_dwordx4 v[132:133], off
	v_lshl_add_u64 v[132:133], v[136:137], 0, s[4:5]
	s_mov_b32 m0, s46
	s_nop 0
	global_load_lds_dwordx4 v[132:133], off
	v_lshl_add_u64 v[132:133], v[138:139], 0, s[4:5]
	s_mov_b32 m0, s47
	s_nop 0
	global_load_lds_dwordx4 v[132:133], off
	s_waitcnt vmcnt(8)
	s_waitcnt lgkmcnt(0)
	s_barrier
	s_setprio 1
	v_mfma_f32_16x16x32_bf16 v[28:31], v[84:87], v[100:103], v[28:31]
	v_mfma_f32_16x16x32_bf16 v[24:27], v[92:95], v[100:103], v[24:27]
	v_mfma_f32_16x16x32_bf16 v[20:23], v[84:87], v[108:111], v[20:23]
	v_mfma_f32_16x16x32_bf16 v[16:19], v[92:95], v[108:111], v[16:19]
	v_mfma_f32_16x16x32_bf16 v[12:15], v[84:87], v[116:119], v[12:15]
	v_mfma_f32_16x16x32_bf16 v[8:11], v[92:95], v[116:119], v[8:11]
	v_mfma_f32_16x16x32_bf16 v[4:7], v[84:87], v[124:127], v[4:7]
	v_mfma_f32_16x16x32_bf16 v[0:3], v[92:95], v[124:127], v[0:3]
	v_mfma_f32_16x16x32_bf16 v[28:31], v[88:91], v[104:107], v[28:31]
	v_mfma_f32_16x16x32_bf16 v[24:27], v[96:99], v[104:107], v[24:27]
	v_mfma_f32_16x16x32_bf16 v[20:23], v[88:91], v[112:115], v[20:23]
	v_mfma_f32_16x16x32_bf16 v[16:19], v[96:99], v[112:115], v[16:19]
	v_mfma_f32_16x16x32_bf16 v[12:15], v[88:91], v[120:123], v[12:15]
	v_mfma_f32_16x16x32_bf16 v[8:11], v[96:99], v[120:123], v[8:11]
	v_mfma_f32_16x16x32_bf16 v[4:7], v[88:91], v[128:131], v[4:7]
	v_mfma_f32_16x16x32_bf16 v[0:3], v[96:99], v[128:131], v[0:3]
	s_setprio 0
	s_setprio 1
	s_setprio 0
	s_barrier
	s_add_i32 s62, s62, 2
	s_add_u32 s24, s24, 0x100
	s_addc_u32 s25, s25, 0
	s_add_u32 s60, s60, 0x100
	s_addc_u32 s61, s61, 0
	s_cmp_gt_u32 s62, 5
	s_cbranch_scc0 .LBB0_1706
	s_and_b64 vcc, exec, s[6:7]
	s_cbranch_vccz .LBB0_1709
	s_barrier

.Llsb_skip_17:
.LBB0_2065:
	ds_read_b128 v[136:139], v154
	ds_read_b128 v[140:143], v154 offset:1024
	ds_read_b128 v[144:147], v154 offset:2048
	ds_read_b128 v[158:161], v154 offset:3072
	ds_read_b128 v[162:165], v155
	ds_read_b128 v[166:169], v155 offset:1024
	ds_read_b128 v[170:173], v155 offset:2048
	ds_read_b128 v[180:183], v155 offset:3072
	s_add_u32 s38, s36, 0xfffa0080
	s_addc_u32 s39, s37, -1
	s_cmp_eq_u32 s67, 4
	s_cselect_b32 s41, s31, s39
	s_cselect_b32 s40, s30, s38
	s_cselect_b32 s39, s35, s66
	s_cselect_b32 s38, s34, s65
	v_lshl_add_u64 v[148:149], s[36:37], 0, v[132:133]
	s_add_i32 m0, s45, 0xc000
	ds_read_b128 v[184:187], v156
	ds_read_b128 v[188:191], v156 offset:1024
	ds_read_b128 v[192:195], v156 offset:2048
	ds_read_b128 v[196:199], v156 offset:3072
	ds_read_b128 v[200:203], v156 offset:4096
	ds_read_b128 v[206:209], v156 offset:5120
	ds_read_b128 v[210:213], v156 offset:6144
	ds_read_b128 v[214:217], v156 offset:7168
	global_load_lds_dwordx4 v[148:149], off
	v_lshl_add_u64 v[148:149], s[36:37], 0, v[134:135]
	s_add_i32 m0, s45, 0xe000
	s_nop 0
	global_load_lds_dwordx4 v[148:149], off
	s_waitcnt vmcnt(8)
	s_waitcnt lgkmcnt(0)
	s_barrier
	s_setprio 1
	v_mfma_f32_16x16x32_bf16 v[124:127], v[136:139], v[184:187], v[124:127]
	v_mfma_f32_16x16x32_bf16 v[120:123], v[144:147], v[184:187], v[120:123]
	v_mfma_f32_16x16x32_bf16 v[112:115], v[136:139], v[192:195], v[112:115]
	v_mfma_f32_16x16x32_bf16 v[104:107], v[144:147], v[192:195], v[104:107]
	v_mfma_f32_16x16x32_bf16 v[96:99], v[136:139], v[200:203], v[96:99]
	v_mfma_f32_16x16x32_bf16 v[88:91], v[144:147], v[200:203], v[88:91]
	v_mfma_f32_16x16x32_bf16 v[80:83], v[136:139], v[210:213], v[80:83]
	v_mfma_f32_16x16x32_bf16 v[72:75], v[144:147], v[210:213], v[72:75]
	v_mfma_f32_16x16x32_bf16 v[124:127], v[140:143], v[188:191], v[124:127]
	v_mfma_f32_16x16x32_bf16 v[120:123], v[158:161], v[188:191], v[120:123]
	v_mfma_f32_16x16x32_bf16 v[112:115], v[140:143], v[196:199], v[112:115]
	v_mfma_f32_16x16x32_bf16 v[104:107], v[158:161], v[196:199], v[104:107]
	v_mfma_f32_16x16x32_bf16 v[96:99], v[140:143], v[206:209], v[96:99]
	v_mfma_f32_16x16x32_bf16 v[88:91], v[158:161], v[206:209], v[88:91]
	v_mfma_f32_16x16x32_bf16 v[80:83], v[140:143], v[214:217], v[80:83]
	v_mfma_f32_16x16x32_bf16 v[72:75], v[158:161], v[214:217], v[72:75]
	s_setprio 0
	s_setprio 1
	v_mfma_f32_16x16x32_bf16 v[116:119], v[162:165], v[184:187], v[116:119]
	v_mfma_f32_16x16x32_bf16 v[108:111], v[170:173], v[184:187], v[108:111]
	v_mfma_f32_16x16x32_bf16 v[100:103], v[162:165], v[192:195], v[100:103]
	v_mfma_f32_16x16x32_bf16 v[92:95], v[170:173], v[192:195], v[92:95]
	v_mfma_f32_16x16x32_bf16 v[84:87], v[162:165], v[200:203], v[84:87]
	v_mfma_f32_16x16x32_bf16 v[76:79], v[170:173], v[200:203], v[76:79]
	v_mfma_f32_16x16x32_bf16 v[68:71], v[162:165], v[210:213], v[68:71]
	v_mfma_f32_16x16x32_bf16 v[64:67], v[170:173], v[210:213], v[64:67]
	v_mfma_f32_16x16x32_bf16 v[116:119], v[166:169], v[188:191], v[116:119]
	v_mfma_f32_16x16x32_bf16 v[108:111], v[180:183], v[188:191], v[108:111]
	v_mfma_f32_16x16x32_bf16 v[100:103], v[166:169], v[196:199], v[100:103]
	v_mfma_f32_16x16x32_bf16 v[92:95], v[180:183], v[196:199], v[92:95]
	v_mfma_f32_16x16x32_bf16 v[84:87], v[166:169], v[206:209], v[84:87]
	v_mfma_f32_16x16x32_bf16 v[76:79], v[180:183], v[206:209], v[76:79]
	v_mfma_f32_16x16x32_bf16 v[68:71], v[166:169], v[214:217], v[68:71]
	v_mfma_f32_16x16x32_bf16 v[64:67], v[180:183], v[214:217], v[64:67]
	s_setprio 0
	s_barrier
	s_add_i32 s68, s52, s44
	v_lshl_add_u64 v[148:149], s[38:39], 0, v[130:131]
	s_mov_b32 m0, s68
	ds_read_b128 v[184:187], v156 offset:16384
	ds_read_b128 v[188:191], v156 offset:17408
	ds_read_b128 v[192:195], v156 offset:18432
	ds_read_b128 v[196:199], v156 offset:19456
	ds_read_b128 v[200:203], v156 offset:20480
	ds_read_b128 v[206:209], v156 offset:21504
	ds_read_b128 v[210:213], v156 offset:22528
	ds_read_b128 v[214:217], v156 offset:23552
	global_load_lds_dwordx4 v[148:149], off
	s_add_i32 m0, s68, 0x2000
	s_add_u32 s68, s38, 0x60000
	v_lshl_add_u64 v[174:175], s[38:39], 0, v[128:129]
	s_addc_u32 s69, s39, 0
	s_add_i32 s70, s53, s44
	global_load_lds_dwordx4 v[174:175], off
	v_lshl_add_u64 v[218:219], s[68:69], 0, v[130:131]
	s_mov_b32 m0, s70
	v_lshl_add_u64 v[220:221], s[40:41], 0, v[128:129]
	global_load_lds_dwordx4 v[218:219], off
	v_lshl_add_u64 v[218:219], s[68:69], 0, v[128:129]
	s_add_i32 m0, s70, 0x2000
	s_nop 0
	global_load_lds_dwordx4 v[218:219], off
	v_lshl_add_u64 v[218:219], s[40:41], 0, v[130:131]
	s_mov_b32 m0, s45
	s_nop 0
	global_load_lds_dwordx4 v[218:219], off
	s_mov_b32 m0, s46
	s_nop 0
	global_load_lds_dwordx4 v[220:221], off
	s_waitcnt vmcnt(8)
	s_waitcnt lgkmcnt(0)
	s_barrier
	s_setprio 1
	v_mfma_f32_16x16x32_bf16 v[60:63], v[136:139], v[184:187], v[60:63]
	v_mfma_f32_16x16x32_bf16 v[56:59], v[144:147], v[184:187], v[56:59]
	v_mfma_f32_16x16x32_bf16 v[48:51], v[136:139], v[192:195], v[48:51]
	v_mfma_f32_16x16x32_bf16 v[40:43], v[144:147], v[192:195], v[40:43]
	v_mfma_f32_16x16x32_bf16 v[32:35], v[136:139], v[200:203], v[32:35]
	v_mfma_f32_16x16x32_bf16 v[24:27], v[144:147], v[200:203], v[24:27]
	v_mfma_f32_16x16x32_bf16 v[16:19], v[136:139], v[210:213], v[16:19]
	v_mfma_f32_16x16x32_bf16 v[8:11], v[144:147], v[210:213], v[8:11]
	v_mfma_f32_16x16x32_bf16 v[60:63], v[140:143], v[188:191], v[60:63]
	v_mfma_f32_16x16x32_bf16 v[56:59], v[158:161], v[188:191], v[56:59]
	v_mfma_f32_16x16x32_bf16 v[48:51], v[140:143], v[196:199], v[48:51]
	v_mfma_f32_16x16x32_bf16 v[40:43], v[158:161], v[196:199], v[40:43]
	v_mfma_f32_16x16x32_bf16 v[32:35], v[140:143], v[206:209], v[32:35]
	v_mfma_f32_16x16x32_bf16 v[24:27], v[158:161], v[206:209], v[24:27]
	v_mfma_f32_16x16x32_bf16 v[16:19], v[140:143], v[214:217], v[16:19]
	v_mfma_f32_16x16x32_bf16 v[8:11], v[158:161], v[214:217], v[8:11]
	s_setprio 0
	s_setprio 1
	v_mfma_f32_16x16x32_bf16 v[52:55], v[162:165], v[184:187], v[52:55]
	v_mfma_f32_16x16x32_bf16 v[44:47], v[170:173], v[184:187], v[44:47]
	v_mfma_f32_16x16x32_bf16 v[36:39], v[162:165], v[192:195], v[36:39]
	v_mfma_f32_16x16x32_bf16 v[28:31], v[170:173], v[192:195], v[28:31]
	v_mfma_f32_16x16x32_bf16 v[20:23], v[162:165], v[200:203], v[20:23]
	v_mfma_f32_16x16x32_bf16 v[12:15], v[170:173], v[200:203], v[12:15]
	v_mfma_f32_16x16x32_bf16 v[4:7], v[162:165], v[210:213], v[4:7]
	v_mfma_f32_16x16x32_bf16 v[0:3], v[170:173], v[210:213], v[0:3]
	v_mfma_f32_16x16x32_bf16 v[52:55], v[166:169], v[188:191], v[52:55]
	v_mfma_f32_16x16x32_bf16 v[44:47], v[180:183], v[188:191], v[44:47]
	v_mfma_f32_16x16x32_bf16 v[36:39], v[166:169], v[196:199], v[36:39]
	v_mfma_f32_16x16x32_bf16 v[28:31], v[180:183], v[196:199], v[28:31]
	v_mfma_f32_16x16x32_bf16 v[20:23], v[166:169], v[206:209], v[20:23]
	v_mfma_f32_16x16x32_bf16 v[12:15], v[180:183], v[206:209], v[12:15]
	v_mfma_f32_16x16x32_bf16 v[4:7], v[166:169], v[214:217], v[4:7]
	v_mfma_f32_16x16x32_bf16 v[0:3], v[180:183], v[214:217], v[0:3]
	s_setprio 0
	s_barrier
	s_add_i32 s68, 0, 0x18000
	v_add_u32_e32 v157, s68, v152
	s_add_i32 s69, 0, 0x1c000
	ds_read_b128 v[136:139], v157
	ds_read_b128 v[140:143], v157 offset:1024
	ds_read_b128 v[144:147], v157 offset:2048
	ds_read_b128 v[158:161], v157 offset:3072
	v_add_u32_e32 v157, s69, v152
	ds_read_b128 v[162:165], v157
	ds_read_b128 v[166:169], v157 offset:1024
	ds_read_b128 v[170:173], v157 offset:2048
	ds_read_b128 v[180:183], v157 offset:3072
	s_add_u32 s40, s40, 0x60000
	s_addc_u32 s41, s41, 0
	s_mov_b32 m0, s47
	v_lshl_add_u64 v[222:223], s[40:41], 0, v[130:131]
	ds_read_b128 v[184:187], v156 offset:32768
	ds_read_b128 v[188:191], v156 offset:33792
	ds_read_b128 v[192:195], v156 offset:34816
	ds_read_b128 v[196:199], v156 offset:35840
	ds_read_b128 v[200:203], v156 offset:36864
	ds_read_b128 v[206:209], v156 offset:37888
	ds_read_b128 v[210:213], v156 offset:38912
	ds_read_b128 v[214:217], v156 offset:39936
	global_load_lds_dwordx4 v[222:223], off
	v_lshl_add_u64 v[222:223], s[40:41], 0, v[128:129]
	s_mov_b32 m0, s48
	s_nop 0
	global_load_lds_dwordx4 v[222:223], off
	s_waitcnt vmcnt(8)
	s_waitcnt lgkmcnt(0)
	s_barrier
	s_setprio 1
	v_mfma_f32_16x16x32_bf16 v[124:127], v[136:139], v[184:187], v[124:127]
	v_mfma_f32_16x16x32_bf16 v[120:123], v[144:147], v[184:187], v[120:123]
	v_mfma_f32_16x16x32_bf16 v[112:115], v[136:139], v[192:195], v[112:115]
	v_mfma_f32_16x16x32_bf16 v[104:107], v[144:147], v[192:195], v[104:107]
	v_mfma_f32_16x16x32_bf16 v[96:99], v[136:139], v[200:203], v[96:99]
	v_mfma_f32_16x16x32_bf16 v[88:91], v[144:147], v[200:203], v[88:91]
	v_mfma_f32_16x16x32_bf16 v[80:83], v[136:139], v[210:213], v[80:83]
	v_mfma_f32_16x16x32_bf16 v[72:75], v[144:147], v[210:213], v[72:75]
	v_mfma_f32_16x16x32_bf16 v[124:127], v[140:143], v[188:191], v[124:127]
	v_mfma_f32_16x16x32_bf16 v[120:123], v[158:161], v[188:191], v[120:123]
	v_mfma_f32_16x16x32_bf16 v[112:115], v[140:143], v[196:199], v[112:115]
	v_mfma_f32_16x16x32_bf16 v[104:107], v[158:161], v[196:199], v[104:107]
	v_mfma_f32_16x16x32_bf16 v[96:99], v[140:143], v[206:209], v[96:99]
	v_mfma_f32_16x16x32_bf16 v[88:91], v[158:161], v[206:209], v[88:91]
	v_mfma_f32_16x16x32_bf16 v[80:83], v[140:143], v[214:217], v[80:83]
	v_mfma_f32_16x16x32_bf16 v[72:75], v[158:161], v[214:217], v[72:75]
	s_setprio 0
	s_setprio 1
	v_mfma_f32_16x16x32_bf16 v[116:119], v[162:165], v[184:187], v[116:119]
	v_mfma_f32_16x16x32_bf16 v[108:111], v[170:173], v[184:187], v[108:111]
	v_mfma_f32_16x16x32_bf16 v[100:103], v[162:165], v[192:195], v[100:103]
	v_mfma_f32_16x16x32_bf16 v[92:95], v[170:173], v[192:195], v[92:95]
	v_mfma_f32_16x16x32_bf16 v[84:87], v[162:165], v[200:203], v[84:87]
	v_mfma_f32_16x16x32_bf16 v[76:79], v[170:173], v[200:203], v[76:79]
	v_mfma_f32_16x16x32_bf16 v[68:71], v[162:165], v[210:213], v[68:71]
	v_mfma_f32_16x16x32_bf16 v[64:67], v[170:173], v[210:213], v[64:67]
	v_mfma_f32_16x16x32_bf16 v[116:119], v[166:169], v[188:191], v[116:119]
	v_mfma_f32_16x16x32_bf16 v[108:111], v[180:183], v[188:191], v[108:111]
	v_mfma_f32_16x16x32_bf16 v[100:103], v[166:169], v[196:199], v[100:103]
	v_mfma_f32_16x16x32_bf16 v[92:95], v[180:183], v[196:199], v[92:95]
	v_mfma_f32_16x16x32_bf16 v[84:87], v[166:169], v[206:209], v[84:87]
	v_mfma_f32_16x16x32_bf16 v[76:79], v[180:183], v[206:209], v[76:79]
	v_mfma_f32_16x16x32_bf16 v[68:71], v[166:169], v[214:217], v[68:71]
	v_mfma_f32_16x16x32_bf16 v[64:67], v[180:183], v[214:217], v[64:67]
	s_setprio 0
	s_barrier
	s_add_i32 s40, s68, s44
	v_lshl_add_u64 v[148:149], v[148:149], 0, s[16:17]
	s_mov_b32 m0, s40
	ds_read_b128 v[184:187], v156 offset:49152
	ds_read_b128 v[188:191], v156 offset:50176
	ds_read_b128 v[192:195], v156 offset:51200
	ds_read_b128 v[196:199], v156 offset:52224
	ds_read_b128 v[200:203], v156 offset:53248
	ds_read_b128 v[206:209], v156 offset:54272
	ds_read_b128 v[210:213], v156 offset:55296
	ds_read_b128 v[214:217], v156 offset:56320
	global_load_lds_dwordx4 v[148:149], off
	s_add_i32 m0, s40, 0x2000
	s_add_u32 s38, s38, 0x60080
	v_lshl_add_u64 v[148:149], v[174:175], 0, s[16:17]
	s_addc_u32 s39, s39, 0
	s_add_i32 s40, s69, s44
	global_load_lds_dwordx4 v[148:149], off
	v_lshl_add_u64 v[148:149], s[38:39], 0, v[130:131]
	s_mov_b32 m0, s40
	s_nop 0
	global_load_lds_dwordx4 v[148:149], off
	v_lshl_add_u64 v[148:149], s[38:39], 0, v[128:129]
	s_add_i32 m0, s40, 0x2000
	s_nop 0
	global_load_lds_dwordx4 v[148:149], off
	v_lshl_add_u64 v[148:149], v[218:219], 0, s[16:17]
	s_mov_b32 m0, s49
	s_nop 0
	global_load_lds_dwordx4 v[148:149], off
	v_lshl_add_u64 v[148:149], v[220:221], 0, s[16:17]
	s_mov_b32 m0, s50
	s_nop 0
	global_load_lds_dwordx4 v[148:149], off
	s_waitcnt vmcnt(8)
	s_waitcnt lgkmcnt(0)
	s_barrier
	s_setprio 1
	v_mfma_f32_16x16x32_bf16 v[60:63], v[136:139], v[184:187], v[60:63]
	v_mfma_f32_16x16x32_bf16 v[56:59], v[144:147], v[184:187], v[56:59]
	v_mfma_f32_16x16x32_bf16 v[48:51], v[136:139], v[192:195], v[48:51]
	v_mfma_f32_16x16x32_bf16 v[40:43], v[144:147], v[192:195], v[40:43]
	v_mfma_f32_16x16x32_bf16 v[32:35], v[136:139], v[200:203], v[32:35]
	v_mfma_f32_16x16x32_bf16 v[24:27], v[144:147], v[200:203], v[24:27]
	v_mfma_f32_16x16x32_bf16 v[16:19], v[136:139], v[210:213], v[16:19]
	v_mfma_f32_16x16x32_bf16 v[8:11], v[144:147], v[210:213], v[8:11]
	v_mfma_f32_16x16x32_bf16 v[60:63], v[140:143], v[188:191], v[60:63]
	v_mfma_f32_16x16x32_bf16 v[56:59], v[158:161], v[188:191], v[56:59]
	v_mfma_f32_16x16x32_bf16 v[48:51], v[140:143], v[196:199], v[48:51]
	v_mfma_f32_16x16x32_bf16 v[40:43], v[158:161], v[196:199], v[40:43]
	v_mfma_f32_16x16x32_bf16 v[32:35], v[140:143], v[206:209], v[32:35]
	v_mfma_f32_16x16x32_bf16 v[24:27], v[158:161], v[206:209], v[24:27]
	v_mfma_f32_16x16x32_bf16 v[16:19], v[140:143], v[214:217], v[16:19]
	v_mfma_f32_16x16x32_bf16 v[8:11], v[158:161], v[214:217], v[8:11]
	s_setprio 0
	s_setprio 1
	v_mfma_f32_16x16x32_bf16 v[52:55], v[162:165], v[184:187], v[52:55]
	v_mfma_f32_16x16x32_bf16 v[44:47], v[170:173], v[184:187], v[44:47]
	v_mfma_f32_16x16x32_bf16 v[36:39], v[162:165], v[192:195], v[36:39]
	v_mfma_f32_16x16x32_bf16 v[28:31], v[170:173], v[192:195], v[28:31]
	v_mfma_f32_16x16x32_bf16 v[20:23], v[162:165], v[200:203], v[20:23]
	v_mfma_f32_16x16x32_bf16 v[12:15], v[170:173], v[200:203], v[12:15]
	v_mfma_f32_16x16x32_bf16 v[4:7], v[162:165], v[210:213], v[4:7]
	v_mfma_f32_16x16x32_bf16 v[0:3], v[170:173], v[210:213], v[0:3]
	v_mfma_f32_16x16x32_bf16 v[52:55], v[166:169], v[188:191], v[52:55]
	v_mfma_f32_16x16x32_bf16 v[44:47], v[180:183], v[188:191], v[44:47]
	v_mfma_f32_16x16x32_bf16 v[36:39], v[166:169], v[196:199], v[36:39]
	v_mfma_f32_16x16x32_bf16 v[28:31], v[180:183], v[196:199], v[28:31]
	v_mfma_f32_16x16x32_bf16 v[20:23], v[166:169], v[206:209], v[20:23]
	v_mfma_f32_16x16x32_bf16 v[12:15], v[180:183], v[206:209], v[12:15]
	v_mfma_f32_16x16x32_bf16 v[4:7], v[166:169], v[214:217], v[4:7]
	v_mfma_f32_16x16x32_bf16 v[0:3], v[180:183], v[214:217], v[0:3]
	s_setprio 0
	s_barrier
	s_add_i32 s67, s67, 2
	s_add_u32 s36, s36, 0x100
	s_addc_u32 s37, s37, 0
	s_add_u32 s65, s65, 0x100
	s_addc_u32 s66, s66, 0
	s_cmp_gt_u32 s67, 5
	s_cbranch_scc0 .LBB0_2065
	s_and_b64 vcc, exec, s[18:19]
	s_cbranch_vccz .LBB0_2068
	s_barrier

.Llsb_skip_19:
.LBB0_2240:
	ds_read_b128 v[128:131], v212
	ds_read_b128 v[132:135], v212 offset:1024
	ds_read_b128 v[136:139], v212 offset:2048
	ds_read_b128 v[140:143], v212 offset:3072
	ds_read_b128 v[144:147], v213
	ds_read_b128 v[148:151], v213 offset:1024
	ds_read_b128 v[152:155], v213 offset:2048
	ds_read_b128 v[156:159], v213 offset:3072
	s_add_u32 s24, s22, 0xfffc0080
	s_addc_u32 s25, s23, -1
	s_cmp_eq_u32 s56, 12
	s_cselect_b32 s27, s15, s25
	s_cselect_b32 s26, s52, s24
	s_cselect_b32 s25, s13, s55
	s_cselect_b32 s24, s53, s54
	v_lshl_add_u64 v[202:203], s[22:23], 0, v[182:183]
	s_add_i32 m0, s30, 0xc000
	ds_read_b128 v[160:163], v214
	ds_read_b128 v[164:167], v214 offset:1024
	ds_read_b128 v[168:171], v214 offset:2048
	ds_read_b128 v[172:175], v214 offset:3072
	ds_read_b128 v[190:193], v214 offset:4096
	ds_read_b128 v[194:197], v214 offset:5120
	ds_read_b128 v[198:201], v214 offset:6144
	ds_read_b128 v[216:219], v214 offset:7168
	global_load_lds_dwordx4 v[202:203], off
	v_lshl_add_u64 v[202:203], s[22:23], 0, v[184:185]
	s_add_i32 m0, s30, 0xe000
	s_nop 0
	global_load_lds_dwordx4 v[202:203], off
	s_waitcnt vmcnt(8)
	s_waitcnt lgkmcnt(0)
	s_barrier
	s_setprio 1
	v_mfma_f32_16x16x32_bf16 v[124:127], v[128:131], v[160:163], v[124:127]
	v_mfma_f32_16x16x32_bf16 v[120:123], v[136:139], v[160:163], v[120:123]
	v_mfma_f32_16x16x32_bf16 v[112:115], v[128:131], v[168:171], v[112:115]
	v_mfma_f32_16x16x32_bf16 v[104:107], v[136:139], v[168:171], v[104:107]
	v_mfma_f32_16x16x32_bf16 v[96:99], v[128:131], v[190:193], v[96:99]
	v_mfma_f32_16x16x32_bf16 v[88:91], v[136:139], v[190:193], v[88:91]
	v_mfma_f32_16x16x32_bf16 v[84:87], v[128:131], v[198:201], v[84:87]
	v_mfma_f32_16x16x32_bf16 v[76:79], v[136:139], v[198:201], v[76:79]
	v_mfma_f32_16x16x32_bf16 v[124:127], v[132:135], v[164:167], v[124:127]
	v_mfma_f32_16x16x32_bf16 v[120:123], v[140:143], v[164:167], v[120:123]
	v_mfma_f32_16x16x32_bf16 v[112:115], v[132:135], v[172:175], v[112:115]
	v_mfma_f32_16x16x32_bf16 v[104:107], v[140:143], v[172:175], v[104:107]
	v_mfma_f32_16x16x32_bf16 v[96:99], v[132:135], v[194:197], v[96:99]
	v_mfma_f32_16x16x32_bf16 v[88:91], v[140:143], v[194:197], v[88:91]
	v_mfma_f32_16x16x32_bf16 v[84:87], v[132:135], v[216:219], v[84:87]
	v_mfma_f32_16x16x32_bf16 v[76:79], v[140:143], v[216:219], v[76:79]
	s_setprio 0
	s_setprio 1
	v_mfma_f32_16x16x32_bf16 v[116:119], v[144:147], v[160:163], v[116:119]
	v_mfma_f32_16x16x32_bf16 v[108:111], v[152:155], v[160:163], v[108:111]
	v_mfma_f32_16x16x32_bf16 v[100:103], v[144:147], v[168:171], v[100:103]
	v_mfma_f32_16x16x32_bf16 v[92:95], v[152:155], v[168:171], v[92:95]
	v_mfma_f32_16x16x32_bf16 v[80:83], v[144:147], v[190:193], v[80:83]
	v_mfma_f32_16x16x32_bf16 v[72:75], v[152:155], v[190:193], v[72:75]
	v_mfma_f32_16x16x32_bf16 v[68:71], v[144:147], v[198:201], v[68:71]
	v_mfma_f32_16x16x32_bf16 v[64:67], v[152:155], v[198:201], v[64:67]
	v_mfma_f32_16x16x32_bf16 v[116:119], v[148:151], v[164:167], v[116:119]
	v_mfma_f32_16x16x32_bf16 v[108:111], v[156:159], v[164:167], v[108:111]
	v_mfma_f32_16x16x32_bf16 v[100:103], v[148:151], v[172:175], v[100:103]
	v_mfma_f32_16x16x32_bf16 v[92:95], v[156:159], v[172:175], v[92:95]
	v_mfma_f32_16x16x32_bf16 v[80:83], v[148:151], v[194:197], v[80:83]
	v_mfma_f32_16x16x32_bf16 v[72:75], v[156:159], v[194:197], v[72:75]
	v_mfma_f32_16x16x32_bf16 v[68:71], v[148:151], v[216:219], v[68:71]
	v_mfma_f32_16x16x32_bf16 v[64:67], v[156:159], v[216:219], v[64:67]
	s_setprio 0
	s_barrier
	s_add_i32 s57, s45, s29
	v_lshl_add_u64 v[202:203], s[24:25], 0, v[176:177]
	s_mov_b32 m0, s57
	ds_read_b128 v[160:163], v214 offset:16384
	ds_read_b128 v[164:167], v214 offset:17408
	ds_read_b128 v[168:171], v214 offset:18432
	ds_read_b128 v[172:175], v214 offset:19456
	ds_read_b128 v[190:193], v214 offset:20480
	ds_read_b128 v[194:197], v214 offset:21504
	ds_read_b128 v[198:201], v214 offset:22528
	ds_read_b128 v[216:219], v214 offset:23552
	global_load_lds_dwordx4 v[202:203], off
	s_add_i32 m0, s57, 0x2000
	s_add_u32 s58, s24, 0x40000
	v_lshl_add_u64 v[220:221], s[24:25], 0, v[178:179]
	s_addc_u32 s59, s25, 0
	s_add_i32 s57, s46, s29
	global_load_lds_dwordx4 v[220:221], off
	v_lshl_add_u64 v[222:223], s[58:59], 0, v[176:177]
	s_mov_b32 m0, s57
	v_lshl_add_u64 v[224:225], s[26:27], 0, v[178:179]
	global_load_lds_dwordx4 v[222:223], off
	v_lshl_add_u64 v[222:223], s[58:59], 0, v[178:179]
	s_add_i32 m0, s57, 0x2000
	s_nop 0
	global_load_lds_dwordx4 v[222:223], off
	v_lshl_add_u64 v[222:223], s[26:27], 0, v[176:177]
	s_mov_b32 m0, s30
	s_nop 0
	global_load_lds_dwordx4 v[222:223], off
	s_mov_b32 m0, s31
	s_nop 0
	global_load_lds_dwordx4 v[224:225], off
	s_waitcnt vmcnt(8)
	s_waitcnt lgkmcnt(0)
	s_barrier
	s_setprio 1
	v_mfma_f32_16x16x32_bf16 v[60:63], v[128:131], v[160:163], v[60:63]
	v_mfma_f32_16x16x32_bf16 v[56:59], v[136:139], v[160:163], v[56:59]
	v_mfma_f32_16x16x32_bf16 v[48:51], v[128:131], v[168:171], v[48:51]
	v_mfma_f32_16x16x32_bf16 v[40:43], v[136:139], v[168:171], v[40:43]
	v_mfma_f32_16x16x32_bf16 v[32:35], v[128:131], v[190:193], v[32:35]
	v_mfma_f32_16x16x32_bf16 v[24:27], v[136:139], v[190:193], v[24:27]
	v_mfma_f32_16x16x32_bf16 v[20:23], v[128:131], v[198:201], v[20:23]
	v_mfma_f32_16x16x32_bf16 v[12:15], v[136:139], v[198:201], v[12:15]
	v_mfma_f32_16x16x32_bf16 v[60:63], v[132:135], v[164:167], v[60:63]
	v_mfma_f32_16x16x32_bf16 v[56:59], v[140:143], v[164:167], v[56:59]
	v_mfma_f32_16x16x32_bf16 v[48:51], v[132:135], v[172:175], v[48:51]
	v_mfma_f32_16x16x32_bf16 v[40:43], v[140:143], v[172:175], v[40:43]
	v_mfma_f32_16x16x32_bf16 v[32:35], v[132:135], v[194:197], v[32:35]
	v_mfma_f32_16x16x32_bf16 v[24:27], v[140:143], v[194:197], v[24:27]
	v_mfma_f32_16x16x32_bf16 v[20:23], v[132:135], v[216:219], v[20:23]
	v_mfma_f32_16x16x32_bf16 v[12:15], v[140:143], v[216:219], v[12:15]
	s_setprio 0
	s_setprio 1
	v_mfma_f32_16x16x32_bf16 v[52:55], v[144:147], v[160:163], v[52:55]
	v_mfma_f32_16x16x32_bf16 v[44:47], v[152:155], v[160:163], v[44:47]
	v_mfma_f32_16x16x32_bf16 v[36:39], v[144:147], v[168:171], v[36:39]
	v_mfma_f32_16x16x32_bf16 v[28:31], v[152:155], v[168:171], v[28:31]
	v_mfma_f32_16x16x32_bf16 v[16:19], v[144:147], v[190:193], v[16:19]
	v_mfma_f32_16x16x32_bf16 v[8:11], v[152:155], v[190:193], v[8:11]
	v_mfma_f32_16x16x32_bf16 v[4:7], v[144:147], v[198:201], v[4:7]
	v_mfma_f32_16x16x32_bf16 v[0:3], v[152:155], v[198:201], v[0:3]
	v_mfma_f32_16x16x32_bf16 v[52:55], v[148:151], v[164:167], v[52:55]
	v_mfma_f32_16x16x32_bf16 v[44:47], v[156:159], v[164:167], v[44:47]
	v_mfma_f32_16x16x32_bf16 v[36:39], v[148:151], v[172:175], v[36:39]
	v_mfma_f32_16x16x32_bf16 v[28:31], v[156:159], v[172:175], v[28:31]
	v_mfma_f32_16x16x32_bf16 v[16:19], v[148:151], v[194:197], v[16:19]
	v_mfma_f32_16x16x32_bf16 v[8:11], v[156:159], v[194:197], v[8:11]
	v_mfma_f32_16x16x32_bf16 v[4:7], v[148:151], v[216:219], v[4:7]
	v_mfma_f32_16x16x32_bf16 v[0:3], v[156:159], v[216:219], v[0:3]
	s_setprio 0
	s_barrier
	s_add_i32 s57, 0, 0x18000
	s_add_i32 s58, 0, 0x1c000
	v_add_u32_e32 v140, s57, v210
	v_add_u32_e32 v156, s58, v210
	ds_read_b128 v[128:131], v140
	ds_read_b128 v[132:135], v140 offset:1024
	ds_read_b128 v[136:139], v140 offset:2048
	ds_read_b128 v[140:143], v140 offset:3072
	ds_read_b128 v[144:147], v156
	ds_read_b128 v[148:151], v156 offset:1024
	ds_read_b128 v[152:155], v156 offset:2048
	ds_read_b128 v[156:159], v156 offset:3072
	s_add_u32 s26, s26, 0x40000
	s_addc_u32 s27, s27, 0
	s_mov_b32 m0, s34
	v_lshl_add_u64 v[226:227], s[26:27], 0, v[176:177]
	ds_read_b128 v[160:163], v214 offset:32768
	ds_read_b128 v[164:167], v214 offset:33792
	ds_read_b128 v[168:171], v214 offset:34816
	ds_read_b128 v[172:175], v214 offset:35840
	ds_read_b128 v[190:193], v214 offset:36864
	ds_read_b128 v[194:197], v214 offset:37888
	ds_read_b128 v[198:201], v214 offset:38912
	ds_read_b128 v[216:219], v214 offset:39936
	global_load_lds_dwordx4 v[226:227], off
	v_lshl_add_u64 v[226:227], s[26:27], 0, v[178:179]
	s_mov_b32 m0, s35
	s_nop 0
	global_load_lds_dwordx4 v[226:227], off
	s_waitcnt vmcnt(8)
	s_waitcnt lgkmcnt(0)
	s_barrier
	s_setprio 1
	v_mfma_f32_16x16x32_bf16 v[124:127], v[128:131], v[160:163], v[124:127]
	v_mfma_f32_16x16x32_bf16 v[120:123], v[136:139], v[160:163], v[120:123]
	v_mfma_f32_16x16x32_bf16 v[112:115], v[128:131], v[168:171], v[112:115]
	v_mfma_f32_16x16x32_bf16 v[104:107], v[136:139], v[168:171], v[104:107]
	v_mfma_f32_16x16x32_bf16 v[96:99], v[128:131], v[190:193], v[96:99]
	v_mfma_f32_16x16x32_bf16 v[88:91], v[136:139], v[190:193], v[88:91]
	v_mfma_f32_16x16x32_bf16 v[84:87], v[128:131], v[198:201], v[84:87]
	v_mfma_f32_16x16x32_bf16 v[76:79], v[136:139], v[198:201], v[76:79]
	v_mfma_f32_16x16x32_bf16 v[124:127], v[132:135], v[164:167], v[124:127]
	v_mfma_f32_16x16x32_bf16 v[120:123], v[140:143], v[164:167], v[120:123]
	v_mfma_f32_16x16x32_bf16 v[112:115], v[132:135], v[172:175], v[112:115]
	v_mfma_f32_16x16x32_bf16 v[104:107], v[140:143], v[172:175], v[104:107]
	v_mfma_f32_16x16x32_bf16 v[96:99], v[132:135], v[194:197], v[96:99]
	v_mfma_f32_16x16x32_bf16 v[88:91], v[140:143], v[194:197], v[88:91]
	v_mfma_f32_16x16x32_bf16 v[84:87], v[132:135], v[216:219], v[84:87]
	v_mfma_f32_16x16x32_bf16 v[76:79], v[140:143], v[216:219], v[76:79]
	s_setprio 0
	s_setprio 1
	v_mfma_f32_16x16x32_bf16 v[116:119], v[144:147], v[160:163], v[116:119]
	v_mfma_f32_16x16x32_bf16 v[108:111], v[152:155], v[160:163], v[108:111]
	v_mfma_f32_16x16x32_bf16 v[100:103], v[144:147], v[168:171], v[100:103]
	v_mfma_f32_16x16x32_bf16 v[92:95], v[152:155], v[168:171], v[92:95]
	v_mfma_f32_16x16x32_bf16 v[80:83], v[144:147], v[190:193], v[80:83]
	v_mfma_f32_16x16x32_bf16 v[72:75], v[152:155], v[190:193], v[72:75]
	v_mfma_f32_16x16x32_bf16 v[68:71], v[144:147], v[198:201], v[68:71]
	v_mfma_f32_16x16x32_bf16 v[64:67], v[152:155], v[198:201], v[64:67]
	v_mfma_f32_16x16x32_bf16 v[116:119], v[148:151], v[164:167], v[116:119]
	v_mfma_f32_16x16x32_bf16 v[108:111], v[156:159], v[164:167], v[108:111]
	v_mfma_f32_16x16x32_bf16 v[100:103], v[148:151], v[172:175], v[100:103]
	v_mfma_f32_16x16x32_bf16 v[92:95], v[156:159], v[172:175], v[92:95]
	v_mfma_f32_16x16x32_bf16 v[80:83], v[148:151], v[194:197], v[80:83]
	v_mfma_f32_16x16x32_bf16 v[72:75], v[156:159], v[194:197], v[72:75]
	v_mfma_f32_16x16x32_bf16 v[68:71], v[148:151], v[216:219], v[68:71]
	v_mfma_f32_16x16x32_bf16 v[64:67], v[156:159], v[216:219], v[64:67]
	s_setprio 0
	s_barrier
	s_add_i32 s26, s57, s29
	v_lshl_add_u64 v[202:203], v[202:203], 0, s[8:9]
	s_mov_b32 m0, s26
	ds_read_b128 v[160:163], v214 offset:49152
	ds_read_b128 v[164:167], v214 offset:50176
	ds_read_b128 v[168:171], v214 offset:51200
	ds_read_b128 v[172:175], v214 offset:52224
	ds_read_b128 v[190:193], v214 offset:53248
	ds_read_b128 v[194:197], v214 offset:54272
	ds_read_b128 v[198:201], v214 offset:55296
	ds_read_b128 v[216:219], v214 offset:56320
	global_load_lds_dwordx4 v[202:203], off
	s_add_i32 m0, s26, 0x2000
	s_add_u32 s24, s24, 0x40080
	v_lshl_add_u64 v[202:203], v[220:221], 0, s[8:9]
	s_addc_u32 s25, s25, 0
	s_add_i32 s26, s58, s29
	global_load_lds_dwordx4 v[202:203], off
	v_lshl_add_u64 v[202:203], s[24:25], 0, v[176:177]
	s_mov_b32 m0, s26
	s_nop 0
	global_load_lds_dwordx4 v[202:203], off
	v_lshl_add_u64 v[202:203], s[24:25], 0, v[178:179]
	s_add_i32 m0, s26, 0x2000
	s_nop 0
	global_load_lds_dwordx4 v[202:203], off
	v_lshl_add_u64 v[202:203], v[222:223], 0, s[8:9]
	s_mov_b32 m0, s42
	s_nop 0
	global_load_lds_dwordx4 v[202:203], off
	v_lshl_add_u64 v[202:203], v[224:225], 0, s[8:9]
	s_mov_b32 m0, s43
	s_nop 0
	global_load_lds_dwordx4 v[202:203], off
	s_waitcnt vmcnt(8)
	s_waitcnt lgkmcnt(0)
	s_barrier
	s_setprio 1
	v_mfma_f32_16x16x32_bf16 v[60:63], v[128:131], v[160:163], v[60:63]
	v_mfma_f32_16x16x32_bf16 v[56:59], v[136:139], v[160:163], v[56:59]
	v_mfma_f32_16x16x32_bf16 v[48:51], v[128:131], v[168:171], v[48:51]
	v_mfma_f32_16x16x32_bf16 v[40:43], v[136:139], v[168:171], v[40:43]
	v_mfma_f32_16x16x32_bf16 v[32:35], v[128:131], v[190:193], v[32:35]
	v_mfma_f32_16x16x32_bf16 v[24:27], v[136:139], v[190:193], v[24:27]
	v_mfma_f32_16x16x32_bf16 v[20:23], v[128:131], v[198:201], v[20:23]
	v_mfma_f32_16x16x32_bf16 v[12:15], v[136:139], v[198:201], v[12:15]
	v_mfma_f32_16x16x32_bf16 v[60:63], v[132:135], v[164:167], v[60:63]
	v_mfma_f32_16x16x32_bf16 v[56:59], v[140:143], v[164:167], v[56:59]
	v_mfma_f32_16x16x32_bf16 v[48:51], v[132:135], v[172:175], v[48:51]
	v_mfma_f32_16x16x32_bf16 v[40:43], v[140:143], v[172:175], v[40:43]
	v_mfma_f32_16x16x32_bf16 v[32:35], v[132:135], v[194:197], v[32:35]
	v_mfma_f32_16x16x32_bf16 v[24:27], v[140:143], v[194:197], v[24:27]
	v_mfma_f32_16x16x32_bf16 v[20:23], v[132:135], v[216:219], v[20:23]
	v_mfma_f32_16x16x32_bf16 v[12:15], v[140:143], v[216:219], v[12:15]
	s_setprio 0
	s_setprio 1
	v_mfma_f32_16x16x32_bf16 v[52:55], v[144:147], v[160:163], v[52:55]
	v_mfma_f32_16x16x32_bf16 v[44:47], v[152:155], v[160:163], v[44:47]
	v_mfma_f32_16x16x32_bf16 v[36:39], v[144:147], v[168:171], v[36:39]
	v_mfma_f32_16x16x32_bf16 v[28:31], v[152:155], v[168:171], v[28:31]
	v_mfma_f32_16x16x32_bf16 v[16:19], v[144:147], v[190:193], v[16:19]
	v_mfma_f32_16x16x32_bf16 v[8:11], v[152:155], v[190:193], v[8:11]
	v_mfma_f32_16x16x32_bf16 v[4:7], v[144:147], v[198:201], v[4:7]
	v_mfma_f32_16x16x32_bf16 v[0:3], v[152:155], v[198:201], v[0:3]
	v_mfma_f32_16x16x32_bf16 v[52:55], v[148:151], v[164:167], v[52:55]
	v_mfma_f32_16x16x32_bf16 v[44:47], v[156:159], v[164:167], v[44:47]
	v_mfma_f32_16x16x32_bf16 v[36:39], v[148:151], v[172:175], v[36:39]
	v_mfma_f32_16x16x32_bf16 v[28:31], v[156:159], v[172:175], v[28:31]
	v_mfma_f32_16x16x32_bf16 v[16:19], v[148:151], v[194:197], v[16:19]
	v_mfma_f32_16x16x32_bf16 v[8:11], v[156:159], v[194:197], v[8:11]
	v_mfma_f32_16x16x32_bf16 v[4:7], v[148:151], v[216:219], v[4:7]
	v_mfma_f32_16x16x32_bf16 v[0:3], v[156:159], v[216:219], v[0:3]
	s_setprio 0
	s_barrier
	s_add_i32 s56, s56, 2
	s_add_u32 s22, s22, 0x100
	s_addc_u32 s23, s23, 0
	s_add_u32 s54, s54, 0x100
	s_addc_u32 s55, s55, 0
	s_cmp_gt_u32 s56, 13
	s_cbranch_scc0 .LBB0_2240
	s_and_b64 vcc, exec, s[10:11]
	s_cbranch_vccz .LBB0_2243
	s_barrier

.LBB0_2263:
	s_ashr_i32 s19, s18, 31
	s_lshl_b64 s[22:23], s[18:19], 19
	s_add_u32 s19, s36, s22
	s_addc_u32 s21, s37, s23
	s_ashr_i32 s66, s65, 31
	ds_read_b128 v[0:3], v130
	ds_read_b128 v[4:7], v130 offset:1024
	ds_read_b128 v[8:11], v130 offset:2048
	ds_read_b128 v[12:15], v130 offset:3072
	ds_read_b128 v[16:19], v131
	ds_read_b128 v[20:23], v131 offset:1024
	ds_read_b128 v[24:27], v131 offset:2048
	ds_read_b128 v[28:31], v131 offset:3072
	s_add_u32 s22, s19, s65
	s_addc_u32 s23, s21, s66
	s_and_b64 s[26:27], s[24:25], exec
	s_cselect_b32 s35, s23, s31
	s_cselect_b32 s34, s22, s30
	s_ashr_i32 s21, s20, 31
	s_lshl_b64 s[26:27], s[20:21], 19
	s_add_u32 s19, s38, s26
	s_addc_u32 s21, s39, s27
	s_add_u32 s26, s19, s65
	s_addc_u32 s27, s21, s66
	s_and_b64 s[66:67], s[24:25], exec
	s_cselect_b32 s29, s27, s29
	s_cselect_b32 s28, s26, s28
	s_add_u32 s30, s30, 0x40080
	s_addc_u32 s31, s31, 0
	s_mov_b32 m0, s52
	v_lshl_add_u64 v[64:65], s[30:31], 0, v[176:177]
	ds_read_b128 v[32:35], v132
	ds_read_b128 v[36:39], v132 offset:1024
	ds_read_b128 v[40:43], v132 offset:2048
	ds_read_b128 v[44:47], v132 offset:3072
	ds_read_b128 v[48:51], v132 offset:4096
	ds_read_b128 v[52:55], v132 offset:5120
	ds_read_b128 v[56:59], v132 offset:6144
	ds_read_b128 v[60:63], v132 offset:7168
	global_load_lds_dwordx4 v[64:65], off
	v_lshl_add_u64 v[64:65], s[30:31], 0, v[178:179]
	s_mov_b32 m0, s53
	s_nop 0
	global_load_lds_dwordx4 v[64:65], off
	s_waitcnt vmcnt(8)
	s_waitcnt lgkmcnt(0)
	s_barrier
	s_setprio 1
	v_mfma_f32_16x16x32_bf16 v[64:67], v[0:3], v[32:35], 0
	v_mfma_f32_16x16x32_bf16 v[68:71], v[8:11], v[32:35], 0
	v_mfma_f32_16x16x32_bf16 v[72:75], v[0:3], v[40:43], 0
	v_mfma_f32_16x16x32_bf16 v[76:79], v[8:11], v[40:43], 0
	v_mfma_f32_16x16x32_bf16 v[80:83], v[0:3], v[48:51], 0
	v_mfma_f32_16x16x32_bf16 v[84:87], v[8:11], v[48:51], 0
	v_mfma_f32_16x16x32_bf16 v[88:91], v[0:3], v[56:59], 0
	v_mfma_f32_16x16x32_bf16 v[92:95], v[8:11], v[56:59], 0
	v_mfma_f32_16x16x32_bf16 v[64:67], v[4:7], v[36:39], v[64:67]
	v_mfma_f32_16x16x32_bf16 v[68:71], v[12:15], v[36:39], v[68:71]
	v_mfma_f32_16x16x32_bf16 v[72:75], v[4:7], v[44:47], v[72:75]
	v_mfma_f32_16x16x32_bf16 v[76:79], v[12:15], v[44:47], v[76:79]
	v_mfma_f32_16x16x32_bf16 v[80:83], v[4:7], v[52:55], v[80:83]
	v_mfma_f32_16x16x32_bf16 v[84:87], v[12:15], v[52:55], v[84:87]
	v_mfma_f32_16x16x32_bf16 v[88:91], v[4:7], v[60:63], v[88:91]
	v_mfma_f32_16x16x32_bf16 v[92:95], v[12:15], v[60:63], v[92:95]
	s_setprio 0
	s_setprio 1
	v_mfma_f32_16x16x32_bf16 v[96:99], v[16:19], v[32:35], 0
	v_mfma_f32_16x16x32_bf16 v[32:35], v[24:27], v[32:35], 0
	v_mfma_f32_16x16x32_bf16 v[96:99], v[20:23], v[36:39], v[96:99]
	v_mfma_f32_16x16x32_bf16 v[32:35], v[28:31], v[36:39], v[32:35]
	v_mfma_f32_16x16x32_bf16 v[36:39], v[16:19], v[40:43], 0
	v_mfma_f32_16x16x32_bf16 v[40:43], v[24:27], v[40:43], 0
	v_mfma_f32_16x16x32_bf16 v[36:39], v[20:23], v[44:47], v[36:39]
	v_mfma_f32_16x16x32_bf16 v[40:43], v[28:31], v[44:47], v[40:43]
	v_mfma_f32_16x16x32_bf16 v[44:47], v[16:19], v[48:51], 0
	v_mfma_f32_16x16x32_bf16 v[48:51], v[24:27], v[48:51], 0
	v_mfma_f32_16x16x32_bf16 v[100:103], v[28:31], v[52:55], v[48:51]
	v_mfma_f32_16x16x32_bf16 v[48:51], v[16:19], v[56:59], 0
	v_mfma_f32_16x16x32_bf16 v[104:107], v[20:23], v[60:63], v[48:51]
	v_mfma_f32_16x16x32_bf16 v[48:51], v[24:27], v[56:59], 0
	v_mfma_f32_16x16x32_bf16 v[44:47], v[20:23], v[52:55], v[44:47]
	v_mfma_f32_16x16x32_bf16 v[108:111], v[28:31], v[60:63], v[48:51]
	s_setprio 0
	s_barrier
	s_mov_b32 m0, s54
	v_lshl_add_u64 v[246:247], s[28:29], 0, v[176:177]
	s_add_u32 s30, s28, 0x40000
	s_nop 0
	ds_read_b128 v[48:51], v132 offset:16384
	ds_read_b128 v[52:55], v132 offset:17408
	ds_read_b128 v[56:59], v132 offset:18432
	ds_read_b128 v[60:63], v132 offset:19456
	ds_read_b128 v[112:115], v132 offset:20480
	ds_read_b128 v[116:119], v132 offset:21504
	ds_read_b128 v[120:123], v132 offset:22528
	ds_read_b128 v[124:127], v132 offset:23552
	global_load_lds_dwordx4 v[246:247], off
	v_lshl_add_u64 v[248:249], s[28:29], 0, v[178:179]
	s_mov_b32 m0, s55
	s_addc_u32 s31, s29, 0
	global_load_lds_dwordx4 v[248:249], off
	v_lshl_add_u64 v[136:137], s[30:31], 0, v[176:177]
	s_mov_b32 m0, s56
	v_lshl_add_u64 v[250:251], s[34:35], 0, v[176:177]
	global_load_lds_dwordx4 v[136:137], off
	v_lshl_add_u64 v[136:137], s[30:31], 0, v[178:179]
	s_mov_b32 m0, s57
	v_lshl_add_u64 v[252:253], s[34:35], 0, v[178:179]
	global_load_lds_dwordx4 v[136:137], off
	s_mov_b32 m0, s40
	s_nop 0
	global_load_lds_dwordx4 v[250:251], off
	s_mov_b32 m0, s41
	s_nop 0
	global_load_lds_dwordx4 v[252:253], off
	s_waitcnt vmcnt(8)
	s_waitcnt lgkmcnt(0)
	s_barrier
	s_setprio 1
	v_mfma_f32_16x16x32_bf16 v[136:139], v[0:3], v[48:51], 0
	v_mfma_f32_16x16x32_bf16 v[144:147], v[0:3], v[56:59], 0
	v_mfma_f32_16x16x32_bf16 v[152:155], v[0:3], v[112:115], 0
	v_mfma_f32_16x16x32_bf16 v[0:3], v[0:3], v[120:123], 0
	v_mfma_f32_16x16x32_bf16 v[140:143], v[8:11], v[48:51], 0
	v_mfma_f32_16x16x32_bf16 v[148:151], v[8:11], v[56:59], 0
	v_mfma_f32_16x16x32_bf16 v[156:159], v[8:11], v[112:115], 0
	v_mfma_f32_16x16x32_bf16 v[160:163], v[4:7], v[124:127], v[0:3]
	v_mfma_f32_16x16x32_bf16 v[0:3], v[8:11], v[120:123], 0
	v_mfma_f32_16x16x32_bf16 v[136:139], v[4:7], v[52:55], v[136:139]
	v_mfma_f32_16x16x32_bf16 v[140:143], v[12:15], v[52:55], v[140:143]
	v_mfma_f32_16x16x32_bf16 v[144:147], v[4:7], v[60:63], v[144:147]
	v_mfma_f32_16x16x32_bf16 v[148:151], v[12:15], v[60:63], v[148:151]
	v_mfma_f32_16x16x32_bf16 v[152:155], v[4:7], v[116:119], v[152:155]
	v_mfma_f32_16x16x32_bf16 v[156:159], v[12:15], v[116:119], v[156:159]
	v_mfma_f32_16x16x32_bf16 v[164:167], v[12:15], v[124:127], v[0:3]
	s_setprio 0
	s_setprio 1
	v_mfma_f32_16x16x32_bf16 v[0:3], v[16:19], v[48:51], 0
	v_mfma_f32_16x16x32_bf16 v[168:171], v[20:23], v[52:55], v[0:3]
	v_mfma_f32_16x16x32_bf16 v[0:3], v[24:27], v[48:51], 0
	v_mfma_f32_16x16x32_bf16 v[172:175], v[28:31], v[52:55], v[0:3]
	v_mfma_f32_16x16x32_bf16 v[0:3], v[16:19], v[56:59], 0
	v_mfma_f32_16x16x32_bf16 v[180:183], v[20:23], v[60:63], v[0:3]
	v_mfma_f32_16x16x32_bf16 v[0:3], v[24:27], v[56:59], 0
	v_mfma_f32_16x16x32_bf16 v[184:187], v[28:31], v[60:63], v[0:3]
	v_mfma_f32_16x16x32_bf16 v[0:3], v[16:19], v[112:115], 0
	v_mfma_f32_16x16x32_bf16 v[188:191], v[20:23], v[116:119], v[0:3]
	v_mfma_f32_16x16x32_bf16 v[0:3], v[24:27], v[112:115], 0
	v_mfma_f32_16x16x32_bf16 v[192:195], v[28:31], v[116:119], v[0:3]
	v_mfma_f32_16x16x32_bf16 v[0:3], v[16:19], v[120:123], 0
	v_mfma_f32_16x16x32_bf16 v[196:199], v[20:23], v[124:127], v[0:3]
	v_mfma_f32_16x16x32_bf16 v[0:3], v[24:27], v[120:123], 0
	v_mfma_f32_16x16x32_bf16 v[200:203], v[28:31], v[124:127], v[0:3]
	s_setprio 0
	s_barrier
	ds_read_b128 v[112:115], v133
	ds_read_b128 v[116:119], v133 offset:1024
	ds_read_b128 v[120:123], v133 offset:2048
	ds_read_b128 v[124:127], v133 offset:3072
	ds_read_b128 v[206:209], v134
	ds_read_b128 v[210:213], v134 offset:1024
	ds_read_b128 v[214:217], v134 offset:2048
	ds_read_b128 v[218:221], v134 offset:3072
	s_add_u32 s30, s34, 0x40000
	s_addc_u32 s31, s35, 0
	s_mov_b32 m0, s42
	v_lshl_add_u64 v[0:1], s[30:31], 0, v[176:177]
	ds_read_b128 v[48:51], v132 offset:32768
	ds_read_b128 v[52:55], v132 offset:33792
	ds_read_b128 v[222:225], v132 offset:34816
	ds_read_b128 v[226:229], v132 offset:35840
	ds_read_b128 v[230:233], v132 offset:36864
	ds_read_b128 v[234:237], v132 offset:37888
	ds_read_b128 v[238:241], v132 offset:38912
	ds_read_b128 v[242:245], v132 offset:39936
	global_load_lds_dwordx4 v[0:1], off
	v_lshl_add_u64 v[0:1], s[30:31], 0, v[178:179]
	s_mov_b32 m0, s43
	s_nop 0
	global_load_lds_dwordx4 v[0:1], off
	s_waitcnt vmcnt(8)
	s_waitcnt lgkmcnt(0)
	s_barrier
	s_setprio 1
	v_mfma_f32_16x16x32_bf16 v[0:3], v[112:115], v[48:51], v[64:67]
	v_mfma_f32_16x16x32_bf16 v[24:27], v[116:119], v[52:55], v[0:3]
	v_mfma_f32_16x16x32_bf16 v[0:3], v[120:123], v[48:51], v[68:71]
	v_mfma_f32_16x16x32_bf16 v[28:31], v[124:127], v[52:55], v[0:3]
	v_mfma_f32_16x16x32_bf16 v[0:3], v[112:115], v[222:225], v[72:75]
	v_mfma_f32_16x16x32_bf16 v[16:19], v[116:119], v[226:229], v[0:3]
	v_mfma_f32_16x16x32_bf16 v[0:3], v[120:123], v[222:225], v[76:79]
	v_mfma_f32_16x16x32_bf16 v[20:23], v[124:127], v[226:229], v[0:3]
	v_mfma_f32_16x16x32_bf16 v[0:3], v[112:115], v[230:233], v[80:83]
	v_mfma_f32_16x16x32_bf16 v[8:11], v[116:119], v[234:237], v[0:3]
	v_mfma_f32_16x16x32_bf16 v[0:3], v[120:123], v[230:233], v[84:87]
	v_mfma_f32_16x16x32_bf16 v[12:15], v[124:127], v[234:237], v[0:3]
	v_mfma_f32_16x16x32_bf16 v[0:3], v[112:115], v[238:241], v[88:91]
	v_mfma_f32_16x16x32_bf16 v[4:7], v[120:123], v[238:241], v[92:95]
	v_mfma_f32_16x16x32_bf16 v[0:3], v[116:119], v[242:245], v[0:3]
	v_mfma_f32_16x16x32_bf16 v[4:7], v[124:127], v[242:245], v[4:7]
	s_setprio 0
	s_setprio 1
	v_mfma_f32_16x16x32_bf16 v[32:35], v[214:217], v[48:51], v[32:35]
	v_mfma_f32_16x16x32_bf16 v[60:63], v[218:221], v[52:55], v[32:35]
	v_mfma_f32_16x16x32_bf16 v[32:35], v[206:209], v[222:225], v[36:39]
	v_mfma_f32_16x16x32_bf16 v[56:59], v[206:209], v[48:51], v[96:99]
	v_mfma_f32_16x16x32_bf16 v[48:51], v[210:213], v[226:229], v[32:35]
	v_mfma_f32_16x16x32_bf16 v[32:35], v[214:217], v[222:225], v[40:43]
	v_mfma_f32_16x16x32_bf16 v[56:59], v[210:213], v[52:55], v[56:59]
	v_mfma_f32_16x16x32_bf16 v[52:55], v[218:221], v[226:229], v[32:35]
	v_mfma_f32_16x16x32_bf16 v[32:35], v[206:209], v[230:233], v[44:47]
	v_mfma_f32_16x16x32_bf16 v[40:43], v[210:213], v[234:237], v[32:35]
	v_mfma_f32_16x16x32_bf16 v[32:35], v[214:217], v[230:233], v[100:103]
	v_mfma_f32_16x16x32_bf16 v[44:47], v[218:221], v[234:237], v[32:35]
	v_mfma_f32_16x16x32_bf16 v[32:35], v[206:209], v[238:241], v[104:107]
	v_mfma_f32_16x16x32_bf16 v[36:39], v[214:217], v[238:241], v[108:111]
	v_mfma_f32_16x16x32_bf16 v[32:35], v[210:213], v[242:245], v[32:35]
	v_mfma_f32_16x16x32_bf16 v[36:39], v[218:221], v[242:245], v[36:39]
	s_setprio 0
	s_barrier
	s_mov_b32 m0, s61
	v_lshl_add_u64 v[64:65], v[246:247], 0, s[8:9]
	s_add_u32 s28, s28, 0x40080
	ds_read_b128 v[88:91], v132 offset:49152
	ds_read_b128 v[96:99], v132 offset:50176
	ds_read_b128 v[104:107], v132 offset:51200
	ds_read_b128 v[108:111], v132 offset:52224
	ds_read_b128 v[222:225], v132 offset:53248
	ds_read_b128 v[226:229], v132 offset:54272
	ds_read_b128 v[230:233], v132 offset:55296
	ds_read_b128 v[234:237], v132 offset:56320
	global_load_lds_dwordx4 v[64:65], off
	v_lshl_add_u64 v[64:65], v[248:249], 0, s[8:9]
	s_mov_b32 m0, s62
	s_addc_u32 s29, s29, 0
	global_load_lds_dwordx4 v[64:65], off
	v_lshl_add_u64 v[64:65], s[28:29], 0, v[176:177]
	s_mov_b32 m0, s63
	s_nop 0
	global_load_lds_dwordx4 v[64:65], off
	v_lshl_add_u64 v[64:65], s[28:29], 0, v[178:179]
	s_mov_b32 m0, s64
	s_nop 0
	global_load_lds_dwordx4 v[64:65], off
	v_lshl_add_u64 v[64:65], v[250:251], 0, s[8:9]
	s_mov_b32 m0, s44
	s_nop 0
	global_load_lds_dwordx4 v[64:65], off
	v_lshl_add_u64 v[64:65], v[252:253], 0, s[8:9]
	s_mov_b32 m0, s45
	s_nop 0
	global_load_lds_dwordx4 v[64:65], off
	s_waitcnt vmcnt(8)
	s_waitcnt lgkmcnt(0)
	s_barrier
	s_setprio 1
	v_mfma_f32_16x16x32_bf16 v[64:67], v[112:115], v[88:91], v[136:139]
	v_mfma_f32_16x16x32_bf16 v[92:95], v[116:119], v[96:99], v[64:67]
	v_mfma_f32_16x16x32_bf16 v[64:67], v[120:123], v[88:91], v[140:143]
	v_mfma_f32_16x16x32_bf16 v[100:103], v[124:127], v[96:99], v[64:67]
	v_mfma_f32_16x16x32_bf16 v[64:67], v[112:115], v[104:107], v[144:147]
	v_mfma_f32_16x16x32_bf16 v[80:83], v[116:119], v[108:111], v[64:67]
	v_mfma_f32_16x16x32_bf16 v[64:67], v[120:123], v[104:107], v[148:151]
	v_mfma_f32_16x16x32_bf16 v[84:87], v[124:127], v[108:111], v[64:67]
	v_mfma_f32_16x16x32_bf16 v[64:67], v[112:115], v[222:225], v[152:155]
	v_mfma_f32_16x16x32_bf16 v[72:75], v[116:119], v[226:229], v[64:67]
	v_mfma_f32_16x16x32_bf16 v[64:67], v[120:123], v[222:225], v[156:159]
	v_mfma_f32_16x16x32_bf16 v[76:79], v[124:127], v[226:229], v[64:67]
	v_mfma_f32_16x16x32_bf16 v[64:67], v[112:115], v[230:233], v[160:163]
	v_mfma_f32_16x16x32_bf16 v[68:71], v[120:123], v[230:233], v[164:167]
	v_mfma_f32_16x16x32_bf16 v[64:67], v[116:119], v[234:237], v[64:67]
	v_mfma_f32_16x16x32_bf16 v[68:71], v[124:127], v[234:237], v[68:71]
	s_setprio 0
	s_setprio 1
	v_mfma_f32_16x16x32_bf16 v[112:115], v[206:209], v[88:91], v[168:171]
	v_mfma_f32_16x16x32_bf16 v[88:91], v[214:217], v[88:91], v[172:175]
	v_mfma_f32_16x16x32_bf16 v[124:127], v[218:221], v[96:99], v[88:91]
	v_mfma_f32_16x16x32_bf16 v[88:91], v[206:209], v[104:107], v[180:183]
	v_mfma_f32_16x16x32_bf16 v[120:123], v[210:213], v[96:99], v[112:115]
	v_mfma_f32_16x16x32_bf16 v[112:115], v[210:213], v[108:111], v[88:91]
	v_mfma_f32_16x16x32_bf16 v[88:91], v[214:217], v[104:107], v[184:187]
	v_mfma_f32_16x16x32_bf16 v[116:119], v[218:221], v[108:111], v[88:91]
	v_mfma_f32_16x16x32_bf16 v[88:91], v[206:209], v[222:225], v[188:191]
	v_mfma_f32_16x16x32_bf16 v[104:107], v[210:213], v[226:229], v[88:91]
	v_mfma_f32_16x16x32_bf16 v[88:91], v[214:217], v[222:225], v[192:195]
	v_mfma_f32_16x16x32_bf16 v[108:111], v[218:221], v[226:229], v[88:91]
	v_mfma_f32_16x16x32_bf16 v[88:91], v[206:209], v[230:233], v[196:199]
	v_mfma_f32_16x16x32_bf16 v[96:99], v[214:217], v[230:233], v[200:203]
	v_mfma_f32_16x16x32_bf16 v[88:91], v[210:213], v[234:237], v[88:91]
	v_mfma_f32_16x16x32_bf16 v[96:99], v[218:221], v[234:237], v[96:99]
	s_setprio 0
	s_barrier
	s_and_b64 vcc, exec, s[2:3]
	s_cbranch_vccnz .LBB0_2265
	s_barrier

.Llsb_skip_21:
.LBB0_2476:
	ds_read_b128 v[128:131], v212
	ds_read_b128 v[132:135], v212 offset:1024
	ds_read_b128 v[136:139], v212 offset:2048
	ds_read_b128 v[140:143], v212 offset:3072
	ds_read_b128 v[144:147], v213
	ds_read_b128 v[148:151], v213 offset:1024
	ds_read_b128 v[152:155], v213 offset:2048
	ds_read_b128 v[156:159], v213 offset:3072
	s_add_u32 s18, s16, 0xfff50080
	s_addc_u32 s19, s17, -1
	s_cmp_eq_u32 s52, 40
	s_cselect_b32 s21, s5, s19
	s_cselect_b32 s20, s4, s18
	s_cselect_b32 s19, s15, s51
	s_cselect_b32 s18, s14, s50
	v_lshl_add_u64 v[202:203], s[16:17], 0, v[182:183]
	s_add_i32 m0, s23, 0xc000
	ds_read_b128 v[160:163], v214
	ds_read_b128 v[164:167], v214 offset:1024
	ds_read_b128 v[168:171], v214 offset:2048
	ds_read_b128 v[172:175], v214 offset:3072
	ds_read_b128 v[190:193], v214 offset:4096
	ds_read_b128 v[194:197], v214 offset:5120
	ds_read_b128 v[198:201], v214 offset:6144
	ds_read_b128 v[216:219], v214 offset:7168
	global_load_lds_dwordx4 v[202:203], off
	v_lshl_add_u64 v[202:203], s[16:17], 0, v[184:185]
	s_add_i32 m0, s23, 0xe000
	s_nop 0
	global_load_lds_dwordx4 v[202:203], off
	s_waitcnt vmcnt(8)
	s_waitcnt lgkmcnt(0)
	s_barrier
	s_setprio 1
	v_mfma_f32_16x16x32_bf16 v[124:127], v[128:131], v[160:163], v[124:127]
	v_mfma_f32_16x16x32_bf16 v[120:123], v[136:139], v[160:163], v[120:123]
	v_mfma_f32_16x16x32_bf16 v[112:115], v[128:131], v[168:171], v[112:115]
	v_mfma_f32_16x16x32_bf16 v[104:107], v[136:139], v[168:171], v[104:107]
	v_mfma_f32_16x16x32_bf16 v[96:99], v[128:131], v[190:193], v[96:99]
	v_mfma_f32_16x16x32_bf16 v[88:91], v[136:139], v[190:193], v[88:91]
	v_mfma_f32_16x16x32_bf16 v[84:87], v[128:131], v[198:201], v[84:87]
	v_mfma_f32_16x16x32_bf16 v[76:79], v[136:139], v[198:201], v[76:79]
	v_mfma_f32_16x16x32_bf16 v[124:127], v[132:135], v[164:167], v[124:127]
	v_mfma_f32_16x16x32_bf16 v[120:123], v[140:143], v[164:167], v[120:123]
	v_mfma_f32_16x16x32_bf16 v[112:115], v[132:135], v[172:175], v[112:115]
	v_mfma_f32_16x16x32_bf16 v[104:107], v[140:143], v[172:175], v[104:107]
	v_mfma_f32_16x16x32_bf16 v[96:99], v[132:135], v[194:197], v[96:99]
	v_mfma_f32_16x16x32_bf16 v[88:91], v[140:143], v[194:197], v[88:91]
	v_mfma_f32_16x16x32_bf16 v[84:87], v[132:135], v[216:219], v[84:87]
	v_mfma_f32_16x16x32_bf16 v[76:79], v[140:143], v[216:219], v[76:79]
	s_setprio 0
	s_setprio 1
	v_mfma_f32_16x16x32_bf16 v[116:119], v[144:147], v[160:163], v[116:119]
	v_mfma_f32_16x16x32_bf16 v[108:111], v[152:155], v[160:163], v[108:111]
	v_mfma_f32_16x16x32_bf16 v[100:103], v[144:147], v[168:171], v[100:103]
	v_mfma_f32_16x16x32_bf16 v[92:95], v[152:155], v[168:171], v[92:95]
	v_mfma_f32_16x16x32_bf16 v[80:83], v[144:147], v[190:193], v[80:83]
	v_mfma_f32_16x16x32_bf16 v[72:75], v[152:155], v[190:193], v[72:75]
	v_mfma_f32_16x16x32_bf16 v[68:71], v[144:147], v[198:201], v[68:71]
	v_mfma_f32_16x16x32_bf16 v[64:67], v[152:155], v[198:201], v[64:67]
	v_mfma_f32_16x16x32_bf16 v[116:119], v[148:151], v[164:167], v[116:119]
	v_mfma_f32_16x16x32_bf16 v[108:111], v[156:159], v[164:167], v[108:111]
	v_mfma_f32_16x16x32_bf16 v[100:103], v[148:151], v[172:175], v[100:103]
	v_mfma_f32_16x16x32_bf16 v[92:95], v[156:159], v[172:175], v[92:95]
	v_mfma_f32_16x16x32_bf16 v[80:83], v[148:151], v[194:197], v[80:83]
	v_mfma_f32_16x16x32_bf16 v[72:75], v[156:159], v[194:197], v[72:75]
	v_mfma_f32_16x16x32_bf16 v[68:71], v[148:151], v[216:219], v[68:71]
	v_mfma_f32_16x16x32_bf16 v[64:67], v[156:159], v[216:219], v[64:67]
	s_setprio 0
	s_barrier
	s_add_i32 s53, s35, s22
	v_lshl_add_u64 v[202:203], s[18:19], 0, v[176:177]
	s_mov_b32 m0, s53
	ds_read_b128 v[160:163], v214 offset:16384
	ds_read_b128 v[164:167], v214 offset:17408
	ds_read_b128 v[168:171], v214 offset:18432
	ds_read_b128 v[172:175], v214 offset:19456
	ds_read_b128 v[190:193], v214 offset:20480
	ds_read_b128 v[194:197], v214 offset:21504
	ds_read_b128 v[198:201], v214 offset:22528
	ds_read_b128 v[216:219], v214 offset:23552
	global_load_lds_dwordx4 v[202:203], off
	s_add_i32 m0, s53, 0x2000
	s_add_u32 s54, s18, 0xb0000
	v_lshl_add_u64 v[220:221], s[18:19], 0, v[178:179]
	s_addc_u32 s55, s19, 0
	s_add_i32 s53, s36, s22
	global_load_lds_dwordx4 v[220:221], off
	v_lshl_add_u64 v[222:223], s[54:55], 0, v[176:177]
	s_mov_b32 m0, s53
	v_lshl_add_u64 v[224:225], s[20:21], 0, v[178:179]
	global_load_lds_dwordx4 v[222:223], off
	v_lshl_add_u64 v[222:223], s[54:55], 0, v[178:179]
	s_add_i32 m0, s53, 0x2000
	s_nop 0
	global_load_lds_dwordx4 v[222:223], off
	v_lshl_add_u64 v[222:223], s[20:21], 0, v[176:177]
	s_mov_b32 m0, s23
	s_nop 0
	global_load_lds_dwordx4 v[222:223], off
	s_mov_b32 m0, s24
	s_nop 0
	global_load_lds_dwordx4 v[224:225], off
	s_waitcnt vmcnt(8)
	s_waitcnt lgkmcnt(0)
	s_barrier
	s_setprio 1
	v_mfma_f32_16x16x32_bf16 v[60:63], v[128:131], v[160:163], v[60:63]
	v_mfma_f32_16x16x32_bf16 v[56:59], v[136:139], v[160:163], v[56:59]
	v_mfma_f32_16x16x32_bf16 v[48:51], v[128:131], v[168:171], v[48:51]
	v_mfma_f32_16x16x32_bf16 v[40:43], v[136:139], v[168:171], v[40:43]
	v_mfma_f32_16x16x32_bf16 v[32:35], v[128:131], v[190:193], v[32:35]
	v_mfma_f32_16x16x32_bf16 v[24:27], v[136:139], v[190:193], v[24:27]
	v_mfma_f32_16x16x32_bf16 v[20:23], v[128:131], v[198:201], v[20:23]
	v_mfma_f32_16x16x32_bf16 v[12:15], v[136:139], v[198:201], v[12:15]
	v_mfma_f32_16x16x32_bf16 v[60:63], v[132:135], v[164:167], v[60:63]
	v_mfma_f32_16x16x32_bf16 v[56:59], v[140:143], v[164:167], v[56:59]
	v_mfma_f32_16x16x32_bf16 v[48:51], v[132:135], v[172:175], v[48:51]
	v_mfma_f32_16x16x32_bf16 v[40:43], v[140:143], v[172:175], v[40:43]
	v_mfma_f32_16x16x32_bf16 v[32:35], v[132:135], v[194:197], v[32:35]
	v_mfma_f32_16x16x32_bf16 v[24:27], v[140:143], v[194:197], v[24:27]
	v_mfma_f32_16x16x32_bf16 v[20:23], v[132:135], v[216:219], v[20:23]
	v_mfma_f32_16x16x32_bf16 v[12:15], v[140:143], v[216:219], v[12:15]
	s_setprio 0
	s_setprio 1
	v_mfma_f32_16x16x32_bf16 v[52:55], v[144:147], v[160:163], v[52:55]
	v_mfma_f32_16x16x32_bf16 v[44:47], v[152:155], v[160:163], v[44:47]
	v_mfma_f32_16x16x32_bf16 v[36:39], v[144:147], v[168:171], v[36:39]
	v_mfma_f32_16x16x32_bf16 v[28:31], v[152:155], v[168:171], v[28:31]
	v_mfma_f32_16x16x32_bf16 v[16:19], v[144:147], v[190:193], v[16:19]
	v_mfma_f32_16x16x32_bf16 v[8:11], v[152:155], v[190:193], v[8:11]
	v_mfma_f32_16x16x32_bf16 v[4:7], v[144:147], v[198:201], v[4:7]
	v_mfma_f32_16x16x32_bf16 v[0:3], v[152:155], v[198:201], v[0:3]
	v_mfma_f32_16x16x32_bf16 v[52:55], v[148:151], v[164:167], v[52:55]
	v_mfma_f32_16x16x32_bf16 v[44:47], v[156:159], v[164:167], v[44:47]
	v_mfma_f32_16x16x32_bf16 v[36:39], v[148:151], v[172:175], v[36:39]
	v_mfma_f32_16x16x32_bf16 v[28:31], v[156:159], v[172:175], v[28:31]
	v_mfma_f32_16x16x32_bf16 v[16:19], v[148:151], v[194:197], v[16:19]
	v_mfma_f32_16x16x32_bf16 v[8:11], v[156:159], v[194:197], v[8:11]
	v_mfma_f32_16x16x32_bf16 v[4:7], v[148:151], v[216:219], v[4:7]
	v_mfma_f32_16x16x32_bf16 v[0:3], v[156:159], v[216:219], v[0:3]
	s_setprio 0
	s_barrier
	s_add_i32 s53, 0, 0x18000
	s_add_i32 s54, 0, 0x1c000
	v_add_u32_e32 v140, s53, v210
	v_add_u32_e32 v156, s54, v210
	ds_read_b128 v[128:131], v140
	ds_read_b128 v[132:135], v140 offset:1024
	ds_read_b128 v[136:139], v140 offset:2048
	ds_read_b128 v[140:143], v140 offset:3072
	ds_read_b128 v[144:147], v156
	ds_read_b128 v[148:151], v156 offset:1024
	ds_read_b128 v[152:155], v156 offset:2048
	ds_read_b128 v[156:159], v156 offset:3072
	s_add_u32 s20, s20, 0xb0000
	s_addc_u32 s21, s21, 0
	s_mov_b32 m0, s25
	v_lshl_add_u64 v[226:227], s[20:21], 0, v[176:177]
	ds_read_b128 v[160:163], v214 offset:32768
	ds_read_b128 v[164:167], v214 offset:33792
	ds_read_b128 v[168:171], v214 offset:34816
	ds_read_b128 v[172:175], v214 offset:35840
	ds_read_b128 v[190:193], v214 offset:36864
	ds_read_b128 v[194:197], v214 offset:37888
	ds_read_b128 v[198:201], v214 offset:38912
	ds_read_b128 v[216:219], v214 offset:39936
	global_load_lds_dwordx4 v[226:227], off
	v_lshl_add_u64 v[226:227], s[20:21], 0, v[178:179]
	s_mov_b32 m0, s26
	s_nop 0
	global_load_lds_dwordx4 v[226:227], off
	s_waitcnt vmcnt(8)
	s_waitcnt lgkmcnt(0)
	s_barrier
	s_setprio 1
	v_mfma_f32_16x16x32_bf16 v[124:127], v[128:131], v[160:163], v[124:127]
	v_mfma_f32_16x16x32_bf16 v[120:123], v[136:139], v[160:163], v[120:123]
	v_mfma_f32_16x16x32_bf16 v[112:115], v[128:131], v[168:171], v[112:115]
	v_mfma_f32_16x16x32_bf16 v[104:107], v[136:139], v[168:171], v[104:107]
	v_mfma_f32_16x16x32_bf16 v[96:99], v[128:131], v[190:193], v[96:99]
	v_mfma_f32_16x16x32_bf16 v[88:91], v[136:139], v[190:193], v[88:91]
	v_mfma_f32_16x16x32_bf16 v[84:87], v[128:131], v[198:201], v[84:87]
	v_mfma_f32_16x16x32_bf16 v[76:79], v[136:139], v[198:201], v[76:79]
	v_mfma_f32_16x16x32_bf16 v[124:127], v[132:135], v[164:167], v[124:127]
	v_mfma_f32_16x16x32_bf16 v[120:123], v[140:143], v[164:167], v[120:123]
	v_mfma_f32_16x16x32_bf16 v[112:115], v[132:135], v[172:175], v[112:115]
	v_mfma_f32_16x16x32_bf16 v[104:107], v[140:143], v[172:175], v[104:107]
	v_mfma_f32_16x16x32_bf16 v[96:99], v[132:135], v[194:197], v[96:99]
	v_mfma_f32_16x16x32_bf16 v[88:91], v[140:143], v[194:197], v[88:91]
	v_mfma_f32_16x16x32_bf16 v[84:87], v[132:135], v[216:219], v[84:87]
	v_mfma_f32_16x16x32_bf16 v[76:79], v[140:143], v[216:219], v[76:79]
	s_setprio 0
	s_setprio 1
	v_mfma_f32_16x16x32_bf16 v[116:119], v[144:147], v[160:163], v[116:119]
	v_mfma_f32_16x16x32_bf16 v[108:111], v[152:155], v[160:163], v[108:111]
	v_mfma_f32_16x16x32_bf16 v[100:103], v[144:147], v[168:171], v[100:103]
	v_mfma_f32_16x16x32_bf16 v[92:95], v[152:155], v[168:171], v[92:95]
	v_mfma_f32_16x16x32_bf16 v[80:83], v[144:147], v[190:193], v[80:83]
	v_mfma_f32_16x16x32_bf16 v[72:75], v[152:155], v[190:193], v[72:75]
	v_mfma_f32_16x16x32_bf16 v[68:71], v[144:147], v[198:201], v[68:71]
	v_mfma_f32_16x16x32_bf16 v[64:67], v[152:155], v[198:201], v[64:67]
	v_mfma_f32_16x16x32_bf16 v[116:119], v[148:151], v[164:167], v[116:119]
	v_mfma_f32_16x16x32_bf16 v[108:111], v[156:159], v[164:167], v[108:111]
	v_mfma_f32_16x16x32_bf16 v[100:103], v[148:151], v[172:175], v[100:103]
	v_mfma_f32_16x16x32_bf16 v[92:95], v[156:159], v[172:175], v[92:95]
	v_mfma_f32_16x16x32_bf16 v[80:83], v[148:151], v[194:197], v[80:83]
	v_mfma_f32_16x16x32_bf16 v[72:75], v[156:159], v[194:197], v[72:75]
	v_mfma_f32_16x16x32_bf16 v[68:71], v[148:151], v[216:219], v[68:71]
	v_mfma_f32_16x16x32_bf16 v[64:67], v[156:159], v[216:219], v[64:67]
	s_setprio 0
	s_barrier
	s_add_i32 s20, s53, s22
	v_lshl_add_u64 v[202:203], v[202:203], 0, s[10:11]
	s_mov_b32 m0, s20
	ds_read_b128 v[160:163], v214 offset:49152
	ds_read_b128 v[164:167], v214 offset:50176
	ds_read_b128 v[168:171], v214 offset:51200
	ds_read_b128 v[172:175], v214 offset:52224
	ds_read_b128 v[190:193], v214 offset:53248
	ds_read_b128 v[194:197], v214 offset:54272
	ds_read_b128 v[198:201], v214 offset:55296
	ds_read_b128 v[216:219], v214 offset:56320
	global_load_lds_dwordx4 v[202:203], off
	s_add_i32 m0, s20, 0x2000
	s_add_u32 s18, s18, 0xb0080
	v_lshl_add_u64 v[202:203], v[220:221], 0, s[10:11]
	s_addc_u32 s19, s19, 0
	s_add_i32 s20, s54, s22
	global_load_lds_dwordx4 v[202:203], off
	v_lshl_add_u64 v[202:203], s[18:19], 0, v[176:177]
	s_mov_b32 m0, s20
	s_nop 0
	global_load_lds_dwordx4 v[202:203], off
	v_lshl_add_u64 v[202:203], s[18:19], 0, v[178:179]
	s_add_i32 m0, s20, 0x2000
	s_nop 0
	global_load_lds_dwordx4 v[202:203], off
	v_lshl_add_u64 v[202:203], v[222:223], 0, s[10:11]
	s_mov_b32 m0, s29
	s_nop 0
	global_load_lds_dwordx4 v[202:203], off
	v_lshl_add_u64 v[202:203], v[224:225], 0, s[10:11]
	s_mov_b32 m0, s30
	s_nop 0
	global_load_lds_dwordx4 v[202:203], off
	s_waitcnt vmcnt(8)
	s_waitcnt lgkmcnt(0)
	s_barrier
	s_setprio 1
	v_mfma_f32_16x16x32_bf16 v[60:63], v[128:131], v[160:163], v[60:63]
	v_mfma_f32_16x16x32_bf16 v[56:59], v[136:139], v[160:163], v[56:59]
	v_mfma_f32_16x16x32_bf16 v[48:51], v[128:131], v[168:171], v[48:51]
	v_mfma_f32_16x16x32_bf16 v[40:43], v[136:139], v[168:171], v[40:43]
	v_mfma_f32_16x16x32_bf16 v[32:35], v[128:131], v[190:193], v[32:35]
	v_mfma_f32_16x16x32_bf16 v[24:27], v[136:139], v[190:193], v[24:27]
	v_mfma_f32_16x16x32_bf16 v[20:23], v[128:131], v[198:201], v[20:23]
	v_mfma_f32_16x16x32_bf16 v[12:15], v[136:139], v[198:201], v[12:15]
	v_mfma_f32_16x16x32_bf16 v[60:63], v[132:135], v[164:167], v[60:63]
	v_mfma_f32_16x16x32_bf16 v[56:59], v[140:143], v[164:167], v[56:59]
	v_mfma_f32_16x16x32_bf16 v[48:51], v[132:135], v[172:175], v[48:51]
	v_mfma_f32_16x16x32_bf16 v[40:43], v[140:143], v[172:175], v[40:43]
	v_mfma_f32_16x16x32_bf16 v[32:35], v[132:135], v[194:197], v[32:35]
	v_mfma_f32_16x16x32_bf16 v[24:27], v[140:143], v[194:197], v[24:27]
	v_mfma_f32_16x16x32_bf16 v[20:23], v[132:135], v[216:219], v[20:23]
	v_mfma_f32_16x16x32_bf16 v[12:15], v[140:143], v[216:219], v[12:15]
	s_setprio 0
	s_setprio 1
	v_mfma_f32_16x16x32_bf16 v[52:55], v[144:147], v[160:163], v[52:55]
	v_mfma_f32_16x16x32_bf16 v[44:47], v[152:155], v[160:163], v[44:47]
	v_mfma_f32_16x16x32_bf16 v[36:39], v[144:147], v[168:171], v[36:39]
	v_mfma_f32_16x16x32_bf16 v[28:31], v[152:155], v[168:171], v[28:31]
	v_mfma_f32_16x16x32_bf16 v[16:19], v[144:147], v[190:193], v[16:19]
	v_mfma_f32_16x16x32_bf16 v[8:11], v[152:155], v[190:193], v[8:11]
	v_mfma_f32_16x16x32_bf16 v[4:7], v[144:147], v[198:201], v[4:7]
	v_mfma_f32_16x16x32_bf16 v[0:3], v[152:155], v[198:201], v[0:3]
	v_mfma_f32_16x16x32_bf16 v[52:55], v[148:151], v[164:167], v[52:55]
	v_mfma_f32_16x16x32_bf16 v[44:47], v[156:159], v[164:167], v[44:47]
	v_mfma_f32_16x16x32_bf16 v[36:39], v[148:151], v[172:175], v[36:39]
	v_mfma_f32_16x16x32_bf16 v[28:31], v[156:159], v[172:175], v[28:31]
	v_mfma_f32_16x16x32_bf16 v[16:19], v[148:151], v[194:197], v[16:19]
	v_mfma_f32_16x16x32_bf16 v[8:11], v[156:159], v[194:197], v[8:11]
	v_mfma_f32_16x16x32_bf16 v[4:7], v[148:151], v[216:219], v[4:7]
	v_mfma_f32_16x16x32_bf16 v[0:3], v[156:159], v[216:219], v[0:3]
	s_setprio 0
	s_barrier
	s_add_i32 s52, s52, 2
	s_add_u32 s16, s16, 0x100
	s_addc_u32 s17, s17, 0
	s_add_u32 s50, s50, 0x100
	s_addc_u32 s51, s51, 0
	s_cmp_gt_u32 s52, 41
	s_cbranch_scc0 .LBB0_2476
	s_and_b64 vcc, exec, s[12:13]
	s_cbranch_vccz .LBB0_2479
	s_barrier

.Llsb_skip_22:
.LBB0_2504:
	s_add_u32 s35, s22, s34
	s_addc_u32 s40, s23, 0
	s_add_u32 s38, s35, 0x100
	s_addc_u32 s39, s40, 0
	s_and_b64 s[36:37], s[30:31], exec
	s_cselect_b32 s37, s25, s39
	s_cselect_b32 s36, s24, s38
	s_add_u32 s34, s14, s34
	s_addc_u32 s38, s15, 0
	s_add_u32 s34, s34, 0x100
	s_addc_u32 s38, s38, 0
	ds_read_b128 v[136:139], v131
	ds_read_b128 v[140:143], v131 offset:1024
	ds_read_b128 v[144:147], v131 offset:2048
	ds_read_b128 v[148:151], v131 offset:3072
	ds_read_b128 v[152:155], v132
	ds_read_b128 v[156:159], v132 offset:1024
	ds_read_b128 v[160:163], v132 offset:2048
	ds_read_b128 v[164:167], v132 offset:3072
	s_and_b64 s[30:31], s[30:31], exec
	s_cselect_b32 s39, s27, s38
	s_cselect_b32 s38, s26, s34
	s_add_u32 s42, s35, 0xb0080
	s_addc_u32 s43, s40, 0
	s_add_u32 s40, s38, 0xb0000
	s_addc_u32 s41, s39, 0
	s_add_i32 s75, 0, 0x1c000
	s_add_u32 s34, s36, 0xb0000
	s_addc_u32 s35, s37, 0
	s_add_i32 s74, s69, s49
	s_add_i32 s73, s74, 0x2000
	s_add_u32 s30, s38, 0xb0080
	s_addc_u32 s31, s39, 0
	s_add_i32 s77, s75, s49
	s_add_i32 s76, s77, 0x2000
	s_mov_b32 m0, s63
	v_lshl_add_u64 v[206:207], s[42:43], 0, v[176:177]
	ds_read_b128 v[168:171], v133
	ds_read_b128 v[172:175], v133 offset:1024
	ds_read_b128 v[180:183], v133 offset:2048
	ds_read_b128 v[184:187], v133 offset:3072
	ds_read_b128 v[188:191], v133 offset:4096
	ds_read_b128 v[192:195], v133 offset:5120
	ds_read_b128 v[196:199], v133 offset:6144
	ds_read_b128 v[200:203], v133 offset:7168
	global_load_lds_dwordx4 v[206:207], off
	v_lshl_add_u64 v[206:207], s[42:43], 0, v[178:179]
	s_mov_b32 m0, s64
	s_nop 0
	global_load_lds_dwordx4 v[206:207], off
	s_waitcnt vmcnt(8)
	s_waitcnt lgkmcnt(0)
	s_barrier
	s_setprio 1
	v_mfma_f32_16x16x32_bf16 v[124:127], v[136:139], v[168:171], v[124:127]
	v_mfma_f32_16x16x32_bf16 v[120:123], v[144:147], v[168:171], v[120:123]
	v_mfma_f32_16x16x32_bf16 v[116:119], v[136:139], v[180:183], v[116:119]
	v_mfma_f32_16x16x32_bf16 v[112:115], v[144:147], v[180:183], v[112:115]
	v_mfma_f32_16x16x32_bf16 v[108:111], v[136:139], v[188:191], v[108:111]
	v_mfma_f32_16x16x32_bf16 v[100:103], v[144:147], v[188:191], v[100:103]
	v_mfma_f32_16x16x32_bf16 v[92:95], v[136:139], v[196:199], v[92:95]
	v_mfma_f32_16x16x32_bf16 v[84:87], v[144:147], v[196:199], v[84:87]
	v_mfma_f32_16x16x32_bf16 v[124:127], v[140:143], v[172:175], v[124:127]
	v_mfma_f32_16x16x32_bf16 v[120:123], v[148:151], v[172:175], v[120:123]
	v_mfma_f32_16x16x32_bf16 v[116:119], v[140:143], v[184:187], v[116:119]
	v_mfma_f32_16x16x32_bf16 v[112:115], v[148:151], v[184:187], v[112:115]
	v_mfma_f32_16x16x32_bf16 v[108:111], v[140:143], v[192:195], v[108:111]
	v_mfma_f32_16x16x32_bf16 v[100:103], v[148:151], v[192:195], v[100:103]
	v_mfma_f32_16x16x32_bf16 v[92:95], v[140:143], v[200:203], v[92:95]
	v_mfma_f32_16x16x32_bf16 v[84:87], v[148:151], v[200:203], v[84:87]
	s_setprio 0
	s_setprio 1
	v_mfma_f32_16x16x32_bf16 v[104:107], v[152:155], v[168:171], v[104:107]
	v_mfma_f32_16x16x32_bf16 v[96:99], v[160:163], v[168:171], v[96:99]
	v_mfma_f32_16x16x32_bf16 v[88:91], v[152:155], v[180:183], v[88:91]
	v_mfma_f32_16x16x32_bf16 v[80:83], v[160:163], v[180:183], v[80:83]
	v_mfma_f32_16x16x32_bf16 v[76:79], v[152:155], v[188:191], v[76:79]
	v_mfma_f32_16x16x32_bf16 v[72:75], v[160:163], v[188:191], v[72:75]
	v_mfma_f32_16x16x32_bf16 v[68:71], v[152:155], v[196:199], v[68:71]
	v_mfma_f32_16x16x32_bf16 v[64:67], v[160:163], v[196:199], v[64:67]
	v_mfma_f32_16x16x32_bf16 v[104:107], v[156:159], v[172:175], v[104:107]
	v_mfma_f32_16x16x32_bf16 v[96:99], v[164:167], v[172:175], v[96:99]
	v_mfma_f32_16x16x32_bf16 v[88:91], v[156:159], v[184:187], v[88:91]
	v_mfma_f32_16x16x32_bf16 v[80:83], v[164:167], v[184:187], v[80:83]
	v_mfma_f32_16x16x32_bf16 v[76:79], v[156:159], v[192:195], v[76:79]
	v_mfma_f32_16x16x32_bf16 v[72:75], v[164:167], v[192:195], v[72:75]
	v_mfma_f32_16x16x32_bf16 v[68:71], v[156:159], v[200:203], v[68:71]
	v_mfma_f32_16x16x32_bf16 v[64:67], v[164:167], v[200:203], v[64:67]
	s_setprio 0
	s_barrier
	s_mov_b32 m0, s65
	v_lshl_add_u64 v[206:207], s[38:39], 0, v[176:177]
	ds_read_b128 v[168:171], v133 offset:16384
	ds_read_b128 v[172:175], v133 offset:17408
	ds_read_b128 v[180:183], v133 offset:18432
	ds_read_b128 v[184:187], v133 offset:19456
	ds_read_b128 v[188:191], v133 offset:20480
	ds_read_b128 v[192:195], v133 offset:21504
	ds_read_b128 v[196:199], v133 offset:22528
	ds_read_b128 v[200:203], v133 offset:23552
	global_load_lds_dwordx4 v[206:207], off
	v_lshl_add_u64 v[208:209], s[38:39], 0, v[178:179]
	s_mov_b32 m0, s66
	v_lshl_add_u64 v[210:211], s[40:41], 0, v[176:177]
	global_load_lds_dwordx4 v[208:209], off
	s_mov_b32 m0, s67
	v_lshl_add_u64 v[212:213], s[36:37], 0, v[178:179]
	global_load_lds_dwordx4 v[210:211], off
	v_lshl_add_u64 v[210:211], s[40:41], 0, v[178:179]
	s_mov_b32 m0, s68
	s_nop 0
	global_load_lds_dwordx4 v[210:211], off
	v_lshl_add_u64 v[210:211], s[36:37], 0, v[176:177]
	s_mov_b32 m0, s50
	s_nop 0
	global_load_lds_dwordx4 v[210:211], off
	s_mov_b32 m0, s51
	s_nop 0
	global_load_lds_dwordx4 v[212:213], off
	s_waitcnt vmcnt(8)
	s_waitcnt lgkmcnt(0)
	s_barrier
	s_setprio 1
	v_mfma_f32_16x16x32_bf16 v[60:63], v[136:139], v[168:171], v[60:63]
	v_mfma_f32_16x16x32_bf16 v[56:59], v[144:147], v[168:171], v[56:59]
	v_mfma_f32_16x16x32_bf16 v[52:55], v[136:139], v[180:183], v[52:55]
	v_mfma_f32_16x16x32_bf16 v[48:51], v[144:147], v[180:183], v[48:51]
	v_mfma_f32_16x16x32_bf16 v[40:43], v[136:139], v[188:191], v[40:43]
	v_mfma_f32_16x16x32_bf16 v[32:35], v[144:147], v[188:191], v[32:35]
	v_mfma_f32_16x16x32_bf16 v[24:27], v[136:139], v[196:199], v[24:27]
	v_mfma_f32_16x16x32_bf16 v[16:19], v[144:147], v[196:199], v[16:19]
	v_mfma_f32_16x16x32_bf16 v[60:63], v[140:143], v[172:175], v[60:63]
	v_mfma_f32_16x16x32_bf16 v[56:59], v[148:151], v[172:175], v[56:59]
	v_mfma_f32_16x16x32_bf16 v[52:55], v[140:143], v[184:187], v[52:55]
	v_mfma_f32_16x16x32_bf16 v[48:51], v[148:151], v[184:187], v[48:51]
	v_mfma_f32_16x16x32_bf16 v[40:43], v[140:143], v[192:195], v[40:43]
	v_mfma_f32_16x16x32_bf16 v[32:35], v[148:151], v[192:195], v[32:35]
	v_mfma_f32_16x16x32_bf16 v[24:27], v[140:143], v[200:203], v[24:27]
	v_mfma_f32_16x16x32_bf16 v[16:19], v[148:151], v[200:203], v[16:19]
	s_setprio 0
	s_setprio 1
	v_mfma_f32_16x16x32_bf16 v[44:47], v[152:155], v[168:171], v[44:47]
	v_mfma_f32_16x16x32_bf16 v[36:39], v[160:163], v[168:171], v[36:39]
	v_mfma_f32_16x16x32_bf16 v[28:31], v[152:155], v[180:183], v[28:31]
	v_mfma_f32_16x16x32_bf16 v[20:23], v[160:163], v[180:183], v[20:23]
	v_mfma_f32_16x16x32_bf16 v[12:15], v[152:155], v[188:191], v[12:15]
	v_mfma_f32_16x16x32_bf16 v[8:11], v[160:163], v[188:191], v[8:11]
	v_mfma_f32_16x16x32_bf16 v[4:7], v[152:155], v[196:199], v[4:7]
	v_mfma_f32_16x16x32_bf16 v[0:3], v[160:163], v[196:199], v[0:3]
	v_mfma_f32_16x16x32_bf16 v[44:47], v[156:159], v[172:175], v[44:47]
	v_mfma_f32_16x16x32_bf16 v[36:39], v[164:167], v[172:175], v[36:39]
	v_mfma_f32_16x16x32_bf16 v[28:31], v[156:159], v[184:187], v[28:31]
	v_mfma_f32_16x16x32_bf16 v[20:23], v[164:167], v[184:187], v[20:23]
	v_mfma_f32_16x16x32_bf16 v[12:15], v[156:159], v[192:195], v[12:15]
	v_mfma_f32_16x16x32_bf16 v[8:11], v[164:167], v[192:195], v[8:11]
	v_mfma_f32_16x16x32_bf16 v[4:7], v[156:159], v[200:203], v[4:7]
	v_mfma_f32_16x16x32_bf16 v[0:3], v[164:167], v[200:203], v[0:3]
	s_setprio 0
	s_barrier
	v_add_u32_e32 v135, s75, v128
	ds_read_b128 v[136:139], v134
	ds_read_b128 v[140:143], v134 offset:1024
	ds_read_b128 v[144:147], v134 offset:2048
	ds_read_b128 v[148:151], v134 offset:3072
	ds_read_b128 v[152:155], v135
	ds_read_b128 v[156:159], v135 offset:1024
	ds_read_b128 v[160:163], v135 offset:2048
	ds_read_b128 v[164:167], v135 offset:3072
	s_mov_b32 m0, s52
	v_lshl_add_u64 v[214:215], s[34:35], 0, v[176:177]
	ds_read_b128 v[168:171], v133 offset:32768
	ds_read_b128 v[172:175], v133 offset:33792
	ds_read_b128 v[180:183], v133 offset:34816
	ds_read_b128 v[184:187], v133 offset:35840
	ds_read_b128 v[188:191], v133 offset:36864
	ds_read_b128 v[192:195], v133 offset:37888
	ds_read_b128 v[196:199], v133 offset:38912
	ds_read_b128 v[200:203], v133 offset:39936
	global_load_lds_dwordx4 v[214:215], off
	v_lshl_add_u64 v[214:215], s[34:35], 0, v[178:179]
	s_mov_b32 m0, s53
	s_nop 0
	global_load_lds_dwordx4 v[214:215], off
	s_waitcnt vmcnt(8)
	s_waitcnt lgkmcnt(0)
	s_barrier
	s_setprio 1
	v_mfma_f32_16x16x32_bf16 v[124:127], v[136:139], v[168:171], v[124:127]
	v_mfma_f32_16x16x32_bf16 v[120:123], v[144:147], v[168:171], v[120:123]
	v_mfma_f32_16x16x32_bf16 v[116:119], v[136:139], v[180:183], v[116:119]
	v_mfma_f32_16x16x32_bf16 v[112:115], v[144:147], v[180:183], v[112:115]
	v_mfma_f32_16x16x32_bf16 v[108:111], v[136:139], v[188:191], v[108:111]
	v_mfma_f32_16x16x32_bf16 v[100:103], v[144:147], v[188:191], v[100:103]
	v_mfma_f32_16x16x32_bf16 v[92:95], v[136:139], v[196:199], v[92:95]
	v_mfma_f32_16x16x32_bf16 v[84:87], v[144:147], v[196:199], v[84:87]
	v_mfma_f32_16x16x32_bf16 v[124:127], v[140:143], v[172:175], v[124:127]
	v_mfma_f32_16x16x32_bf16 v[120:123], v[148:151], v[172:175], v[120:123]
	v_mfma_f32_16x16x32_bf16 v[116:119], v[140:143], v[184:187], v[116:119]
	v_mfma_f32_16x16x32_bf16 v[112:115], v[148:151], v[184:187], v[112:115]
	v_mfma_f32_16x16x32_bf16 v[108:111], v[140:143], v[192:195], v[108:111]
	v_mfma_f32_16x16x32_bf16 v[100:103], v[148:151], v[192:195], v[100:103]
	v_mfma_f32_16x16x32_bf16 v[92:95], v[140:143], v[200:203], v[92:95]
	v_mfma_f32_16x16x32_bf16 v[84:87], v[148:151], v[200:203], v[84:87]
	s_setprio 0
	s_setprio 1
	v_mfma_f32_16x16x32_bf16 v[104:107], v[152:155], v[168:171], v[104:107]
	v_mfma_f32_16x16x32_bf16 v[96:99], v[160:163], v[168:171], v[96:99]
	v_mfma_f32_16x16x32_bf16 v[88:91], v[152:155], v[180:183], v[88:91]
	v_mfma_f32_16x16x32_bf16 v[80:83], v[160:163], v[180:183], v[80:83]
	v_mfma_f32_16x16x32_bf16 v[76:79], v[152:155], v[188:191], v[76:79]
	v_mfma_f32_16x16x32_bf16 v[72:75], v[160:163], v[188:191], v[72:75]
	v_mfma_f32_16x16x32_bf16 v[68:71], v[152:155], v[196:199], v[68:71]
	v_mfma_f32_16x16x32_bf16 v[64:67], v[160:163], v[196:199], v[64:67]
	v_mfma_f32_16x16x32_bf16 v[104:107], v[156:159], v[172:175], v[104:107]
	v_mfma_f32_16x16x32_bf16 v[96:99], v[164:167], v[172:175], v[96:99]
	v_mfma_f32_16x16x32_bf16 v[88:91], v[156:159], v[184:187], v[88:91]
	v_mfma_f32_16x16x32_bf16 v[80:83], v[164:167], v[184:187], v[80:83]
	v_mfma_f32_16x16x32_bf16 v[76:79], v[156:159], v[192:195], v[76:79]
	v_mfma_f32_16x16x32_bf16 v[72:75], v[164:167], v[192:195], v[72:75]
	v_mfma_f32_16x16x32_bf16 v[68:71], v[156:159], v[200:203], v[68:71]
	v_mfma_f32_16x16x32_bf16 v[64:67], v[164:167], v[200:203], v[64:67]
	s_setprio 0
	s_barrier
	s_mov_b32 m0, s74
	v_lshl_add_u64 v[206:207], v[206:207], 0, s[10:11]
	ds_read_b128 v[168:171], v133 offset:49152
	ds_read_b128 v[172:175], v133 offset:50176
	ds_read_b128 v[180:183], v133 offset:51200
	ds_read_b128 v[184:187], v133 offset:52224
	ds_read_b128 v[188:191], v133 offset:53248
	ds_read_b128 v[192:195], v133 offset:54272
	ds_read_b128 v[196:199], v133 offset:55296
	ds_read_b128 v[200:203], v133 offset:56320
	global_load_lds_dwordx4 v[206:207], off
	v_lshl_add_u64 v[206:207], v[208:209], 0, s[10:11]
	s_mov_b32 m0, s73
	s_nop 0
	global_load_lds_dwordx4 v[206:207], off
	v_lshl_add_u64 v[206:207], s[30:31], 0, v[176:177]
	s_mov_b32 m0, s77
	s_nop 0
	global_load_lds_dwordx4 v[206:207], off
	v_lshl_add_u64 v[206:207], s[30:31], 0, v[178:179]
	s_mov_b32 m0, s76
	s_nop 0
	global_load_lds_dwordx4 v[206:207], off
	v_lshl_add_u64 v[206:207], v[210:211], 0, s[10:11]
	s_mov_b32 m0, s55
	s_nop 0
	global_load_lds_dwordx4 v[206:207], off
	v_lshl_add_u64 v[206:207], v[212:213], 0, s[10:11]
	s_mov_b32 m0, s56
	s_nop 0
	global_load_lds_dwordx4 v[206:207], off
	s_waitcnt vmcnt(8)
	s_waitcnt lgkmcnt(0)
	s_barrier
	s_setprio 1
	v_mfma_f32_16x16x32_bf16 v[60:63], v[136:139], v[168:171], v[60:63]
	v_mfma_f32_16x16x32_bf16 v[56:59], v[144:147], v[168:171], v[56:59]
	v_mfma_f32_16x16x32_bf16 v[52:55], v[136:139], v[180:183], v[52:55]
	v_mfma_f32_16x16x32_bf16 v[48:51], v[144:147], v[180:183], v[48:51]
	v_mfma_f32_16x16x32_bf16 v[40:43], v[136:139], v[188:191], v[40:43]
	v_mfma_f32_16x16x32_bf16 v[32:35], v[144:147], v[188:191], v[32:35]
	v_mfma_f32_16x16x32_bf16 v[24:27], v[136:139], v[196:199], v[24:27]
	v_mfma_f32_16x16x32_bf16 v[16:19], v[144:147], v[196:199], v[16:19]
	v_mfma_f32_16x16x32_bf16 v[60:63], v[140:143], v[172:175], v[60:63]
	v_mfma_f32_16x16x32_bf16 v[56:59], v[148:151], v[172:175], v[56:59]
	v_mfma_f32_16x16x32_bf16 v[52:55], v[140:143], v[184:187], v[52:55]
	v_mfma_f32_16x16x32_bf16 v[48:51], v[148:151], v[184:187], v[48:51]
	v_mfma_f32_16x16x32_bf16 v[40:43], v[140:143], v[192:195], v[40:43]
	v_mfma_f32_16x16x32_bf16 v[32:35], v[148:151], v[192:195], v[32:35]
	v_mfma_f32_16x16x32_bf16 v[24:27], v[140:143], v[200:203], v[24:27]
	v_mfma_f32_16x16x32_bf16 v[16:19], v[148:151], v[200:203], v[16:19]
	s_setprio 0
	s_setprio 1
	v_mfma_f32_16x16x32_bf16 v[44:47], v[152:155], v[168:171], v[44:47]
	v_mfma_f32_16x16x32_bf16 v[36:39], v[160:163], v[168:171], v[36:39]
	v_mfma_f32_16x16x32_bf16 v[28:31], v[152:155], v[180:183], v[28:31]
	v_mfma_f32_16x16x32_bf16 v[20:23], v[160:163], v[180:183], v[20:23]
	v_mfma_f32_16x16x32_bf16 v[12:15], v[152:155], v[188:191], v[12:15]
	v_mfma_f32_16x16x32_bf16 v[8:11], v[160:163], v[188:191], v[8:11]
	v_mfma_f32_16x16x32_bf16 v[4:7], v[152:155], v[196:199], v[4:7]
	v_mfma_f32_16x16x32_bf16 v[0:3], v[160:163], v[196:199], v[0:3]
	v_mfma_f32_16x16x32_bf16 v[44:47], v[156:159], v[172:175], v[44:47]
	v_mfma_f32_16x16x32_bf16 v[36:39], v[164:167], v[172:175], v[36:39]
	v_mfma_f32_16x16x32_bf16 v[28:31], v[156:159], v[184:187], v[28:31]
	v_mfma_f32_16x16x32_bf16 v[20:23], v[164:167], v[184:187], v[20:23]
	v_mfma_f32_16x16x32_bf16 v[12:15], v[156:159], v[192:195], v[12:15]
	v_mfma_f32_16x16x32_bf16 v[8:11], v[164:167], v[192:195], v[8:11]
	v_mfma_f32_16x16x32_bf16 v[4:7], v[156:159], v[200:203], v[4:7]
	v_mfma_f32_16x16x32_bf16 v[0:3], v[164:167], v[200:203], v[0:3]
	s_setprio 0
	s_barrier
	s_movk_i32 s34, 0x100
	s_andn2_b64 vcc, exec, s[28:29]
	s_mov_b64 s[30:31], -1
	s_mov_b64 s[28:29], 0
	s_cbranch_vccz .LBB0_2504
	s_and_b64 vcc, exec, s[12:13]
	s_cbranch_vccz .LBB0_2507
	s_barrier
